# stale-wait cleanup: 228 provably redundant lgkmcnt waits removed, combined with static first work item and asynchronous queue claim
# speedup vs baseline: 1.0067x; 1.0031x over previous
; #define PG8_STAGE(bufoff, gbase, voff) do { _Pragma("unroll") for (int _i = 0; _i < 2; ++_i) \
;         __builtin_amdgcn_global_load_lds((const unsigned*)((const char*)(gbase) + (voff)[_i]), (LAS unsigned*)(lds + (bufoff) + ldsw + _i * 8192), 16, 0, 0); } while (0)
; #define PG8_LDA(dst, b, h) do { _Pragma("unroll") for (int m = 0; m < 4; ++m) _Pragma("unroll") for (int k = 0; k < 2; ++k) dst[m][k] = *(const LAS bf16x8*)(lds + PG8_SA(b, h) + aoff + m * 2048 + k * 1024); } while (0)
; #define PG8_LDB(dst, b, h) do { _Pragma("unroll") for (int n = 0; n < 2; ++n) _Pragma("unroll") for (int k = 0; k < 2; ++k) dst[n][k] = *(const LAS bf16x8*)(lds + PG8_SB(b, h) + boff + n * 2048 + k * 1024); } while (0)
; #define PG8_WAIT_V(n) asm volatile("s_waitcnt vmcnt(" #n ")" ::: "memory")
; #define PG8_WAIT_L(n) asm volatile("s_waitcnt lgkmcnt(" #n ")" ::: "memory")
; template <class Epi>
; __device__ __forceinline__ void gemm_phase(LAS unsigned char* lds, const Gemm g, const Order& S, const Epi& E) {
;     ...
;         for (int t = 0; t < nt; t += 2) {
;             const bool last = (t == nt - 2);
;             const char* a1 = cA + (size_t)(t + 1) * kstep;
;             const char* a2 = last ? nA : cA + (size_t)(t + 2) * kstep; const char* b2 = last ? nB : cB + (size_t)(t + 2) * kstep;
;             const char* a3 = a2 + kstep; const char* b3 = b2 + kstep;
;             PG8_LDB(B0, 0, 0); PG8_LDB(B1, 0, 1); PG8_SCHED; PG8_LDA(At, 0, 0); PG8_STAGE(PG8_SA(1, 1), a1 + hstepA, voffA);
;             PG8_WAIT_V(8); PG8_WAIT_L(0); PG8_BAR; PG8_MMA(0, 0, At, B0); PG8_MMA(0, 1, At, B1); PG8_BAR; PG8_SCHED;
;             PG8_LDA(At, 0, 1); PG8_STAGE(PG8_SB(0, 0), b2, voffB); PG8_STAGE(PG8_SB(0, 1), b2 + hstepB, voffB); PG8_STAGE(PG8_SA(0, 0), a2, voffA);
;             PG8_WAIT_V(8); PG8_WAIT_L(0); PG8_BAR; PG8_MMA(1, 0, At, B0); PG8_MMA(1, 1, At, B1); PG8_BAR; PG8_SCHED;
;             PG8_LDB(B0, 1, 0); PG8_LDB(B1, 1, 1); PG8_SCHED; PG8_LDA(At, 1, 0); PG8_STAGE(PG8_SA(0, 1), a2 + hstepA, voffA);
;             PG8_WAIT_V(8); PG8_WAIT_L(0); PG8_BAR; PG8_MMA(0, 0, At, B0); PG8_MMA(0, 1, At, B1); PG8_BAR; PG8_SCHED;
;             PG8_LDA(At, 1, 1); PG8_STAGE(PG8_SB(1, 0), b3, voffB); PG8_STAGE(PG8_SB(1, 1), b3 + hstepB, voffB); PG8_STAGE(PG8_SA(1, 0), a3, voffA);
;             PG8_WAIT_V(8); PG8_WAIT_L(0); PG8_BAR; PG8_MMA(1, 0, At, B0); PG8_MMA(1, 1, At, B1); PG8_BAR; PG8_SCHED;
.LBB0_38:
	s_add_u32 s44, s42, 0x100
	s_addc_u32 s45, s43, 0
	s_add_i32 s18, 0, 0x10000
	s_cmp_eq_u32 s17, 40
	s_cselect_b32 s51, s1, s45
	s_cselect_b32 s50, s0, s44
	v_add_u32_e32 v140, s18, v143
	s_cselect_b32 s47, s41, s16
	s_cselect_b32 s46, s40, s15
	s_add_i32 s20, 0, 0x14000
	ds_read_b128 v[146:149], v140
	ds_read_b128 v[150:153], v140 offset:1024
	ds_read_b128 v[154:157], v140 offset:2048
	ds_read_b128 v[158:161], v140 offset:3072
	v_add_u32_e32 v140, s20, v143
	ds_read_b128 v[162:165], v140
	ds_read_b128 v[166:169], v140 offset:1024
	ds_read_b128 v[170:173], v140 offset:2048
	ds_read_b128 v[174:177], v140 offset:3072
	v_lshl_add_u64 v[140:141], s[42:43], 0, v[136:137]
	s_add_i32 m0, s4, 0xc000
	ds_read_b128 v[178:181], v145
	ds_read_b128 v[182:185], v145 offset:1024
	ds_read_b128 v[186:189], v145 offset:2048
	ds_read_b128 v[190:193], v145 offset:3072
	ds_read_b128 v[204:207], v145 offset:4096
	ds_read_b128 v[208:211], v145 offset:5120
	ds_read_b128 v[212:215], v145 offset:6144
	ds_read_b128 v[216:219], v145 offset:7168
	global_load_lds_dwordx4 v[140:141], off
	v_lshl_add_u64 v[140:141], s[42:43], 0, v[138:139]
	s_add_i32 m0, s4, 0xe000
	s_nop 0
	global_load_lds_dwordx4 v[140:141], off
	s_waitcnt vmcnt(8)
	s_waitcnt lgkmcnt(0)
	s_barrier
	s_setprio 1
	v_mfma_f32_16x16x32_bf16 v[126:129], v[146:149], v[178:181], v[126:129]
	v_mfma_f32_16x16x32_bf16 v[122:125], v[154:157], v[178:181], v[122:125]
	v_mfma_f32_16x16x32_bf16 v[114:117], v[146:149], v[186:189], v[114:117]
	v_mfma_f32_16x16x32_bf16 v[106:109], v[154:157], v[186:189], v[106:109]
	v_mfma_f32_16x16x32_bf16 v[98:101], v[146:149], v[204:207], v[98:101]
	v_mfma_f32_16x16x32_bf16 v[90:93], v[154:157], v[204:207], v[90:93]
	v_mfma_f32_16x16x32_bf16 v[82:85], v[146:149], v[212:215], v[82:85]
	v_mfma_f32_16x16x32_bf16 v[74:77], v[154:157], v[212:215], v[74:77]
	v_mfma_f32_16x16x32_bf16 v[126:129], v[150:153], v[182:185], v[126:129]
	v_mfma_f32_16x16x32_bf16 v[122:125], v[158:161], v[182:185], v[122:125]
	v_mfma_f32_16x16x32_bf16 v[114:117], v[150:153], v[190:193], v[114:117]
	v_mfma_f32_16x16x32_bf16 v[106:109], v[158:161], v[190:193], v[106:109]
	v_mfma_f32_16x16x32_bf16 v[98:101], v[150:153], v[208:211], v[98:101]
	v_mfma_f32_16x16x32_bf16 v[90:93], v[158:161], v[208:211], v[90:93]
	v_mfma_f32_16x16x32_bf16 v[82:85], v[150:153], v[216:219], v[82:85]
	v_mfma_f32_16x16x32_bf16 v[74:77], v[158:161], v[216:219], v[74:77]
	s_setprio 0
	s_setprio 1
	v_mfma_f32_16x16x32_bf16 v[118:121], v[162:165], v[178:181], v[118:121]
	v_mfma_f32_16x16x32_bf16 v[110:113], v[170:173], v[178:181], v[110:113]
	v_mfma_f32_16x16x32_bf16 v[102:105], v[162:165], v[186:189], v[102:105]
	v_mfma_f32_16x16x32_bf16 v[94:97], v[170:173], v[186:189], v[94:97]
	v_mfma_f32_16x16x32_bf16 v[86:89], v[162:165], v[204:207], v[86:89]
	v_mfma_f32_16x16x32_bf16 v[78:81], v[170:173], v[204:207], v[78:81]
	v_mfma_f32_16x16x32_bf16 v[70:73], v[162:165], v[212:215], v[70:73]
	v_mfma_f32_16x16x32_bf16 v[66:69], v[170:173], v[212:215], v[66:69]
	v_mfma_f32_16x16x32_bf16 v[118:121], v[166:169], v[182:185], v[118:121]
	v_mfma_f32_16x16x32_bf16 v[110:113], v[174:177], v[182:185], v[110:113]
	v_mfma_f32_16x16x32_bf16 v[102:105], v[166:169], v[190:193], v[102:105]
	v_mfma_f32_16x16x32_bf16 v[94:97], v[174:177], v[190:193], v[94:97]
	v_mfma_f32_16x16x32_bf16 v[86:89], v[166:169], v[208:211], v[86:89]
	v_mfma_f32_16x16x32_bf16 v[78:81], v[174:177], v[208:211], v[78:81]
	v_mfma_f32_16x16x32_bf16 v[70:73], v[166:169], v[216:219], v[70:73]
	v_mfma_f32_16x16x32_bf16 v[66:69], v[174:177], v[216:219], v[66:69]
	s_setprio 0
	s_barrier
	s_add_i32 s18, s18, s2
	v_lshl_add_u64 v[140:141], s[46:47], 0, v[194:195]
	s_mov_b32 m0, s18
	ds_read_b128 v[178:181], v145 offset:16384
	ds_read_b128 v[182:185], v145 offset:17408
	ds_read_b128 v[186:189], v145 offset:18432
	ds_read_b128 v[190:193], v145 offset:19456
	ds_read_b128 v[204:207], v145 offset:20480
	ds_read_b128 v[208:211], v145 offset:21504
	ds_read_b128 v[212:215], v145 offset:22528
	ds_read_b128 v[216:219], v145 offset:23552
	global_load_lds_dwordx4 v[140:141], off
	s_add_i32 m0, s18, 0x2000
	s_add_u32 s18, s46, 0xb0000
	v_lshl_add_u64 v[200:201], s[46:47], 0, v[130:131]
	s_addc_u32 s19, s47, 0
	s_add_i32 s20, s20, s2
	global_load_lds_dwordx4 v[200:201], off
	v_lshl_add_u64 v[220:221], s[18:19], 0, v[194:195]
	s_mov_b32 m0, s20
	v_lshl_add_u64 v[222:223], s[50:51], 0, v[132:133]
	global_load_lds_dwordx4 v[220:221], off
	v_lshl_add_u64 v[220:221], s[18:19], 0, v[130:131]
	s_add_i32 m0, s20, 0x2000
	s_nop 0
	global_load_lds_dwordx4 v[220:221], off
	v_lshl_add_u64 v[220:221], s[50:51], 0, v[134:135]
	s_mov_b32 m0, s4
	s_nop 0
	global_load_lds_dwordx4 v[220:221], off
	s_mov_b32 m0, s5
	s_nop 0
	global_load_lds_dwordx4 v[222:223], off
	s_waitcnt vmcnt(8)
	s_waitcnt lgkmcnt(0)
	s_barrier
; #define PG8_STAGE(bufoff, gbase, voff) do { _Pragma("unroll") for (int _i = 0; _i < 2; ++_i) \
;         __builtin_amdgcn_global_load_lds((const unsigned*)((const char*)(gbase) + (voff)[_i]), (LAS unsigned*)(lds + (bufoff) + ldsw + _i * 8192), 16, 0, 0); } while (0)
; #define PG8_LDA(dst, b, h) do { _Pragma("unroll") for (int m = 0; m < 4; ++m) _Pragma("unroll") for (int k = 0; k < 2; ++k) dst[m][k] = *(const LAS bf16x8*)(lds + PG8_SA(b, h) + aoff + m * 2048 + k * 1024); } while (0)
; #define PG8_LDB(dst, b, h) do { _Pragma("unroll") for (int n = 0; n < 2; ++n) _Pragma("unroll") for (int k = 0; k < 2; ++k) dst[n][k] = *(const LAS bf16x8*)(lds + PG8_SB(b, h) + boff + n * 2048 + k * 1024); } while (0)
; #define PG8_MMA(ai, bj, At, Bt) do { __builtin_amdgcn_s_setprio(1); _Pragma("unroll") for (int m = 0; m < 4; ++m) _Pragma("unroll") for (int n = 0; n < 2; ++n) _Pragma("unroll") for (int k = 0; k < 2; ++k) \
;         acc[ai][bj][m][n] = __builtin_amdgcn_mfma_f32_16x16x32_bf16(Bt[n][k], At[m][k], acc[ai][bj][m][n], 0, 0, 0); __builtin_amdgcn_s_setprio(0); } while (0)
; #define PG8_WAIT_V(n) asm volatile("s_waitcnt vmcnt(" #n ")" ::: "memory")
; #define PG8_WAIT_L(n) asm volatile("s_waitcnt lgkmcnt(" #n ")" ::: "memory")
; #define PG8_BAR __builtin_amdgcn_s_barrier()
; #define PG8_SCHED __builtin_amdgcn_sched_barrier(0)
; template <class Epi>
; __device__ __forceinline__ void gemm_phase(LAS unsigned char* lds, const Gemm g, const Order& S, const Epi& E) {
;     ...
;             PG8_WAIT_V(8); PG8_WAIT_L(0); PG8_BAR; PG8_MMA(1, 0, At, B0); PG8_MMA(1, 1, At, B1); PG8_BAR; PG8_SCHED;
;             PG8_LDB(B0, 1, 0); PG8_LDB(B1, 1, 1); PG8_SCHED; PG8_LDA(At, 1, 0); PG8_STAGE(PG8_SA(0, 1), a2 + hstepA, voffA);
;             PG8_WAIT_V(8); PG8_WAIT_L(0); PG8_BAR; PG8_MMA(0, 0, At, B0); PG8_MMA(0, 1, At, B1); PG8_BAR; PG8_SCHED;
;             PG8_LDA(At, 1, 1); PG8_STAGE(PG8_SB(1, 0), b3, voffB); PG8_STAGE(PG8_SB(1, 1), b3 + hstepB, voffB); PG8_STAGE(PG8_SA(1, 0), a3, voffA);
	s_setprio 1
	v_mfma_f32_16x16x32_bf16 v[62:65], v[146:149], v[178:181], v[62:65]
	v_mfma_f32_16x16x32_bf16 v[58:61], v[154:157], v[178:181], v[58:61]
	v_mfma_f32_16x16x32_bf16 v[50:53], v[146:149], v[186:189], v[50:53]
	v_mfma_f32_16x16x32_bf16 v[42:45], v[154:157], v[186:189], v[42:45]
	v_mfma_f32_16x16x32_bf16 v[34:37], v[146:149], v[204:207], v[34:37]
	v_mfma_f32_16x16x32_bf16 v[26:29], v[154:157], v[204:207], v[26:29]
	v_mfma_f32_16x16x32_bf16 v[18:21], v[146:149], v[212:215], v[18:21]
	v_mfma_f32_16x16x32_bf16 v[10:13], v[154:157], v[212:215], v[10:13]
	v_mfma_f32_16x16x32_bf16 v[62:65], v[150:153], v[182:185], v[62:65]
	v_mfma_f32_16x16x32_bf16 v[58:61], v[158:161], v[182:185], v[58:61]
	v_mfma_f32_16x16x32_bf16 v[50:53], v[150:153], v[190:193], v[50:53]
	v_mfma_f32_16x16x32_bf16 v[42:45], v[158:161], v[190:193], v[42:45]
	v_mfma_f32_16x16x32_bf16 v[34:37], v[150:153], v[208:211], v[34:37]
	v_mfma_f32_16x16x32_bf16 v[26:29], v[158:161], v[208:211], v[26:29]
	v_mfma_f32_16x16x32_bf16 v[18:21], v[150:153], v[216:219], v[18:21]
	v_mfma_f32_16x16x32_bf16 v[10:13], v[158:161], v[216:219], v[10:13]
	s_setprio 0
	s_setprio 1
	v_mfma_f32_16x16x32_bf16 v[54:57], v[162:165], v[178:181], v[54:57]
	v_mfma_f32_16x16x32_bf16 v[46:49], v[170:173], v[178:181], v[46:49]
	v_mfma_f32_16x16x32_bf16 v[38:41], v[162:165], v[186:189], v[38:41]
	v_mfma_f32_16x16x32_bf16 v[30:33], v[170:173], v[186:189], v[30:33]
	v_mfma_f32_16x16x32_bf16 v[22:25], v[162:165], v[204:207], v[22:25]
	v_mfma_f32_16x16x32_bf16 v[14:17], v[170:173], v[204:207], v[14:17]
	v_mfma_f32_16x16x32_bf16 v[6:9], v[162:165], v[212:215], v[6:9]
	v_mfma_f32_16x16x32_bf16 v[2:5], v[170:173], v[212:215], v[2:5]
	v_mfma_f32_16x16x32_bf16 v[54:57], v[166:169], v[182:185], v[54:57]
	v_mfma_f32_16x16x32_bf16 v[46:49], v[174:177], v[182:185], v[46:49]
	v_mfma_f32_16x16x32_bf16 v[38:41], v[166:169], v[190:193], v[38:41]
	v_mfma_f32_16x16x32_bf16 v[30:33], v[174:177], v[190:193], v[30:33]
	v_mfma_f32_16x16x32_bf16 v[22:25], v[166:169], v[208:211], v[22:25]
	v_mfma_f32_16x16x32_bf16 v[14:17], v[174:177], v[208:211], v[14:17]
	v_mfma_f32_16x16x32_bf16 v[6:9], v[166:169], v[216:219], v[6:9]
	v_mfma_f32_16x16x32_bf16 v[2:5], v[174:177], v[216:219], v[2:5]
	s_setprio 0
	s_barrier
	s_add_i32 s20, 0, 0x18000
	s_add_i32 s42, 0, 0x1c000
	v_add_u32_e32 v158, s20, v143
	v_add_u32_e32 v174, s42, v143
	ds_read_b128 v[146:149], v158
	ds_read_b128 v[150:153], v158 offset:1024
	ds_read_b128 v[154:157], v158 offset:2048
	ds_read_b128 v[158:161], v158 offset:3072
	ds_read_b128 v[162:165], v174
	ds_read_b128 v[166:169], v174 offset:1024
	ds_read_b128 v[170:173], v174 offset:2048
	ds_read_b128 v[174:177], v174 offset:3072
	s_add_u32 s18, s50, 0xb0000
	s_addc_u32 s19, s51, 0
	s_mov_b32 m0, s6
	v_lshl_add_u64 v[224:225], s[18:19], 0, v[134:135]
	ds_read_b128 v[178:181], v145 offset:32768
	ds_read_b128 v[182:185], v145 offset:33792
	ds_read_b128 v[186:189], v145 offset:34816
	ds_read_b128 v[190:193], v145 offset:35840
	ds_read_b128 v[204:207], v145 offset:36864
	ds_read_b128 v[208:211], v145 offset:37888
	ds_read_b128 v[212:215], v145 offset:38912
	ds_read_b128 v[216:219], v145 offset:39936
	global_load_lds_dwordx4 v[224:225], off
	v_lshl_add_u64 v[224:225], s[18:19], 0, v[132:133]
	s_mov_b32 m0, s7
	s_nop 0
	global_load_lds_dwordx4 v[224:225], off
	s_waitcnt vmcnt(8)
	s_waitcnt lgkmcnt(0)
	s_barrier
	s_setprio 1
	v_mfma_f32_16x16x32_bf16 v[126:129], v[146:149], v[178:181], v[126:129]
	v_mfma_f32_16x16x32_bf16 v[122:125], v[154:157], v[178:181], v[122:125]
	v_mfma_f32_16x16x32_bf16 v[114:117], v[146:149], v[186:189], v[114:117]
	v_mfma_f32_16x16x32_bf16 v[106:109], v[154:157], v[186:189], v[106:109]
	v_mfma_f32_16x16x32_bf16 v[98:101], v[146:149], v[204:207], v[98:101]
	v_mfma_f32_16x16x32_bf16 v[90:93], v[154:157], v[204:207], v[90:93]
	v_mfma_f32_16x16x32_bf16 v[82:85], v[146:149], v[212:215], v[82:85]
	v_mfma_f32_16x16x32_bf16 v[74:77], v[154:157], v[212:215], v[74:77]
	v_mfma_f32_16x16x32_bf16 v[126:129], v[150:153], v[182:185], v[126:129]
	v_mfma_f32_16x16x32_bf16 v[122:125], v[158:161], v[182:185], v[122:125]
	v_mfma_f32_16x16x32_bf16 v[114:117], v[150:153], v[190:193], v[114:117]
	v_mfma_f32_16x16x32_bf16 v[106:109], v[158:161], v[190:193], v[106:109]
	v_mfma_f32_16x16x32_bf16 v[98:101], v[150:153], v[208:211], v[98:101]
	v_mfma_f32_16x16x32_bf16 v[90:93], v[158:161], v[208:211], v[90:93]
	v_mfma_f32_16x16x32_bf16 v[82:85], v[150:153], v[216:219], v[82:85]
	v_mfma_f32_16x16x32_bf16 v[74:77], v[158:161], v[216:219], v[74:77]
	s_setprio 0
	s_setprio 1
	v_mfma_f32_16x16x32_bf16 v[118:121], v[162:165], v[178:181], v[118:121]
	v_mfma_f32_16x16x32_bf16 v[110:113], v[170:173], v[178:181], v[110:113]
	v_mfma_f32_16x16x32_bf16 v[102:105], v[162:165], v[186:189], v[102:105]
	v_mfma_f32_16x16x32_bf16 v[94:97], v[170:173], v[186:189], v[94:97]
	v_mfma_f32_16x16x32_bf16 v[86:89], v[162:165], v[204:207], v[86:89]
	v_mfma_f32_16x16x32_bf16 v[78:81], v[170:173], v[204:207], v[78:81]
	v_mfma_f32_16x16x32_bf16 v[70:73], v[162:165], v[212:215], v[70:73]
	v_mfma_f32_16x16x32_bf16 v[66:69], v[170:173], v[212:215], v[66:69]
	v_mfma_f32_16x16x32_bf16 v[118:121], v[166:169], v[182:185], v[118:121]
	v_mfma_f32_16x16x32_bf16 v[110:113], v[174:177], v[182:185], v[110:113]
	v_mfma_f32_16x16x32_bf16 v[102:105], v[166:169], v[190:193], v[102:105]
	v_mfma_f32_16x16x32_bf16 v[94:97], v[174:177], v[190:193], v[94:97]
	v_mfma_f32_16x16x32_bf16 v[86:89], v[166:169], v[208:211], v[86:89]
	v_mfma_f32_16x16x32_bf16 v[78:81], v[174:177], v[208:211], v[78:81]
	v_mfma_f32_16x16x32_bf16 v[70:73], v[166:169], v[216:219], v[70:73]
	v_mfma_f32_16x16x32_bf16 v[66:69], v[174:177], v[216:219], v[66:69]
	s_setprio 0
	s_barrier
; #define PG8_STAGE(bufoff, gbase, voff) do { _Pragma("unroll") for (int _i = 0; _i < 2; ++_i) \
;         __builtin_amdgcn_global_load_lds((const unsigned*)((const char*)(gbase) + (voff)[_i]), (LAS unsigned*)(lds + (bufoff) + ldsw + _i * 8192), 16, 0, 0); } while (0)
; #define PG8_LDA(dst, b, h) do { _Pragma("unroll") for (int m = 0; m < 4; ++m) _Pragma("unroll") for (int k = 0; k < 2; ++k) dst[m][k] = *(const LAS bf16x8*)(lds + PG8_SA(b, h) + aoff + m * 2048 + k * 1024); } while (0)
; #define PG8_MMA(ai, bj, At, Bt) do { __builtin_amdgcn_s_setprio(1); _Pragma("unroll") for (int m = 0; m < 4; ++m) _Pragma("unroll") for (int n = 0; n < 2; ++n) _Pragma("unroll") for (int k = 0; k < 2; ++k) \
;         acc[ai][bj][m][n] = __builtin_amdgcn_mfma_f32_16x16x32_bf16(Bt[n][k], At[m][k], acc[ai][bj][m][n], 0, 0, 0); __builtin_amdgcn_s_setprio(0); } while (0)
; #define PG8_WAIT_V(n) asm volatile("s_waitcnt vmcnt(" #n ")" ::: "memory")
; #define PG8_WAIT_L(n) asm volatile("s_waitcnt lgkmcnt(" #n ")" ::: "memory")
; #define PG8_BAR __builtin_amdgcn_s_barrier()
; #define PG8_SCHED __builtin_amdgcn_sched_barrier(0)
; template <class Epi>
; __device__ __forceinline__ void gemm_phase(LAS unsigned char* lds, const Gemm g, const Order& S, const Epi& E) {
;     ...
;             PG8_WAIT_V(8); PG8_WAIT_L(0); PG8_BAR; PG8_MMA(0, 0, At, B0); PG8_MMA(0, 1, At, B1); PG8_BAR; PG8_SCHED;
;             PG8_LDA(At, 1, 1); PG8_STAGE(PG8_SB(1, 0), b3, voffB); PG8_STAGE(PG8_SB(1, 1), b3 + hstepB, voffB); PG8_STAGE(PG8_SA(1, 0), a3, voffA);
;             PG8_WAIT_V(8); PG8_WAIT_L(0); PG8_BAR; PG8_MMA(1, 0, At, B0); PG8_MMA(1, 1, At, B1); PG8_BAR; PG8_SCHED;
;         }
;         if (wr == 0) PG8_BAR;
	s_add_i32 s18, s20, s2
	v_lshl_add_u64 v[140:141], v[140:141], 0, s[86:87]
	s_mov_b32 m0, s18
	ds_read_b128 v[178:181], v145 offset:49152
	ds_read_b128 v[182:185], v145 offset:50176
	ds_read_b128 v[186:189], v145 offset:51200
	ds_read_b128 v[190:193], v145 offset:52224
	ds_read_b128 v[204:207], v145 offset:53248
	ds_read_b128 v[208:211], v145 offset:54272
	ds_read_b128 v[212:215], v145 offset:55296
	ds_read_b128 v[216:219], v145 offset:56320
	global_load_lds_dwordx4 v[140:141], off
	s_add_i32 m0, s18, 0x2000
	s_add_u32 s18, s46, 0xb0080
	v_lshl_add_u64 v[140:141], v[200:201], 0, s[86:87]
	s_addc_u32 s19, s47, 0
	s_add_i32 s20, s42, s2
	global_load_lds_dwordx4 v[140:141], off
	v_lshl_add_u64 v[140:141], s[18:19], 0, v[194:195]
	s_mov_b32 m0, s20
	s_nop 0
	global_load_lds_dwordx4 v[140:141], off
	v_lshl_add_u64 v[140:141], s[18:19], 0, v[130:131]
	s_add_i32 m0, s20, 0x2000
	s_nop 0
	global_load_lds_dwordx4 v[140:141], off
	v_lshl_add_u64 v[140:141], v[220:221], 0, s[86:87]
	s_mov_b32 m0, s8
	s_nop 0
	global_load_lds_dwordx4 v[140:141], off
	v_lshl_add_u64 v[140:141], v[222:223], 0, s[86:87]
	s_mov_b32 m0, s9
	s_nop 0
	global_load_lds_dwordx4 v[140:141], off
	s_waitcnt vmcnt(8)
	s_waitcnt lgkmcnt(0)
	s_barrier
	s_setprio 1
	v_mfma_f32_16x16x32_bf16 v[62:65], v[146:149], v[178:181], v[62:65]
	v_mfma_f32_16x16x32_bf16 v[58:61], v[154:157], v[178:181], v[58:61]
	v_mfma_f32_16x16x32_bf16 v[50:53], v[146:149], v[186:189], v[50:53]
	v_mfma_f32_16x16x32_bf16 v[42:45], v[154:157], v[186:189], v[42:45]
	v_mfma_f32_16x16x32_bf16 v[34:37], v[146:149], v[204:207], v[34:37]
	v_mfma_f32_16x16x32_bf16 v[26:29], v[154:157], v[204:207], v[26:29]
	v_mfma_f32_16x16x32_bf16 v[18:21], v[146:149], v[212:215], v[18:21]
	v_mfma_f32_16x16x32_bf16 v[10:13], v[154:157], v[212:215], v[10:13]
	v_mfma_f32_16x16x32_bf16 v[62:65], v[150:153], v[182:185], v[62:65]
	v_mfma_f32_16x16x32_bf16 v[58:61], v[158:161], v[182:185], v[58:61]
	v_mfma_f32_16x16x32_bf16 v[50:53], v[150:153], v[190:193], v[50:53]
	v_mfma_f32_16x16x32_bf16 v[42:45], v[158:161], v[190:193], v[42:45]
	v_mfma_f32_16x16x32_bf16 v[34:37], v[150:153], v[208:211], v[34:37]
	v_mfma_f32_16x16x32_bf16 v[26:29], v[158:161], v[208:211], v[26:29]
	v_mfma_f32_16x16x32_bf16 v[18:21], v[150:153], v[216:219], v[18:21]
	v_mfma_f32_16x16x32_bf16 v[10:13], v[158:161], v[216:219], v[10:13]
	s_setprio 0
	s_setprio 1
	v_mfma_f32_16x16x32_bf16 v[54:57], v[162:165], v[178:181], v[54:57]
	v_mfma_f32_16x16x32_bf16 v[46:49], v[170:173], v[178:181], v[46:49]
	v_mfma_f32_16x16x32_bf16 v[38:41], v[162:165], v[186:189], v[38:41]
	v_mfma_f32_16x16x32_bf16 v[30:33], v[170:173], v[186:189], v[30:33]
	v_mfma_f32_16x16x32_bf16 v[22:25], v[162:165], v[204:207], v[22:25]
	v_mfma_f32_16x16x32_bf16 v[14:17], v[170:173], v[204:207], v[14:17]
	v_mfma_f32_16x16x32_bf16 v[6:9], v[162:165], v[212:215], v[6:9]
	v_mfma_f32_16x16x32_bf16 v[2:5], v[170:173], v[212:215], v[2:5]
	v_mfma_f32_16x16x32_bf16 v[54:57], v[166:169], v[182:185], v[54:57]
	v_mfma_f32_16x16x32_bf16 v[46:49], v[174:177], v[182:185], v[46:49]
	v_mfma_f32_16x16x32_bf16 v[38:41], v[166:169], v[190:193], v[38:41]
	v_mfma_f32_16x16x32_bf16 v[30:33], v[174:177], v[190:193], v[30:33]
	v_mfma_f32_16x16x32_bf16 v[22:25], v[166:169], v[208:211], v[22:25]
	v_mfma_f32_16x16x32_bf16 v[14:17], v[174:177], v[208:211], v[14:17]
	v_mfma_f32_16x16x32_bf16 v[6:9], v[166:169], v[216:219], v[6:9]
	v_mfma_f32_16x16x32_bf16 v[2:5], v[174:177], v[216:219], v[2:5]
	s_setprio 0
	s_barrier
	s_add_i32 s17, s17, 2
	s_add_u32 s15, s15, 0x100
	s_addc_u32 s16, s16, 0
	s_cmp_gt_u32 s17, 41
	s_mov_b64 s[42:43], s[44:45]
	s_cbranch_scc0 .LBB0_38
	s_and_b64 vcc, exec, s[38:39]
	s_cbranch_vccz .LBB0_41
	s_barrier

; #define PG8_STAGE(bufoff, gbase, voff) do { _Pragma("unroll") for (int _i = 0; _i < 2; ++_i) \
;         __builtin_amdgcn_global_load_lds((const unsigned*)((const char*)(gbase) + (voff)[_i]), (LAS unsigned*)(lds + (bufoff) + ldsw + _i * 8192), 16, 0, 0); } while (0)
; #define PG8_LDA(dst, b, h) do { _Pragma("unroll") for (int m = 0; m < 4; ++m) _Pragma("unroll") for (int k = 0; k < 2; ++k) dst[m][k] = *(const LAS bf16x8*)(lds + PG8_SA(b, h) + aoff + m * 2048 + k * 1024); } while (0)
; #define PG8_LDB(dst, b, h) do { _Pragma("unroll") for (int n = 0; n < 2; ++n) _Pragma("unroll") for (int k = 0; k < 2; ++k) dst[n][k] = *(const LAS bf16x8*)(lds + PG8_SB(b, h) + boff + n * 2048 + k * 1024); } while (0)
; #define PG8_MMA(ai, bj, At, Bt) do { __builtin_amdgcn_s_setprio(1); _Pragma("unroll") for (int m = 0; m < 4; ++m) _Pragma("unroll") for (int n = 0; n < 2; ++n) _Pragma("unroll") for (int k = 0; k < 2; ++k) \
;         acc[ai][bj][m][n] = __builtin_amdgcn_mfma_f32_16x16x32_bf16(Bt[n][k], At[m][k], acc[ai][bj][m][n], 0, 0, 0); __builtin_amdgcn_s_setprio(0); } while (0)
; #define PG8_WAIT_V(n) asm volatile("s_waitcnt vmcnt(" #n ")" ::: "memory")
; #define PG8_WAIT_L(n) asm volatile("s_waitcnt lgkmcnt(" #n ")" ::: "memory")
; #define PG8_BAR __builtin_amdgcn_s_barrier()
; #define PG8_SCHED __builtin_amdgcn_sched_barrier(0)
; template <class Epi>
; __device__ __forceinline__ void gemm_phase(LAS unsigned char* lds, const Gemm g, const Order& S, const Epi& E) {
;     ...
;         for (int t = 0; t < nt; t += 2) {
;             const bool last = (t == nt - 2);
;             const char* a1 = cA + (size_t)(t + 1) * kstep;
;             const char* a2 = last ? nA : cA + (size_t)(t + 2) * kstep; const char* b2 = last ? nB : cB + (size_t)(t + 2) * kstep;
;             const char* a3 = a2 + kstep; const char* b3 = b2 + kstep;
;             PG8_LDB(B0, 0, 0); PG8_LDB(B1, 0, 1); PG8_SCHED; PG8_LDA(At, 0, 0); PG8_STAGE(PG8_SA(1, 1), a1 + hstepA, voffA);
;             PG8_WAIT_V(8); PG8_WAIT_L(0); PG8_BAR; PG8_MMA(0, 0, At, B0); PG8_MMA(0, 1, At, B1); PG8_BAR; PG8_SCHED;
;             PG8_LDA(At, 0, 1); PG8_STAGE(PG8_SB(0, 0), b2, voffB); PG8_STAGE(PG8_SB(0, 1), b2 + hstepB, voffB); PG8_STAGE(PG8_SA(0, 0), a2, voffA);
;             PG8_WAIT_V(8); PG8_WAIT_L(0); PG8_BAR; PG8_MMA(1, 0, At, B0); PG8_MMA(1, 1, At, B1); PG8_BAR; PG8_SCHED;
.LBB0_71:
	s_add_u32 s15, s46, 0xfffc0080
	s_addc_u32 s16, s47, -1
	s_add_i32 s17, 0, 0x10000
	s_cmp_eq_u32 s14, 12
	s_cselect_b32 s49, s8, s16
	s_cselect_b32 s48, s9, s15
	s_cselect_b32 vcc_hi, s10, s13
	s_cselect_b32 vcc_lo, s11, s12
	s_add_i32 s15, 0, 0x14000
	v_add_u32_e32 v78, s17, v205
	v_add_u32_e32 v102, s15, v205
	ds_read_b128 v[66:69], v78
	ds_read_b128 v[70:73], v78 offset:1024
	ds_read_b128 v[74:77], v78 offset:2048
	ds_read_b128 v[78:81], v78 offset:3072
	ds_read_b128 v[90:93], v102
	ds_read_b128 v[94:97], v102 offset:1024
	ds_read_b128 v[98:101], v102 offset:2048
	ds_read_b128 v[102:105], v102 offset:3072
	v_lshl_add_u64 v[192:193], s[46:47], 0, v[188:189]
	s_add_i32 m0, s20, 0xc000
	ds_read_b128 v[162:165], v208
	ds_read_b128 v[166:169], v208 offset:1024
	ds_read_b128 v[170:173], v208 offset:2048
	ds_read_b128 v[174:177], v208 offset:3072
	ds_read_b128 v[210:213], v208 offset:4096
	ds_read_b128 v[214:217], v208 offset:5120
	ds_read_b128 v[218:221], v208 offset:6144
	ds_read_b128 v[222:225], v208 offset:7168
	global_load_lds_dwordx4 v[192:193], off
	v_lshl_add_u64 v[192:193], s[46:47], 0, v[190:191]
	s_add_i32 m0, s20, 0xe000
	s_nop 0
	global_load_lds_dwordx4 v[192:193], off
	s_waitcnt vmcnt(8)
	s_waitcnt lgkmcnt(0)
	s_barrier
	s_setprio 1
	v_mfma_f32_16x16x32_bf16 v[150:153], v[66:69], v[162:165], v[150:153]
	v_mfma_f32_16x16x32_bf16 v[146:149], v[74:77], v[162:165], v[146:149]
	v_mfma_f32_16x16x32_bf16 v[134:137], v[66:69], v[170:173], v[134:137]
	v_mfma_f32_16x16x32_bf16 v[130:133], v[74:77], v[170:173], v[130:133]
	v_mfma_f32_16x16x32_bf16 v[118:121], v[66:69], v[210:213], v[118:121]
	v_mfma_f32_16x16x32_bf16 v[114:117], v[74:77], v[210:213], v[114:117]
	v_mfma_f32_16x16x32_bf16 v[110:113], v[66:69], v[218:221], v[110:113]
	v_mfma_f32_16x16x32_bf16 v[106:109], v[74:77], v[218:221], v[106:109]
	v_mfma_f32_16x16x32_bf16 v[150:153], v[70:73], v[166:169], v[150:153]
	v_mfma_f32_16x16x32_bf16 v[146:149], v[78:81], v[166:169], v[146:149]
	v_mfma_f32_16x16x32_bf16 v[134:137], v[70:73], v[174:177], v[134:137]
	v_mfma_f32_16x16x32_bf16 v[130:133], v[78:81], v[174:177], v[130:133]
	v_mfma_f32_16x16x32_bf16 v[118:121], v[70:73], v[214:217], v[118:121]
	v_mfma_f32_16x16x32_bf16 v[114:117], v[78:81], v[214:217], v[114:117]
	v_mfma_f32_16x16x32_bf16 v[110:113], v[70:73], v[222:225], v[110:113]
	v_mfma_f32_16x16x32_bf16 v[106:109], v[78:81], v[222:225], v[106:109]
	s_setprio 0
	s_setprio 1
	v_mfma_f32_16x16x32_bf16 v[154:157], v[90:93], v[162:165], v[154:157]
	v_mfma_f32_16x16x32_bf16 v[158:161], v[98:101], v[162:165], v[158:161]
	v_mfma_f32_16x16x32_bf16 v[142:145], v[90:93], v[170:173], v[142:145]
	v_mfma_f32_16x16x32_bf16 v[138:141], v[98:101], v[170:173], v[138:141]
	v_mfma_f32_16x16x32_bf16 v[126:129], v[90:93], v[210:213], v[126:129]
	v_mfma_f32_16x16x32_bf16 v[122:125], v[98:101], v[210:213], v[122:125]
	v_mfma_f32_16x16x32_bf16 v[86:89], v[90:93], v[218:221], v[86:89]
	v_mfma_f32_16x16x32_bf16 v[82:85], v[98:101], v[218:221], v[82:85]
	v_mfma_f32_16x16x32_bf16 v[154:157], v[94:97], v[166:169], v[154:157]
	v_mfma_f32_16x16x32_bf16 v[158:161], v[102:105], v[166:169], v[158:161]
	v_mfma_f32_16x16x32_bf16 v[142:145], v[94:97], v[174:177], v[142:145]
	v_mfma_f32_16x16x32_bf16 v[138:141], v[102:105], v[174:177], v[138:141]
	v_mfma_f32_16x16x32_bf16 v[126:129], v[94:97], v[214:217], v[126:129]
	v_mfma_f32_16x16x32_bf16 v[122:125], v[102:105], v[214:217], v[122:125]
	v_mfma_f32_16x16x32_bf16 v[86:89], v[94:97], v[222:225], v[86:89]
	v_mfma_f32_16x16x32_bf16 v[82:85], v[102:105], v[222:225], v[82:85]
	s_setprio 0
	s_barrier
	s_add_i32 s16, s17, s2
	v_lshl_add_u64 v[192:193], vcc, 0, v[194:195]
	s_mov_b32 m0, s16
	ds_read_b128 v[162:165], v208 offset:16384
	ds_read_b128 v[166:169], v208 offset:17408
	ds_read_b128 v[170:173], v208 offset:18432
	ds_read_b128 v[174:177], v208 offset:19456
	ds_read_b128 v[210:213], v208 offset:20480
	ds_read_b128 v[214:217], v208 offset:21504
	ds_read_b128 v[218:221], v208 offset:22528
	ds_read_b128 v[222:225], v208 offset:23552
	global_load_lds_dwordx4 v[192:193], off
	s_add_i32 m0, s16, 0x2000
	s_add_u32 s16, vcc_lo, 0x40000
	v_lshl_add_u64 v[200:201], vcc, 0, v[178:179]
	s_addc_u32 s17, vcc_hi, 0
	s_add_i32 s15, s15, s2
	global_load_lds_dwordx4 v[200:201], off
	v_lshl_add_u64 v[226:227], s[16:17], 0, v[194:195]
	s_mov_b32 m0, s15
	v_lshl_add_u64 v[228:229], s[48:49], 0, v[180:181]
	global_load_lds_dwordx4 v[226:227], off
	v_lshl_add_u64 v[226:227], s[16:17], 0, v[178:179]
	s_add_i32 m0, s15, 0x2000
	s_nop 0
	global_load_lds_dwordx4 v[226:227], off
	v_lshl_add_u64 v[226:227], s[48:49], 0, v[182:183]
	s_mov_b32 m0, s20
	s_nop 0
	global_load_lds_dwordx4 v[226:227], off
	s_mov_b32 m0, s88
	s_nop 0
	global_load_lds_dwordx4 v[228:229], off
	s_waitcnt vmcnt(8)
	s_waitcnt lgkmcnt(0)
	s_barrier
; #define PG8_STAGE(bufoff, gbase, voff) do { _Pragma("unroll") for (int _i = 0; _i < 2; ++_i) \
;         __builtin_amdgcn_global_load_lds((const unsigned*)((const char*)(gbase) + (voff)[_i]), (LAS unsigned*)(lds + (bufoff) + ldsw + _i * 8192), 16, 0, 0); } while (0)
; #define PG8_LDA(dst, b, h) do { _Pragma("unroll") for (int m = 0; m < 4; ++m) _Pragma("unroll") for (int k = 0; k < 2; ++k) dst[m][k] = *(const LAS bf16x8*)(lds + PG8_SA(b, h) + aoff + m * 2048 + k * 1024); } while (0)
; #define PG8_LDB(dst, b, h) do { _Pragma("unroll") for (int n = 0; n < 2; ++n) _Pragma("unroll") for (int k = 0; k < 2; ++k) dst[n][k] = *(const LAS bf16x8*)(lds + PG8_SB(b, h) + boff + n * 2048 + k * 1024); } while (0)
; #define PG8_MMA(ai, bj, At, Bt) do { __builtin_amdgcn_s_setprio(1); _Pragma("unroll") for (int m = 0; m < 4; ++m) _Pragma("unroll") for (int n = 0; n < 2; ++n) _Pragma("unroll") for (int k = 0; k < 2; ++k) \
;         acc[ai][bj][m][n] = __builtin_amdgcn_mfma_f32_16x16x32_bf16(Bt[n][k], At[m][k], acc[ai][bj][m][n], 0, 0, 0); __builtin_amdgcn_s_setprio(0); } while (0)
; #define PG8_WAIT_V(n) asm volatile("s_waitcnt vmcnt(" #n ")" ::: "memory")
; #define PG8_WAIT_L(n) asm volatile("s_waitcnt lgkmcnt(" #n ")" ::: "memory")
; #define PG8_BAR __builtin_amdgcn_s_barrier()
; #define PG8_SCHED __builtin_amdgcn_sched_barrier(0)
; template <class Epi>
; __device__ __forceinline__ void gemm_phase(LAS unsigned char* lds, const Gemm g, const Order& S, const Epi& E) {
;     ...
;             PG8_WAIT_V(8); PG8_WAIT_L(0); PG8_BAR; PG8_MMA(1, 0, At, B0); PG8_MMA(1, 1, At, B1); PG8_BAR; PG8_SCHED;
;             PG8_LDB(B0, 1, 0); PG8_LDB(B1, 1, 1); PG8_SCHED; PG8_LDA(At, 1, 0); PG8_STAGE(PG8_SA(0, 1), a2 + hstepA, voffA);
;             PG8_WAIT_V(8); PG8_WAIT_L(0); PG8_BAR; PG8_MMA(0, 0, At, B0); PG8_MMA(0, 1, At, B1); PG8_BAR; PG8_SCHED;
;             PG8_LDA(At, 1, 1); PG8_STAGE(PG8_SB(1, 0), b3, voffB); PG8_STAGE(PG8_SB(1, 1), b3 + hstepB, voffB); PG8_STAGE(PG8_SA(1, 0), a3, voffA);
	s_setprio 1
	v_mfma_f32_16x16x32_bf16 v[54:57], v[66:69], v[162:165], v[54:57]
	v_mfma_f32_16x16x32_bf16 v[50:53], v[74:77], v[162:165], v[50:53]
	v_mfma_f32_16x16x32_bf16 v[38:41], v[66:69], v[170:173], v[38:41]
	v_mfma_f32_16x16x32_bf16 v[34:37], v[74:77], v[170:173], v[34:37]
	v_mfma_f32_16x16x32_bf16 v[22:25], v[66:69], v[210:213], v[22:25]
	v_mfma_f32_16x16x32_bf16 v[18:21], v[74:77], v[210:213], v[18:21]
	v_mfma_f32_16x16x32_bf16 v[14:17], v[66:69], v[218:221], v[14:17]
	v_mfma_f32_16x16x32_bf16 v[10:13], v[74:77], v[218:221], v[10:13]
	v_mfma_f32_16x16x32_bf16 v[54:57], v[70:73], v[166:169], v[54:57]
	v_mfma_f32_16x16x32_bf16 v[50:53], v[78:81], v[166:169], v[50:53]
	v_mfma_f32_16x16x32_bf16 v[38:41], v[70:73], v[174:177], v[38:41]
	v_mfma_f32_16x16x32_bf16 v[34:37], v[78:81], v[174:177], v[34:37]
	v_mfma_f32_16x16x32_bf16 v[22:25], v[70:73], v[214:217], v[22:25]
	v_mfma_f32_16x16x32_bf16 v[18:21], v[78:81], v[214:217], v[18:21]
	v_mfma_f32_16x16x32_bf16 v[14:17], v[70:73], v[222:225], v[14:17]
	v_mfma_f32_16x16x32_bf16 v[10:13], v[78:81], v[222:225], v[10:13]
	s_setprio 0
	s_setprio 1
	v_mfma_f32_16x16x32_bf16 v[58:61], v[90:93], v[162:165], v[58:61]
	v_mfma_f32_16x16x32_bf16 v[62:65], v[98:101], v[162:165], v[62:65]
	v_mfma_f32_16x16x32_bf16 v[46:49], v[90:93], v[170:173], v[46:49]
	v_mfma_f32_16x16x32_bf16 v[42:45], v[98:101], v[170:173], v[42:45]
	v_mfma_f32_16x16x32_bf16 v[30:33], v[90:93], v[210:213], v[30:33]
	v_mfma_f32_16x16x32_bf16 v[26:29], v[98:101], v[210:213], v[26:29]
	v_mfma_f32_16x16x32_bf16 v[6:9], v[90:93], v[218:221], v[6:9]
	v_mfma_f32_16x16x32_bf16 v[2:5], v[98:101], v[218:221], v[2:5]
	v_mfma_f32_16x16x32_bf16 v[58:61], v[94:97], v[166:169], v[58:61]
	v_mfma_f32_16x16x32_bf16 v[62:65], v[102:105], v[166:169], v[62:65]
	v_mfma_f32_16x16x32_bf16 v[46:49], v[94:97], v[174:177], v[46:49]
	v_mfma_f32_16x16x32_bf16 v[42:45], v[102:105], v[174:177], v[42:45]
	v_mfma_f32_16x16x32_bf16 v[30:33], v[94:97], v[214:217], v[30:33]
	v_mfma_f32_16x16x32_bf16 v[26:29], v[102:105], v[214:217], v[26:29]
	v_mfma_f32_16x16x32_bf16 v[6:9], v[94:97], v[222:225], v[6:9]
	v_mfma_f32_16x16x32_bf16 v[2:5], v[102:105], v[222:225], v[2:5]
	s_setprio 0
	s_barrier
	s_add_i32 s15, 0, 0x18000
	s_add_i32 s18, 0, 0x1c000
	v_add_u32_e32 v78, s15, v205
	v_add_u32_e32 v102, s18, v205
	ds_read_b128 v[66:69], v78
	ds_read_b128 v[70:73], v78 offset:1024
	ds_read_b128 v[74:77], v78 offset:2048
	ds_read_b128 v[78:81], v78 offset:3072
	ds_read_b128 v[90:93], v102
	ds_read_b128 v[94:97], v102 offset:1024
	ds_read_b128 v[98:101], v102 offset:2048
	ds_read_b128 v[102:105], v102 offset:3072
	s_add_u32 s16, s48, 0x40000
	s_addc_u32 s17, s49, 0
	s_mov_b32 m0, s89
	v_lshl_add_u64 v[236:237], s[16:17], 0, v[182:183]
	ds_read_b128 v[162:165], v208 offset:32768
	ds_read_b128 v[166:169], v208 offset:33792
	ds_read_b128 v[170:173], v208 offset:34816
	ds_read_b128 v[174:177], v208 offset:35840
	ds_read_b128 v[210:213], v208 offset:36864
	ds_read_b128 v[214:217], v208 offset:37888
	ds_read_b128 v[218:221], v208 offset:38912
	ds_read_b128 v[222:225], v208 offset:39936
	global_load_lds_dwordx4 v[236:237], off
	v_lshl_add_u64 v[236:237], s[16:17], 0, v[180:181]
	s_mov_b32 m0, s93
	s_nop 0
	global_load_lds_dwordx4 v[236:237], off
	s_waitcnt vmcnt(8)
	s_waitcnt lgkmcnt(0)
	s_barrier
	s_setprio 1
	v_mfma_f32_16x16x32_bf16 v[150:153], v[66:69], v[162:165], v[150:153]
	v_mfma_f32_16x16x32_bf16 v[146:149], v[74:77], v[162:165], v[146:149]
	v_mfma_f32_16x16x32_bf16 v[134:137], v[66:69], v[170:173], v[134:137]
	v_mfma_f32_16x16x32_bf16 v[130:133], v[74:77], v[170:173], v[130:133]
	v_mfma_f32_16x16x32_bf16 v[118:121], v[66:69], v[210:213], v[118:121]
	v_mfma_f32_16x16x32_bf16 v[114:117], v[74:77], v[210:213], v[114:117]
	v_mfma_f32_16x16x32_bf16 v[110:113], v[66:69], v[218:221], v[110:113]
	v_mfma_f32_16x16x32_bf16 v[106:109], v[74:77], v[218:221], v[106:109]
	v_mfma_f32_16x16x32_bf16 v[150:153], v[70:73], v[166:169], v[150:153]
	v_mfma_f32_16x16x32_bf16 v[146:149], v[78:81], v[166:169], v[146:149]
	v_mfma_f32_16x16x32_bf16 v[134:137], v[70:73], v[174:177], v[134:137]
	v_mfma_f32_16x16x32_bf16 v[130:133], v[78:81], v[174:177], v[130:133]
	v_mfma_f32_16x16x32_bf16 v[118:121], v[70:73], v[214:217], v[118:121]
	v_mfma_f32_16x16x32_bf16 v[114:117], v[78:81], v[214:217], v[114:117]
	v_mfma_f32_16x16x32_bf16 v[110:113], v[70:73], v[222:225], v[110:113]
	v_mfma_f32_16x16x32_bf16 v[106:109], v[78:81], v[222:225], v[106:109]
	s_setprio 0
	s_setprio 1
	v_mfma_f32_16x16x32_bf16 v[154:157], v[90:93], v[162:165], v[154:157]
	v_mfma_f32_16x16x32_bf16 v[158:161], v[98:101], v[162:165], v[158:161]
	v_mfma_f32_16x16x32_bf16 v[142:145], v[90:93], v[170:173], v[142:145]
	v_mfma_f32_16x16x32_bf16 v[138:141], v[98:101], v[170:173], v[138:141]
	v_mfma_f32_16x16x32_bf16 v[126:129], v[90:93], v[210:213], v[126:129]
	v_mfma_f32_16x16x32_bf16 v[122:125], v[98:101], v[210:213], v[122:125]
	v_mfma_f32_16x16x32_bf16 v[86:89], v[90:93], v[218:221], v[86:89]
	v_mfma_f32_16x16x32_bf16 v[82:85], v[98:101], v[218:221], v[82:85]
	v_mfma_f32_16x16x32_bf16 v[154:157], v[94:97], v[166:169], v[154:157]
	v_mfma_f32_16x16x32_bf16 v[158:161], v[102:105], v[166:169], v[158:161]
	v_mfma_f32_16x16x32_bf16 v[142:145], v[94:97], v[174:177], v[142:145]
	v_mfma_f32_16x16x32_bf16 v[138:141], v[102:105], v[174:177], v[138:141]
	v_mfma_f32_16x16x32_bf16 v[126:129], v[94:97], v[214:217], v[126:129]
	v_mfma_f32_16x16x32_bf16 v[122:125], v[102:105], v[214:217], v[122:125]
	v_mfma_f32_16x16x32_bf16 v[86:89], v[94:97], v[222:225], v[86:89]
	v_mfma_f32_16x16x32_bf16 v[82:85], v[102:105], v[222:225], v[82:85]
	s_setprio 0
	s_barrier
; #define PG8_STAGE(bufoff, gbase, voff) do { _Pragma("unroll") for (int _i = 0; _i < 2; ++_i) \
;         __builtin_amdgcn_global_load_lds((const unsigned*)((const char*)(gbase) + (voff)[_i]), (LAS unsigned*)(lds + (bufoff) + ldsw + _i * 8192), 16, 0, 0); } while (0)
; #define PG8_LDA(dst, b, h) do { _Pragma("unroll") for (int m = 0; m < 4; ++m) _Pragma("unroll") for (int k = 0; k < 2; ++k) dst[m][k] = *(const LAS bf16x8*)(lds + PG8_SA(b, h) + aoff + m * 2048 + k * 1024); } while (0)
; #define PG8_MMA(ai, bj, At, Bt) do { __builtin_amdgcn_s_setprio(1); _Pragma("unroll") for (int m = 0; m < 4; ++m) _Pragma("unroll") for (int n = 0; n < 2; ++n) _Pragma("unroll") for (int k = 0; k < 2; ++k) \
;         acc[ai][bj][m][n] = __builtin_amdgcn_mfma_f32_16x16x32_bf16(Bt[n][k], At[m][k], acc[ai][bj][m][n], 0, 0, 0); __builtin_amdgcn_s_setprio(0); } while (0)
; #define PG8_WAIT_V(n) asm volatile("s_waitcnt vmcnt(" #n ")" ::: "memory")
; #define PG8_WAIT_L(n) asm volatile("s_waitcnt lgkmcnt(" #n ")" ::: "memory")
; #define PG8_BAR __builtin_amdgcn_s_barrier()
; #define PG8_SCHED __builtin_amdgcn_sched_barrier(0)
; template <class Epi>
; __device__ __forceinline__ void gemm_phase(LAS unsigned char* lds, const Gemm g, const Order& S, const Epi& E) {
;     ...
;             PG8_WAIT_V(8); PG8_WAIT_L(0); PG8_BAR; PG8_MMA(0, 0, At, B0); PG8_MMA(0, 1, At, B1); PG8_BAR; PG8_SCHED;
;             PG8_LDA(At, 1, 1); PG8_STAGE(PG8_SB(1, 0), b3, voffB); PG8_STAGE(PG8_SB(1, 1), b3 + hstepB, voffB); PG8_STAGE(PG8_SA(1, 0), a3, voffA);
;             PG8_WAIT_V(8); PG8_WAIT_L(0); PG8_BAR; PG8_MMA(1, 0, At, B0); PG8_MMA(1, 1, At, B1); PG8_BAR; PG8_SCHED;
;         }
;         if (wr == 0) PG8_BAR;
	s_add_i32 s15, s15, s2
	v_lshl_add_u64 v[192:193], v[192:193], 0, s[86:87]
	s_mov_b32 m0, s15
	ds_read_b128 v[162:165], v208 offset:49152
	ds_read_b128 v[166:169], v208 offset:50176
	ds_read_b128 v[170:173], v208 offset:51200
	ds_read_b128 v[174:177], v208 offset:52224
	ds_read_b128 v[210:213], v208 offset:53248
	ds_read_b128 v[214:217], v208 offset:54272
	ds_read_b128 v[218:221], v208 offset:55296
	ds_read_b128 v[222:225], v208 offset:56320
	global_load_lds_dwordx4 v[192:193], off
	s_add_i32 m0, s15, 0x2000
	s_add_u32 s16, vcc_lo, 0x40080
	v_lshl_add_u64 v[192:193], v[200:201], 0, s[86:87]
	s_addc_u32 s17, vcc_hi, 0
	s_add_i32 s15, s18, s2
	global_load_lds_dwordx4 v[192:193], off
	v_lshl_add_u64 v[192:193], s[16:17], 0, v[194:195]
	s_mov_b32 m0, s15
	s_nop 0
	global_load_lds_dwordx4 v[192:193], off
	v_lshl_add_u64 v[192:193], s[16:17], 0, v[178:179]
	s_add_i32 m0, s15, 0x2000
	s_nop 0
	global_load_lds_dwordx4 v[192:193], off
	v_lshl_add_u64 v[192:193], v[226:227], 0, s[86:87]
	s_mov_b32 m0, s4
	s_nop 0
	global_load_lds_dwordx4 v[192:193], off
	v_lshl_add_u64 v[192:193], v[228:229], 0, s[86:87]
	s_mov_b32 m0, s5
	s_nop 0
	global_load_lds_dwordx4 v[192:193], off
	s_waitcnt vmcnt(8)
	s_waitcnt lgkmcnt(0)
	s_barrier
	s_setprio 1
	v_mfma_f32_16x16x32_bf16 v[54:57], v[66:69], v[162:165], v[54:57]
	v_mfma_f32_16x16x32_bf16 v[50:53], v[74:77], v[162:165], v[50:53]
	v_mfma_f32_16x16x32_bf16 v[38:41], v[66:69], v[170:173], v[38:41]
	v_mfma_f32_16x16x32_bf16 v[34:37], v[74:77], v[170:173], v[34:37]
	v_mfma_f32_16x16x32_bf16 v[22:25], v[66:69], v[210:213], v[22:25]
	v_mfma_f32_16x16x32_bf16 v[18:21], v[74:77], v[210:213], v[18:21]
	v_mfma_f32_16x16x32_bf16 v[14:17], v[66:69], v[218:221], v[14:17]
	v_mfma_f32_16x16x32_bf16 v[10:13], v[74:77], v[218:221], v[10:13]
	v_mfma_f32_16x16x32_bf16 v[54:57], v[70:73], v[166:169], v[54:57]
	v_mfma_f32_16x16x32_bf16 v[50:53], v[78:81], v[166:169], v[50:53]
	v_mfma_f32_16x16x32_bf16 v[38:41], v[70:73], v[174:177], v[38:41]
	v_mfma_f32_16x16x32_bf16 v[34:37], v[78:81], v[174:177], v[34:37]
	v_mfma_f32_16x16x32_bf16 v[22:25], v[70:73], v[214:217], v[22:25]
	v_mfma_f32_16x16x32_bf16 v[18:21], v[78:81], v[214:217], v[18:21]
	v_mfma_f32_16x16x32_bf16 v[14:17], v[70:73], v[222:225], v[14:17]
	v_mfma_f32_16x16x32_bf16 v[10:13], v[78:81], v[222:225], v[10:13]
	s_setprio 0
	s_setprio 1
	v_mfma_f32_16x16x32_bf16 v[58:61], v[90:93], v[162:165], v[58:61]
	v_mfma_f32_16x16x32_bf16 v[62:65], v[98:101], v[162:165], v[62:65]
	v_mfma_f32_16x16x32_bf16 v[46:49], v[90:93], v[170:173], v[46:49]
	v_mfma_f32_16x16x32_bf16 v[42:45], v[98:101], v[170:173], v[42:45]
	v_mfma_f32_16x16x32_bf16 v[30:33], v[90:93], v[210:213], v[30:33]
	v_mfma_f32_16x16x32_bf16 v[26:29], v[98:101], v[210:213], v[26:29]
	v_mfma_f32_16x16x32_bf16 v[6:9], v[90:93], v[218:221], v[6:9]
	v_mfma_f32_16x16x32_bf16 v[2:5], v[98:101], v[218:221], v[2:5]
	v_mfma_f32_16x16x32_bf16 v[58:61], v[94:97], v[166:169], v[58:61]
	v_mfma_f32_16x16x32_bf16 v[62:65], v[102:105], v[166:169], v[62:65]
	v_mfma_f32_16x16x32_bf16 v[46:49], v[94:97], v[174:177], v[46:49]
	v_mfma_f32_16x16x32_bf16 v[42:45], v[102:105], v[174:177], v[42:45]
	v_mfma_f32_16x16x32_bf16 v[30:33], v[94:97], v[214:217], v[30:33]
	v_mfma_f32_16x16x32_bf16 v[26:29], v[102:105], v[214:217], v[26:29]
	v_mfma_f32_16x16x32_bf16 v[6:9], v[94:97], v[222:225], v[6:9]
	v_mfma_f32_16x16x32_bf16 v[2:5], v[102:105], v[222:225], v[2:5]
	s_setprio 0
	s_barrier
	s_add_i32 s14, s14, 2
	s_add_u32 s46, s46, 0x100
	s_addc_u32 s47, s47, 0
	s_add_u32 s12, s12, 0x100
	s_addc_u32 s13, s13, 0
	s_cmp_gt_u32 s14, 13
	s_cbranch_scc0 .LBB0_71
	s_and_b64 vcc, exec, s[56:57]
	s_cbranch_vccz .LBB0_74
	s_barrier

.LBB0_109:
	s_or_b64 exec, exec, s[42:43]
	v_and_b32_e32 v101, 0xffff0000, v82
	v_and_b32_e32 v100, 0xffff0000, v76
	v_lshlrev_b32_e32 v99, 16, v82
	v_lshlrev_b32_e32 v98, 16, v76
	v_lshlrev_b32_e32 v102, 16, v77
	v_and_b32_e32 v82, 0xffff0000, v77
	v_lshlrev_b32_e32 v77, 16, v80
	v_lshlrev_b32_e32 v76, 16, v78
	v_and_b32_e32 v105, 0xffff0000, v80
	v_and_b32_e32 v104, 0xffff0000, v78
	v_lshlrev_b32_e32 v106, 16, v79
	v_and_b32_e32 v80, 0xffff0000, v79
	v_pk_mul_f32 v[78:79], v[100:101], v[100:101]
	v_lshlrev_b32_e32 v103, 16, v83
	v_pk_fma_f32 v[78:79], v[98:99], v[98:99], v[78:79]
	v_pk_mul_f32 v[108:109], v[104:105], v[104:105]
	v_and_b32_e32 v83, 0xffff0000, v83
	v_lshlrev_b32_e32 v107, 16, v81
	v_pk_fma_f32 v[78:79], v[102:103], v[102:103], v[78:79]
	v_pk_fma_f32 v[108:109], v[76:77], v[76:77], v[108:109]
	v_and_b32_e32 v81, 0xffff0000, v81
	v_pk_fma_f32 v[78:79], v[82:83], v[82:83], v[78:79]
	v_pk_fma_f32 v[108:109], v[106:107], v[106:107], v[108:109]
	v_add_f32_e32 v67, v78, v79
	v_pk_fma_f32 v[108:109], v[80:81], v[80:81], v[108:109]
	v_mov_b32_e32 v79, v100
	v_add_f32_e32 v67, v67, v108
	v_add_f32_e32 v67, v67, v109
	v_mov_b32_e32 v78, v67
	s_nop 1
	v_permlane32_swap_b32_e32 v78, v67
	s_nop 1
	v_mov_b32_e32 v109, v82
	v_mov_b32_e32 v100, v99
	s_waitcnt lgkmcnt(0)
	v_add_f32_e32 v67, v67, v78
	v_mov_b32_e32 v78, v67
	s_nop 1
	v_permlane16_swap_b32_e32 v78, v67
	s_nop 1
	v_add_f32_e32 v67, v67, v78
	s_nop 1
	v_mov_b32_dpp v78, v67 row_ror:8 row_mask:0xf bank_mask:0xf
	v_add_f32_e32 v67, v67, v78
	s_nop 1
	v_mov_b32_dpp v78, v67 row_shl:4 row_mask:0xf bank_mask:0x5
	s_nop 1
	v_mov_b32_dpp v78, v67 row_shr:4 row_mask:0xf bank_mask:0xa
	v_add_f32_e32 v67, v67, v78
	s_nop 1
	v_mov_b32_dpp v78, v67 quad_perm:[2,3,0,1] row_mask:0xf bank_mask:0xf
	v_add_f32_e32 v67, v67, v78
	s_nop 1
	v_mov_b32_dpp v108, v67 quad_perm:[1,0,3,2] row_mask:0xf bank_mask:0xf
	v_mov_b32_e32 v78, v98
	v_add_f32_e32 v67, v67, v108
	v_fmamk_f32 v67, v67, 0x3a800000, v1
	v_mul_f32_e32 v98, 0x4b800000, v67
	v_cmp_gt_f32_e32 vcc, s33, v67
	v_mov_b32_e32 v108, v102
	s_nop 0
	v_cndmask_b32_e32 v67, v67, v98, vcc
	v_rsq_f32_e32 v67, v67
	s_nop 0
	v_mul_f32_e32 v82, 0x45800000, v67
	v_cndmask_b32_e32 v98, v67, v82, vcc
	v_pk_mul_f32 v[78:79], v[98:99], v[78:79] op_sel_hi:[0,1]
	v_pk_fma_f32 v[46:47], v[2:3], v[78:79], v[46:47]
	v_pk_mul_f32 v[78:79], v[98:99], v[100:101] op_sel_hi:[0,1]
	v_mov_b32_e32 v82, v103
	v_pk_mul_f32 v[82:83], v[98:99], v[82:83] op_sel_hi:[0,1]
	v_pk_fma_f32 v[42:43], v[14:15], v[78:79], v[42:43]
	v_mov_b32_e32 v78, v76
	v_mov_b32_e32 v79, v104
	v_pk_fma_f32 v[44:45], v[16:17], v[82:83], v[44:45]
	v_pk_mul_f32 v[78:79], v[98:99], v[78:79] op_sel_hi:[0,1]
	v_mov_b32_e32 v82, v106
	v_mov_b32_e32 v83, v80
	v_mov_b32_e32 v104, v77
	v_mov_b32_e32 v80, v107
	v_pk_mul_f32 v[108:109], v[98:99], v[108:109] op_sel_hi:[0,1]
	v_pk_mul_f32 v[82:83], v[98:99], v[82:83] op_sel_hi:[0,1]
	v_pk_fma_f32 v[38:39], v[18:19], v[78:79], v[38:39]
	v_pk_mul_f32 v[76:77], v[98:99], v[104:105] op_sel_hi:[0,1]
	v_pk_mul_f32 v[78:79], v[98:99], v[80:81] op_sel_hi:[0,1]
	v_pk_fma_f32 v[48:49], v[4:5], v[108:109], v[48:49]
	v_pk_fma_f32 v[40:41], v[20:21], v[82:83], v[40:41]
	v_pk_fma_f32 v[36:37], v[32:33], v[78:79], v[36:37]
	v_pk_fma_f32 v[34:35], v[30:31], v[76:77], v[34:35]
	s_and_b64 vcc, exec, s[36:37]
	global_store_dwordx4 v[74:75], v[46:49], off offset:-2048
	global_store_dwordx4 v[74:75], v[42:45], off offset:-1024
	global_store_dwordx4 v[74:75], v[38:41], off
	global_store_dwordx4 v[74:75], v[34:37], off offset:1024
	s_cbranch_vccnz .LBB0_106
	v_mov_b32_e32 v82, v47
	v_mov_b32_e32 v83, v43
	v_mov_b32_e32 v80, v46
	v_mov_b32_e32 v81, v42
	v_pk_mul_f32 v[82:83], v[82:83], v[82:83]
	v_mov_b32_e32 v98, v35
	v_mov_b32_e32 v99, v39
	v_mov_b32_e32 v78, v48
	v_mov_b32_e32 v79, v44
	v_pk_fma_f32 v[80:81], v[80:81], v[80:81], v[82:83]
	v_mov_b32_e32 v82, v34
	v_mov_b32_e32 v83, v38
	v_pk_mul_f32 v[98:99], v[98:99], v[98:99]
	v_mov_b32_e32 v76, v49
	v_mov_b32_e32 v77, v45
	v_pk_fma_f32 v[78:79], v[78:79], v[78:79], v[80:81]
	v_mov_b32_e32 v80, v36
	v_mov_b32_e32 v81, v40
	v_pk_fma_f32 v[82:83], v[82:83], v[82:83], v[98:99]
	v_pk_fma_f32 v[76:77], v[76:77], v[76:77], v[78:79]
	v_mov_b32_e32 v78, v37
	v_mov_b32_e32 v79, v41
	v_pk_fma_f32 v[80:81], v[80:81], v[80:81], v[82:83]
	v_add_f32_e32 v67, v76, v77
	v_pk_fma_f32 v[78:79], v[78:79], v[78:79], v[80:81]
	s_nop 0
	v_add_f32_e32 v67, v79, v67
	v_add_f32_e32 v67, v78, v67
	v_mov_b32_e32 v76, v67
	s_nop 1
	v_permlane32_swap_b32_e32 v76, v67
	s_nop 1
	v_add_f32_e32 v67, v67, v76
	v_mov_b32_e32 v76, v67
	s_nop 1
	v_permlane16_swap_b32_e32 v76, v67
	s_nop 1
	v_add_f32_e32 v67, v67, v76
	s_nop 1
	v_mov_b32_dpp v76, v67 row_ror:8 row_mask:0xf bank_mask:0xf
	v_add_f32_e32 v67, v67, v76
	s_nop 1
	v_mov_b32_dpp v76, v67 row_shl:4 row_mask:0xf bank_mask:0x5
	s_nop 1
	v_mov_b32_dpp v76, v67 row_shr:4 row_mask:0xf bank_mask:0xa
	v_add_f32_e32 v67, v67, v76
	s_nop 1
	v_mov_b32_dpp v76, v67 quad_perm:[2,3,0,1] row_mask:0xf bank_mask:0xf
	v_add_f32_e32 v67, v67, v76
	s_nop 1
	v_mov_b32_dpp v76, v67 quad_perm:[1,0,3,2] row_mask:0xf bank_mask:0xf
	v_add_f32_e32 v67, v67, v76
	v_fmamk_f32 v67, v67, 0x3a800000, v1
	v_mul_f32_e32 v76, 0x4b800000, v67
	v_cmp_gt_f32_e32 vcc, s33, v67
	s_nop 1
	v_cndmask_b32_e32 v67, v67, v76, vcc
	v_rsq_f32_e32 v67, v67
	s_nop 0
	v_mul_f32_e32 v76, 0x45800000, v67
	v_cndmask_b32_e32 v76, v67, v76, vcc
	v_pk_mul_f32 v[46:47], v[46:47], v[76:77] op_sel_hi:[1,0]
	v_pk_mul_f32 v[42:43], v[42:43], v[76:77] op_sel_hi:[1,0]
	v_pk_mul_f32 v[38:39], v[38:39], v[76:77] op_sel_hi:[1,0]
	v_pk_mul_f32 v[34:35], v[34:35], v[76:77] op_sel_hi:[1,0]
	v_pk_mul_f32 v[48:49], v[48:49], v[76:77] op_sel_hi:[1,0]
	v_pk_mul_f32 v[44:45], v[44:45], v[76:77] op_sel_hi:[1,0]
	v_pk_mul_f32 v[46:47], v[10:11], v[46:47]
	v_pk_mul_f32 v[42:43], v[6:7], v[42:43]
	v_pk_mul_f32 v[40:41], v[40:41], v[76:77] op_sel_hi:[1,0]
	v_pk_mul_f32 v[38:39], v[26:27], v[38:39]
	v_pk_mul_f32 v[36:37], v[36:37], v[76:77] op_sel_hi:[1,0]
	v_pk_mul_f32 v[34:35], v[22:23], v[34:35]
	v_pk_mul_f32 v[48:49], v[12:13], v[48:49]
	v_pk_mul_f32 v[44:45], v[8:9], v[44:45]
	v_cvt_pk_bf16_f32 v46, v46, v47
	v_cvt_pk_bf16_f32 v47, v48, v49
	global_store_dwordx2 v[72:73], v[46:47], off offset:-1024
	v_cvt_pk_bf16_f32 v42, v42, v43
	v_cvt_pk_bf16_f32 v43, v44, v45
	global_store_dwordx2 v[72:73], v[42:43], off offset:-512
	v_pk_mul_f32 v[40:41], v[28:29], v[40:41]
	v_cvt_pk_bf16_f32 v38, v38, v39
	v_pk_mul_f32 v[36:37], v[24:25], v[36:37]
	v_cvt_pk_bf16_f32 v39, v40, v41
	global_store_dwordx2 v[72:73], v[38:39], off
	v_cvt_pk_bf16_f32 v34, v34, v35
	v_cvt_pk_bf16_f32 v35, v36, v37
	global_store_dwordx2 v[72:73], v[34:35], off offset:512
	s_branch .LBB0_106

.LBB0_120:
	s_or_b64 exec, exec, s[30:31]
	v_mul_f32_e32 v51, v47, v47
	v_mul_f32_e32 v58, v43, v43
	v_fmac_f32_e32 v51, v46, v46
	v_fmac_f32_e32 v58, v42, v42
	v_fmac_f32_e32 v51, v48, v48
	v_fmac_f32_e32 v58, v44, v44
	v_fmac_f32_e32 v51, v49, v49
	v_fmac_f32_e32 v58, v45, v45
	v_add_f32_e32 v51, v51, v58
	v_mul_f32_e32 v58, v39, v39
	v_fmac_f32_e32 v58, v38, v38
	v_fmac_f32_e32 v58, v40, v40
	v_fmac_f32_e32 v58, v41, v41
	v_add_f32_e32 v51, v51, v58
	v_mul_f32_e32 v58, v35, v35
	v_fmac_f32_e32 v58, v34, v34
	v_fmac_f32_e32 v58, v36, v36
	v_fmac_f32_e32 v58, v37, v37
	v_add_f32_e32 v51, v51, v58
	v_mov_b32_e32 v58, v51
	s_nop 1
	v_permlane32_swap_b32_e32 v58, v51
	s_nop 1
	v_lshl_add_u64 v[68:69], s[74:75], 0, v[56:57]
	s_waitcnt lgkmcnt(0)
	v_add_f32_e32 v51, v51, v58
	v_mov_b32_e32 v58, v51
	s_nop 1
	v_permlane16_swap_b32_e32 v58, v51
	s_nop 1
	v_add_f32_e32 v51, v51, v58
	s_nop 1
	v_mov_b32_dpp v58, v51 row_ror:8 row_mask:0xf bank_mask:0xf
	v_add_f32_e32 v51, v51, v58
	s_nop 1
	v_mov_b32_dpp v58, v51 row_shl:4 row_mask:0xf bank_mask:0x5
	s_nop 1
	v_mov_b32_dpp v58, v51 row_shr:4 row_mask:0xf bank_mask:0xa
	v_add_f32_e32 v51, v51, v58
	s_nop 1
	v_mov_b32_dpp v58, v51 quad_perm:[2,3,0,1] row_mask:0xf bank_mask:0xf
	v_add_f32_e32 v51, v51, v58
	s_nop 1
	v_mov_b32_dpp v58, v51 quad_perm:[1,0,3,2] row_mask:0xf bank_mask:0xf
	v_add_f32_e32 v51, v51, v58
	v_fmamk_f32 v51, v51, 0x3a800000, v1
	v_cmp_gt_f32_e64 s[0:1], s33, v51
	v_mul_f32_e32 v58, 0x4b800000, v51
	s_nop 0
	v_cndmask_b32_e64 v51, v51, v58, s[0:1]
	v_rsq_f32_e32 v51, v51
	s_nop 0
	v_mul_f32_e32 v58, 0x45800000, v51
	v_cndmask_b32_e64 v58, v51, v58, s[0:1]
	v_pk_mul_f32 v[46:47], v[46:47], v[58:59] op_sel_hi:[1,0]
	s_mov_b32 s0, 0x5a88000
	v_pk_mul_f32 v[48:49], v[48:49], v[58:59] op_sel_hi:[1,0]
	v_pk_mul_f32 v[60:61], v[14:15], v[46:47]
	v_add_co_u32_e64 v46, s[0:1], s0, v68
	v_pk_mul_f32 v[48:49], v[16:17], v[48:49]
	v_cvt_pk_bf16_f32 v70, v60, v61
	s_nop 0
	v_addc_co_u32_e64 v47, s[0:1], 0, v69, s[0:1]
	v_cvt_pk_bf16_f32 v71, v48, v49
	global_store_dwordx2 v[46:47], v[70:71], off
	ds_read_b128 v[100:103], v67
	ds_read_b128 v[104:107], v67 offset:4096
	ds_read_b128 v[108:111], v67 offset:8192
	ds_read_b128 v[112:115], v67 offset:12288
	ds_read_b128 v[116:119], v67 offset:16384
	ds_read_b128 v[120:123], v67 offset:20480
	ds_read_b128 v[124:127], v67 offset:24576
	s_waitcnt lgkmcnt(6)
	v_pk_mul_f32 v[148:149], v[100:101], v[60:61]
	v_pk_fma_f32 v[148:149], v[102:103], v[48:49], v[148:149]
	ds_read_b128 v[128:131], v67 offset:28672
	s_waitcnt lgkmcnt(6)
	v_pk_mul_f32 v[150:151], v[104:105], v[60:61]
	v_pk_fma_f32 v[150:151], v[106:107], v[48:49], v[150:151]
	ds_read_b128 v[100:103], v67 offset:32768
	s_waitcnt lgkmcnt(6)
	v_pk_mul_f32 v[152:153], v[108:109], v[60:61]
	v_pk_fma_f32 v[152:153], v[110:111], v[48:49], v[152:153]
	ds_read_b128 v[104:107], v67 offset:36864
	s_waitcnt lgkmcnt(6)
	v_pk_mul_f32 v[154:155], v[112:113], v[60:61]
	v_pk_fma_f32 v[154:155], v[114:115], v[48:49], v[154:155]
	ds_read_b128 v[108:111], v67 offset:40960
	s_waitcnt lgkmcnt(6)
	v_pk_mul_f32 v[156:157], v[116:117], v[60:61]
	v_pk_fma_f32 v[156:157], v[118:119], v[48:49], v[156:157]
	ds_read_b128 v[112:115], v67 offset:45056
	s_waitcnt lgkmcnt(6)
	v_pk_mul_f32 v[158:159], v[120:121], v[60:61]
	v_pk_fma_f32 v[158:159], v[122:123], v[48:49], v[158:159]
	ds_read_b128 v[116:119], v67 offset:49152
	s_waitcnt lgkmcnt(6)
	v_pk_mul_f32 v[160:161], v[124:125], v[60:61]
	v_pk_fma_f32 v[160:161], v[126:127], v[48:49], v[160:161]
	ds_read_b128 v[120:123], v67 offset:53248
	s_waitcnt lgkmcnt(6)
	v_pk_mul_f32 v[162:163], v[128:129], v[60:61]
	v_pk_fma_f32 v[162:163], v[130:131], v[48:49], v[162:163]
	ds_read_b128 v[124:127], v67 offset:57344
	s_waitcnt lgkmcnt(6)
	v_pk_mul_f32 v[164:165], v[100:101], v[60:61]
	v_pk_fma_f32 v[164:165], v[102:103], v[48:49], v[164:165]
	ds_read_b128 v[128:131], v67 offset:61440
	s_waitcnt lgkmcnt(6)
	v_pk_mul_f32 v[168:169], v[104:105], v[60:61]
	v_pk_fma_f32 v[168:169], v[106:107], v[48:49], v[168:169]
	ds_read_b128 v[100:103], v67 offset:1024
	s_waitcnt lgkmcnt(6)
	v_pk_mul_f32 v[170:171], v[108:109], v[60:61]
	v_pk_fma_f32 v[170:171], v[110:111], v[48:49], v[170:171]
	ds_read_b128 v[104:107], v67 offset:5120
	s_waitcnt lgkmcnt(6)
	v_pk_mul_f32 v[172:173], v[112:113], v[60:61]
	v_pk_fma_f32 v[172:173], v[114:115], v[48:49], v[172:173]
	ds_read_b128 v[108:111], v67 offset:9216
	s_waitcnt lgkmcnt(6)
	v_pk_mul_f32 v[174:175], v[116:117], v[60:61]
	v_pk_fma_f32 v[174:175], v[118:119], v[48:49], v[174:175]
	ds_read_b128 v[112:115], v67 offset:13312
	s_waitcnt lgkmcnt(6)
	v_pk_mul_f32 v[176:177], v[120:121], v[60:61]
	v_pk_fma_f32 v[176:177], v[122:123], v[48:49], v[176:177]
	ds_read_b128 v[116:119], v67 offset:17408
	s_waitcnt lgkmcnt(6)
	v_pk_mul_f32 v[178:179], v[124:125], v[60:61]
	v_pk_fma_f32 v[178:179], v[126:127], v[48:49], v[178:179]
	ds_read_b128 v[120:123], v67 offset:21504
	s_waitcnt lgkmcnt(6)
	v_pk_mul_f32 v[180:181], v[128:129], v[60:61]
	v_pk_fma_f32 v[180:181], v[130:131], v[48:49], v[180:181]
	v_pk_mul_f32 v[60:61], v[42:43], v[58:59] op_sel_hi:[1,0]
	v_pk_mul_f32 v[42:43], v[44:45], v[58:59] op_sel_hi:[1,0]
	v_pk_mul_f32 v[44:45], v[10:11], v[60:61]
	v_pk_mul_f32 v[42:43], v[12:13], v[42:43]
	v_cvt_pk_bf16_f32 v60, v44, v45
	s_nop 0
	v_cvt_pk_bf16_f32 v61, v42, v43
	ds_read_b128 v[124:127], v67 offset:25600
	global_store_dwordx2 v[46:47], v[60:61], off offset:512
	s_waitcnt lgkmcnt(6)
	v_pk_fma_f32 v[148:149], v[100:101], v[44:45], v[148:149]
	v_pk_fma_f32 v[148:149], v[102:103], v[42:43], v[148:149]
	ds_read_b128 v[128:131], v67 offset:29696
	s_waitcnt lgkmcnt(6)
	v_pk_fma_f32 v[150:151], v[104:105], v[44:45], v[150:151]
	v_pk_fma_f32 v[150:151], v[106:107], v[42:43], v[150:151]
	ds_read_b128 v[100:103], v67 offset:33792
	s_waitcnt lgkmcnt(6)
	v_pk_fma_f32 v[152:153], v[108:109], v[44:45], v[152:153]
	v_pk_fma_f32 v[152:153], v[110:111], v[42:43], v[152:153]
	ds_read_b128 v[104:107], v67 offset:37888
	s_waitcnt lgkmcnt(6)
	v_pk_fma_f32 v[154:155], v[112:113], v[44:45], v[154:155]
	v_pk_fma_f32 v[154:155], v[114:115], v[42:43], v[154:155]
	ds_read_b128 v[108:111], v67 offset:41984
	s_waitcnt lgkmcnt(6)
	v_pk_fma_f32 v[156:157], v[116:117], v[44:45], v[156:157]
	v_pk_fma_f32 v[156:157], v[118:119], v[42:43], v[156:157]
	ds_read_b128 v[112:115], v67 offset:46080
	s_waitcnt lgkmcnt(6)
	v_pk_fma_f32 v[158:159], v[120:121], v[44:45], v[158:159]
	v_pk_fma_f32 v[158:159], v[122:123], v[42:43], v[158:159]
	ds_read_b128 v[116:119], v67 offset:50176
	s_waitcnt lgkmcnt(6)
	v_pk_fma_f32 v[160:161], v[124:125], v[44:45], v[160:161]
	v_pk_fma_f32 v[160:161], v[126:127], v[42:43], v[160:161]
	ds_read_b128 v[120:123], v67 offset:54272
	s_waitcnt lgkmcnt(6)
	v_pk_fma_f32 v[162:163], v[128:129], v[44:45], v[162:163]
	v_pk_fma_f32 v[162:163], v[130:131], v[42:43], v[162:163]
	ds_read_b128 v[124:127], v67 offset:58368
	s_waitcnt lgkmcnt(6)
	v_pk_fma_f32 v[164:165], v[100:101], v[44:45], v[164:165]
	v_pk_fma_f32 v[164:165], v[102:103], v[42:43], v[164:165]
	ds_read_b128 v[128:131], v67 offset:62464
	s_waitcnt lgkmcnt(6)
	v_pk_fma_f32 v[168:169], v[104:105], v[44:45], v[168:169]
	v_pk_fma_f32 v[168:169], v[106:107], v[42:43], v[168:169]
	ds_read_b128 v[100:103], v67 offset:2048
	s_waitcnt lgkmcnt(6)
	v_pk_fma_f32 v[170:171], v[108:109], v[44:45], v[170:171]
	v_pk_fma_f32 v[170:171], v[110:111], v[42:43], v[170:171]
	ds_read_b128 v[104:107], v67 offset:6144
	s_waitcnt lgkmcnt(6)
	v_pk_fma_f32 v[172:173], v[112:113], v[44:45], v[172:173]
	v_pk_fma_f32 v[172:173], v[114:115], v[42:43], v[172:173]
	ds_read_b128 v[108:111], v67 offset:10240
	s_waitcnt lgkmcnt(6)
	v_pk_fma_f32 v[174:175], v[116:117], v[44:45], v[174:175]
	v_pk_fma_f32 v[174:175], v[118:119], v[42:43], v[174:175]
	ds_read_b128 v[112:115], v67 offset:14336
	s_waitcnt lgkmcnt(6)
	v_pk_fma_f32 v[176:177], v[120:121], v[44:45], v[176:177]
	v_pk_fma_f32 v[176:177], v[122:123], v[42:43], v[176:177]
	ds_read_b128 v[116:119], v67 offset:18432
	s_waitcnt lgkmcnt(6)
	v_pk_fma_f32 v[178:179], v[124:125], v[44:45], v[178:179]
	v_pk_fma_f32 v[178:179], v[126:127], v[42:43], v[178:179]
	ds_read_b128 v[120:123], v67 offset:22528
	s_waitcnt lgkmcnt(6)
	v_pk_fma_f32 v[180:181], v[128:129], v[44:45], v[180:181]
	v_pk_fma_f32 v[180:181], v[130:131], v[42:43], v[180:181]
	v_pk_mul_f32 v[42:43], v[38:39], v[58:59] op_sel_hi:[1,0]
	v_pk_mul_f32 v[38:39], v[40:41], v[58:59] op_sel_hi:[1,0]
	v_pk_mul_f32 v[40:41], v[6:7], v[42:43]
	v_pk_mul_f32 v[38:39], v[8:9], v[38:39]
	v_cvt_pk_bf16_f32 v42, v40, v41
	v_cvt_pk_bf16_f32 v43, v38, v39
	global_store_dwordx2 v[46:47], v[42:43], off offset:1024
	ds_read_b128 v[124:127], v67 offset:26624
	ds_read_b128 v[128:131], v67 offset:30720
	s_waitcnt lgkmcnt(7)
	v_pk_fma_f32 v[148:149], v[100:101], v[40:41], v[148:149]
	v_pk_fma_f32 v[148:149], v[102:103], v[38:39], v[148:149]
	s_waitcnt lgkmcnt(6)
	v_pk_fma_f32 v[150:151], v[104:105], v[40:41], v[150:151]
	v_pk_fma_f32 v[150:151], v[106:107], v[38:39], v[150:151]
	ds_read_b128 v[100:103], v67 offset:34816
	s_waitcnt lgkmcnt(6)
	v_pk_fma_f32 v[152:153], v[108:109], v[40:41], v[152:153]
	v_pk_fma_f32 v[152:153], v[110:111], v[38:39], v[152:153]
	ds_read_b128 v[104:107], v67 offset:38912
	s_waitcnt lgkmcnt(6)
	v_pk_fma_f32 v[154:155], v[112:113], v[40:41], v[154:155]
	v_pk_fma_f32 v[154:155], v[114:115], v[38:39], v[154:155]
	ds_read_b128 v[108:111], v67 offset:43008
	s_waitcnt lgkmcnt(6)
	v_pk_fma_f32 v[156:157], v[116:117], v[40:41], v[156:157]
	v_pk_fma_f32 v[156:157], v[118:119], v[38:39], v[156:157]
	ds_read_b128 v[112:115], v67 offset:47104
	s_waitcnt lgkmcnt(6)
	v_pk_fma_f32 v[158:159], v[120:121], v[40:41], v[158:159]
	v_pk_fma_f32 v[158:159], v[122:123], v[38:39], v[158:159]
	ds_read_b128 v[116:119], v67 offset:51200
	s_waitcnt lgkmcnt(6)
	v_pk_fma_f32 v[160:161], v[124:125], v[40:41], v[160:161]
	v_pk_fma_f32 v[160:161], v[126:127], v[38:39], v[160:161]
	ds_read_b128 v[120:123], v67 offset:55296
	s_waitcnt lgkmcnt(6)
	v_pk_fma_f32 v[162:163], v[128:129], v[40:41], v[162:163]
	v_pk_fma_f32 v[162:163], v[130:131], v[38:39], v[162:163]
	ds_read_b128 v[124:127], v67 offset:59392
	s_waitcnt lgkmcnt(6)
	v_pk_fma_f32 v[164:165], v[100:101], v[40:41], v[164:165]
	v_pk_fma_f32 v[164:165], v[102:103], v[38:39], v[164:165]
	ds_read_b128 v[128:131], v67 offset:63488
	s_waitcnt lgkmcnt(6)
	v_pk_fma_f32 v[168:169], v[104:105], v[40:41], v[168:169]
	v_pk_fma_f32 v[168:169], v[106:107], v[38:39], v[168:169]
	ds_read_b128 v[100:103], v67 offset:3072
	s_waitcnt lgkmcnt(6)
	v_pk_fma_f32 v[170:171], v[108:109], v[40:41], v[170:171]
	v_pk_fma_f32 v[170:171], v[110:111], v[38:39], v[170:171]
	ds_read_b128 v[104:107], v67 offset:7168
	s_waitcnt lgkmcnt(6)
	v_pk_fma_f32 v[172:173], v[112:113], v[40:41], v[172:173]
	v_pk_fma_f32 v[172:173], v[114:115], v[38:39], v[172:173]
	ds_read_b128 v[108:111], v67 offset:11264
	s_waitcnt lgkmcnt(6)
	v_pk_fma_f32 v[174:175], v[116:117], v[40:41], v[174:175]
	v_pk_fma_f32 v[174:175], v[118:119], v[38:39], v[174:175]
	ds_read_b128 v[112:115], v67 offset:15360
	s_waitcnt lgkmcnt(6)
	v_pk_fma_f32 v[176:177], v[120:121], v[40:41], v[176:177]
	v_pk_fma_f32 v[176:177], v[122:123], v[38:39], v[176:177]
	ds_read_b128 v[116:119], v67 offset:19456
	s_waitcnt lgkmcnt(6)
	v_pk_fma_f32 v[178:179], v[124:125], v[40:41], v[178:179]
	v_pk_fma_f32 v[178:179], v[126:127], v[38:39], v[178:179]
	ds_read_b128 v[120:123], v67 offset:23552
	s_waitcnt lgkmcnt(6)
	v_pk_fma_f32 v[180:181], v[128:129], v[40:41], v[180:181]
	v_pk_fma_f32 v[180:181], v[130:131], v[38:39], v[180:181]
	v_pk_mul_f32 v[40:41], v[34:35], v[58:59] op_sel_hi:[1,0]
	v_pk_mul_f32 v[34:35], v[36:37], v[58:59] op_sel_hi:[1,0]
	v_pk_mul_f32 v[36:37], v[2:3], v[40:41]
	v_pk_mul_f32 v[34:35], v[4:5], v[34:35]
	v_cvt_pk_bf16_f32 v40, v36, v37
	s_nop 0
	v_cvt_pk_bf16_f32 v41, v34, v35
	ds_read_b128 v[124:127], v67 offset:27648
	global_store_dwordx2 v[46:47], v[40:41], off offset:1536
	s_waitcnt lgkmcnt(6)
	v_pk_fma_f32 v[148:149], v[100:101], v[36:37], v[148:149]
	v_pk_fma_f32 v[148:149], v[102:103], v[34:35], v[148:149]
	ds_read_b128 v[128:131], v67 offset:31744
	v_add_f32_e32 v39, v148, v149
	s_waitcnt lgkmcnt(6)
	v_pk_fma_f32 v[150:151], v[104:105], v[36:37], v[150:151]
	v_pk_fma_f32 v[150:151], v[106:107], v[34:35], v[150:151]
	ds_read_b128 v[100:103], v67 offset:35840
	v_add_f32_e32 v40, v150, v151
	s_waitcnt lgkmcnt(6)
	v_pk_fma_f32 v[152:153], v[108:109], v[36:37], v[152:153]
	v_pk_fma_f32 v[152:153], v[110:111], v[34:35], v[152:153]
	ds_read_b128 v[104:107], v67 offset:39936
	v_add_f32_e32 v41, v152, v153
	s_waitcnt lgkmcnt(6)
	v_pk_fma_f32 v[154:155], v[112:113], v[36:37], v[154:155]
	v_pk_fma_f32 v[154:155], v[114:115], v[34:35], v[154:155]
	v_add_f32_e32 v42, v154, v155
	ds_read_b128 v[108:111], v67 offset:44032
	s_waitcnt lgkmcnt(6)
	v_pk_fma_f32 v[156:157], v[116:117], v[36:37], v[156:157]
	v_pk_fma_f32 v[156:157], v[118:119], v[34:35], v[156:157]
	ds_read_b128 v[112:115], v67 offset:48128
	v_add_f32_e32 v43, v156, v157
	s_waitcnt lgkmcnt(6)
	v_pk_fma_f32 v[158:159], v[120:121], v[36:37], v[158:159]
	v_pk_fma_f32 v[158:159], v[122:123], v[34:35], v[158:159]
	v_add_f32_e32 v48, v158, v159
	ds_read_b128 v[116:119], v67 offset:52224
	s_waitcnt lgkmcnt(6)
	v_pk_fma_f32 v[160:161], v[124:125], v[36:37], v[160:161]
	v_pk_fma_f32 v[160:161], v[126:127], v[34:35], v[160:161]
	v_add_f32_e32 v49, v160, v161
	ds_read_b128 v[120:123], v67 offset:56320
	s_waitcnt lgkmcnt(6)
	v_pk_fma_f32 v[162:163], v[128:129], v[36:37], v[162:163]
	v_pk_fma_f32 v[162:163], v[130:131], v[34:35], v[162:163]
	v_add_f32_e32 v51, v162, v163
	ds_read_b128 v[124:127], v67 offset:60416
	s_waitcnt lgkmcnt(6)
	v_pk_fma_f32 v[164:165], v[100:101], v[36:37], v[164:165]
	v_pk_fma_f32 v[164:165], v[102:103], v[34:35], v[164:165]
	v_add_f32_e32 v58, v164, v165
	ds_read_b128 v[128:131], v67 offset:64512
	s_waitcnt lgkmcnt(6)
	v_pk_fma_f32 v[168:169], v[104:105], v[36:37], v[168:169]
	v_pk_fma_f32 v[168:169], v[106:107], v[34:35], v[168:169]
	v_add_f32_e32 v60, v168, v169
	s_waitcnt lgkmcnt(5)
	v_pk_fma_f32 v[170:171], v[108:109], v[36:37], v[170:171]
	v_pk_fma_f32 v[170:171], v[110:111], v[34:35], v[170:171]
	v_add_f32_e32 v61, v170, v171
	s_waitcnt lgkmcnt(4)
	v_pk_fma_f32 v[172:173], v[112:113], v[36:37], v[172:173]
	v_pk_fma_f32 v[172:173], v[114:115], v[34:35], v[172:173]
	v_add_f32_e32 v68, v172, v173
	s_waitcnt lgkmcnt(3)
	v_pk_fma_f32 v[174:175], v[116:117], v[36:37], v[174:175]
	v_pk_fma_f32 v[174:175], v[118:119], v[34:35], v[174:175]
	v_add_f32_e32 v69, v174, v175
	s_waitcnt lgkmcnt(2)
	v_pk_fma_f32 v[176:177], v[120:121], v[36:37], v[176:177]
	v_pk_fma_f32 v[176:177], v[122:123], v[34:35], v[176:177]
	v_add_f32_e32 v70, v176, v177
	s_waitcnt lgkmcnt(1)
	v_pk_fma_f32 v[178:179], v[124:125], v[36:37], v[178:179]
	v_pk_fma_f32 v[178:179], v[126:127], v[34:35], v[178:179]
	v_add_f32_e32 v71, v178, v179
	s_waitcnt lgkmcnt(0)
	v_pk_fma_f32 v[180:181], v[128:129], v[36:37], v[180:181]
	v_pk_fma_f32 v[180:181], v[130:131], v[34:35], v[180:181]
	v_add_f32_e32 v34, v180, v181
	s_nop 1
	v_permlane32_swap_b32_e32 v39, v58
	s_nop 1
	v_add_f32_e32 v39, v39, v58
	s_nop 1
	v_permlane32_swap_b32_e32 v40, v60
	s_nop 1
	v_add_f32_e32 v40, v40, v60
	s_nop 1
	v_permlane32_swap_b32_e32 v41, v61
	s_nop 1
	v_add_f32_e32 v41, v41, v61
	s_nop 1
	v_permlane32_swap_b32_e32 v42, v68
	s_nop 1
	v_add_f32_e32 v42, v42, v68
	s_nop 1
	v_permlane32_swap_b32_e32 v43, v69
	s_nop 1
	v_add_f32_e32 v43, v43, v69
	s_nop 1
	v_permlane32_swap_b32_e32 v48, v70
	s_nop 1
	v_add_f32_e32 v48, v48, v70
	s_nop 1
	v_permlane32_swap_b32_e32 v49, v71
	s_nop 1
	v_add_f32_e32 v49, v49, v71
	s_nop 1
	v_permlane32_swap_b32_e32 v51, v34
	s_nop 1
	v_add_f32_e32 v51, v51, v34
	s_nop 1
	v_permlane16_swap_b32_e32 v40, v48
	s_nop 1
	v_add_f32_e32 v40, v40, v48
	s_nop 1
	v_permlane16_swap_b32_e32 v39, v43
	s_nop 1
	v_add_f32_e32 v39, v39, v43
	s_nop 1
	v_permlane16_swap_b32_e32 v41, v49
	s_nop 1
	v_add_f32_e32 v41, v41, v49
	s_nop 1
	v_permlane16_swap_b32_e32 v42, v51
	s_nop 1
	v_add_f32_e32 v42, v42, v51
	s_nop 1
	v_add_f32_dpp v39, v39, v39 row_ror:8 row_mask:0xf bank_mask:0x3
	s_nop 1
	v_add_f32_dpp v39, v41, v41 row_ror:8 row_mask:0xf bank_mask:0xc
	s_nop 1
	v_add_f32_dpp v40, v40, v40 row_ror:8 row_mask:0xf bank_mask:0x3
	s_nop 1
	v_add_f32_dpp v40, v42, v42 row_ror:8 row_mask:0xf bank_mask:0xc
	s_nop 1
	v_add_f32_dpp v39, v39, v39 row_shl:4 row_mask:0xf bank_mask:0x5
	s_nop 1
	v_add_f32_dpp v39, v40, v40 row_shr:4 row_mask:0xf bank_mask:0xa
	v_mov_b32_e32 v34, v39
	s_nop 0
	s_nop 1
	v_mov_b32_dpp v35, v34 quad_perm:[2,3,0,1] row_mask:0xf bank_mask:0xf
	v_add_f32_e32 v34, v34, v35
	s_nop 1
	v_mov_b32_dpp v35, v34 quad_perm:[1,0,3,2] row_mask:0xf bank_mask:0xf
	s_and_saveexec_b64 s[0:1], s[42:43]
	s_cbranch_execz .LBB0_117
	v_lshl_add_u64 v[36:37], s[74:75], 0, v[54:55]
	v_add_f32_e32 v34, v34, v35
	global_store_dword v[36:37], v34, off
	s_branch .LBB0_117

.LBB0_139:
	s_add_u32 s20, s46, 0xfffc0080
	s_addc_u32 s39, s47, -1
	s_add_i32 s41, 0, 0x10000
	s_cmp_eq_u32 s19, 12
	s_cselect_b32 s49, s13, s39
	s_cselect_b32 s48, s14, s20
	v_add_u32_e32 v140, s41, v143
	s_cselect_b32 s51, s15, s18
	s_cselect_b32 s50, s16, s17
	s_add_i32 s20, 0, 0x14000
	ds_read_b128 v[146:149], v140
	ds_read_b128 v[150:153], v140 offset:1024
	ds_read_b128 v[154:157], v140 offset:2048
	ds_read_b128 v[158:161], v140 offset:3072
	v_add_u32_e32 v140, s20, v143
	ds_read_b128 v[162:165], v140
	ds_read_b128 v[166:169], v140 offset:1024
	ds_read_b128 v[170:173], v140 offset:2048
	ds_read_b128 v[174:177], v140 offset:3072
	v_lshl_add_u64 v[140:141], s[46:47], 0, v[136:137]
	s_add_i32 m0, s4, 0xc000
	ds_read_b128 v[178:181], v145
	ds_read_b128 v[182:185], v145 offset:1024
	ds_read_b128 v[186:189], v145 offset:2048
	ds_read_b128 v[190:193], v145 offset:3072
	ds_read_b128 v[204:207], v145 offset:4096
	ds_read_b128 v[208:211], v145 offset:5120
	ds_read_b128 v[212:215], v145 offset:6144
	ds_read_b128 v[216:219], v145 offset:7168
	global_load_lds_dwordx4 v[140:141], off
	v_lshl_add_u64 v[140:141], s[46:47], 0, v[138:139]
	s_add_i32 m0, s4, 0xe000
	s_nop 0
	global_load_lds_dwordx4 v[140:141], off
	s_waitcnt vmcnt(8)
	s_waitcnt lgkmcnt(0)
	s_barrier
	s_setprio 1
	v_mfma_f32_16x16x32_bf16 v[126:129], v[146:149], v[178:181], v[126:129]
	v_mfma_f32_16x16x32_bf16 v[122:125], v[154:157], v[178:181], v[122:125]
	v_mfma_f32_16x16x32_bf16 v[114:117], v[146:149], v[186:189], v[114:117]
	v_mfma_f32_16x16x32_bf16 v[106:109], v[154:157], v[186:189], v[106:109]
	v_mfma_f32_16x16x32_bf16 v[98:101], v[146:149], v[204:207], v[98:101]
	v_mfma_f32_16x16x32_bf16 v[90:93], v[154:157], v[204:207], v[90:93]
	v_mfma_f32_16x16x32_bf16 v[82:85], v[146:149], v[212:215], v[82:85]
	v_mfma_f32_16x16x32_bf16 v[74:77], v[154:157], v[212:215], v[74:77]
	v_mfma_f32_16x16x32_bf16 v[126:129], v[150:153], v[182:185], v[126:129]
	v_mfma_f32_16x16x32_bf16 v[122:125], v[158:161], v[182:185], v[122:125]
	v_mfma_f32_16x16x32_bf16 v[114:117], v[150:153], v[190:193], v[114:117]
	v_mfma_f32_16x16x32_bf16 v[106:109], v[158:161], v[190:193], v[106:109]
	v_mfma_f32_16x16x32_bf16 v[98:101], v[150:153], v[208:211], v[98:101]
	v_mfma_f32_16x16x32_bf16 v[90:93], v[158:161], v[208:211], v[90:93]
	v_mfma_f32_16x16x32_bf16 v[82:85], v[150:153], v[216:219], v[82:85]
	v_mfma_f32_16x16x32_bf16 v[74:77], v[158:161], v[216:219], v[74:77]
	s_setprio 0
	s_setprio 1
	v_mfma_f32_16x16x32_bf16 v[118:121], v[162:165], v[178:181], v[118:121]
	v_mfma_f32_16x16x32_bf16 v[110:113], v[170:173], v[178:181], v[110:113]
	v_mfma_f32_16x16x32_bf16 v[102:105], v[162:165], v[186:189], v[102:105]
	v_mfma_f32_16x16x32_bf16 v[94:97], v[170:173], v[186:189], v[94:97]
	v_mfma_f32_16x16x32_bf16 v[86:89], v[162:165], v[204:207], v[86:89]
	v_mfma_f32_16x16x32_bf16 v[78:81], v[170:173], v[204:207], v[78:81]
	v_mfma_f32_16x16x32_bf16 v[70:73], v[162:165], v[212:215], v[70:73]
	v_mfma_f32_16x16x32_bf16 v[66:69], v[170:173], v[212:215], v[66:69]
	v_mfma_f32_16x16x32_bf16 v[118:121], v[166:169], v[182:185], v[118:121]
	v_mfma_f32_16x16x32_bf16 v[110:113], v[174:177], v[182:185], v[110:113]
	v_mfma_f32_16x16x32_bf16 v[102:105], v[166:169], v[190:193], v[102:105]
	v_mfma_f32_16x16x32_bf16 v[94:97], v[174:177], v[190:193], v[94:97]
	v_mfma_f32_16x16x32_bf16 v[86:89], v[166:169], v[208:211], v[86:89]
	v_mfma_f32_16x16x32_bf16 v[78:81], v[174:177], v[208:211], v[78:81]
	v_mfma_f32_16x16x32_bf16 v[70:73], v[166:169], v[216:219], v[70:73]
	v_mfma_f32_16x16x32_bf16 v[66:69], v[174:177], v[216:219], v[66:69]
	s_setprio 0
	s_barrier
	s_add_i32 s39, s41, s2
	v_lshl_add_u64 v[140:141], s[50:51], 0, v[194:195]
	s_mov_b32 m0, s39
	ds_read_b128 v[178:181], v145 offset:16384
	ds_read_b128 v[182:185], v145 offset:17408
	ds_read_b128 v[186:189], v145 offset:18432
	ds_read_b128 v[190:193], v145 offset:19456
	ds_read_b128 v[204:207], v145 offset:20480
	ds_read_b128 v[208:211], v145 offset:21504
	ds_read_b128 v[212:215], v145 offset:22528
	ds_read_b128 v[216:219], v145 offset:23552
	global_load_lds_dwordx4 v[140:141], off
	s_add_i32 m0, s39, 0x2000
	s_add_u32 s52, s50, 0x40000
	v_lshl_add_u64 v[200:201], s[50:51], 0, v[130:131]
	s_addc_u32 s53, s51, 0
	s_add_i32 s20, s20, s2
	global_load_lds_dwordx4 v[200:201], off
	v_lshl_add_u64 v[220:221], s[52:53], 0, v[194:195]
	s_mov_b32 m0, s20
	v_lshl_add_u64 v[222:223], s[48:49], 0, v[132:133]
	global_load_lds_dwordx4 v[220:221], off
	v_lshl_add_u64 v[220:221], s[52:53], 0, v[130:131]
	s_add_i32 m0, s20, 0x2000
	s_nop 0
	global_load_lds_dwordx4 v[220:221], off
	v_lshl_add_u64 v[220:221], s[48:49], 0, v[134:135]
	s_mov_b32 m0, s4
	s_nop 0
	global_load_lds_dwordx4 v[220:221], off
	s_mov_b32 m0, s5
	s_nop 0
	global_load_lds_dwordx4 v[222:223], off
	s_waitcnt vmcnt(8)
	s_waitcnt lgkmcnt(0)
	s_barrier
	s_setprio 1
	v_mfma_f32_16x16x32_bf16 v[62:65], v[146:149], v[178:181], v[62:65]
	v_mfma_f32_16x16x32_bf16 v[58:61], v[154:157], v[178:181], v[58:61]
	v_mfma_f32_16x16x32_bf16 v[50:53], v[146:149], v[186:189], v[50:53]
	v_mfma_f32_16x16x32_bf16 v[42:45], v[154:157], v[186:189], v[42:45]
	v_mfma_f32_16x16x32_bf16 v[34:37], v[146:149], v[204:207], v[34:37]
	v_mfma_f32_16x16x32_bf16 v[26:29], v[154:157], v[204:207], v[26:29]
	v_mfma_f32_16x16x32_bf16 v[18:21], v[146:149], v[212:215], v[18:21]
	v_mfma_f32_16x16x32_bf16 v[10:13], v[154:157], v[212:215], v[10:13]
	v_mfma_f32_16x16x32_bf16 v[62:65], v[150:153], v[182:185], v[62:65]
	v_mfma_f32_16x16x32_bf16 v[58:61], v[158:161], v[182:185], v[58:61]
	v_mfma_f32_16x16x32_bf16 v[50:53], v[150:153], v[190:193], v[50:53]
	v_mfma_f32_16x16x32_bf16 v[42:45], v[158:161], v[190:193], v[42:45]
	v_mfma_f32_16x16x32_bf16 v[34:37], v[150:153], v[208:211], v[34:37]
	v_mfma_f32_16x16x32_bf16 v[26:29], v[158:161], v[208:211], v[26:29]
	v_mfma_f32_16x16x32_bf16 v[18:21], v[150:153], v[216:219], v[18:21]
	v_mfma_f32_16x16x32_bf16 v[10:13], v[158:161], v[216:219], v[10:13]
	s_setprio 0
	s_setprio 1
	v_mfma_f32_16x16x32_bf16 v[54:57], v[162:165], v[178:181], v[54:57]
	v_mfma_f32_16x16x32_bf16 v[46:49], v[170:173], v[178:181], v[46:49]
	v_mfma_f32_16x16x32_bf16 v[38:41], v[162:165], v[186:189], v[38:41]
	v_mfma_f32_16x16x32_bf16 v[30:33], v[170:173], v[186:189], v[30:33]
	v_mfma_f32_16x16x32_bf16 v[22:25], v[162:165], v[204:207], v[22:25]
	v_mfma_f32_16x16x32_bf16 v[14:17], v[170:173], v[204:207], v[14:17]
	v_mfma_f32_16x16x32_bf16 v[6:9], v[162:165], v[212:215], v[6:9]
	v_mfma_f32_16x16x32_bf16 v[2:5], v[170:173], v[212:215], v[2:5]
	v_mfma_f32_16x16x32_bf16 v[54:57], v[166:169], v[182:185], v[54:57]
	v_mfma_f32_16x16x32_bf16 v[46:49], v[174:177], v[182:185], v[46:49]
	v_mfma_f32_16x16x32_bf16 v[38:41], v[166:169], v[190:193], v[38:41]
	v_mfma_f32_16x16x32_bf16 v[30:33], v[174:177], v[190:193], v[30:33]
	v_mfma_f32_16x16x32_bf16 v[22:25], v[166:169], v[208:211], v[22:25]
	v_mfma_f32_16x16x32_bf16 v[14:17], v[174:177], v[208:211], v[14:17]
	v_mfma_f32_16x16x32_bf16 v[6:9], v[166:169], v[216:219], v[6:9]
	v_mfma_f32_16x16x32_bf16 v[2:5], v[174:177], v[216:219], v[2:5]
	s_setprio 0
	s_barrier
	s_add_i32 s20, 0, 0x18000
	s_add_i32 s39, 0, 0x1c000
	v_add_u32_e32 v158, s20, v143
	v_add_u32_e32 v174, s39, v143
	ds_read_b128 v[146:149], v158
	ds_read_b128 v[150:153], v158 offset:1024
	ds_read_b128 v[154:157], v158 offset:2048
	ds_read_b128 v[158:161], v158 offset:3072
	ds_read_b128 v[162:165], v174
	ds_read_b128 v[166:169], v174 offset:1024
	ds_read_b128 v[170:173], v174 offset:2048
	ds_read_b128 v[174:177], v174 offset:3072
	s_add_u32 s48, s48, 0x40000
	s_addc_u32 s49, s49, 0
	s_mov_b32 m0, s6
	v_lshl_add_u64 v[224:225], s[48:49], 0, v[134:135]
	ds_read_b128 v[178:181], v145 offset:32768
	ds_read_b128 v[182:185], v145 offset:33792
	ds_read_b128 v[186:189], v145 offset:34816
	ds_read_b128 v[190:193], v145 offset:35840
	ds_read_b128 v[204:207], v145 offset:36864
	ds_read_b128 v[208:211], v145 offset:37888
	ds_read_b128 v[212:215], v145 offset:38912
	ds_read_b128 v[216:219], v145 offset:39936
	global_load_lds_dwordx4 v[224:225], off
	v_lshl_add_u64 v[224:225], s[48:49], 0, v[132:133]
	s_mov_b32 m0, s7
	s_nop 0
	global_load_lds_dwordx4 v[224:225], off
	s_waitcnt vmcnt(8)
	s_waitcnt lgkmcnt(0)
	s_barrier
	s_setprio 1
	v_mfma_f32_16x16x32_bf16 v[126:129], v[146:149], v[178:181], v[126:129]
	v_mfma_f32_16x16x32_bf16 v[122:125], v[154:157], v[178:181], v[122:125]
	v_mfma_f32_16x16x32_bf16 v[114:117], v[146:149], v[186:189], v[114:117]
	v_mfma_f32_16x16x32_bf16 v[106:109], v[154:157], v[186:189], v[106:109]
	v_mfma_f32_16x16x32_bf16 v[98:101], v[146:149], v[204:207], v[98:101]
	v_mfma_f32_16x16x32_bf16 v[90:93], v[154:157], v[204:207], v[90:93]
	v_mfma_f32_16x16x32_bf16 v[82:85], v[146:149], v[212:215], v[82:85]
	v_mfma_f32_16x16x32_bf16 v[74:77], v[154:157], v[212:215], v[74:77]
	v_mfma_f32_16x16x32_bf16 v[126:129], v[150:153], v[182:185], v[126:129]
	v_mfma_f32_16x16x32_bf16 v[122:125], v[158:161], v[182:185], v[122:125]
	v_mfma_f32_16x16x32_bf16 v[114:117], v[150:153], v[190:193], v[114:117]
	v_mfma_f32_16x16x32_bf16 v[106:109], v[158:161], v[190:193], v[106:109]
	v_mfma_f32_16x16x32_bf16 v[98:101], v[150:153], v[208:211], v[98:101]
	v_mfma_f32_16x16x32_bf16 v[90:93], v[158:161], v[208:211], v[90:93]
	v_mfma_f32_16x16x32_bf16 v[82:85], v[150:153], v[216:219], v[82:85]
	v_mfma_f32_16x16x32_bf16 v[74:77], v[158:161], v[216:219], v[74:77]
	s_setprio 0
	s_setprio 1
	v_mfma_f32_16x16x32_bf16 v[118:121], v[162:165], v[178:181], v[118:121]
	v_mfma_f32_16x16x32_bf16 v[110:113], v[170:173], v[178:181], v[110:113]
	v_mfma_f32_16x16x32_bf16 v[102:105], v[162:165], v[186:189], v[102:105]
	v_mfma_f32_16x16x32_bf16 v[94:97], v[170:173], v[186:189], v[94:97]
	v_mfma_f32_16x16x32_bf16 v[86:89], v[162:165], v[204:207], v[86:89]
	v_mfma_f32_16x16x32_bf16 v[78:81], v[170:173], v[204:207], v[78:81]
	v_mfma_f32_16x16x32_bf16 v[70:73], v[162:165], v[212:215], v[70:73]
	v_mfma_f32_16x16x32_bf16 v[66:69], v[170:173], v[212:215], v[66:69]
	v_mfma_f32_16x16x32_bf16 v[118:121], v[166:169], v[182:185], v[118:121]
	v_mfma_f32_16x16x32_bf16 v[110:113], v[174:177], v[182:185], v[110:113]
	v_mfma_f32_16x16x32_bf16 v[102:105], v[166:169], v[190:193], v[102:105]
	v_mfma_f32_16x16x32_bf16 v[94:97], v[174:177], v[190:193], v[94:97]
	v_mfma_f32_16x16x32_bf16 v[86:89], v[166:169], v[208:211], v[86:89]
	v_mfma_f32_16x16x32_bf16 v[78:81], v[174:177], v[208:211], v[78:81]
	v_mfma_f32_16x16x32_bf16 v[70:73], v[166:169], v[216:219], v[70:73]
	v_mfma_f32_16x16x32_bf16 v[66:69], v[174:177], v[216:219], v[66:69]
	s_setprio 0
	s_barrier
	s_add_i32 s20, s20, s2
	v_lshl_add_u64 v[140:141], v[140:141], 0, s[86:87]
	s_mov_b32 m0, s20
	ds_read_b128 v[178:181], v145 offset:49152
	ds_read_b128 v[182:185], v145 offset:50176
	ds_read_b128 v[186:189], v145 offset:51200
	ds_read_b128 v[190:193], v145 offset:52224
	ds_read_b128 v[204:207], v145 offset:53248
	ds_read_b128 v[208:211], v145 offset:54272
	ds_read_b128 v[212:215], v145 offset:55296
	ds_read_b128 v[216:219], v145 offset:56320
	global_load_lds_dwordx4 v[140:141], off
	s_add_i32 m0, s20, 0x2000
	s_add_u32 s48, s50, 0x40080
	v_lshl_add_u64 v[140:141], v[200:201], 0, s[86:87]
	s_addc_u32 s49, s51, 0
	s_add_i32 s20, s39, s2
	global_load_lds_dwordx4 v[140:141], off
	v_lshl_add_u64 v[140:141], s[48:49], 0, v[194:195]
	s_mov_b32 m0, s20
	s_nop 0
	global_load_lds_dwordx4 v[140:141], off
	v_lshl_add_u64 v[140:141], s[48:49], 0, v[130:131]
	s_add_i32 m0, s20, 0x2000
	s_nop 0
	global_load_lds_dwordx4 v[140:141], off
	v_lshl_add_u64 v[140:141], v[220:221], 0, s[86:87]
	s_mov_b32 m0, s8
	s_nop 0
	global_load_lds_dwordx4 v[140:141], off
	v_lshl_add_u64 v[140:141], v[222:223], 0, s[86:87]
	s_mov_b32 m0, s9
	s_nop 0
	global_load_lds_dwordx4 v[140:141], off
	s_waitcnt vmcnt(8)
	s_waitcnt lgkmcnt(0)
	s_barrier
	s_setprio 1
	v_mfma_f32_16x16x32_bf16 v[62:65], v[146:149], v[178:181], v[62:65]
	v_mfma_f32_16x16x32_bf16 v[58:61], v[154:157], v[178:181], v[58:61]
	v_mfma_f32_16x16x32_bf16 v[50:53], v[146:149], v[186:189], v[50:53]
	v_mfma_f32_16x16x32_bf16 v[42:45], v[154:157], v[186:189], v[42:45]
	v_mfma_f32_16x16x32_bf16 v[34:37], v[146:149], v[204:207], v[34:37]
	v_mfma_f32_16x16x32_bf16 v[26:29], v[154:157], v[204:207], v[26:29]
	v_mfma_f32_16x16x32_bf16 v[18:21], v[146:149], v[212:215], v[18:21]
	v_mfma_f32_16x16x32_bf16 v[10:13], v[154:157], v[212:215], v[10:13]
	v_mfma_f32_16x16x32_bf16 v[62:65], v[150:153], v[182:185], v[62:65]
	v_mfma_f32_16x16x32_bf16 v[58:61], v[158:161], v[182:185], v[58:61]
	v_mfma_f32_16x16x32_bf16 v[50:53], v[150:153], v[190:193], v[50:53]
	v_mfma_f32_16x16x32_bf16 v[42:45], v[158:161], v[190:193], v[42:45]
	v_mfma_f32_16x16x32_bf16 v[34:37], v[150:153], v[208:211], v[34:37]
	v_mfma_f32_16x16x32_bf16 v[26:29], v[158:161], v[208:211], v[26:29]
	v_mfma_f32_16x16x32_bf16 v[18:21], v[150:153], v[216:219], v[18:21]
	v_mfma_f32_16x16x32_bf16 v[10:13], v[158:161], v[216:219], v[10:13]
	s_setprio 0
	s_setprio 1
	v_mfma_f32_16x16x32_bf16 v[54:57], v[162:165], v[178:181], v[54:57]
	v_mfma_f32_16x16x32_bf16 v[46:49], v[170:173], v[178:181], v[46:49]
	v_mfma_f32_16x16x32_bf16 v[38:41], v[162:165], v[186:189], v[38:41]
	v_mfma_f32_16x16x32_bf16 v[30:33], v[170:173], v[186:189], v[30:33]
	v_mfma_f32_16x16x32_bf16 v[22:25], v[162:165], v[204:207], v[22:25]
	v_mfma_f32_16x16x32_bf16 v[14:17], v[170:173], v[204:207], v[14:17]
	v_mfma_f32_16x16x32_bf16 v[6:9], v[162:165], v[212:215], v[6:9]
	v_mfma_f32_16x16x32_bf16 v[2:5], v[170:173], v[212:215], v[2:5]
	v_mfma_f32_16x16x32_bf16 v[54:57], v[166:169], v[182:185], v[54:57]
	v_mfma_f32_16x16x32_bf16 v[46:49], v[174:177], v[182:185], v[46:49]
	v_mfma_f32_16x16x32_bf16 v[38:41], v[166:169], v[190:193], v[38:41]
	v_mfma_f32_16x16x32_bf16 v[30:33], v[174:177], v[190:193], v[30:33]
	v_mfma_f32_16x16x32_bf16 v[22:25], v[166:169], v[208:211], v[22:25]
	v_mfma_f32_16x16x32_bf16 v[14:17], v[174:177], v[208:211], v[14:17]
	v_mfma_f32_16x16x32_bf16 v[6:9], v[166:169], v[216:219], v[6:9]
	v_mfma_f32_16x16x32_bf16 v[2:5], v[174:177], v[216:219], v[2:5]
	s_setprio 0
	s_barrier
	s_add_i32 s19, s19, 2
	s_add_u32 s46, s46, 0x100
	s_addc_u32 s47, s47, 0
	s_add_u32 s17, s17, 0x100
	s_addc_u32 s18, s18, 0
	s_cmp_gt_u32 s19, 13
	s_cbranch_scc0 .LBB0_139
	v_readlane_b32 s16, v255, 27
	s_and_b64 vcc, exec, s[30:31]
	v_readlane_b32 s17, v255, 28
	s_cbranch_vccz .LBB0_142
	s_barrier

.LBB0_159:
	s_add_u32 s47, s54, s56
	s_addc_u32 s48, s55, s57
	s_add_u32 s47, s47, 0x100
	s_addc_u32 s48, s48, 0
	s_add_u32 s49, s16, s56
	s_addc_u32 s58, s17, s57
	s_add_i32 s62, 0, 0x10000
	s_cmpk_eq_i32 s56, 0x700
	s_cselect_b32 s61, s18, s48
	s_cselect_b32 s60, s19, s47
	v_add_u32_e32 v143, s62, v141
	s_cselect_b32 s59, s20, s58
	s_cselect_b32 s58, s41, s49
	s_add_i32 s47, 0, 0x14000
	ds_read_b128 v[144:147], v143
	ds_read_b128 v[148:151], v143 offset:1024
	ds_read_b128 v[152:155], v143 offset:2048
	ds_read_b128 v[158:161], v143 offset:3072
	v_add_u32_e32 v143, s47, v141
	ds_read_b128 v[162:165], v143
	ds_read_b128 v[166:169], v143 offset:1024
	ds_read_b128 v[170:173], v143 offset:2048
	ds_read_b128 v[176:179], v143 offset:3072
	v_lshl_add_u64 v[192:193], v[136:137], 0, s[56:57]
	s_add_i32 m0, s8, 0xc000
	ds_read_b128 v[180:183], v142
	ds_read_b128 v[184:187], v142 offset:1024
	ds_read_b128 v[188:191], v142 offset:2048
	ds_read_b128 v[204:207], v142 offset:3072
	ds_read_b128 v[208:211], v142 offset:4096
	ds_read_b128 v[212:215], v142 offset:5120
	ds_read_b128 v[216:219], v142 offset:6144
	ds_read_b128 v[220:223], v142 offset:7168
	global_load_lds_dwordx4 v[192:193], off
	v_lshl_add_u64 v[192:193], v[138:139], 0, s[56:57]
	s_add_i32 m0, s8, 0xe000
	s_nop 0
	global_load_lds_dwordx4 v[192:193], off
	s_waitcnt vmcnt(8)
	s_waitcnt lgkmcnt(0)
	s_barrier
	s_setprio 1
	v_mfma_f32_16x16x32_bf16 v[126:129], v[144:147], v[180:183], v[126:129]
	v_mfma_f32_16x16x32_bf16 v[122:125], v[152:155], v[180:183], v[122:125]
	v_mfma_f32_16x16x32_bf16 v[118:121], v[144:147], v[188:191], v[118:121]
	v_mfma_f32_16x16x32_bf16 v[106:109], v[152:155], v[188:191], v[106:109]
	v_mfma_f32_16x16x32_bf16 v[98:101], v[144:147], v[208:211], v[98:101]
	v_mfma_f32_16x16x32_bf16 v[90:93], v[152:155], v[208:211], v[90:93]
	v_mfma_f32_16x16x32_bf16 v[82:85], v[144:147], v[216:219], v[82:85]
	v_mfma_f32_16x16x32_bf16 v[74:77], v[152:155], v[216:219], v[74:77]
	v_mfma_f32_16x16x32_bf16 v[126:129], v[148:151], v[184:187], v[126:129]
	v_mfma_f32_16x16x32_bf16 v[122:125], v[158:161], v[184:187], v[122:125]
	v_mfma_f32_16x16x32_bf16 v[118:121], v[148:151], v[204:207], v[118:121]
	v_mfma_f32_16x16x32_bf16 v[106:109], v[158:161], v[204:207], v[106:109]
	v_mfma_f32_16x16x32_bf16 v[98:101], v[148:151], v[212:215], v[98:101]
	v_mfma_f32_16x16x32_bf16 v[90:93], v[158:161], v[212:215], v[90:93]
	v_mfma_f32_16x16x32_bf16 v[82:85], v[148:151], v[220:223], v[82:85]
	v_mfma_f32_16x16x32_bf16 v[74:77], v[158:161], v[220:223], v[74:77]
	s_setprio 0
	s_setprio 1
	v_mfma_f32_16x16x32_bf16 v[114:117], v[162:165], v[180:183], v[114:117]
	v_mfma_f32_16x16x32_bf16 v[110:113], v[170:173], v[180:183], v[110:113]
	v_mfma_f32_16x16x32_bf16 v[102:105], v[162:165], v[188:191], v[102:105]
	v_mfma_f32_16x16x32_bf16 v[94:97], v[170:173], v[188:191], v[94:97]
	v_mfma_f32_16x16x32_bf16 v[86:89], v[162:165], v[208:211], v[86:89]
	v_mfma_f32_16x16x32_bf16 v[78:81], v[170:173], v[208:211], v[78:81]
	v_mfma_f32_16x16x32_bf16 v[70:73], v[162:165], v[216:219], v[70:73]
	v_mfma_f32_16x16x32_bf16 v[66:69], v[170:173], v[216:219], v[66:69]
	v_mfma_f32_16x16x32_bf16 v[114:117], v[166:169], v[184:187], v[114:117]
	v_mfma_f32_16x16x32_bf16 v[110:113], v[176:179], v[184:187], v[110:113]
	v_mfma_f32_16x16x32_bf16 v[102:105], v[166:169], v[204:207], v[102:105]
	v_mfma_f32_16x16x32_bf16 v[94:97], v[176:179], v[204:207], v[94:97]
	v_mfma_f32_16x16x32_bf16 v[86:89], v[166:169], v[212:215], v[86:89]
	v_mfma_f32_16x16x32_bf16 v[78:81], v[176:179], v[212:215], v[78:81]
	v_mfma_f32_16x16x32_bf16 v[70:73], v[166:169], v[220:223], v[70:73]
	v_mfma_f32_16x16x32_bf16 v[66:69], v[176:179], v[220:223], v[66:69]
	s_setprio 0
	s_barrier
	s_add_i32 s48, s62, s7
	v_lshl_add_u64 v[192:193], s[58:59], 0, v[194:195]
	s_mov_b32 m0, s48
	ds_read_b128 v[180:183], v142 offset:16384
	ds_read_b128 v[184:187], v142 offset:17408
	ds_read_b128 v[188:191], v142 offset:18432
	ds_read_b128 v[204:207], v142 offset:19456
	ds_read_b128 v[208:211], v142 offset:20480
	ds_read_b128 v[212:215], v142 offset:21504
	ds_read_b128 v[216:219], v142 offset:22528
	ds_read_b128 v[220:223], v142 offset:23552
	global_load_lds_dwordx4 v[192:193], off
	s_add_i32 m0, s48, 0x2000
	s_add_u32 s48, s58, 0x40000
	v_lshl_add_u64 v[224:225], s[58:59], 0, v[130:131]
	s_addc_u32 s49, s59, 0
	s_add_i32 s47, s47, s7
	global_load_lds_dwordx4 v[224:225], off
	v_lshl_add_u64 v[226:227], s[48:49], 0, v[194:195]
	s_mov_b32 m0, s47
	v_lshl_add_u64 v[238:239], s[60:61], 0, v[130:131]
	global_load_lds_dwordx4 v[226:227], off
	v_lshl_add_u64 v[226:227], s[48:49], 0, v[130:131]
	s_add_i32 m0, s47, 0x2000
	s_nop 0
	global_load_lds_dwordx4 v[226:227], off
	v_lshl_add_u64 v[226:227], s[60:61], 0, v[194:195]
	s_mov_b32 m0, s8
	s_nop 0
	global_load_lds_dwordx4 v[226:227], off
	s_mov_b32 m0, s9
	s_nop 0
	global_load_lds_dwordx4 v[238:239], off
	s_waitcnt vmcnt(8)
	s_waitcnt lgkmcnt(0)
	s_barrier
	s_setprio 1
	v_mfma_f32_16x16x32_bf16 v[62:65], v[144:147], v[180:183], v[62:65]
	v_mfma_f32_16x16x32_bf16 v[58:61], v[152:155], v[180:183], v[58:61]
	v_mfma_f32_16x16x32_bf16 v[50:53], v[144:147], v[188:191], v[50:53]
	v_mfma_f32_16x16x32_bf16 v[42:45], v[152:155], v[188:191], v[42:45]
	v_mfma_f32_16x16x32_bf16 v[34:37], v[144:147], v[208:211], v[34:37]
	v_mfma_f32_16x16x32_bf16 v[26:29], v[152:155], v[208:211], v[26:29]
	v_mfma_f32_16x16x32_bf16 v[18:21], v[144:147], v[216:219], v[18:21]
	v_mfma_f32_16x16x32_bf16 v[10:13], v[152:155], v[216:219], v[10:13]
	v_mfma_f32_16x16x32_bf16 v[62:65], v[148:151], v[184:187], v[62:65]
	v_mfma_f32_16x16x32_bf16 v[58:61], v[158:161], v[184:187], v[58:61]
	v_mfma_f32_16x16x32_bf16 v[50:53], v[148:151], v[204:207], v[50:53]
	v_mfma_f32_16x16x32_bf16 v[42:45], v[158:161], v[204:207], v[42:45]
	v_mfma_f32_16x16x32_bf16 v[34:37], v[148:151], v[212:215], v[34:37]
	v_mfma_f32_16x16x32_bf16 v[26:29], v[158:161], v[212:215], v[26:29]
	v_mfma_f32_16x16x32_bf16 v[18:21], v[148:151], v[220:223], v[18:21]
	v_mfma_f32_16x16x32_bf16 v[10:13], v[158:161], v[220:223], v[10:13]
	s_setprio 0
	s_setprio 1
	v_mfma_f32_16x16x32_bf16 v[54:57], v[162:165], v[180:183], v[54:57]
	v_mfma_f32_16x16x32_bf16 v[46:49], v[170:173], v[180:183], v[46:49]
	v_mfma_f32_16x16x32_bf16 v[38:41], v[162:165], v[188:191], v[38:41]
	v_mfma_f32_16x16x32_bf16 v[30:33], v[170:173], v[188:191], v[30:33]
	v_mfma_f32_16x16x32_bf16 v[22:25], v[162:165], v[208:211], v[22:25]
	v_mfma_f32_16x16x32_bf16 v[14:17], v[170:173], v[208:211], v[14:17]
	v_mfma_f32_16x16x32_bf16 v[6:9], v[162:165], v[216:219], v[6:9]
	v_mfma_f32_16x16x32_bf16 v[2:5], v[170:173], v[216:219], v[2:5]
	v_mfma_f32_16x16x32_bf16 v[54:57], v[166:169], v[184:187], v[54:57]
	v_mfma_f32_16x16x32_bf16 v[46:49], v[176:179], v[184:187], v[46:49]
	v_mfma_f32_16x16x32_bf16 v[38:41], v[166:169], v[204:207], v[38:41]
	v_mfma_f32_16x16x32_bf16 v[30:33], v[176:179], v[204:207], v[30:33]
	v_mfma_f32_16x16x32_bf16 v[22:25], v[166:169], v[212:215], v[22:25]
	v_mfma_f32_16x16x32_bf16 v[14:17], v[176:179], v[212:215], v[14:17]
	v_mfma_f32_16x16x32_bf16 v[6:9], v[166:169], v[220:223], v[6:9]
	v_mfma_f32_16x16x32_bf16 v[2:5], v[176:179], v[220:223], v[2:5]
	s_setprio 0
	s_barrier
	s_add_i32 s47, 0, 0x18000
	v_add_u32_e32 v143, s47, v141
	s_add_i32 s62, 0, 0x1c000
	ds_read_b128 v[144:147], v143
	ds_read_b128 v[148:151], v143 offset:1024
	ds_read_b128 v[152:155], v143 offset:2048
	ds_read_b128 v[158:161], v143 offset:3072
	v_add_u32_e32 v143, s62, v141
	ds_read_b128 v[162:165], v143
	ds_read_b128 v[166:169], v143 offset:1024
	ds_read_b128 v[170:173], v143 offset:2048
	ds_read_b128 v[176:179], v143 offset:3072
	s_add_u32 s48, s60, 0x40000
	s_addc_u32 s49, s61, 0
	s_mov_b32 m0, s10
	v_lshl_add_u64 v[240:241], s[48:49], 0, v[194:195]
	ds_read_b128 v[180:183], v142 offset:32768
	ds_read_b128 v[184:187], v142 offset:33792
	ds_read_b128 v[188:191], v142 offset:34816
	ds_read_b128 v[204:207], v142 offset:35840
	ds_read_b128 v[208:211], v142 offset:36864
	ds_read_b128 v[212:215], v142 offset:37888
	ds_read_b128 v[216:219], v142 offset:38912
	ds_read_b128 v[220:223], v142 offset:39936
	global_load_lds_dwordx4 v[240:241], off
	v_lshl_add_u64 v[240:241], s[48:49], 0, v[130:131]
	s_mov_b32 m0, s11
	s_nop 0
	global_load_lds_dwordx4 v[240:241], off
	s_waitcnt vmcnt(8)
	s_waitcnt lgkmcnt(0)
	s_barrier
	s_setprio 1
	v_mfma_f32_16x16x32_bf16 v[126:129], v[144:147], v[180:183], v[126:129]
	v_mfma_f32_16x16x32_bf16 v[122:125], v[152:155], v[180:183], v[122:125]
	v_mfma_f32_16x16x32_bf16 v[118:121], v[144:147], v[188:191], v[118:121]
	v_mfma_f32_16x16x32_bf16 v[106:109], v[152:155], v[188:191], v[106:109]
	v_mfma_f32_16x16x32_bf16 v[98:101], v[144:147], v[208:211], v[98:101]
	v_mfma_f32_16x16x32_bf16 v[90:93], v[152:155], v[208:211], v[90:93]
	v_mfma_f32_16x16x32_bf16 v[82:85], v[144:147], v[216:219], v[82:85]
	v_mfma_f32_16x16x32_bf16 v[74:77], v[152:155], v[216:219], v[74:77]
	v_mfma_f32_16x16x32_bf16 v[126:129], v[148:151], v[184:187], v[126:129]
	v_mfma_f32_16x16x32_bf16 v[122:125], v[158:161], v[184:187], v[122:125]
	v_mfma_f32_16x16x32_bf16 v[118:121], v[148:151], v[204:207], v[118:121]
	v_mfma_f32_16x16x32_bf16 v[106:109], v[158:161], v[204:207], v[106:109]
	v_mfma_f32_16x16x32_bf16 v[98:101], v[148:151], v[212:215], v[98:101]
	v_mfma_f32_16x16x32_bf16 v[90:93], v[158:161], v[212:215], v[90:93]
	v_mfma_f32_16x16x32_bf16 v[82:85], v[148:151], v[220:223], v[82:85]
	v_mfma_f32_16x16x32_bf16 v[74:77], v[158:161], v[220:223], v[74:77]
	s_setprio 0
	s_setprio 1
	v_mfma_f32_16x16x32_bf16 v[114:117], v[162:165], v[180:183], v[114:117]
	v_mfma_f32_16x16x32_bf16 v[110:113], v[170:173], v[180:183], v[110:113]
	v_mfma_f32_16x16x32_bf16 v[102:105], v[162:165], v[188:191], v[102:105]
	v_mfma_f32_16x16x32_bf16 v[94:97], v[170:173], v[188:191], v[94:97]
	v_mfma_f32_16x16x32_bf16 v[86:89], v[162:165], v[208:211], v[86:89]
	v_mfma_f32_16x16x32_bf16 v[78:81], v[170:173], v[208:211], v[78:81]
	v_mfma_f32_16x16x32_bf16 v[70:73], v[162:165], v[216:219], v[70:73]
	v_mfma_f32_16x16x32_bf16 v[66:69], v[170:173], v[216:219], v[66:69]
	v_mfma_f32_16x16x32_bf16 v[114:117], v[166:169], v[184:187], v[114:117]
	v_mfma_f32_16x16x32_bf16 v[110:113], v[176:179], v[184:187], v[110:113]
	v_mfma_f32_16x16x32_bf16 v[102:105], v[166:169], v[204:207], v[102:105]
	v_mfma_f32_16x16x32_bf16 v[94:97], v[176:179], v[204:207], v[94:97]
	v_mfma_f32_16x16x32_bf16 v[86:89], v[166:169], v[212:215], v[86:89]
	v_mfma_f32_16x16x32_bf16 v[78:81], v[176:179], v[212:215], v[78:81]
	v_mfma_f32_16x16x32_bf16 v[70:73], v[166:169], v[220:223], v[70:73]
	v_mfma_f32_16x16x32_bf16 v[66:69], v[176:179], v[220:223], v[66:69]
	s_setprio 0
	s_barrier
	s_add_i32 s47, s47, s7
	v_lshl_add_u64 v[192:193], v[192:193], 0, s[86:87]
	s_mov_b32 m0, s47
	ds_read_b128 v[180:183], v142 offset:49152
	ds_read_b128 v[184:187], v142 offset:50176
	ds_read_b128 v[188:191], v142 offset:51200
	ds_read_b128 v[204:207], v142 offset:52224
	ds_read_b128 v[208:211], v142 offset:53248
	ds_read_b128 v[212:215], v142 offset:54272
	ds_read_b128 v[216:219], v142 offset:55296
	ds_read_b128 v[220:223], v142 offset:56320
	global_load_lds_dwordx4 v[192:193], off
	s_add_i32 m0, s47, 0x2000
	s_add_u32 s48, s58, 0x40080
	v_lshl_add_u64 v[192:193], v[224:225], 0, s[86:87]
	s_addc_u32 s49, s59, 0
	s_add_i32 s47, s62, s7
	global_load_lds_dwordx4 v[192:193], off
	v_lshl_add_u64 v[192:193], s[48:49], 0, v[194:195]
	s_mov_b32 m0, s47
	s_nop 0
	global_load_lds_dwordx4 v[192:193], off
	v_lshl_add_u64 v[192:193], s[48:49], 0, v[130:131]
	s_add_i32 m0, s47, 0x2000
	s_nop 0
	global_load_lds_dwordx4 v[192:193], off
	v_lshl_add_u64 v[192:193], v[226:227], 0, s[86:87]
	s_mov_b32 m0, s12
	s_nop 0
	global_load_lds_dwordx4 v[192:193], off
	v_lshl_add_u64 v[192:193], v[238:239], 0, s[86:87]
	s_mov_b32 m0, s13
	s_nop 0
	global_load_lds_dwordx4 v[192:193], off
	s_waitcnt vmcnt(8)
	s_waitcnt lgkmcnt(0)
	s_barrier
	s_setprio 1
	v_mfma_f32_16x16x32_bf16 v[62:65], v[144:147], v[180:183], v[62:65]
	v_mfma_f32_16x16x32_bf16 v[58:61], v[152:155], v[180:183], v[58:61]
	v_mfma_f32_16x16x32_bf16 v[50:53], v[144:147], v[188:191], v[50:53]
	v_mfma_f32_16x16x32_bf16 v[42:45], v[152:155], v[188:191], v[42:45]
	v_mfma_f32_16x16x32_bf16 v[34:37], v[144:147], v[208:211], v[34:37]
	v_mfma_f32_16x16x32_bf16 v[26:29], v[152:155], v[208:211], v[26:29]
	v_mfma_f32_16x16x32_bf16 v[18:21], v[144:147], v[216:219], v[18:21]
	v_mfma_f32_16x16x32_bf16 v[10:13], v[152:155], v[216:219], v[10:13]
	v_mfma_f32_16x16x32_bf16 v[62:65], v[148:151], v[184:187], v[62:65]
	v_mfma_f32_16x16x32_bf16 v[58:61], v[158:161], v[184:187], v[58:61]
	v_mfma_f32_16x16x32_bf16 v[50:53], v[148:151], v[204:207], v[50:53]
	v_mfma_f32_16x16x32_bf16 v[42:45], v[158:161], v[204:207], v[42:45]
	v_mfma_f32_16x16x32_bf16 v[34:37], v[148:151], v[212:215], v[34:37]
	v_mfma_f32_16x16x32_bf16 v[26:29], v[158:161], v[212:215], v[26:29]
	v_mfma_f32_16x16x32_bf16 v[18:21], v[148:151], v[220:223], v[18:21]
	v_mfma_f32_16x16x32_bf16 v[10:13], v[158:161], v[220:223], v[10:13]
	s_setprio 0
	s_setprio 1
	v_mfma_f32_16x16x32_bf16 v[54:57], v[162:165], v[180:183], v[54:57]
	v_mfma_f32_16x16x32_bf16 v[46:49], v[170:173], v[180:183], v[46:49]
	v_mfma_f32_16x16x32_bf16 v[38:41], v[162:165], v[188:191], v[38:41]
	v_mfma_f32_16x16x32_bf16 v[30:33], v[170:173], v[188:191], v[30:33]
	v_mfma_f32_16x16x32_bf16 v[22:25], v[162:165], v[208:211], v[22:25]
	v_mfma_f32_16x16x32_bf16 v[14:17], v[170:173], v[208:211], v[14:17]
	v_mfma_f32_16x16x32_bf16 v[6:9], v[162:165], v[216:219], v[6:9]
	v_mfma_f32_16x16x32_bf16 v[2:5], v[170:173], v[216:219], v[2:5]
	v_mfma_f32_16x16x32_bf16 v[54:57], v[166:169], v[184:187], v[54:57]
	v_mfma_f32_16x16x32_bf16 v[46:49], v[176:179], v[184:187], v[46:49]
	v_mfma_f32_16x16x32_bf16 v[38:41], v[166:169], v[204:207], v[38:41]
	v_mfma_f32_16x16x32_bf16 v[30:33], v[176:179], v[204:207], v[30:33]
	v_mfma_f32_16x16x32_bf16 v[22:25], v[166:169], v[212:215], v[22:25]
	v_mfma_f32_16x16x32_bf16 v[14:17], v[176:179], v[212:215], v[14:17]
	v_mfma_f32_16x16x32_bf16 v[6:9], v[166:169], v[220:223], v[6:9]
	v_mfma_f32_16x16x32_bf16 v[2:5], v[176:179], v[220:223], v[2:5]
	s_setprio 0
	s_barrier
	s_add_i32 s45, s45, 2
	s_add_u32 s56, s56, 0x100
	s_addc_u32 s57, s57, 0
	s_cmp_gt_u32 s45, 13
	s_cbranch_scc0 .LBB0_159
	s_and_b64 vcc, exec, s[42:43]
	s_cbranch_vccz .LBB0_162
	s_barrier

.LBB0_170:
	s_or_b64 exec, exec, s[30:31]
	v_mul_f32_e32 v131, v119, v119
	s_waitcnt lgkmcnt(0)
	v_mul_f32_e32 v132, v121, v121
	v_fmac_f32_e32 v131, v118, v118
	v_fmac_f32_e32 v132, v120, v120
	v_add_f32_e32 v131, v131, v132
	v_mul_f32_e32 v132, v107, v107
	v_mul_f32_e32 v133, v109, v109
	v_fmac_f32_e32 v132, v106, v106
	v_fmac_f32_e32 v133, v108, v108
	v_add_f32_e32 v132, v132, v133
	v_add_f32_e32 v131, v132, v131
	v_mul_f32_e32 v132, v103, v103
	v_mul_f32_e32 v133, v105, v105
	v_fmac_f32_e32 v132, v102, v102
	v_fmac_f32_e32 v133, v104, v104
	v_add_f32_e32 v132, v132, v133
	v_add_f32_e32 v131, v132, v131
	v_mul_f32_e32 v132, v95, v95
	v_mul_f32_e32 v133, v97, v97
	v_fmac_f32_e32 v132, v94, v94
	v_fmac_f32_e32 v133, v96, v96
	v_add_f32_e32 v132, v132, v133
	v_add_f32_e32 v131, v132, v131
	v_mov_b32_e32 v132, v131
	s_nop 1
	v_permlane16_swap_b32_e32 v132, v131
	s_nop 1
	v_add_f32_e32 v131, v131, v132
	v_mov_b32_e32 v132, v131
	s_nop 1
	v_permlane32_swap_b32_e32 v132, v131
	s_nop 1
	s_and_saveexec_b64 s[30:31], s[36:37]
	s_cbranch_execz .LBB0_172
	s_lshl_b32 s8, s2, 10
	s_add_i32 s8, s7, s8
	v_lshl_add_u32 v133, v174, 4, s8
	v_add_f32_e32 v131, v131, v132
	ds_write_b32 v133, v131 offset:256
.LBB0_172:
	s_or_b64 exec, exec, s[30:31]
	v_mul_f32_e32 v131, v99, v99
	s_waitcnt lgkmcnt(0)
	v_mul_f32_e32 v132, v101, v101
	v_fmac_f32_e32 v131, v98, v98
	v_fmac_f32_e32 v132, v100, v100
	v_add_f32_e32 v131, v131, v132
	v_mul_f32_e32 v132, v91, v91
	v_mul_f32_e32 v133, v93, v93
	v_fmac_f32_e32 v132, v90, v90
	v_fmac_f32_e32 v133, v92, v92
	v_add_f32_e32 v132, v132, v133
	v_add_f32_e32 v131, v132, v131
	v_mul_f32_e32 v132, v87, v87
	v_mul_f32_e32 v133, v89, v89
	v_fmac_f32_e32 v132, v86, v86
	v_fmac_f32_e32 v133, v88, v88
	v_add_f32_e32 v132, v132, v133
	v_add_f32_e32 v131, v132, v131
	v_mul_f32_e32 v132, v79, v79
	v_mul_f32_e32 v133, v81, v81
	v_fmac_f32_e32 v132, v78, v78
	v_fmac_f32_e32 v133, v80, v80
	v_add_f32_e32 v132, v132, v133
	v_add_f32_e32 v131, v132, v131
	v_mov_b32_e32 v132, v131
	s_nop 1
	v_permlane16_swap_b32_e32 v132, v131
	s_nop 1
	v_add_f32_e32 v131, v131, v132
	v_mov_b32_e32 v132, v131
	s_nop 1
	v_permlane32_swap_b32_e32 v132, v131
	s_nop 1
	s_and_saveexec_b64 s[30:31], s[36:37]
	s_cbranch_execz .LBB0_174
	s_lshl_b32 s8, s2, 10
	s_add_i32 s8, s7, s8
	v_lshl_add_u32 v133, v174, 4, s8
	v_add_f32_e32 v131, v131, v132
	ds_write_b32 v133, v131 offset:512
.LBB0_174:
	s_or_b64 exec, exec, s[30:31]
	v_mul_f32_e32 v131, v83, v83
	s_waitcnt lgkmcnt(0)
	v_mul_f32_e32 v132, v85, v85
	v_fmac_f32_e32 v131, v82, v82
	v_fmac_f32_e32 v132, v84, v84
	v_add_f32_e32 v131, v131, v132
	v_mul_f32_e32 v132, v75, v75
	v_mul_f32_e32 v133, v77, v77
	v_fmac_f32_e32 v132, v74, v74
	v_fmac_f32_e32 v133, v76, v76
	v_add_f32_e32 v132, v132, v133
	v_add_f32_e32 v131, v132, v131
	v_mul_f32_e32 v132, v71, v71
	v_mul_f32_e32 v133, v73, v73
	v_fmac_f32_e32 v132, v70, v70
	v_fmac_f32_e32 v133, v72, v72
	v_add_f32_e32 v132, v132, v133
	v_add_f32_e32 v131, v132, v131
	v_mul_f32_e32 v132, v67, v67
	v_mul_f32_e32 v133, v69, v69
	v_fmac_f32_e32 v132, v66, v66
	v_fmac_f32_e32 v133, v68, v68
	v_add_f32_e32 v132, v132, v133
	v_add_f32_e32 v131, v132, v131
	v_mov_b32_e32 v132, v131
	s_nop 1
	v_permlane16_swap_b32_e32 v132, v131
	s_nop 1
	v_add_f32_e32 v131, v131, v132
	v_mov_b32_e32 v132, v131
	s_nop 1
	v_permlane32_swap_b32_e32 v132, v131
	s_nop 1
	s_and_saveexec_b64 s[30:31], s[36:37]
	s_cbranch_execz .LBB0_176
	s_lshl_b32 s8, s2, 10
	s_add_i32 s8, s7, s8
	v_lshl_add_u32 v133, v174, 4, s8
	v_add_f32_e32 v131, v131, v132
	ds_write_b32 v133, v131 offset:768
.LBB0_176:
	s_or_b64 exec, exec, s[30:31]
	v_mul_f32_e32 v131, v63, v63
	s_waitcnt lgkmcnt(0)
	v_mul_f32_e32 v132, v65, v65
	v_fmac_f32_e32 v131, v62, v62
	v_fmac_f32_e32 v132, v64, v64
	v_add_f32_e32 v131, v131, v132
	v_mul_f32_e32 v132, v59, v59
	v_mul_f32_e32 v133, v61, v61
	v_fmac_f32_e32 v132, v58, v58
	v_fmac_f32_e32 v133, v60, v60
	v_add_f32_e32 v132, v132, v133
	v_add_f32_e32 v131, v132, v131
	v_mul_f32_e32 v132, v55, v55
	v_mul_f32_e32 v133, v57, v57
	v_fmac_f32_e32 v132, v54, v54
	v_fmac_f32_e32 v133, v56, v56
	v_add_f32_e32 v132, v132, v133
	v_add_f32_e32 v131, v132, v131
	v_mul_f32_e32 v132, v47, v47
	v_mul_f32_e32 v133, v49, v49
	v_fmac_f32_e32 v132, v46, v46
	v_fmac_f32_e32 v133, v48, v48
	v_add_f32_e32 v132, v132, v133
	v_add_f32_e32 v131, v132, v131
	v_mov_b32_e32 v132, v131
	s_nop 1
	v_permlane16_swap_b32_e32 v132, v131
	s_nop 1
	v_add_f32_e32 v131, v131, v132
	v_mov_b32_e32 v132, v131
	s_nop 1
	v_permlane32_swap_b32_e32 v132, v131
	s_nop 1
	s_and_saveexec_b64 s[30:31], s[36:37]
	s_cbranch_execz .LBB0_178
	s_lshl_b32 s8, s2, 10
	s_add_i32 s8, s7, s8
	v_lshl_add_u32 v133, v174, 4, s8
	v_add_f32_e32 v131, v131, v132
	ds_write_b32 v133, v131 offset:2048
.LBB0_178:
	s_or_b64 exec, exec, s[30:31]
	v_mul_f32_e32 v131, v51, v51
	s_waitcnt lgkmcnt(0)
	v_mul_f32_e32 v132, v53, v53
	v_fmac_f32_e32 v131, v50, v50
	v_fmac_f32_e32 v132, v52, v52
	v_add_f32_e32 v131, v131, v132
	v_mul_f32_e32 v132, v43, v43
	v_mul_f32_e32 v133, v45, v45
	v_fmac_f32_e32 v132, v42, v42
	v_fmac_f32_e32 v133, v44, v44
	v_add_f32_e32 v132, v132, v133
	v_add_f32_e32 v131, v132, v131
	v_mul_f32_e32 v132, v39, v39
	v_mul_f32_e32 v133, v41, v41
	v_fmac_f32_e32 v132, v38, v38
	v_fmac_f32_e32 v133, v40, v40
	v_add_f32_e32 v132, v132, v133
	v_add_f32_e32 v131, v132, v131
	v_mul_f32_e32 v132, v31, v31
	v_mul_f32_e32 v133, v33, v33
	v_fmac_f32_e32 v132, v30, v30
	v_fmac_f32_e32 v133, v32, v32
	v_add_f32_e32 v132, v132, v133
	v_add_f32_e32 v131, v132, v131
	v_mov_b32_e32 v132, v131
	s_nop 1
	v_permlane16_swap_b32_e32 v132, v131
	s_nop 1
	v_add_f32_e32 v131, v131, v132
	v_mov_b32_e32 v132, v131
	s_nop 1
	v_permlane32_swap_b32_e32 v132, v131
	s_nop 1
	s_and_saveexec_b64 s[30:31], s[36:37]
	s_cbranch_execz .LBB0_180
	s_lshl_b32 s8, s2, 10
	s_add_i32 s8, s7, s8
	v_lshl_add_u32 v133, v174, 4, s8
	v_add_f32_e32 v131, v131, v132
	ds_write_b32 v133, v131 offset:2304
.LBB0_180:
	s_or_b64 exec, exec, s[30:31]
	v_mul_f32_e32 v131, v35, v35
	s_waitcnt lgkmcnt(0)
	v_mul_f32_e32 v132, v37, v37
	v_fmac_f32_e32 v131, v34, v34
	v_fmac_f32_e32 v132, v36, v36
	v_add_f32_e32 v131, v131, v132
	v_mul_f32_e32 v132, v27, v27
	v_mul_f32_e32 v133, v29, v29
	v_fmac_f32_e32 v132, v26, v26
	v_fmac_f32_e32 v133, v28, v28
	v_add_f32_e32 v132, v132, v133
	v_add_f32_e32 v131, v132, v131
	v_mul_f32_e32 v132, v23, v23
	v_mul_f32_e32 v133, v25, v25
	v_fmac_f32_e32 v132, v22, v22
	v_fmac_f32_e32 v133, v24, v24
	v_add_f32_e32 v132, v132, v133
	v_add_f32_e32 v131, v132, v131
	v_mul_f32_e32 v132, v15, v15
	v_mul_f32_e32 v133, v17, v17
	v_fmac_f32_e32 v132, v14, v14
	v_fmac_f32_e32 v133, v16, v16
	v_add_f32_e32 v132, v132, v133
	v_add_f32_e32 v131, v132, v131
	v_mov_b32_e32 v132, v131
	s_nop 1
	v_permlane16_swap_b32_e32 v132, v131
	s_nop 1
	v_add_f32_e32 v131, v131, v132
	v_mov_b32_e32 v132, v131
	s_nop 1
	v_permlane32_swap_b32_e32 v132, v131
	s_nop 1
	s_and_saveexec_b64 s[30:31], s[36:37]
	s_cbranch_execz .LBB0_182
	s_lshl_b32 s8, s2, 10
	s_add_i32 s8, s7, s8
	v_lshl_add_u32 v133, v174, 4, s8
	v_add_f32_e32 v131, v131, v132
	ds_write_b32 v133, v131 offset:2560
.LBB0_182:
	s_or_b64 exec, exec, s[30:31]
	v_mul_f32_e32 v131, v19, v19
	s_waitcnt lgkmcnt(0)
	v_mul_f32_e32 v132, v21, v21
	v_fmac_f32_e32 v131, v18, v18
	v_fmac_f32_e32 v132, v20, v20
	v_add_f32_e32 v131, v131, v132
	v_mul_f32_e32 v132, v11, v11
	v_mul_f32_e32 v133, v13, v13
	v_fmac_f32_e32 v132, v10, v10
	v_fmac_f32_e32 v133, v12, v12
	v_add_f32_e32 v132, v132, v133
	v_add_f32_e32 v131, v132, v131
	v_mul_f32_e32 v132, v7, v7
	v_mul_f32_e32 v133, v9, v9
	v_fmac_f32_e32 v132, v6, v6
	v_fmac_f32_e32 v133, v8, v8
	v_add_f32_e32 v132, v132, v133
	v_add_f32_e32 v131, v132, v131
	v_mul_f32_e32 v132, v3, v3
	v_mul_f32_e32 v133, v5, v5
	v_fmac_f32_e32 v132, v2, v2
	v_fmac_f32_e32 v133, v4, v4
	v_add_f32_e32 v132, v132, v133
	v_add_f32_e32 v131, v132, v131
	v_mov_b32_e32 v132, v131
	s_nop 1
	v_permlane16_swap_b32_e32 v132, v131
	s_nop 1
	v_add_f32_e32 v131, v131, v132
	v_mov_b32_e32 v132, v131
	s_nop 1
	v_permlane32_swap_b32_e32 v132, v131
	s_nop 1
	s_and_saveexec_b64 s[30:31], s[36:37]
	s_cbranch_execz .LBB0_184
	s_lshl_b32 s8, s2, 10
	s_add_i32 s8, s7, s8
	v_lshl_add_u32 v133, v174, 4, s8
	v_add_f32_e32 v131, v131, v132
	ds_write_b32 v133, v131 offset:2816
.LBB0_184:
	s_or_b64 exec, exec, s[30:31]
	v_readlane_b32 s8, v255, 29
	v_readlane_b32 s9, v255, 30
	s_lshl_b32 s10, s8, 2
	v_readlane_b32 s8, v255, 32
	v_readlane_b32 s9, v255, 33
	s_and_b64 s[8:9], s[8:9], exec
	s_cselect_b32 s8, 2, 0
	s_or_b32 s30, s8, s10
	s_ashr_i32 s31, s30, 31
	s_lshl_b64 s[8:9], s[30:31], 18
	v_readlane_b32 s10, v251, 27
	s_add_u32 s42, s10, s8
	v_readlane_b32 s8, v251, 28
	s_waitcnt lgkmcnt(0)
	s_barrier
	s_addc_u32 s43, s8, s9
	s_movk_i32 s8, 0x100
	v_cmp_gt_i32_e64 s[38:39], s8, v130
	s_and_saveexec_b64 s[44:45], s[38:39]
	s_cbranch_execz .LBB0_186
	v_lshl_add_u32 v131, v130, 4, 0
	ds_read_b128 v[132:135], v131
	v_lshl_add_u32 v136, s4, 8, v130
	v_ashrrev_i32_e32 v137, 31, v136
	v_lshl_add_u64 v[136:137], v[136:137], 4, s[42:43]
	s_ashr_i32 s41, s40, 31
	s_waitcnt lgkmcnt(0)
	v_mov_b32_e32 v138, v133
	v_mov_b32_e32 v139, v134
	v_mov_b32_e32 v133, v135
	v_pk_add_f32 v[132:133], v[138:139], v[132:133]
	v_lshl_add_u64 v[136:137], s[40:41], 2, v[136:137]
	v_pk_add_f32 v[132:133], v[132:133], v[132:133] op_sel:[0,1] op_sel_hi:[1,0]
	global_store_dword v[136:137], v132, off sc1

.LBB0_200:
	s_or_b64 exec, exec, s[44:45]
	s_lshl_b32 s6, s6, 5
	s_lshl_b32 s9, s40, 8
	v_readlane_b32 s10, v255, 32
	s_or_b32 s6, s9, s6
	v_readlane_b32 s11, v255, 33
	s_and_b64 s[10:11], s[10:11], exec
	v_lshl_or_b32 v154, v140, 2, s6
	s_cselect_b32 s6, 0x1000000, 0
	s_lshl_b32 s9, s6, 2
	s_add_u32 s10, s0, s9
	s_addc_u32 s11, s1, 0
	v_readlane_b32 s12, v255, 29
	s_add_u32 s38, s72, s9
	v_readlane_b32 s13, v255, 30
	v_readlane_b32 s44, v252, 25
	s_addc_u32 s39, s73, 0
	s_lshl_b64 s[12:13], s[12:13], 12
	v_readlane_b32 s52, v252, 33
	v_readlane_b32 s53, v252, 34
	s_add_u32 s12, s52, s12
	s_addc_u32 s13, s53, s13
	s_add_i32 s5, s8, s5
	v_ashrrev_i32_e32 v155, 31, v154
	v_or_b32_e32 v152, s5, v174
	v_lshlrev_b64 v[172:173], 2, v[154:155]
	v_ashrrev_i32_e32 v153, 31, v152
	v_lshl_add_u64 v[150:151], s[10:11], 0, v[172:173]
	v_lshlrev_b64 v[130:131], 12, v[152:153]
	v_lshl_add_u64 v[134:135], s[12:13], 0, v[172:173]
	v_lshl_add_u64 v[158:159], v[150:151], 0, v[130:131]
	s_waitcnt lgkmcnt(0)
	s_barrier
	global_load_dwordx4 v[130:133], v[158:159], off
	global_load_dwordx4 v[146:149], v[134:135], off
	global_load_dwordx4 v[142:145], v[134:135], off offset:64
	global_load_dwordx4 v[160:163], v[158:159], off offset:64
	global_load_dwordx4 v[166:169], v[158:159], off offset:512
	global_load_dwordx4 v[138:141], v[134:135], off offset:512
	s_nop 0
	global_load_dwordx4 v[134:137], v[134:135], off offset:576
	s_nop 0
	global_load_dwordx4 v[178:181], v[158:159], off offset:576
	v_or_b32_e32 v158, 16, v152
	v_ashrrev_i32_e32 v159, 31, v158
	v_lshlrev_b64 v[158:159], 12, v[158:159]
	v_lshl_add_u64 v[158:159], v[150:151], 0, v[158:159]
	global_load_dwordx4 v[182:185], v[158:159], off
	global_load_dwordx4 v[186:189], v[158:159], off offset:64
	global_load_dwordx4 v[190:193], v[158:159], off offset:512
	global_load_dwordx4 v[204:207], v[158:159], off offset:576
	v_or_b32_e32 v158, 32, v152
	v_ashrrev_i32_e32 v159, 31, v158
	v_lshlrev_b64 v[158:159], 12, v[158:159]
	v_lshl_add_u32 v175, v156, 2, 0
	v_lshl_add_u64 v[170:171], v[150:151], 0, v[158:159]
	v_add_u32_e32 v194, 0x1000, v175
	global_load_dwordx4 v[208:211], v[170:171], off
	global_load_dwordx4 v[212:215], v[170:171], off offset:64
	v_add_u32_e32 v164, s8, v156
	ds_read2_b32 v[156:157], v194 offset1:16
	global_load_dwordx4 v[216:219], v[170:171], off offset:512
	global_load_dwordx4 v[220:223], v[170:171], off offset:576
	v_or_b32_e32 v224, 48, v152
	v_add_u32_e32 v158, 16, v164
	v_ashrrev_i32_e32 v225, 31, v224
	v_ashrrev_i32_e32 v159, 31, v158
	v_lshlrev_b64 v[224:225], 12, v[224:225]
	v_lshlrev_b64 v[246:247], 12, v[158:159]
	s_waitcnt lgkmcnt(0)
	v_pk_mul_f32 v[126:127], v[126:127], v[156:157] op_sel_hi:[1,0]
	v_lshl_add_u64 v[248:249], v[150:151], 0, v[224:225]
	v_pk_mul_f32 v[128:129], v[128:129], v[156:157] op_sel_hi:[1,0]
	v_pk_mul_f32 v[122:123], v[122:123], v[156:157] op_sel_hi:[1,0]
	v_pk_mul_f32 v[124:125], v[124:125], v[156:157] op_sel_hi:[1,0]
	v_pk_mul_f32 v[114:115], v[114:115], v[156:157] op_sel_hi:[1,0]
	v_pk_mul_f32 v[116:117], v[116:117], v[156:157] op_sel_hi:[1,0]
	v_pk_mul_f32 v[110:111], v[110:111], v[156:157] op_sel_hi:[1,0]
	v_pk_mul_f32 v[112:113], v[112:113], v[156:157] op_sel_hi:[1,0]
	v_mov_b32_e32 v156, v157
	global_load_dwordx4 v[224:227], v[248:249], off
	global_load_dwordx4 v[238:241], v[248:249], off offset:64
	v_pk_mul_f32 v[228:229], v[120:121], v[156:157] op_sel_hi:[1,0]
	global_load_dwordx4 v[242:245], v[248:249], off offset:512
	v_lshl_add_u64 v[120:121], s[38:39], 0, v[246:247]
	global_load_dwordx4 v[246:249], v[248:249], off offset:576
	v_ashrrev_i32_e32 v165, 31, v164
	v_lshlrev_b64 v[170:171], 12, v[164:165]
	v_pk_mul_f32 v[236:237], v[118:119], v[156:157] op_sel_hi:[1,0]
	v_lshl_add_u64 v[118:119], s[38:39], 0, v[170:171]
	v_lshl_add_u64 v[170:171], v[118:119], 0, v[172:173]
	v_lshl_add_u64 v[200:201], v[120:121], 0, v[172:173]
	v_pk_mul_f32 v[106:107], v[106:107], v[156:157] op_sel_hi:[1,0]
	v_pk_mul_f32 v[108:109], v[108:109], v[156:157] op_sel_hi:[1,0]
	v_pk_mul_f32 v[102:103], v[102:103], v[156:157] op_sel_hi:[1,0]
	v_pk_mul_f32 v[104:105], v[104:105], v[156:157] op_sel_hi:[1,0]
	v_pk_mul_f32 v[94:95], v[94:95], v[156:157] op_sel_hi:[1,0]
	v_pk_mul_f32 v[96:97], v[96:97], v[156:157] op_sel_hi:[1,0]
	v_readlane_b32 s45, v252, 26
	v_readlane_b32 s46, v252, 27
	v_readlane_b32 s47, v252, 28
	v_readlane_b32 s48, v252, 29
	v_readlane_b32 s49, v252, 30
	v_readlane_b32 s50, v252, 31
	v_readlane_b32 s51, v252, 32
	v_readlane_b32 s54, v252, 35
	v_readlane_b32 s55, v252, 36
	v_readlane_b32 s56, v252, 37
	v_readlane_b32 s57, v252, 38
	v_readlane_b32 s58, v252, 39
	v_readlane_b32 s59, v252, 40
	s_waitcnt vmcnt(18)
	v_pk_fma_f32 v[132:133], v[148:149], v[128:129], v[132:133]
	v_pk_fma_f32 v[130:131], v[146:147], v[126:127], v[130:131]
	s_waitcnt vmcnt(16)
	v_pk_fma_f32 v[128:129], v[144:145], v[124:125], v[162:163]
	v_pk_fma_f32 v[126:127], v[142:143], v[122:123], v[160:161]
	s_waitcnt vmcnt(14)
	v_pk_fma_f32 v[124:125], v[140:141], v[116:117], v[168:169]
	v_pk_fma_f32 v[122:123], v[138:139], v[114:115], v[166:167]
	s_waitcnt vmcnt(12)
	v_pk_fma_f32 v[120:121], v[136:137], v[112:113], v[180:181]
	v_pk_fma_f32 v[118:119], v[134:135], v[110:111], v[178:179]
	global_store_dwordx4 v[170:171], v[130:133], off
	global_store_dwordx4 v[170:171], v[126:129], off offset:64
	global_store_dwordx4 v[170:171], v[122:125], off offset:512
	global_store_dwordx4 v[170:171], v[118:121], off offset:576
	ds_read2_b32 v[162:163], v194 offset0:32 offset1:48
	v_add_u32_e32 v160, 32, v164
	v_ashrrev_i32_e32 v161, 31, v160
	v_lshlrev_b64 v[156:157], 12, v[160:161]
	s_waitcnt vmcnt(14)
	v_pk_fma_f32 v[116:117], v[144:145], v[108:109], v[188:189]
	v_pk_fma_f32 v[114:115], v[142:143], v[106:107], v[186:187]
	s_waitcnt vmcnt(13)
	v_pk_fma_f32 v[108:109], v[140:141], v[104:105], v[192:193]
	v_pk_fma_f32 v[106:107], v[138:139], v[102:103], v[190:191]
	s_waitcnt vmcnt(12)
	v_pk_fma_f32 v[104:105], v[136:137], v[96:97], v[206:207]
	v_pk_fma_f32 v[102:103], v[134:135], v[94:95], v[204:205]
	s_waitcnt lgkmcnt(0)
	v_pk_mul_f32 v[94:95], v[98:99], v[162:163] op_sel_hi:[1,0]
	v_pk_mul_f32 v[96:97], v[100:101], v[162:163] op_sel_hi:[1,0]
	v_lshl_add_u64 v[98:99], s[38:39], 0, v[156:157]
	v_pk_mul_f32 v[90:91], v[90:91], v[162:163] op_sel_hi:[1,0]
	v_pk_mul_f32 v[92:93], v[92:93], v[162:163] op_sel_hi:[1,0]
	v_pk_mul_f32 v[86:87], v[86:87], v[162:163] op_sel_hi:[1,0]
	v_pk_mul_f32 v[88:89], v[88:89], v[162:163] op_sel_hi:[1,0]
	v_pk_mul_f32 v[78:79], v[78:79], v[162:163] op_sel_hi:[1,0]
	v_pk_mul_f32 v[80:81], v[80:81], v[162:163] op_sel_hi:[1,0]
	s_waitcnt vmcnt(11)
	v_pk_fma_f32 v[96:97], v[148:149], v[96:97], v[210:211]
	v_pk_fma_f32 v[94:95], v[146:147], v[94:95], v[208:209]
	v_lshl_add_u64 v[156:157], v[98:99], 0, v[172:173]
	s_waitcnt vmcnt(10)
	v_pk_fma_f32 v[100:101], v[144:145], v[92:93], v[214:215]
	v_pk_fma_f32 v[98:99], v[142:143], v[90:91], v[212:213]
	s_waitcnt vmcnt(9)
	v_pk_fma_f32 v[92:93], v[140:141], v[88:89], v[218:219]
	v_pk_fma_f32 v[90:91], v[138:139], v[86:87], v[216:217]
	s_waitcnt vmcnt(8)
	v_pk_fma_f32 v[88:89], v[136:137], v[80:81], v[222:223]
	v_pk_fma_f32 v[86:87], v[134:135], v[78:79], v[220:221]
	global_store_dwordx4 v[156:157], v[94:97], off
	global_store_dwordx4 v[156:157], v[98:101], off offset:64
	global_store_dwordx4 v[156:157], v[90:93], off offset:512
	global_store_dwordx4 v[156:157], v[86:89], off offset:576
	v_add_u32_e32 v156, 48, v164
	v_ashrrev_i32_e32 v157, 31, v156
	v_lshlrev_b64 v[166:167], 12, v[156:157]
	v_mov_b32_e32 v162, v163
	v_pk_mul_f32 v[78:79], v[82:83], v[162:163] op_sel_hi:[1,0]
	v_pk_mul_f32 v[80:81], v[84:85], v[162:163] op_sel_hi:[1,0]
	v_lshl_add_u64 v[82:83], s[38:39], 0, v[166:167]
	v_pk_mul_f32 v[74:75], v[74:75], v[162:163] op_sel_hi:[1,0]
	v_pk_mul_f32 v[76:77], v[76:77], v[162:163] op_sel_hi:[1,0]
	v_pk_mul_f32 v[70:71], v[70:71], v[162:163] op_sel_hi:[1,0]
	v_pk_mul_f32 v[72:73], v[72:73], v[162:163] op_sel_hi:[1,0]
	v_pk_mul_f32 v[66:67], v[66:67], v[162:163] op_sel_hi:[1,0]
	v_pk_mul_f32 v[68:69], v[68:69], v[162:163] op_sel_hi:[1,0]
	s_waitcnt vmcnt(11)
	v_pk_fma_f32 v[80:81], v[148:149], v[80:81], v[226:227]
	v_pk_fma_f32 v[78:79], v[146:147], v[78:79], v[224:225]
	v_lshl_add_u64 v[82:83], v[82:83], 0, v[172:173]
	s_waitcnt vmcnt(10)
	v_pk_fma_f32 v[76:77], v[144:145], v[76:77], v[240:241]
	v_pk_fma_f32 v[74:75], v[142:143], v[74:75], v[238:239]
	s_waitcnt vmcnt(9)
	v_pk_fma_f32 v[72:73], v[140:141], v[72:73], v[244:245]
	v_pk_fma_f32 v[70:71], v[138:139], v[70:71], v[242:243]
	s_waitcnt vmcnt(8)
	v_pk_fma_f32 v[68:69], v[136:137], v[68:69], v[248:249]
	v_pk_fma_f32 v[66:67], v[134:135], v[66:67], v[246:247]
	global_store_dwordx4 v[82:83], v[78:81], off
	global_store_dwordx4 v[82:83], v[74:77], off offset:64
	global_store_dwordx4 v[82:83], v[70:73], off offset:512
	global_store_dwordx4 v[82:83], v[66:69], off offset:576
	v_add_u32_e32 v82, 0x80, v152
	v_ashrrev_i32_e32 v83, 31, v82
	v_pk_fma_f32 v[112:113], v[148:149], v[228:229], v[184:185]
	v_pk_fma_f32 v[110:111], v[146:147], v[236:237], v[182:183]
	v_lshlrev_b64 v[82:83], 12, v[82:83]
	global_store_dwordx4 v[200:201], v[110:113], off
	global_store_dwordx4 v[200:201], v[114:117], off offset:64
	global_store_dwordx4 v[200:201], v[106:109], off offset:512
	global_store_dwordx4 v[200:201], v[102:105], off offset:576
	v_lshl_add_u64 v[162:163], v[150:151], 0, v[82:83]
	global_load_dwordx4 v[82:85], v[162:163], off
	global_load_dwordx4 v[166:169], v[162:163], off offset:64
	global_load_dwordx4 v[178:181], v[162:163], off offset:512
	global_load_dwordx4 v[182:185], v[162:163], off offset:576
	v_add_u32_e32 v162, 0x90, v152
	v_ashrrev_i32_e32 v163, 31, v162
	v_lshlrev_b64 v[162:163], 12, v[162:163]
	v_lshl_add_u64 v[162:163], v[150:151], 0, v[162:163]
	global_load_dwordx4 v[186:189], v[162:163], off
	global_load_dwordx4 v[190:193], v[162:163], off offset:64
	global_load_dwordx4 v[204:207], v[162:163], off offset:512
	global_load_dwordx4 v[208:211], v[162:163], off offset:576
	v_add_u32_e32 v162, 0xa0, v152
	v_ashrrev_i32_e32 v163, 31, v162
	v_lshlrev_b64 v[162:163], 12, v[162:163]
	v_add_u32_e32 v152, 0xb0, v152
	v_lshl_add_u64 v[162:163], v[150:151], 0, v[162:163]
	v_ashrrev_i32_e32 v153, 31, v152
	global_load_dwordx4 v[212:215], v[162:163], off
	global_load_dwordx4 v[216:219], v[162:163], off offset:64
	global_load_dwordx4 v[220:223], v[162:163], off offset:512
	global_load_dwordx4 v[224:227], v[162:163], off offset:576
	v_lshlrev_b64 v[152:153], 12, v[152:153]
	v_lshl_add_u64 v[150:151], v[150:151], 0, v[152:153]
	global_load_dwordx4 v[238:241], v[150:151], off
	global_load_dwordx4 v[242:245], v[150:151], off offset:64
	ds_read2_b32 v[162:163], v194 offset0:128 offset1:144
	global_load_dwordx4 v[246:249], v[150:151], off offset:512
	s_nop 0
	global_load_dwordx4 v[150:153], v[150:151], off offset:576
	v_add_u32_e32 v170, 0x80, v164
	v_ashrrev_i32_e32 v171, 31, v170
	v_lshlrev_b64 v[200:201], 12, v[170:171]
	s_waitcnt lgkmcnt(0)
	v_pk_mul_f32 v[62:63], v[62:63], v[162:163] op_sel_hi:[1,0]
	v_pk_mul_f32 v[58:59], v[58:59], v[162:163] op_sel_hi:[1,0]
	v_pk_mul_f32 v[54:55], v[54:55], v[162:163] op_sel_hi:[1,0]
	v_pk_mul_f32 v[64:65], v[64:65], v[162:163] op_sel_hi:[1,0]
	v_pk_mul_f32 v[60:61], v[60:61], v[162:163] op_sel_hi:[1,0]
	v_pk_mul_f32 v[56:57], v[56:57], v[162:163] op_sel_hi:[1,0]
	v_pk_mul_f32 v[46:47], v[46:47], v[162:163] op_sel_hi:[1,0]
	v_pk_mul_f32 v[48:49], v[48:49], v[162:163] op_sel_hi:[1,0]
	v_mov_b32_e32 v162, v163
	v_pk_mul_f32 v[44:45], v[44:45], v[162:163] op_sel_hi:[1,0]
	v_pk_mul_f32 v[32:33], v[32:33], v[162:163] op_sel_hi:[1,0]
	v_pk_mul_f32 v[42:43], v[42:43], v[162:163] op_sel_hi:[1,0]
	v_pk_mul_f32 v[38:39], v[38:39], v[162:163] op_sel_hi:[1,0]
	v_pk_mul_f32 v[40:41], v[40:41], v[162:163] op_sel_hi:[1,0]
	v_pk_mul_f32 v[30:31], v[30:31], v[162:163] op_sel_hi:[1,0]
	s_waitcnt vmcnt(15)
	v_pk_fma_f32 v[82:83], v[146:147], v[62:63], v[82:83]
	v_lshl_add_u64 v[62:63], s[38:39], 0, v[200:201]
	v_lshl_add_u64 v[200:201], v[62:63], 0, v[172:173]
	s_waitcnt vmcnt(14)
	v_pk_fma_f32 v[62:63], v[142:143], v[58:59], v[166:167]
	s_waitcnt vmcnt(13)
	v_pk_fma_f32 v[58:59], v[138:139], v[54:55], v[178:179]
	ds_read2_b32 v[178:179], v194 offset0:160 offset1:176
	v_pk_fma_f32 v[84:85], v[148:149], v[64:65], v[84:85]
	v_pk_fma_f32 v[64:65], v[144:145], v[60:61], v[168:169]
	v_pk_fma_f32 v[60:61], v[140:141], v[56:57], v[180:181]
	s_waitcnt vmcnt(12)
	v_pk_fma_f32 v[56:57], v[136:137], v[48:49], v[184:185]
	v_pk_mul_f32 v[48:49], v[50:51], v[162:163] op_sel_hi:[1,0]
	v_pk_mul_f32 v[50:51], v[52:53], v[162:163] op_sel_hi:[1,0]
	s_waitcnt lgkmcnt(0)
	v_pk_mul_f32 v[34:35], v[34:35], v[178:179] op_sel_hi:[1,0]
	v_pk_mul_f32 v[36:37], v[36:37], v[178:179] op_sel_hi:[1,0]
	v_pk_mul_f32 v[26:27], v[26:27], v[178:179] op_sel_hi:[1,0]
	v_pk_mul_f32 v[28:29], v[28:29], v[178:179] op_sel_hi:[1,0]
	v_pk_mul_f32 v[22:23], v[22:23], v[178:179] op_sel_hi:[1,0]
	v_pk_mul_f32 v[24:25], v[24:25], v[178:179] op_sel_hi:[1,0]
	v_pk_mul_f32 v[14:15], v[14:15], v[178:179] op_sel_hi:[1,0]
	v_pk_mul_f32 v[16:17], v[16:17], v[178:179] op_sel_hi:[1,0]
	v_mov_b32_e32 v178, v179
	s_waitcnt vmcnt(11)
	v_pk_fma_f32 v[52:53], v[148:149], v[50:51], v[188:189]
	v_pk_fma_f32 v[50:51], v[146:147], v[48:49], v[186:187]
	s_waitcnt vmcnt(10)
	v_pk_fma_f32 v[48:49], v[144:145], v[44:45], v[192:193]
	s_waitcnt vmcnt(7)
	v_pk_fma_f32 v[44:45], v[148:149], v[36:37], v[214:215]
	s_waitcnt vmcnt(6)
	v_pk_fma_f32 v[36:37], v[144:145], v[28:29], v[218:219]
	s_waitcnt vmcnt(5)
	v_pk_fma_f32 v[28:29], v[140:141], v[24:25], v[222:223]
	s_waitcnt vmcnt(4)
	v_pk_fma_f32 v[24:25], v[136:137], v[16:17], v[226:227]
	v_pk_mul_f32 v[16:17], v[20:21], v[178:179] op_sel_hi:[1,0]
	v_mul_f32_e32 v20, v131, v131
	v_mul_f32_e32 v21, v133, v133
	v_pk_mul_f32 v[4:5], v[4:5], v[178:179] op_sel_hi:[1,0]
	v_fmac_f32_e32 v20, v130, v130
	v_fmac_f32_e32 v21, v132, v132
	v_add_u32_e32 v168, 0x90, v164
	v_pk_fma_f32 v[32:33], v[136:137], v[32:33], v[210:211]
	s_waitcnt vmcnt(0)
	v_pk_fma_f32 v[4:5], v[136:137], v[4:5], v[152:153]
	v_add_f32_e32 v20, v20, v21
	v_mul_f32_e32 v21, v127, v127
	v_mul_f32_e32 v136, v129, v129
	v_ashrrev_i32_e32 v169, 31, v168
	v_fmac_f32_e32 v21, v126, v126
	v_fmac_f32_e32 v136, v128, v128
	v_pk_fma_f32 v[54:55], v[134:135], v[46:47], v[182:183]
	v_lshlrev_b64 v[46:47], 12, v[168:169]
	v_add_f32_e32 v21, v21, v136
	v_lshl_add_u64 v[46:47], s[38:39], 0, v[46:47]
	v_add_f32_e32 v20, v20, v21
	v_mul_f32_e32 v21, v123, v123
	v_mul_f32_e32 v136, v125, v125
	v_lshl_add_u64 v[166:167], v[46:47], 0, v[172:173]
	v_pk_fma_f32 v[46:47], v[142:143], v[42:43], v[190:191]
	v_pk_fma_f32 v[40:41], v[140:141], v[40:41], v[206:207]
	v_pk_fma_f32 v[38:39], v[138:139], v[38:39], v[204:205]
	v_pk_fma_f32 v[30:31], v[134:135], v[30:31], v[208:209]
	v_fmac_f32_e32 v21, v122, v122
	v_fmac_f32_e32 v136, v124, v124
	global_store_dwordx4 v[166:167], v[50:53], off
	global_store_dwordx4 v[166:167], v[46:49], off offset:64
	global_store_dwordx4 v[166:167], v[38:41], off offset:512
	global_store_dwordx4 v[166:167], v[30:33], off offset:576
	v_add_u32_e32 v166, 0xa0, v164
	v_add_f32_e32 v21, v21, v136
	v_ashrrev_i32_e32 v167, 31, v166
	v_add_f32_e32 v20, v21, v20
	v_mul_f32_e32 v21, v119, v119
	v_mul_f32_e32 v136, v121, v121
	v_lshlrev_b64 v[162:163], 12, v[166:167]
	v_fmac_f32_e32 v21, v118, v118
	v_fmac_f32_e32 v136, v120, v120
	v_pk_fma_f32 v[42:43], v[146:147], v[34:35], v[212:213]
	v_lshl_add_u64 v[34:35], s[38:39], 0, v[162:163]
	v_add_f32_e32 v21, v21, v136
	v_lshl_add_u64 v[162:163], v[34:35], 0, v[172:173]
	v_pk_fma_f32 v[34:35], v[142:143], v[26:27], v[216:217]
	v_pk_fma_f32 v[26:27], v[138:139], v[22:23], v[220:221]
	v_pk_fma_f32 v[22:23], v[134:135], v[14:15], v[224:225]
	v_add_f32_e32 v20, v21, v20
	global_store_dwordx4 v[162:163], v[42:45], off
	global_store_dwordx4 v[162:163], v[34:37], off offset:64
	global_store_dwordx4 v[162:163], v[26:29], off offset:512
	global_store_dwordx4 v[162:163], v[22:25], off offset:576
	v_add_u32_e32 v162, 0xb0, v164
	ds_bpermute_b32 v21, v176, v20
	v_ashrrev_i32_e32 v163, 31, v162
	v_lshlrev_b64 v[180:181], 12, v[162:163]
	v_pk_mul_f32 v[14:15], v[18:19], v[178:179] op_sel_hi:[1,0]
	v_lshl_add_u64 v[18:19], s[38:39], 0, v[180:181]
	v_pk_mul_f32 v[10:11], v[10:11], v[178:179] op_sel_hi:[1,0]
	v_pk_mul_f32 v[12:13], v[12:13], v[178:179] op_sel_hi:[1,0]
	v_pk_mul_f32 v[6:7], v[6:7], v[178:179] op_sel_hi:[1,0]
	v_pk_mul_f32 v[8:9], v[8:9], v[178:179] op_sel_hi:[1,0]
	v_pk_mul_f32 v[2:3], v[2:3], v[178:179] op_sel_hi:[1,0]
	v_pk_fma_f32 v[16:17], v[148:149], v[16:17], v[240:241]
	v_pk_fma_f32 v[14:15], v[146:147], v[14:15], v[238:239]
	v_lshl_add_u64 v[18:19], v[18:19], 0, v[172:173]
	v_pk_fma_f32 v[12:13], v[144:145], v[12:13], v[244:245]
	v_pk_fma_f32 v[10:11], v[142:143], v[10:11], v[242:243]
	v_pk_fma_f32 v[8:9], v[140:141], v[8:9], v[248:249]
	v_pk_fma_f32 v[6:7], v[138:139], v[6:7], v[246:247]
	v_pk_fma_f32 v[2:3], v[134:135], v[2:3], v[150:151]
	global_store_dwordx4 v[18:19], v[14:17], off
	global_store_dwordx4 v[18:19], v[10:13], off offset:64
	global_store_dwordx4 v[18:19], v[6:9], off offset:512
	global_store_dwordx4 v[18:19], v[2:5], off offset:576
	s_waitcnt lgkmcnt(0)
	v_add_f32_e32 v18, v20, v21
	ds_bpermute_b32 v19, v177, v18
	global_store_dwordx4 v[200:201], v[82:85], off
	global_store_dwordx4 v[200:201], v[62:65], off offset:64
	global_store_dwordx4 v[200:201], v[58:61], off offset:512
	global_store_dwordx4 v[200:201], v[54:57], off offset:576
	s_waitcnt lgkmcnt(0)
	v_mov_b32_e32 v20, v0
	s_barrier
	s_and_saveexec_b64 s[38:39], s[36:37]
	s_lshl_b32 s5, s2, 10
	s_add_i32 s5, s7, s5
	v_lshl_add_u32 v21, v174, 4, s5
	v_add_f32_e32 v18, v18, v19
	ds_write_b32 v21, v18
	s_or_b64 exec, exec, s[38:39]
	v_mul_f32_e32 v18, v111, v111
	v_mul_f32_e32 v19, v113, v113
	v_fmac_f32_e32 v18, v110, v110
	v_fmac_f32_e32 v19, v112, v112
	v_add_f32_e32 v18, v18, v19
	v_mul_f32_e32 v19, v115, v115
	v_mul_f32_e32 v21, v117, v117
	v_fmac_f32_e32 v19, v114, v114
	v_fmac_f32_e32 v21, v116, v116
	v_add_f32_e32 v19, v19, v21
	v_add_f32_e32 v18, v18, v19
	v_mul_f32_e32 v19, v107, v107
	v_mul_f32_e32 v21, v109, v109
	v_fmac_f32_e32 v19, v106, v106
	v_fmac_f32_e32 v21, v108, v108
	v_add_f32_e32 v19, v19, v21
	v_add_f32_e32 v18, v19, v18
	v_mul_f32_e32 v19, v103, v103
	v_mul_f32_e32 v21, v105, v105
	v_fmac_f32_e32 v19, v102, v102
	v_fmac_f32_e32 v21, v104, v104
	v_add_f32_e32 v19, v19, v21
	v_add_f32_e32 v18, v19, v18
	v_mov_b32_e32 v19, v18
	s_nop 1
	v_permlane16_swap_b32_e32 v19, v18
	s_nop 1
	s_waitcnt lgkmcnt(0)
	v_add_f32_e32 v18, v18, v19
	v_mov_b32_e32 v19, v18
	s_nop 1
	v_permlane32_swap_b32_e32 v19, v18
	s_nop 1
	s_and_saveexec_b64 s[38:39], s[36:37]
	s_cbranch_execz .LBB0_204
	s_lshl_b32 s5, s2, 10
	s_add_i32 s5, s7, s5
	v_lshl_add_u32 v21, v174, 4, s5
	v_add_f32_e32 v18, v18, v19
	ds_write_b32 v21, v18 offset:256
.LBB0_204:
	s_or_b64 exec, exec, s[38:39]
	v_mul_f32_e32 v18, v95, v95
	s_waitcnt lgkmcnt(0)
	v_mul_f32_e32 v19, v97, v97
	v_fmac_f32_e32 v18, v94, v94
	v_fmac_f32_e32 v19, v96, v96
	v_add_f32_e32 v18, v18, v19
	v_mul_f32_e32 v19, v99, v99
	v_mul_f32_e32 v21, v101, v101
	v_fmac_f32_e32 v19, v98, v98
	v_fmac_f32_e32 v21, v100, v100
	v_add_f32_e32 v19, v19, v21
	v_add_f32_e32 v18, v18, v19
	v_mul_f32_e32 v19, v91, v91
	v_mul_f32_e32 v21, v93, v93
	v_fmac_f32_e32 v19, v90, v90
	v_fmac_f32_e32 v21, v92, v92
	v_add_f32_e32 v19, v19, v21
	v_add_f32_e32 v18, v19, v18
	v_mul_f32_e32 v19, v87, v87
	v_mul_f32_e32 v21, v89, v89
	v_fmac_f32_e32 v19, v86, v86
	v_fmac_f32_e32 v21, v88, v88
	v_add_f32_e32 v19, v19, v21
	v_add_f32_e32 v18, v19, v18
	v_mov_b32_e32 v19, v18
	s_nop 1
	v_permlane16_swap_b32_e32 v19, v18
	s_nop 1
	v_add_f32_e32 v18, v18, v19
	v_mov_b32_e32 v19, v18
	s_nop 1
	v_permlane32_swap_b32_e32 v19, v18
	s_nop 1
	s_and_saveexec_b64 s[38:39], s[36:37]
	s_cbranch_execz .LBB0_206
	s_lshl_b32 s5, s2, 10
	s_add_i32 s5, s7, s5
	v_lshl_add_u32 v21, v174, 4, s5
	v_add_f32_e32 v18, v18, v19
	ds_write_b32 v21, v18 offset:512
.LBB0_206:
	s_or_b64 exec, exec, s[38:39]
	v_mul_f32_e32 v18, v79, v79
	s_waitcnt lgkmcnt(0)
	v_mul_f32_e32 v19, v81, v81
	v_fmac_f32_e32 v18, v78, v78
	v_fmac_f32_e32 v19, v80, v80
	v_add_f32_e32 v18, v18, v19
	v_mul_f32_e32 v19, v75, v75
	v_mul_f32_e32 v21, v77, v77
	v_fmac_f32_e32 v19, v74, v74
	v_fmac_f32_e32 v21, v76, v76
	v_add_f32_e32 v19, v19, v21
	v_add_f32_e32 v18, v18, v19
	v_mul_f32_e32 v19, v71, v71
	v_mul_f32_e32 v21, v73, v73
	v_fmac_f32_e32 v19, v70, v70
	v_fmac_f32_e32 v21, v72, v72
	v_add_f32_e32 v19, v19, v21
	v_add_f32_e32 v18, v19, v18
	v_mul_f32_e32 v19, v67, v67
	v_mul_f32_e32 v21, v69, v69
	v_fmac_f32_e32 v19, v66, v66
	v_fmac_f32_e32 v21, v68, v68
	v_add_f32_e32 v19, v19, v21
	v_add_f32_e32 v18, v19, v18
	v_mov_b32_e32 v19, v18
	s_nop 1
	v_permlane16_swap_b32_e32 v19, v18
	s_nop 1
	v_add_f32_e32 v18, v18, v19
	v_mov_b32_e32 v19, v18
	s_nop 1
	v_permlane32_swap_b32_e32 v19, v18
	s_nop 1
	s_and_saveexec_b64 s[38:39], s[36:37]
	s_cbranch_execz .LBB0_208
	s_lshl_b32 s5, s2, 10
	s_add_i32 s5, s7, s5
	v_lshl_add_u32 v21, v174, 4, s5
	v_add_f32_e32 v18, v18, v19
	ds_write_b32 v21, v18 offset:768
.LBB0_208:
	s_or_b64 exec, exec, s[38:39]
	v_mul_f32_e32 v18, v83, v83
	s_waitcnt lgkmcnt(0)
	v_mul_f32_e32 v19, v85, v85
	v_fmac_f32_e32 v18, v82, v82
	v_fmac_f32_e32 v19, v84, v84
	v_add_f32_e32 v18, v18, v19
	v_mul_f32_e32 v19, v63, v63
	v_mul_f32_e32 v21, v65, v65
	v_fmac_f32_e32 v19, v62, v62
	v_fmac_f32_e32 v21, v64, v64
	v_add_f32_e32 v19, v19, v21
	v_add_f32_e32 v18, v18, v19
	v_mul_f32_e32 v19, v59, v59
	v_mul_f32_e32 v21, v61, v61
	v_fmac_f32_e32 v19, v58, v58
	v_fmac_f32_e32 v21, v60, v60
	v_add_f32_e32 v19, v19, v21
	v_add_f32_e32 v18, v19, v18
	v_mul_f32_e32 v19, v55, v55
	v_mul_f32_e32 v21, v57, v57
	v_fmac_f32_e32 v19, v54, v54
	v_fmac_f32_e32 v21, v56, v56
	v_add_f32_e32 v19, v19, v21
	v_add_f32_e32 v18, v19, v18
	v_mov_b32_e32 v19, v18
	s_nop 1
	v_permlane16_swap_b32_e32 v19, v18
	s_nop 1
	v_add_f32_e32 v18, v18, v19
	v_mov_b32_e32 v19, v18
	s_nop 1
	v_permlane32_swap_b32_e32 v19, v18
	s_nop 1
	s_and_saveexec_b64 s[38:39], s[36:37]
	s_cbranch_execz .LBB0_210
	s_lshl_b32 s5, s2, 10
	s_add_i32 s5, s7, s5
	v_lshl_add_u32 v21, v174, 4, s5
	v_add_f32_e32 v18, v18, v19
	ds_write_b32 v21, v18 offset:2048
.LBB0_210:
	s_or_b64 exec, exec, s[38:39]
	v_mul_f32_e32 v18, v51, v51
	s_waitcnt lgkmcnt(0)
	v_mul_f32_e32 v19, v53, v53
	v_fmac_f32_e32 v18, v50, v50
	v_fmac_f32_e32 v19, v52, v52
	v_add_f32_e32 v18, v18, v19
	v_mul_f32_e32 v19, v47, v47
	v_mul_f32_e32 v21, v49, v49
	v_fmac_f32_e32 v19, v46, v46
	v_fmac_f32_e32 v21, v48, v48
	v_add_f32_e32 v19, v19, v21
	v_add_f32_e32 v18, v18, v19
	v_mul_f32_e32 v19, v39, v39
	v_mul_f32_e32 v21, v41, v41
	v_fmac_f32_e32 v19, v38, v38
	v_fmac_f32_e32 v21, v40, v40
	v_add_f32_e32 v19, v19, v21
	v_add_f32_e32 v18, v19, v18
	v_mul_f32_e32 v19, v31, v31
	v_mul_f32_e32 v21, v33, v33
	v_fmac_f32_e32 v19, v30, v30
	v_fmac_f32_e32 v21, v32, v32
	v_add_f32_e32 v19, v19, v21
	v_add_f32_e32 v18, v19, v18
	v_mov_b32_e32 v19, v18
	s_nop 1
	v_permlane16_swap_b32_e32 v19, v18
	s_nop 1
	v_add_f32_e32 v18, v18, v19
	v_mov_b32_e32 v19, v18
	s_nop 1
	v_permlane32_swap_b32_e32 v19, v18
	s_nop 1
	s_and_saveexec_b64 s[38:39], s[36:37]
	s_cbranch_execz .LBB0_212
	s_lshl_b32 s5, s2, 10
	s_add_i32 s5, s7, s5
	v_lshl_add_u32 v21, v174, 4, s5
	v_add_f32_e32 v18, v18, v19
	ds_write_b32 v21, v18 offset:2304
.LBB0_212:
	s_or_b64 exec, exec, s[38:39]
	v_mul_f32_e32 v18, v43, v43
	s_waitcnt lgkmcnt(0)
	v_mul_f32_e32 v19, v45, v45
	v_fmac_f32_e32 v18, v42, v42
	v_fmac_f32_e32 v19, v44, v44
	v_add_f32_e32 v18, v18, v19
	v_mul_f32_e32 v19, v35, v35
	v_mul_f32_e32 v21, v37, v37
	v_fmac_f32_e32 v19, v34, v34
	v_fmac_f32_e32 v21, v36, v36
	v_add_f32_e32 v19, v19, v21
	v_add_f32_e32 v18, v18, v19
	v_mul_f32_e32 v19, v27, v27
	v_mul_f32_e32 v21, v29, v29
	v_fmac_f32_e32 v19, v26, v26
	v_fmac_f32_e32 v21, v28, v28
	v_add_f32_e32 v19, v19, v21
	v_add_f32_e32 v18, v19, v18
	v_mul_f32_e32 v19, v23, v23
	v_mul_f32_e32 v21, v25, v25
	v_fmac_f32_e32 v19, v22, v22
	v_fmac_f32_e32 v21, v24, v24
	v_add_f32_e32 v19, v19, v21
	v_add_f32_e32 v18, v19, v18
	v_mov_b32_e32 v19, v18
	s_nop 1
	v_permlane16_swap_b32_e32 v19, v18
	s_nop 1
	v_add_f32_e32 v18, v18, v19
	v_mov_b32_e32 v19, v18
	s_nop 1
	v_permlane32_swap_b32_e32 v19, v18
	s_nop 1
	s_and_saveexec_b64 s[38:39], s[36:37]
	s_cbranch_execz .LBB0_214
	s_lshl_b32 s5, s2, 10
	s_add_i32 s5, s7, s5
	v_lshl_add_u32 v21, v174, 4, s5
	v_add_f32_e32 v18, v18, v19
	ds_write_b32 v21, v18 offset:2560
.LBB0_214:
	s_or_b64 exec, exec, s[38:39]
	v_mul_f32_e32 v18, v15, v15
	s_waitcnt lgkmcnt(0)
	v_mul_f32_e32 v19, v17, v17
	v_fmac_f32_e32 v18, v14, v14
	v_fmac_f32_e32 v19, v16, v16
	v_add_f32_e32 v18, v18, v19
	v_mul_f32_e32 v19, v11, v11
	v_mul_f32_e32 v21, v13, v13
	v_fmac_f32_e32 v19, v10, v10
	v_fmac_f32_e32 v21, v12, v12
	v_add_f32_e32 v19, v19, v21
	v_add_f32_e32 v18, v18, v19
	v_mul_f32_e32 v19, v7, v7
	v_mul_f32_e32 v21, v9, v9
	v_fmac_f32_e32 v19, v6, v6
	v_fmac_f32_e32 v21, v8, v8
	v_add_f32_e32 v19, v19, v21
	v_add_f32_e32 v18, v19, v18
	v_mul_f32_e32 v19, v3, v3
	v_mul_f32_e32 v21, v5, v5
	v_fmac_f32_e32 v19, v2, v2
	v_fmac_f32_e32 v21, v4, v4
	v_add_f32_e32 v19, v19, v21
	v_add_f32_e32 v18, v19, v18
	v_mov_b32_e32 v19, v18
	s_nop 1
	v_permlane16_swap_b32_e32 v19, v18
	s_nop 1
	v_add_f32_e32 v18, v18, v19
	v_mov_b32_e32 v19, v18
	s_nop 1
	v_permlane32_swap_b32_e32 v19, v18
	s_nop 1
	s_and_saveexec_b64 s[38:39], s[36:37]
	s_cbranch_execz .LBB0_216
	s_lshl_b32 s2, s2, 10
	s_add_i32 s7, s7, s2
	v_lshl_add_u32 v21, v174, 4, s7
	v_add_f32_e32 v18, v18, v19
	ds_write_b32 v21, v18 offset:2816
.LBB0_216:
	s_or_b64 exec, exec, s[38:39]
	s_or_b32 s42, s30, 1
	s_ashr_i32 s43, s42, 31
	s_lshl_b64 s[10:11], s[42:43], 18
	v_readlane_b32 s2, v251, 27
	s_add_u32 s30, s2, s10
	v_readlane_b32 s2, v251, 28
	s_waitcnt lgkmcnt(0)
	s_barrier
	s_addc_u32 s31, s2, s11
	s_movk_i32 s2, 0x100
	v_add_u32_e32 v18, s8, v20
	v_cmp_gt_i32_e64 s[36:37], s2, v20
	v_ashrrev_i32_e32 v19, 31, v18
	s_and_saveexec_b64 s[38:39], s[36:37]
	s_cbranch_execz .LBB0_218
	v_lshl_add_u32 v21, v20, 4, 0
	ds_read_b128 v[134:137], v21
	v_lshl_add_u64 v[138:139], v[18:19], 4, s[30:31]
	s_ashr_i32 s41, s40, 31
	v_lshl_add_u64 v[138:139], s[40:41], 2, v[138:139]
	s_waitcnt lgkmcnt(0)
	v_mov_b32_e32 v140, v135
	v_mov_b32_e32 v141, v136
	v_mov_b32_e32 v135, v137
	v_pk_add_f32 v[134:135], v[140:141], v[134:135]
	s_nop 0
	v_pk_add_f32 v[134:135], v[134:135], v[134:135] op_sel:[0,1] op_sel_hi:[1,0]
	global_store_dword v[138:139], v134, off sc1

.LBB0_232:
	s_or_b64 exec, exec, s[40:41]
	s_lshl_b32 s2, s6, 1
	v_readlane_b32 s4, v254, 24
	s_add_u32 s30, s4, s2
	v_readlane_b32 s2, v254, 25
	s_addc_u32 s31, s2, 0
	s_lshl_b64 s[4:5], s[38:39], 2
	v_readlane_b32 s36, v252, 25
	v_readlane_b32 s46, v252, 35
	v_readlane_b32 s47, v252, 36
	s_add_u32 s4, s46, s4
	s_addc_u32 s5, s47, s5
	v_lshl_add_u64 v[18:19], v[154:155], 2, s[4:5]
	s_waitcnt lgkmcnt(0)
	s_barrier
	global_load_dwordx4 v[142:145], v[18:19], off
	global_load_dwordx4 v[138:141], v[18:19], off offset:64
	global_load_dwordx4 v[134:137], v[18:19], off offset:512
	s_nop 0
	global_load_dwordx4 v[18:21], v[18:19], off offset:576
	ds_read_b32 v148, v175 offset:4096
	v_lshlrev_b64 v[150:151], 11, v[164:165]
	v_lshlrev_b64 v[146:147], 1, v[154:155]
	v_lshl_add_u64 v[150:151], s[30:31], 0, v[150:151]
	v_lshl_add_u64 v[150:151], v[150:151], 0, v[146:147]
	s_waitcnt lgkmcnt(0)
	v_pk_mul_f32 v[130:131], v[130:131], v[148:149] op_sel_hi:[1,0]
	v_pk_mul_f32 v[126:127], v[126:127], v[148:149] op_sel_hi:[1,0]
	v_pk_mul_f32 v[122:123], v[122:123], v[148:149] op_sel_hi:[1,0]
	v_pk_mul_f32 v[120:121], v[120:121], v[148:149] op_sel_hi:[1,0]
	v_pk_mul_f32 v[118:119], v[118:119], v[148:149] op_sel_hi:[1,0]
	v_pk_mul_f32 v[132:133], v[132:133], v[148:149] op_sel_hi:[1,0]
	v_pk_mul_f32 v[128:129], v[128:129], v[148:149] op_sel_hi:[1,0]
	v_pk_mul_f32 v[124:125], v[124:125], v[148:149] op_sel_hi:[1,0]
	v_readlane_b32 s37, v252, 26
	v_readlane_b32 s38, v252, 27
	v_readlane_b32 s39, v252, 28
	v_readlane_b32 s40, v252, 29
	v_readlane_b32 s41, v252, 30
	v_readlane_b32 s42, v252, 31
	v_readlane_b32 s43, v252, 32
	v_readlane_b32 s44, v252, 33
	v_readlane_b32 s45, v252, 34
	v_readlane_b32 s48, v252, 37
	v_readlane_b32 s49, v252, 38
	v_readlane_b32 s50, v252, 39
	v_readlane_b32 s51, v252, 40
	s_waitcnt vmcnt(3)
	v_pk_mul_f32 v[130:131], v[142:143], v[130:131]
	s_waitcnt vmcnt(2)
	v_pk_mul_f32 v[126:127], v[138:139], v[126:127]
	s_waitcnt vmcnt(1)
	v_pk_mul_f32 v[122:123], v[134:135], v[122:123]
	s_waitcnt vmcnt(0)
	v_pk_mul_f32 v[120:121], v[20:21], v[120:121]
	v_pk_mul_f32 v[118:119], v[18:19], v[118:119]
	v_pk_mul_f32 v[132:133], v[144:145], v[132:133]
	v_pk_mul_f32 v[128:129], v[140:141], v[128:129]
	v_pk_mul_f32 v[124:125], v[136:137], v[124:125]
	v_cvt_pk_bf16_f32 v130, v130, v131
	v_cvt_pk_bf16_f32 v131, v132, v133
	global_store_dwordx2 v[150:151], v[130:131], off
	v_cvt_pk_bf16_f32 v126, v126, v127
	v_cvt_pk_bf16_f32 v127, v128, v129
	global_store_dwordx2 v[150:151], v[126:127], off offset:32
	v_cvt_pk_bf16_f32 v122, v122, v123
	v_cvt_pk_bf16_f32 v123, v124, v125
	global_store_dwordx2 v[150:151], v[122:123], off offset:256
	v_cvt_pk_bf16_f32 v118, v118, v119
	v_cvt_pk_bf16_f32 v119, v120, v121
	ds_read_b32 v120, v175 offset:4160
	v_lshlrev_b64 v[122:123], 11, v[158:159]
	v_lshl_add_u64 v[122:123], s[30:31], 0, v[122:123]
	v_lshl_add_u64 v[122:123], v[122:123], 0, v[146:147]
	global_store_dwordx2 v[150:151], v[118:119], off offset:288
	s_waitcnt lgkmcnt(0)
	v_pk_mul_f32 v[110:111], v[110:111], v[120:121] op_sel_hi:[1,0]
	v_pk_mul_f32 v[112:113], v[112:113], v[120:121] op_sel_hi:[1,0]
	v_pk_mul_f32 v[106:107], v[106:107], v[120:121] op_sel_hi:[1,0]
	v_pk_mul_f32 v[104:105], v[104:105], v[120:121] op_sel_hi:[1,0]
	v_pk_mul_f32 v[102:103], v[102:103], v[120:121] op_sel_hi:[1,0]
	v_pk_mul_f32 v[110:111], v[142:143], v[110:111]
	v_pk_mul_f32 v[116:117], v[116:117], v[120:121] op_sel_hi:[1,0]
	v_pk_mul_f32 v[114:115], v[114:115], v[120:121] op_sel_hi:[1,0]
	v_pk_mul_f32 v[108:109], v[108:109], v[120:121] op_sel_hi:[1,0]
	v_pk_mul_f32 v[112:113], v[144:145], v[112:113]
	v_pk_mul_f32 v[106:107], v[134:135], v[106:107]
	v_pk_mul_f32 v[104:105], v[20:21], v[104:105]
	v_pk_mul_f32 v[102:103], v[18:19], v[102:103]
	v_cvt_pk_bf16_f32 v110, v110, v111
	v_cvt_pk_bf16_f32 v111, v112, v113
	v_pk_mul_f32 v[116:117], v[140:141], v[116:117]
	v_pk_mul_f32 v[114:115], v[138:139], v[114:115]
	v_pk_mul_f32 v[108:109], v[136:137], v[108:109]
	global_store_dwordx2 v[122:123], v[110:111], off
	v_cvt_pk_bf16_f32 v110, v114, v115
	v_cvt_pk_bf16_f32 v111, v116, v117
	global_store_dwordx2 v[122:123], v[110:111], off offset:32
	v_cvt_pk_bf16_f32 v106, v106, v107
	v_cvt_pk_bf16_f32 v107, v108, v109
	global_store_dwordx2 v[122:123], v[106:107], off offset:256
	v_cvt_pk_bf16_f32 v102, v102, v103
	v_cvt_pk_bf16_f32 v103, v104, v105
	ds_read_b32 v104, v175 offset:4224
	v_lshlrev_b64 v[106:107], 11, v[160:161]
	v_lshl_add_u64 v[106:107], s[30:31], 0, v[106:107]
	v_lshl_add_u64 v[106:107], v[106:107], 0, v[146:147]
	global_store_dwordx2 v[122:123], v[102:103], off offset:288
	s_waitcnt lgkmcnt(0)
	v_pk_mul_f32 v[94:95], v[94:95], v[104:105] op_sel_hi:[1,0]
	v_pk_mul_f32 v[96:97], v[96:97], v[104:105] op_sel_hi:[1,0]
	v_pk_mul_f32 v[90:91], v[90:91], v[104:105] op_sel_hi:[1,0]
	v_pk_mul_f32 v[88:89], v[88:89], v[104:105] op_sel_hi:[1,0]
	v_pk_mul_f32 v[86:87], v[86:87], v[104:105] op_sel_hi:[1,0]
	v_pk_mul_f32 v[94:95], v[142:143], v[94:95]
	v_pk_mul_f32 v[100:101], v[100:101], v[104:105] op_sel_hi:[1,0]
	v_pk_mul_f32 v[98:99], v[98:99], v[104:105] op_sel_hi:[1,0]
	v_pk_mul_f32 v[92:93], v[92:93], v[104:105] op_sel_hi:[1,0]
	v_pk_mul_f32 v[96:97], v[144:145], v[96:97]
	v_pk_mul_f32 v[90:91], v[134:135], v[90:91]
	v_pk_mul_f32 v[88:89], v[20:21], v[88:89]
	v_pk_mul_f32 v[86:87], v[18:19], v[86:87]
	v_cvt_pk_bf16_f32 v94, v94, v95
	v_cvt_pk_bf16_f32 v95, v96, v97
	v_pk_mul_f32 v[100:101], v[140:141], v[100:101]
	v_pk_mul_f32 v[98:99], v[138:139], v[98:99]
	v_pk_mul_f32 v[92:93], v[136:137], v[92:93]
	global_store_dwordx2 v[106:107], v[94:95], off
	v_cvt_pk_bf16_f32 v94, v98, v99
	v_cvt_pk_bf16_f32 v95, v100, v101
	global_store_dwordx2 v[106:107], v[94:95], off offset:32
	v_cvt_pk_bf16_f32 v90, v90, v91
	v_cvt_pk_bf16_f32 v91, v92, v93
	global_store_dwordx2 v[106:107], v[90:91], off offset:256
	v_cvt_pk_bf16_f32 v86, v86, v87
	v_cvt_pk_bf16_f32 v87, v88, v89
	ds_read_b32 v88, v175 offset:4288
	v_lshlrev_b64 v[90:91], 11, v[156:157]
	global_store_dwordx2 v[106:107], v[86:87], off offset:288
	s_waitcnt lgkmcnt(0)
	v_pk_mul_f32 v[80:81], v[80:81], v[88:89] op_sel_hi:[1,0]
	v_pk_mul_f32 v[78:79], v[78:79], v[88:89] op_sel_hi:[1,0]
	v_pk_mul_f32 v[80:81], v[144:145], v[80:81]
	v_pk_mul_f32 v[78:79], v[142:143], v[78:79]
	v_pk_mul_f32 v[74:75], v[74:75], v[88:89] op_sel_hi:[1,0]
	v_cvt_pk_bf16_f32 v78, v78, v79
	v_cvt_pk_bf16_f32 v79, v80, v81
	v_lshl_add_u64 v[80:81], s[30:31], 0, v[90:91]
	v_pk_mul_f32 v[70:71], v[70:71], v[88:89] op_sel_hi:[1,0]
	v_pk_mul_f32 v[68:69], v[68:69], v[88:89] op_sel_hi:[1,0]
	v_pk_mul_f32 v[66:67], v[66:67], v[88:89] op_sel_hi:[1,0]
	v_lshl_add_u64 v[80:81], v[80:81], 0, v[146:147]
	v_pk_mul_f32 v[76:77], v[76:77], v[88:89] op_sel_hi:[1,0]
	v_pk_mul_f32 v[74:75], v[138:139], v[74:75]
	v_pk_mul_f32 v[72:73], v[72:73], v[88:89] op_sel_hi:[1,0]
	v_pk_mul_f32 v[70:71], v[134:135], v[70:71]
	v_pk_mul_f32 v[68:69], v[20:21], v[68:69]
	v_pk_mul_f32 v[66:67], v[18:19], v[66:67]
	global_store_dwordx2 v[80:81], v[78:79], off
	v_pk_mul_f32 v[76:77], v[140:141], v[76:77]
	v_cvt_pk_bf16_f32 v74, v74, v75
	v_pk_mul_f32 v[72:73], v[136:137], v[72:73]
	v_cvt_pk_bf16_f32 v75, v76, v77
	global_store_dwordx2 v[80:81], v[74:75], off offset:32
	v_cvt_pk_bf16_f32 v70, v70, v71
	v_cvt_pk_bf16_f32 v71, v72, v73
	global_store_dwordx2 v[80:81], v[70:71], off offset:256
	v_cvt_pk_bf16_f32 v66, v66, v67
	v_cvt_pk_bf16_f32 v67, v68, v69
	ds_read_b32 v68, v175 offset:4608
	global_store_dwordx2 v[80:81], v[66:67], off offset:288
	v_lshlrev_b64 v[66:67], 11, v[170:171]
	v_lshl_add_u64 v[66:67], s[30:31], 0, v[66:67]
	v_lshl_add_u64 v[66:67], v[66:67], 0, v[146:147]
	s_waitcnt lgkmcnt(0)
	v_pk_mul_f32 v[72:73], v[82:83], v[68:69] op_sel_hi:[1,0]
	v_pk_mul_f32 v[62:63], v[62:63], v[68:69] op_sel_hi:[1,0]
	v_pk_mul_f32 v[58:59], v[58:59], v[68:69] op_sel_hi:[1,0]
	v_pk_mul_f32 v[56:57], v[56:57], v[68:69] op_sel_hi:[1,0]
	v_pk_mul_f32 v[54:55], v[54:55], v[68:69] op_sel_hi:[1,0]
	v_pk_mul_f32 v[70:71], v[84:85], v[68:69] op_sel_hi:[1,0]
	v_pk_mul_f32 v[72:73], v[142:143], v[72:73]
	v_pk_mul_f32 v[64:65], v[64:65], v[68:69] op_sel_hi:[1,0]
	v_pk_mul_f32 v[62:63], v[138:139], v[62:63]
	v_pk_mul_f32 v[60:61], v[60:61], v[68:69] op_sel_hi:[1,0]
	v_pk_mul_f32 v[58:59], v[134:135], v[58:59]
	v_pk_mul_f32 v[56:57], v[20:21], v[56:57]
	v_pk_mul_f32 v[54:55], v[18:19], v[54:55]
	v_pk_mul_f32 v[70:71], v[144:145], v[70:71]
	v_cvt_pk_bf16_f32 v72, v72, v73
	v_pk_mul_f32 v[64:65], v[140:141], v[64:65]
	v_cvt_pk_bf16_f32 v73, v70, v71
	global_store_dwordx2 v[66:67], v[72:73], off
	v_cvt_pk_bf16_f32 v62, v62, v63
	v_cvt_pk_bf16_f32 v63, v64, v65
	global_store_dwordx2 v[66:67], v[62:63], off offset:32
	v_pk_mul_f32 v[60:61], v[136:137], v[60:61]
	v_cvt_pk_bf16_f32 v58, v58, v59
	s_nop 0
	v_cvt_pk_bf16_f32 v59, v60, v61
	global_store_dwordx2 v[66:67], v[58:59], off offset:256
	v_cvt_pk_bf16_f32 v54, v54, v55
	v_cvt_pk_bf16_f32 v55, v56, v57
	ds_read_b32 v56, v175 offset:4672
	global_store_dwordx2 v[66:67], v[54:55], off offset:288
	v_lshlrev_b64 v[54:55], 11, v[168:169]
	s_waitcnt lgkmcnt(0)
	v_pk_mul_f32 v[52:53], v[52:53], v[56:57] op_sel_hi:[1,0]
	v_pk_mul_f32 v[50:51], v[50:51], v[56:57] op_sel_hi:[1,0]
	v_pk_mul_f32 v[52:53], v[144:145], v[52:53]
	v_pk_mul_f32 v[50:51], v[142:143], v[50:51]
	v_pk_mul_f32 v[46:47], v[46:47], v[56:57] op_sel_hi:[1,0]
	v_cvt_pk_bf16_f32 v50, v50, v51
	v_cvt_pk_bf16_f32 v51, v52, v53
	v_lshl_add_u64 v[52:53], s[30:31], 0, v[54:55]
	v_pk_mul_f32 v[38:39], v[38:39], v[56:57] op_sel_hi:[1,0]
	v_pk_mul_f32 v[32:33], v[32:33], v[56:57] op_sel_hi:[1,0]
	v_pk_mul_f32 v[30:31], v[30:31], v[56:57] op_sel_hi:[1,0]
	v_lshl_add_u64 v[52:53], v[52:53], 0, v[146:147]
	v_pk_mul_f32 v[48:49], v[48:49], v[56:57] op_sel_hi:[1,0]
	v_pk_mul_f32 v[46:47], v[138:139], v[46:47]
	v_pk_mul_f32 v[40:41], v[40:41], v[56:57] op_sel_hi:[1,0]
	v_pk_mul_f32 v[38:39], v[134:135], v[38:39]
	v_pk_mul_f32 v[32:33], v[20:21], v[32:33]
	v_pk_mul_f32 v[30:31], v[18:19], v[30:31]
	global_store_dwordx2 v[52:53], v[50:51], off
	v_pk_mul_f32 v[48:49], v[140:141], v[48:49]
	v_cvt_pk_bf16_f32 v46, v46, v47
	v_pk_mul_f32 v[40:41], v[136:137], v[40:41]
	v_cvt_pk_bf16_f32 v47, v48, v49
	global_store_dwordx2 v[52:53], v[46:47], off offset:32
	v_cvt_pk_bf16_f32 v38, v38, v39
	v_cvt_pk_bf16_f32 v39, v40, v41
	global_store_dwordx2 v[52:53], v[38:39], off offset:256
	v_cvt_pk_bf16_f32 v30, v30, v31
	v_cvt_pk_bf16_f32 v31, v32, v33
	ds_read_b32 v32, v175 offset:4736
	global_store_dwordx2 v[52:53], v[30:31], off offset:288
	v_lshlrev_b64 v[30:31], 11, v[166:167]
	v_lshl_add_u64 v[30:31], s[30:31], 0, v[30:31]
	v_lshl_add_u64 v[30:31], v[30:31], 0, v[146:147]
	s_waitcnt lgkmcnt(0)
	v_pk_mul_f32 v[40:41], v[42:43], v[32:33] op_sel_hi:[1,0]
	v_pk_mul_f32 v[34:35], v[34:35], v[32:33] op_sel_hi:[1,0]
	v_pk_mul_f32 v[26:27], v[26:27], v[32:33] op_sel_hi:[1,0]
	v_pk_mul_f32 v[24:25], v[24:25], v[32:33] op_sel_hi:[1,0]
	v_pk_mul_f32 v[22:23], v[22:23], v[32:33] op_sel_hi:[1,0]
	v_pk_mul_f32 v[38:39], v[44:45], v[32:33] op_sel_hi:[1,0]
	v_pk_mul_f32 v[40:41], v[142:143], v[40:41]
	v_pk_mul_f32 v[36:37], v[36:37], v[32:33] op_sel_hi:[1,0]
	v_pk_mul_f32 v[34:35], v[138:139], v[34:35]
	v_pk_mul_f32 v[28:29], v[28:29], v[32:33] op_sel_hi:[1,0]
	v_pk_mul_f32 v[26:27], v[134:135], v[26:27]
	v_pk_mul_f32 v[24:25], v[20:21], v[24:25]
	v_pk_mul_f32 v[22:23], v[18:19], v[22:23]
	v_pk_mul_f32 v[38:39], v[144:145], v[38:39]
	v_cvt_pk_bf16_f32 v40, v40, v41
	v_pk_mul_f32 v[36:37], v[140:141], v[36:37]
	v_cvt_pk_bf16_f32 v41, v38, v39
	global_store_dwordx2 v[30:31], v[40:41], off
	v_cvt_pk_bf16_f32 v34, v34, v35
	v_cvt_pk_bf16_f32 v35, v36, v37
	global_store_dwordx2 v[30:31], v[34:35], off offset:32
	v_pk_mul_f32 v[28:29], v[136:137], v[28:29]
	v_cvt_pk_bf16_f32 v26, v26, v27
	s_nop 0
	v_cvt_pk_bf16_f32 v27, v28, v29
	global_store_dwordx2 v[30:31], v[26:27], off offset:256
	v_cvt_pk_bf16_f32 v22, v22, v23
	v_cvt_pk_bf16_f32 v23, v24, v25
	ds_read_b32 v24, v175 offset:4800
	global_store_dwordx2 v[30:31], v[22:23], off offset:288
	v_lshlrev_b64 v[22:23], 11, v[162:163]
	s_waitcnt lgkmcnt(0)
	v_pk_mul_f32 v[16:17], v[16:17], v[24:25] op_sel_hi:[1,0]
	v_pk_mul_f32 v[14:15], v[14:15], v[24:25] op_sel_hi:[1,0]
	v_pk_mul_f32 v[16:17], v[144:145], v[16:17]
	v_pk_mul_f32 v[14:15], v[142:143], v[14:15]
	v_pk_mul_f32 v[10:11], v[10:11], v[24:25] op_sel_hi:[1,0]
	v_cvt_pk_bf16_f32 v14, v14, v15
	v_cvt_pk_bf16_f32 v15, v16, v17
	v_lshl_add_u64 v[16:17], s[30:31], 0, v[22:23]
	v_pk_mul_f32 v[6:7], v[6:7], v[24:25] op_sel_hi:[1,0]
	v_pk_mul_f32 v[2:3], v[2:3], v[24:25] op_sel_hi:[1,0]
	v_lshl_add_u64 v[16:17], v[16:17], 0, v[146:147]
	v_pk_mul_f32 v[12:13], v[12:13], v[24:25] op_sel_hi:[1,0]
	v_pk_mul_f32 v[10:11], v[138:139], v[10:11]
	v_pk_mul_f32 v[8:9], v[8:9], v[24:25] op_sel_hi:[1,0]
	v_pk_mul_f32 v[6:7], v[134:135], v[6:7]
	v_pk_mul_f32 v[4:5], v[4:5], v[24:25] op_sel_hi:[1,0]
	v_pk_mul_f32 v[2:3], v[18:19], v[2:3]
	global_store_dwordx2 v[16:17], v[14:15], off
	v_pk_mul_f32 v[12:13], v[140:141], v[12:13]
	v_cvt_pk_bf16_f32 v10, v10, v11
	v_pk_mul_f32 v[8:9], v[136:137], v[8:9]
	v_cvt_pk_bf16_f32 v11, v12, v13
	global_store_dwordx2 v[16:17], v[10:11], off offset:32
	v_cvt_pk_bf16_f32 v6, v6, v7
	v_cvt_pk_bf16_f32 v7, v8, v9
	global_store_dwordx2 v[16:17], v[6:7], off offset:256
	v_pk_mul_f32 v[4:5], v[20:21], v[4:5]
	v_cvt_pk_bf16_f32 v2, v2, v3
	s_nop 0
	v_cvt_pk_bf16_f32 v3, v4, v5
	global_store_dwordx2 v[16:17], v[2:3], off offset:288
	s_barrier

.LBB0_242:
	s_or_b64 exec, exec, s[30:31]
	v_mul_f32_e32 v51, v47, v47
	v_mul_f32_e32 v58, v43, v43
	v_fmac_f32_e32 v51, v46, v46
	v_fmac_f32_e32 v58, v42, v42
	v_fmac_f32_e32 v51, v48, v48
	v_fmac_f32_e32 v58, v44, v44
	v_fmac_f32_e32 v51, v49, v49
	v_fmac_f32_e32 v58, v45, v45
	v_add_f32_e32 v51, v51, v58
	v_mul_f32_e32 v58, v39, v39
	v_fmac_f32_e32 v58, v38, v38
	v_fmac_f32_e32 v58, v40, v40
	v_fmac_f32_e32 v58, v41, v41
	v_add_f32_e32 v51, v51, v58
	v_mul_f32_e32 v58, v35, v35
	v_fmac_f32_e32 v58, v34, v34
	v_fmac_f32_e32 v58, v36, v36
	v_fmac_f32_e32 v58, v37, v37
	v_add_f32_e32 v51, v51, v58
	v_mov_b32_e32 v58, v51
	s_nop 1
	v_permlane32_swap_b32_e32 v58, v51
	s_nop 1
	v_lshl_add_u64 v[68:69], s[74:75], 0, v[54:55]
	s_waitcnt lgkmcnt(0)
	v_add_f32_e32 v51, v51, v58
	v_mov_b32_e32 v58, v51
	s_nop 1
	v_permlane16_swap_b32_e32 v58, v51
	s_nop 1
	v_add_f32_e32 v51, v51, v58
	s_nop 1
	v_mov_b32_dpp v58, v51 row_ror:8 row_mask:0xf bank_mask:0xf
	v_add_f32_e32 v51, v51, v58
	s_nop 1
	v_mov_b32_dpp v58, v51 row_shl:4 row_mask:0xf bank_mask:0x5
	s_nop 1
	v_mov_b32_dpp v58, v51 row_shr:4 row_mask:0xf bank_mask:0xa
	v_add_f32_e32 v51, v51, v58
	s_nop 1
	v_mov_b32_dpp v58, v51 quad_perm:[2,3,0,1] row_mask:0xf bank_mask:0xf
	v_add_f32_e32 v51, v51, v58
	s_nop 1
	v_mov_b32_dpp v58, v51 quad_perm:[1,0,3,2] row_mask:0xf bank_mask:0xf
	v_add_f32_e32 v51, v51, v58
	v_fmamk_f32 v51, v51, 0x3a800000, v1
	v_cmp_gt_f32_e64 s[0:1], s33, v51
	v_mul_f32_e32 v58, 0x4b800000, v51
	s_nop 0
	v_cndmask_b32_e64 v51, v51, v58, s[0:1]
	v_rsq_f32_e32 v51, v51
	s_nop 0
	v_mul_f32_e32 v58, 0x45800000, v51
	v_cndmask_b32_e64 v58, v51, v58, s[0:1]
	v_pk_mul_f32 v[46:47], v[46:47], v[58:59] op_sel_hi:[1,0]
	s_mov_b32 s0, 0x5a88000
	v_pk_mul_f32 v[48:49], v[48:49], v[58:59] op_sel_hi:[1,0]
	v_pk_mul_f32 v[60:61], v[14:15], v[46:47]
	v_add_co_u32_e64 v46, s[0:1], s0, v68
	v_pk_mul_f32 v[48:49], v[16:17], v[48:49]
	v_cvt_pk_bf16_f32 v70, v60, v61
	s_nop 0
	v_addc_co_u32_e64 v47, s[0:1], 0, v69, s[0:1]
	v_cvt_pk_bf16_f32 v71, v48, v49
	global_store_dwordx2 v[46:47], v[70:71], off
	ds_read_b128 v[100:103], v67
	ds_read_b128 v[104:107], v67 offset:4096
	ds_read_b128 v[108:111], v67 offset:8192
	ds_read_b128 v[112:115], v67 offset:12288
	ds_read_b128 v[116:119], v67 offset:16384
	ds_read_b128 v[120:123], v67 offset:20480
	ds_read_b128 v[124:127], v67 offset:24576
	s_waitcnt lgkmcnt(6)
	v_pk_mul_f32 v[148:149], v[100:101], v[60:61]
	v_pk_fma_f32 v[148:149], v[102:103], v[48:49], v[148:149]
	ds_read_b128 v[128:131], v67 offset:28672
	s_waitcnt lgkmcnt(6)
	v_pk_mul_f32 v[150:151], v[104:105], v[60:61]
	v_pk_fma_f32 v[150:151], v[106:107], v[48:49], v[150:151]
	ds_read_b128 v[100:103], v67 offset:32768
	s_waitcnt lgkmcnt(6)
	v_pk_mul_f32 v[152:153], v[108:109], v[60:61]
	v_pk_fma_f32 v[152:153], v[110:111], v[48:49], v[152:153]
	ds_read_b128 v[104:107], v67 offset:36864
	s_waitcnt lgkmcnt(6)
	v_pk_mul_f32 v[154:155], v[112:113], v[60:61]
	v_pk_fma_f32 v[154:155], v[114:115], v[48:49], v[154:155]
	ds_read_b128 v[108:111], v67 offset:40960
	s_waitcnt lgkmcnt(6)
	v_pk_mul_f32 v[156:157], v[116:117], v[60:61]
	v_pk_fma_f32 v[156:157], v[118:119], v[48:49], v[156:157]
	ds_read_b128 v[112:115], v67 offset:45056
	s_waitcnt lgkmcnt(6)
	v_pk_mul_f32 v[158:159], v[120:121], v[60:61]
	v_pk_fma_f32 v[158:159], v[122:123], v[48:49], v[158:159]
	ds_read_b128 v[116:119], v67 offset:49152
	s_waitcnt lgkmcnt(6)
	v_pk_mul_f32 v[160:161], v[124:125], v[60:61]
	v_pk_fma_f32 v[160:161], v[126:127], v[48:49], v[160:161]
	ds_read_b128 v[120:123], v67 offset:53248
	s_waitcnt lgkmcnt(6)
	v_pk_mul_f32 v[162:163], v[128:129], v[60:61]
	v_pk_fma_f32 v[162:163], v[130:131], v[48:49], v[162:163]
	ds_read_b128 v[124:127], v67 offset:57344
	s_waitcnt lgkmcnt(6)
	v_pk_mul_f32 v[164:165], v[100:101], v[60:61]
	v_pk_fma_f32 v[164:165], v[102:103], v[48:49], v[164:165]
	ds_read_b128 v[128:131], v67 offset:61440
	s_waitcnt lgkmcnt(6)
	v_pk_mul_f32 v[168:169], v[104:105], v[60:61]
	v_pk_fma_f32 v[168:169], v[106:107], v[48:49], v[168:169]
	ds_read_b128 v[100:103], v67 offset:1024
	s_waitcnt lgkmcnt(6)
	v_pk_mul_f32 v[170:171], v[108:109], v[60:61]
	v_pk_fma_f32 v[170:171], v[110:111], v[48:49], v[170:171]
	ds_read_b128 v[104:107], v67 offset:5120
	s_waitcnt lgkmcnt(6)
	v_pk_mul_f32 v[172:173], v[112:113], v[60:61]
	v_pk_fma_f32 v[172:173], v[114:115], v[48:49], v[172:173]
	ds_read_b128 v[108:111], v67 offset:9216
	s_waitcnt lgkmcnt(6)
	v_pk_mul_f32 v[174:175], v[116:117], v[60:61]
	v_pk_fma_f32 v[174:175], v[118:119], v[48:49], v[174:175]
	ds_read_b128 v[112:115], v67 offset:13312
	s_waitcnt lgkmcnt(6)
	v_pk_mul_f32 v[176:177], v[120:121], v[60:61]
	v_pk_fma_f32 v[176:177], v[122:123], v[48:49], v[176:177]
	ds_read_b128 v[116:119], v67 offset:17408
	s_waitcnt lgkmcnt(6)
	v_pk_mul_f32 v[178:179], v[124:125], v[60:61]
	v_pk_fma_f32 v[178:179], v[126:127], v[48:49], v[178:179]
	ds_read_b128 v[120:123], v67 offset:21504
	s_waitcnt lgkmcnt(6)
	v_pk_mul_f32 v[180:181], v[128:129], v[60:61]
	v_pk_fma_f32 v[180:181], v[130:131], v[48:49], v[180:181]
	v_pk_mul_f32 v[60:61], v[42:43], v[58:59] op_sel_hi:[1,0]
	v_pk_mul_f32 v[42:43], v[44:45], v[58:59] op_sel_hi:[1,0]
	v_pk_mul_f32 v[44:45], v[10:11], v[60:61]
	v_pk_mul_f32 v[42:43], v[12:13], v[42:43]
	v_cvt_pk_bf16_f32 v60, v44, v45
	s_nop 0
	v_cvt_pk_bf16_f32 v61, v42, v43
	ds_read_b128 v[124:127], v67 offset:25600
	global_store_dwordx2 v[46:47], v[60:61], off offset:512
	s_waitcnt lgkmcnt(6)
	v_pk_fma_f32 v[148:149], v[100:101], v[44:45], v[148:149]
	v_pk_fma_f32 v[148:149], v[102:103], v[42:43], v[148:149]
	ds_read_b128 v[128:131], v67 offset:29696
	s_waitcnt lgkmcnt(6)
	v_pk_fma_f32 v[150:151], v[104:105], v[44:45], v[150:151]
	v_pk_fma_f32 v[150:151], v[106:107], v[42:43], v[150:151]
	ds_read_b128 v[100:103], v67 offset:33792
	s_waitcnt lgkmcnt(6)
	v_pk_fma_f32 v[152:153], v[108:109], v[44:45], v[152:153]
	v_pk_fma_f32 v[152:153], v[110:111], v[42:43], v[152:153]
	ds_read_b128 v[104:107], v67 offset:37888
	s_waitcnt lgkmcnt(6)
	v_pk_fma_f32 v[154:155], v[112:113], v[44:45], v[154:155]
	v_pk_fma_f32 v[154:155], v[114:115], v[42:43], v[154:155]
	ds_read_b128 v[108:111], v67 offset:41984
	s_waitcnt lgkmcnt(6)
	v_pk_fma_f32 v[156:157], v[116:117], v[44:45], v[156:157]
	v_pk_fma_f32 v[156:157], v[118:119], v[42:43], v[156:157]
	ds_read_b128 v[112:115], v67 offset:46080
	s_waitcnt lgkmcnt(6)
	v_pk_fma_f32 v[158:159], v[120:121], v[44:45], v[158:159]
	v_pk_fma_f32 v[158:159], v[122:123], v[42:43], v[158:159]
	ds_read_b128 v[116:119], v67 offset:50176
	s_waitcnt lgkmcnt(6)
	v_pk_fma_f32 v[160:161], v[124:125], v[44:45], v[160:161]
	v_pk_fma_f32 v[160:161], v[126:127], v[42:43], v[160:161]
	ds_read_b128 v[120:123], v67 offset:54272
	s_waitcnt lgkmcnt(6)
	v_pk_fma_f32 v[162:163], v[128:129], v[44:45], v[162:163]
	v_pk_fma_f32 v[162:163], v[130:131], v[42:43], v[162:163]
	ds_read_b128 v[124:127], v67 offset:58368
	s_waitcnt lgkmcnt(6)
	v_pk_fma_f32 v[164:165], v[100:101], v[44:45], v[164:165]
	v_pk_fma_f32 v[164:165], v[102:103], v[42:43], v[164:165]
	ds_read_b128 v[128:131], v67 offset:62464
	s_waitcnt lgkmcnt(6)
	v_pk_fma_f32 v[168:169], v[104:105], v[44:45], v[168:169]
	v_pk_fma_f32 v[168:169], v[106:107], v[42:43], v[168:169]
	ds_read_b128 v[100:103], v67 offset:2048
	s_waitcnt lgkmcnt(6)
	v_pk_fma_f32 v[170:171], v[108:109], v[44:45], v[170:171]
	v_pk_fma_f32 v[170:171], v[110:111], v[42:43], v[170:171]
	ds_read_b128 v[104:107], v67 offset:6144
	s_waitcnt lgkmcnt(6)
	v_pk_fma_f32 v[172:173], v[112:113], v[44:45], v[172:173]
	v_pk_fma_f32 v[172:173], v[114:115], v[42:43], v[172:173]
	ds_read_b128 v[108:111], v67 offset:10240
	s_waitcnt lgkmcnt(6)
	v_pk_fma_f32 v[174:175], v[116:117], v[44:45], v[174:175]
	v_pk_fma_f32 v[174:175], v[118:119], v[42:43], v[174:175]
	ds_read_b128 v[112:115], v67 offset:14336
	s_waitcnt lgkmcnt(6)
	v_pk_fma_f32 v[176:177], v[120:121], v[44:45], v[176:177]
	v_pk_fma_f32 v[176:177], v[122:123], v[42:43], v[176:177]
	ds_read_b128 v[116:119], v67 offset:18432
	s_waitcnt lgkmcnt(6)
	v_pk_fma_f32 v[178:179], v[124:125], v[44:45], v[178:179]
	v_pk_fma_f32 v[178:179], v[126:127], v[42:43], v[178:179]
	ds_read_b128 v[120:123], v67 offset:22528
	s_waitcnt lgkmcnt(6)
	v_pk_fma_f32 v[180:181], v[128:129], v[44:45], v[180:181]
	v_pk_fma_f32 v[180:181], v[130:131], v[42:43], v[180:181]
	v_pk_mul_f32 v[42:43], v[38:39], v[58:59] op_sel_hi:[1,0]
	v_pk_mul_f32 v[38:39], v[40:41], v[58:59] op_sel_hi:[1,0]
	v_pk_mul_f32 v[40:41], v[6:7], v[42:43]
	v_pk_mul_f32 v[38:39], v[8:9], v[38:39]
	v_cvt_pk_bf16_f32 v42, v40, v41
	v_cvt_pk_bf16_f32 v43, v38, v39
	global_store_dwordx2 v[46:47], v[42:43], off offset:1024
	ds_read_b128 v[124:127], v67 offset:26624
	ds_read_b128 v[128:131], v67 offset:30720
	s_waitcnt lgkmcnt(7)
	v_pk_fma_f32 v[148:149], v[100:101], v[40:41], v[148:149]
	v_pk_fma_f32 v[148:149], v[102:103], v[38:39], v[148:149]
	s_waitcnt lgkmcnt(6)
	v_pk_fma_f32 v[150:151], v[104:105], v[40:41], v[150:151]
	v_pk_fma_f32 v[150:151], v[106:107], v[38:39], v[150:151]
	ds_read_b128 v[100:103], v67 offset:34816
	s_waitcnt lgkmcnt(6)
	v_pk_fma_f32 v[152:153], v[108:109], v[40:41], v[152:153]
	v_pk_fma_f32 v[152:153], v[110:111], v[38:39], v[152:153]
	ds_read_b128 v[104:107], v67 offset:38912
	s_waitcnt lgkmcnt(6)
	v_pk_fma_f32 v[154:155], v[112:113], v[40:41], v[154:155]
	v_pk_fma_f32 v[154:155], v[114:115], v[38:39], v[154:155]
	ds_read_b128 v[108:111], v67 offset:43008
	s_waitcnt lgkmcnt(6)
	v_pk_fma_f32 v[156:157], v[116:117], v[40:41], v[156:157]
	v_pk_fma_f32 v[156:157], v[118:119], v[38:39], v[156:157]
	ds_read_b128 v[112:115], v67 offset:47104
	s_waitcnt lgkmcnt(6)
	v_pk_fma_f32 v[158:159], v[120:121], v[40:41], v[158:159]
	v_pk_fma_f32 v[158:159], v[122:123], v[38:39], v[158:159]
	ds_read_b128 v[116:119], v67 offset:51200
	s_waitcnt lgkmcnt(6)
	v_pk_fma_f32 v[160:161], v[124:125], v[40:41], v[160:161]
	v_pk_fma_f32 v[160:161], v[126:127], v[38:39], v[160:161]
	ds_read_b128 v[120:123], v67 offset:55296
	s_waitcnt lgkmcnt(6)
	v_pk_fma_f32 v[162:163], v[128:129], v[40:41], v[162:163]
	v_pk_fma_f32 v[162:163], v[130:131], v[38:39], v[162:163]
	ds_read_b128 v[124:127], v67 offset:59392
	s_waitcnt lgkmcnt(6)
	v_pk_fma_f32 v[164:165], v[100:101], v[40:41], v[164:165]
	v_pk_fma_f32 v[164:165], v[102:103], v[38:39], v[164:165]
	ds_read_b128 v[128:131], v67 offset:63488
	s_waitcnt lgkmcnt(6)
	v_pk_fma_f32 v[168:169], v[104:105], v[40:41], v[168:169]
	v_pk_fma_f32 v[168:169], v[106:107], v[38:39], v[168:169]
	ds_read_b128 v[100:103], v67 offset:3072
	s_waitcnt lgkmcnt(6)
	v_pk_fma_f32 v[170:171], v[108:109], v[40:41], v[170:171]
	v_pk_fma_f32 v[170:171], v[110:111], v[38:39], v[170:171]
	ds_read_b128 v[104:107], v67 offset:7168
	s_waitcnt lgkmcnt(6)
	v_pk_fma_f32 v[172:173], v[112:113], v[40:41], v[172:173]
	v_pk_fma_f32 v[172:173], v[114:115], v[38:39], v[172:173]
	ds_read_b128 v[108:111], v67 offset:11264
	s_waitcnt lgkmcnt(6)
	v_pk_fma_f32 v[174:175], v[116:117], v[40:41], v[174:175]
	v_pk_fma_f32 v[174:175], v[118:119], v[38:39], v[174:175]
	ds_read_b128 v[112:115], v67 offset:15360
	s_waitcnt lgkmcnt(6)
	v_pk_fma_f32 v[176:177], v[120:121], v[40:41], v[176:177]
	v_pk_fma_f32 v[176:177], v[122:123], v[38:39], v[176:177]
	ds_read_b128 v[116:119], v67 offset:19456
	s_waitcnt lgkmcnt(6)
	v_pk_fma_f32 v[178:179], v[124:125], v[40:41], v[178:179]
	v_pk_fma_f32 v[178:179], v[126:127], v[38:39], v[178:179]
	ds_read_b128 v[120:123], v67 offset:23552
	s_waitcnt lgkmcnt(6)
	v_pk_fma_f32 v[180:181], v[128:129], v[40:41], v[180:181]
	v_pk_fma_f32 v[180:181], v[130:131], v[38:39], v[180:181]
	v_pk_mul_f32 v[40:41], v[34:35], v[58:59] op_sel_hi:[1,0]
	v_pk_mul_f32 v[34:35], v[36:37], v[58:59] op_sel_hi:[1,0]
	v_pk_mul_f32 v[36:37], v[2:3], v[40:41]
	v_pk_mul_f32 v[34:35], v[4:5], v[34:35]
	v_cvt_pk_bf16_f32 v40, v36, v37
	s_nop 0
	v_cvt_pk_bf16_f32 v41, v34, v35
	ds_read_b128 v[124:127], v67 offset:27648
	global_store_dwordx2 v[46:47], v[40:41], off offset:1536
	s_waitcnt lgkmcnt(6)
	v_pk_fma_f32 v[148:149], v[100:101], v[36:37], v[148:149]
	v_pk_fma_f32 v[148:149], v[102:103], v[34:35], v[148:149]
	ds_read_b128 v[128:131], v67 offset:31744
	v_add_f32_e32 v39, v148, v149
	s_waitcnt lgkmcnt(6)
	v_pk_fma_f32 v[150:151], v[104:105], v[36:37], v[150:151]
	v_pk_fma_f32 v[150:151], v[106:107], v[34:35], v[150:151]
	ds_read_b128 v[100:103], v67 offset:35840
	v_add_f32_e32 v40, v150, v151
	s_waitcnt lgkmcnt(6)
	v_pk_fma_f32 v[152:153], v[108:109], v[36:37], v[152:153]
	v_pk_fma_f32 v[152:153], v[110:111], v[34:35], v[152:153]
	ds_read_b128 v[104:107], v67 offset:39936
	v_add_f32_e32 v41, v152, v153
	s_waitcnt lgkmcnt(6)
	v_pk_fma_f32 v[154:155], v[112:113], v[36:37], v[154:155]
	v_pk_fma_f32 v[154:155], v[114:115], v[34:35], v[154:155]
	v_add_f32_e32 v42, v154, v155
	ds_read_b128 v[108:111], v67 offset:44032
	s_waitcnt lgkmcnt(6)
	v_pk_fma_f32 v[156:157], v[116:117], v[36:37], v[156:157]
	v_pk_fma_f32 v[156:157], v[118:119], v[34:35], v[156:157]
	ds_read_b128 v[112:115], v67 offset:48128
	v_add_f32_e32 v43, v156, v157
	s_waitcnt lgkmcnt(6)
	v_pk_fma_f32 v[158:159], v[120:121], v[36:37], v[158:159]
	v_pk_fma_f32 v[158:159], v[122:123], v[34:35], v[158:159]
	v_add_f32_e32 v48, v158, v159
	ds_read_b128 v[116:119], v67 offset:52224
	s_waitcnt lgkmcnt(6)
	v_pk_fma_f32 v[160:161], v[124:125], v[36:37], v[160:161]
	v_pk_fma_f32 v[160:161], v[126:127], v[34:35], v[160:161]
	v_add_f32_e32 v49, v160, v161
	ds_read_b128 v[120:123], v67 offset:56320
	s_waitcnt lgkmcnt(6)
	v_pk_fma_f32 v[162:163], v[128:129], v[36:37], v[162:163]
	v_pk_fma_f32 v[162:163], v[130:131], v[34:35], v[162:163]
	v_add_f32_e32 v51, v162, v163
	ds_read_b128 v[124:127], v67 offset:60416
	s_waitcnt lgkmcnt(6)
	v_pk_fma_f32 v[164:165], v[100:101], v[36:37], v[164:165]
	v_pk_fma_f32 v[164:165], v[102:103], v[34:35], v[164:165]
	v_add_f32_e32 v58, v164, v165
	ds_read_b128 v[128:131], v67 offset:64512
	s_waitcnt lgkmcnt(6)
	v_pk_fma_f32 v[168:169], v[104:105], v[36:37], v[168:169]
	v_pk_fma_f32 v[168:169], v[106:107], v[34:35], v[168:169]
	v_add_f32_e32 v60, v168, v169
	s_waitcnt lgkmcnt(5)
	v_pk_fma_f32 v[170:171], v[108:109], v[36:37], v[170:171]
	v_pk_fma_f32 v[170:171], v[110:111], v[34:35], v[170:171]
	v_add_f32_e32 v61, v170, v171
	s_waitcnt lgkmcnt(4)
	v_pk_fma_f32 v[172:173], v[112:113], v[36:37], v[172:173]
	v_pk_fma_f32 v[172:173], v[114:115], v[34:35], v[172:173]
	v_add_f32_e32 v68, v172, v173
	s_waitcnt lgkmcnt(3)
	v_pk_fma_f32 v[174:175], v[116:117], v[36:37], v[174:175]
	v_pk_fma_f32 v[174:175], v[118:119], v[34:35], v[174:175]
	v_add_f32_e32 v69, v174, v175
	s_waitcnt lgkmcnt(2)
	v_pk_fma_f32 v[176:177], v[120:121], v[36:37], v[176:177]
	v_pk_fma_f32 v[176:177], v[122:123], v[34:35], v[176:177]
	v_add_f32_e32 v70, v176, v177
	s_waitcnt lgkmcnt(1)
	v_pk_fma_f32 v[178:179], v[124:125], v[36:37], v[178:179]
	v_pk_fma_f32 v[178:179], v[126:127], v[34:35], v[178:179]
	v_add_f32_e32 v71, v178, v179
	s_waitcnt lgkmcnt(0)
	v_pk_fma_f32 v[180:181], v[128:129], v[36:37], v[180:181]
	v_pk_fma_f32 v[180:181], v[130:131], v[34:35], v[180:181]
	v_add_f32_e32 v34, v180, v181
	s_nop 1
	v_permlane32_swap_b32_e32 v39, v58
	s_nop 1
	v_add_f32_e32 v39, v39, v58
	s_nop 1
	v_permlane32_swap_b32_e32 v40, v60
	s_nop 1
	v_add_f32_e32 v40, v40, v60
	s_nop 1
	v_permlane32_swap_b32_e32 v41, v61
	s_nop 1
	v_add_f32_e32 v41, v41, v61
	s_nop 1
	v_permlane32_swap_b32_e32 v42, v68
	s_nop 1
	v_add_f32_e32 v42, v42, v68
	s_nop 1
	v_permlane32_swap_b32_e32 v43, v69
	s_nop 1
	v_add_f32_e32 v43, v43, v69
	s_nop 1
	v_permlane32_swap_b32_e32 v48, v70
	s_nop 1
	v_add_f32_e32 v48, v48, v70
	s_nop 1
	v_permlane32_swap_b32_e32 v49, v71
	s_nop 1
	v_add_f32_e32 v49, v49, v71
	s_nop 1
	v_permlane32_swap_b32_e32 v51, v34
	s_nop 1
	v_add_f32_e32 v51, v51, v34
	s_nop 1
	v_permlane16_swap_b32_e32 v40, v48
	s_nop 1
	v_add_f32_e32 v40, v40, v48
	s_nop 1
	v_permlane16_swap_b32_e32 v39, v43
	s_nop 1
	v_add_f32_e32 v39, v39, v43
	s_nop 1
	v_permlane16_swap_b32_e32 v41, v49
	s_nop 1
	v_add_f32_e32 v41, v41, v49
	s_nop 1
	v_permlane16_swap_b32_e32 v42, v51
	s_nop 1
	v_add_f32_e32 v42, v42, v51
	s_nop 1
	v_add_f32_dpp v39, v39, v39 row_ror:8 row_mask:0xf bank_mask:0x3
	s_nop 1
	v_add_f32_dpp v39, v41, v41 row_ror:8 row_mask:0xf bank_mask:0xc
	s_nop 1
	v_add_f32_dpp v40, v40, v40 row_ror:8 row_mask:0xf bank_mask:0x3
	s_nop 1
	v_add_f32_dpp v40, v42, v42 row_ror:8 row_mask:0xf bank_mask:0xc
	s_nop 1
	v_add_f32_dpp v39, v39, v39 row_shl:4 row_mask:0xf bank_mask:0x5
	s_nop 1
	v_add_f32_dpp v39, v40, v40 row_shr:4 row_mask:0xf bank_mask:0xa
	v_mov_b32_e32 v34, v39
	s_nop 0
	s_nop 1
	v_mov_b32_dpp v35, v34 quad_perm:[2,3,0,1] row_mask:0xf bank_mask:0xf
	v_add_f32_e32 v34, v34, v35
	s_nop 1
	v_mov_b32_dpp v35, v34 quad_perm:[1,0,3,2] row_mask:0xf bank_mask:0xf
	s_and_saveexec_b64 s[0:1], s[42:43]
	s_cbranch_execz .LBB0_239
	v_lshl_add_u64 v[36:37], s[74:75], 0, v[52:53]
	v_add_f32_e32 v34, v34, v35
	global_store_dword v[36:37], v34, off
	s_branch .LBB0_239

; #define PG8_STAGE(bufoff, gbase, voff) do { _Pragma("unroll") for (int _i = 0; _i < 2; ++_i) \
;         __builtin_amdgcn_global_load_lds((const unsigned*)((const char*)(gbase) + (voff)[_i]), (LAS unsigned*)(lds + (bufoff) + ldsw + _i * 8192), 16, 0, 0); } while (0)
; #define PG8_LDA(dst, b, h) do { _Pragma("unroll") for (int m = 0; m < 4; ++m) _Pragma("unroll") for (int k = 0; k < 2; ++k) dst[m][k] = *(const LAS bf16x8*)(lds + PG8_SA(b, h) + aoff + m * 2048 + k * 1024); } while (0)
; #define PG8_LDB(dst, b, h) do { _Pragma("unroll") for (int n = 0; n < 2; ++n) _Pragma("unroll") for (int k = 0; k < 2; ++k) dst[n][k] = *(const LAS bf16x8*)(lds + PG8_SB(b, h) + boff + n * 2048 + k * 1024); } while (0)
; #define PG8_WAIT_V(n) asm volatile("s_waitcnt vmcnt(" #n ")" ::: "memory")
; #define PG8_WAIT_L(n) asm volatile("s_waitcnt lgkmcnt(" #n ")" ::: "memory")
; template <class Epi>
; __device__ __forceinline__ void gemm_phase(LAS unsigned char* lds, const Gemm g, const Order& S, const Epi& E) {
;     ...
;         for (int t = 0; t < nt; t += 2) {
;             const bool last = (t == nt - 2);
;             const char* a1 = cA + (size_t)(t + 1) * kstep;
;             const char* a2 = last ? nA : cA + (size_t)(t + 2) * kstep; const char* b2 = last ? nB : cB + (size_t)(t + 2) * kstep;
;             const char* a3 = a2 + kstep; const char* b3 = b2 + kstep;
;             PG8_LDB(B0, 0, 0); PG8_LDB(B1, 0, 1); PG8_SCHED; PG8_LDA(At, 0, 0); PG8_STAGE(PG8_SA(1, 1), a1 + hstepA, voffA);
;             PG8_WAIT_V(8); PG8_WAIT_L(0); PG8_BAR; PG8_MMA(0, 0, At, B0); PG8_MMA(0, 1, At, B1); PG8_BAR; PG8_SCHED;
;             PG8_LDA(At, 0, 1); PG8_STAGE(PG8_SB(0, 0), b2, voffB); PG8_STAGE(PG8_SB(0, 1), b2 + hstepB, voffB); PG8_STAGE(PG8_SA(0, 0), a2, voffA);
;             PG8_WAIT_V(8); PG8_WAIT_L(0); PG8_BAR; PG8_MMA(1, 0, At, B0); PG8_MMA(1, 1, At, B1); PG8_BAR; PG8_SCHED;
;             PG8_LDB(B0, 1, 0); PG8_LDB(B1, 1, 1); PG8_SCHED; PG8_LDA(At, 1, 0); PG8_STAGE(PG8_SA(0, 1), a2 + hstepA, voffA);
;             PG8_WAIT_V(8); PG8_WAIT_L(0); PG8_BAR; PG8_MMA(0, 0, At, B0); PG8_MMA(0, 1, At, B1); PG8_BAR; PG8_SCHED;
;             PG8_LDA(At, 1, 1); PG8_STAGE(PG8_SB(1, 0), b3, voffB); PG8_STAGE(PG8_SB(1, 1), b3 + hstepB, voffB); PG8_STAGE(PG8_SA(1, 0), a3, voffA);
;             PG8_WAIT_V(8); PG8_WAIT_L(0); PG8_BAR; PG8_MMA(1, 0, At, B0); PG8_MMA(1, 1, At, B1); PG8_BAR; PG8_SCHED;
.LBB0_262:
	s_add_u32 s0, s30, 0x100
	s_addc_u32 s1, s31, 0
	s_add_i32 s11, 0, 0x10000
	s_cmp_eq_u32 s10, 4
	s_cselect_b32 s49, s51, s1
	s_cselect_b32 s48, s50, s0
	s_cselect_b32 s39, s6, s9
	s_cselect_b32 s38, s7, s8
	s_add_i32 s14, 0, 0x14000
	v_add_u32_e32 v142, s11, v239
	v_add_u32_e32 v158, s14, v239
	ds_read_b128 v[130:133], v142
	ds_read_b128 v[134:137], v142 offset:1024
	ds_read_b128 v[138:141], v142 offset:2048
	ds_read_b128 v[142:145], v142 offset:3072
	ds_read_b128 v[146:149], v158
	ds_read_b128 v[150:153], v158 offset:1024
	ds_read_b128 v[154:157], v158 offset:2048
	ds_read_b128 v[158:161], v158 offset:3072
	v_lshl_add_u64 v[214:215], s[30:31], 0, v[210:211]
	s_add_i32 m0, s54, 0xc000
	ds_read_b128 v[162:165], v241
	ds_read_b128 v[166:169], v241 offset:1024
	ds_read_b128 v[170:173], v241 offset:2048
	ds_read_b128 v[174:177], v241 offset:3072
	ds_read_b128 v[178:181], v241 offset:4096
	ds_read_b128 v[182:185], v241 offset:5120
	ds_read_b128 v[186:189], v241 offset:6144
	ds_read_b128 v[190:193], v241 offset:7168
	global_load_lds_dwordx4 v[214:215], off
	v_lshl_add_u64 v[214:215], s[30:31], 0, v[212:213]
	s_add_i32 m0, s54, 0xe000
	s_nop 0
	global_load_lds_dwordx4 v[214:215], off
	s_waitcnt vmcnt(8)
	s_waitcnt lgkmcnt(0)
	s_barrier
	s_setprio 1
	v_mfma_f32_16x16x32_bf16 v[126:129], v[130:133], v[162:165], v[126:129]
	v_mfma_f32_16x16x32_bf16 v[122:125], v[138:141], v[162:165], v[122:125]
	v_mfma_f32_16x16x32_bf16 v[118:121], v[130:133], v[170:173], v[118:121]
	v_mfma_f32_16x16x32_bf16 v[114:117], v[138:141], v[170:173], v[114:117]
	v_mfma_f32_16x16x32_bf16 v[110:113], v[130:133], v[178:181], v[110:113]
	v_mfma_f32_16x16x32_bf16 v[106:109], v[138:141], v[178:181], v[106:109]
	v_mfma_f32_16x16x32_bf16 v[102:105], v[130:133], v[186:189], v[102:105]
	v_mfma_f32_16x16x32_bf16 v[98:101], v[138:141], v[186:189], v[98:101]
	v_mfma_f32_16x16x32_bf16 v[126:129], v[134:137], v[166:169], v[126:129]
	v_mfma_f32_16x16x32_bf16 v[122:125], v[142:145], v[166:169], v[122:125]
	v_mfma_f32_16x16x32_bf16 v[118:121], v[134:137], v[174:177], v[118:121]
	v_mfma_f32_16x16x32_bf16 v[114:117], v[142:145], v[174:177], v[114:117]
	v_mfma_f32_16x16x32_bf16 v[110:113], v[134:137], v[182:185], v[110:113]
	v_mfma_f32_16x16x32_bf16 v[106:109], v[142:145], v[182:185], v[106:109]
	v_mfma_f32_16x16x32_bf16 v[102:105], v[134:137], v[190:193], v[102:105]
	v_mfma_f32_16x16x32_bf16 v[98:101], v[142:145], v[190:193], v[98:101]
	s_setprio 0
	s_setprio 1
	v_mfma_f32_16x16x32_bf16 v[94:97], v[146:149], v[162:165], v[94:97]
	v_mfma_f32_16x16x32_bf16 v[90:93], v[154:157], v[162:165], v[90:93]
	v_mfma_f32_16x16x32_bf16 v[86:89], v[146:149], v[170:173], v[86:89]
	v_mfma_f32_16x16x32_bf16 v[82:85], v[154:157], v[170:173], v[82:85]
	v_mfma_f32_16x16x32_bf16 v[78:81], v[146:149], v[178:181], v[78:81]
	v_mfma_f32_16x16x32_bf16 v[74:77], v[154:157], v[178:181], v[74:77]
	v_mfma_f32_16x16x32_bf16 v[70:73], v[146:149], v[186:189], v[70:73]
	v_mfma_f32_16x16x32_bf16 v[66:69], v[154:157], v[186:189], v[66:69]
	v_mfma_f32_16x16x32_bf16 v[94:97], v[150:153], v[166:169], v[94:97]
	v_mfma_f32_16x16x32_bf16 v[90:93], v[158:161], v[166:169], v[90:93]
	v_mfma_f32_16x16x32_bf16 v[86:89], v[150:153], v[174:177], v[86:89]
	v_mfma_f32_16x16x32_bf16 v[82:85], v[158:161], v[174:177], v[82:85]
	v_mfma_f32_16x16x32_bf16 v[78:81], v[150:153], v[182:185], v[78:81]
	v_mfma_f32_16x16x32_bf16 v[74:77], v[158:161], v[182:185], v[74:77]
	v_mfma_f32_16x16x32_bf16 v[70:73], v[150:153], v[190:193], v[70:73]
	v_mfma_f32_16x16x32_bf16 v[66:69], v[158:161], v[190:193], v[66:69]
	s_setprio 0
	s_barrier
	s_add_i32 s11, s11, s20
	v_lshl_add_u64 v[214:215], s[38:39], 0, v[194:195]
	s_mov_b32 m0, s11
	ds_read_b128 v[162:165], v241 offset:16384
	ds_read_b128 v[166:169], v241 offset:17408
	ds_read_b128 v[170:173], v241 offset:18432
	ds_read_b128 v[174:177], v241 offset:19456
	ds_read_b128 v[178:181], v241 offset:20480
	ds_read_b128 v[182:185], v241 offset:21504
	ds_read_b128 v[186:189], v241 offset:22528
	ds_read_b128 v[190:193], v241 offset:23552
	global_load_lds_dwordx4 v[214:215], off
	s_add_i32 m0, s11, 0x2000
	s_add_u32 s12, s38, 0x20000
	v_lshl_add_u64 v[216:217], s[38:39], 0, v[204:205]
	s_addc_u32 s13, s39, 0
	s_add_i32 s11, s14, s20
	global_load_lds_dwordx4 v[216:217], off
	v_lshl_add_u64 v[218:219], s[12:13], 0, v[194:195]
	s_mov_b32 m0, s11
	v_lshl_add_u64 v[220:221], s[48:49], 0, v[206:207]
	global_load_lds_dwordx4 v[218:219], off
	v_lshl_add_u64 v[218:219], s[12:13], 0, v[204:205]
	s_add_i32 m0, s11, 0x2000
	s_nop 0
	global_load_lds_dwordx4 v[218:219], off
	v_lshl_add_u64 v[218:219], s[48:49], 0, v[208:209]
	s_mov_b32 m0, s54
	s_nop 0
	global_load_lds_dwordx4 v[218:219], off
	s_mov_b32 m0, s55
	s_nop 0
	global_load_lds_dwordx4 v[220:221], off
	s_waitcnt vmcnt(8)
	s_waitcnt lgkmcnt(0)
	s_barrier
; #define PG8_STAGE(bufoff, gbase, voff) do { _Pragma("unroll") for (int _i = 0; _i < 2; ++_i) \
;         __builtin_amdgcn_global_load_lds((const unsigned*)((const char*)(gbase) + (voff)[_i]), (LAS unsigned*)(lds + (bufoff) + ldsw + _i * 8192), 16, 0, 0); } while (0)
; #define PG8_LDA(dst, b, h) do { _Pragma("unroll") for (int m = 0; m < 4; ++m) _Pragma("unroll") for (int k = 0; k < 2; ++k) dst[m][k] = *(const LAS bf16x8*)(lds + PG8_SA(b, h) + aoff + m * 2048 + k * 1024); } while (0)
; #define PG8_LDB(dst, b, h) do { _Pragma("unroll") for (int n = 0; n < 2; ++n) _Pragma("unroll") for (int k = 0; k < 2; ++k) dst[n][k] = *(const LAS bf16x8*)(lds + PG8_SB(b, h) + boff + n * 2048 + k * 1024); } while (0)
; #define PG8_MMA(ai, bj, At, Bt) do { __builtin_amdgcn_s_setprio(1); _Pragma("unroll") for (int m = 0; m < 4; ++m) _Pragma("unroll") for (int n = 0; n < 2; ++n) _Pragma("unroll") for (int k = 0; k < 2; ++k) \
;         acc[ai][bj][m][n] = __builtin_amdgcn_mfma_f32_16x16x32_bf16(Bt[n][k], At[m][k], acc[ai][bj][m][n], 0, 0, 0); __builtin_amdgcn_s_setprio(0); } while (0)
; #define PG8_WAIT_V(n) asm volatile("s_waitcnt vmcnt(" #n ")" ::: "memory")
; #define PG8_WAIT_L(n) asm volatile("s_waitcnt lgkmcnt(" #n ")" ::: "memory")
; #define PG8_BAR __builtin_amdgcn_s_barrier()
; #define PG8_SCHED __builtin_amdgcn_sched_barrier(0)
; template <class Epi>
; __device__ __forceinline__ void gemm_phase(LAS unsigned char* lds, const Gemm g, const Order& S, const Epi& E) {
;     ...
;             PG8_LDA(At, 0, 1); PG8_STAGE(PG8_SB(0, 0), b2, voffB); PG8_STAGE(PG8_SB(0, 1), b2 + hstepB, voffB); PG8_STAGE(PG8_SA(0, 0), a2, voffA);
;             PG8_WAIT_V(8); PG8_WAIT_L(0); PG8_BAR; PG8_MMA(1, 0, At, B0); PG8_MMA(1, 1, At, B1); PG8_BAR; PG8_SCHED;
;             PG8_LDB(B0, 1, 0); PG8_LDB(B1, 1, 1); PG8_SCHED; PG8_LDA(At, 1, 0); PG8_STAGE(PG8_SA(0, 1), a2 + hstepA, voffA);
;             PG8_WAIT_V(8); PG8_WAIT_L(0); PG8_BAR; PG8_MMA(0, 0, At, B0); PG8_MMA(0, 1, At, B1); PG8_BAR; PG8_SCHED;
;             PG8_LDA(At, 1, 1); PG8_STAGE(PG8_SB(1, 0), b3, voffB); PG8_STAGE(PG8_SB(1, 1), b3 + hstepB, voffB); PG8_STAGE(PG8_SA(1, 0), a3, voffA);
;             PG8_WAIT_V(8); PG8_WAIT_L(0); PG8_BAR; PG8_MMA(1, 0, At, B0); PG8_MMA(1, 1, At, B1); PG8_BAR; PG8_SCHED;
	s_setprio 1
	v_mfma_f32_16x16x32_bf16 v[62:65], v[130:133], v[162:165], v[62:65]
	v_mfma_f32_16x16x32_bf16 v[58:61], v[138:141], v[162:165], v[58:61]
	v_mfma_f32_16x16x32_bf16 v[54:57], v[130:133], v[170:173], v[54:57]
	v_mfma_f32_16x16x32_bf16 v[50:53], v[138:141], v[170:173], v[50:53]
	v_mfma_f32_16x16x32_bf16 v[46:49], v[130:133], v[178:181], v[46:49]
	v_mfma_f32_16x16x32_bf16 v[42:45], v[138:141], v[178:181], v[42:45]
	v_mfma_f32_16x16x32_bf16 v[38:41], v[130:133], v[186:189], v[38:41]
	v_mfma_f32_16x16x32_bf16 v[34:37], v[138:141], v[186:189], v[34:37]
	v_mfma_f32_16x16x32_bf16 v[62:65], v[134:137], v[166:169], v[62:65]
	v_mfma_f32_16x16x32_bf16 v[58:61], v[142:145], v[166:169], v[58:61]
	v_mfma_f32_16x16x32_bf16 v[54:57], v[134:137], v[174:177], v[54:57]
	v_mfma_f32_16x16x32_bf16 v[50:53], v[142:145], v[174:177], v[50:53]
	v_mfma_f32_16x16x32_bf16 v[46:49], v[134:137], v[182:185], v[46:49]
	v_mfma_f32_16x16x32_bf16 v[42:45], v[142:145], v[182:185], v[42:45]
	v_mfma_f32_16x16x32_bf16 v[38:41], v[134:137], v[190:193], v[38:41]
	v_mfma_f32_16x16x32_bf16 v[34:37], v[142:145], v[190:193], v[34:37]
	s_setprio 0
	s_setprio 1
	v_mfma_f32_16x16x32_bf16 v[30:33], v[146:149], v[162:165], v[30:33]
	v_mfma_f32_16x16x32_bf16 v[26:29], v[154:157], v[162:165], v[26:29]
	v_mfma_f32_16x16x32_bf16 v[22:25], v[146:149], v[170:173], v[22:25]
	v_mfma_f32_16x16x32_bf16 v[18:21], v[154:157], v[170:173], v[18:21]
	v_mfma_f32_16x16x32_bf16 v[14:17], v[146:149], v[178:181], v[14:17]
	v_mfma_f32_16x16x32_bf16 v[10:13], v[154:157], v[178:181], v[10:13]
	v_mfma_f32_16x16x32_bf16 v[6:9], v[146:149], v[186:189], v[6:9]
	v_mfma_f32_16x16x32_bf16 v[2:5], v[154:157], v[186:189], v[2:5]
	v_mfma_f32_16x16x32_bf16 v[30:33], v[150:153], v[166:169], v[30:33]
	v_mfma_f32_16x16x32_bf16 v[26:29], v[158:161], v[166:169], v[26:29]
	v_mfma_f32_16x16x32_bf16 v[22:25], v[150:153], v[174:177], v[22:25]
	v_mfma_f32_16x16x32_bf16 v[18:21], v[158:161], v[174:177], v[18:21]
	v_mfma_f32_16x16x32_bf16 v[14:17], v[150:153], v[182:185], v[14:17]
	v_mfma_f32_16x16x32_bf16 v[10:13], v[158:161], v[182:185], v[10:13]
	v_mfma_f32_16x16x32_bf16 v[6:9], v[150:153], v[190:193], v[6:9]
	v_mfma_f32_16x16x32_bf16 v[2:5], v[158:161], v[190:193], v[2:5]
	s_setprio 0
	s_barrier
	s_add_i32 s11, 0, 0x18000
	s_add_i32 s14, 0, 0x1c000
	v_add_u32_e32 v142, s11, v239
	v_add_u32_e32 v158, s14, v239
	ds_read_b128 v[130:133], v142
	ds_read_b128 v[134:137], v142 offset:1024
	ds_read_b128 v[138:141], v142 offset:2048
	ds_read_b128 v[142:145], v142 offset:3072
	ds_read_b128 v[146:149], v158
	ds_read_b128 v[150:153], v158 offset:1024
	ds_read_b128 v[154:157], v158 offset:2048
	ds_read_b128 v[158:161], v158 offset:3072
	s_add_u32 s12, s48, 0x1e0000
	s_addc_u32 s13, s49, 0
	s_mov_b32 m0, s56
	v_lshl_add_u64 v[222:223], s[12:13], 0, v[208:209]
	ds_read_b128 v[162:165], v241 offset:32768
	ds_read_b128 v[166:169], v241 offset:33792
	ds_read_b128 v[170:173], v241 offset:34816
	ds_read_b128 v[174:177], v241 offset:35840
	ds_read_b128 v[178:181], v241 offset:36864
	ds_read_b128 v[182:185], v241 offset:37888
	ds_read_b128 v[186:189], v241 offset:38912
	ds_read_b128 v[190:193], v241 offset:39936
	global_load_lds_dwordx4 v[222:223], off
	v_lshl_add_u64 v[222:223], s[12:13], 0, v[206:207]
	s_mov_b32 m0, s57
	s_nop 0
	global_load_lds_dwordx4 v[222:223], off
	s_waitcnt vmcnt(8)
	s_waitcnt lgkmcnt(0)
	s_barrier
	s_setprio 1
	v_mfma_f32_16x16x32_bf16 v[126:129], v[130:133], v[162:165], v[126:129]
	v_mfma_f32_16x16x32_bf16 v[122:125], v[138:141], v[162:165], v[122:125]
	v_mfma_f32_16x16x32_bf16 v[118:121], v[130:133], v[170:173], v[118:121]
	v_mfma_f32_16x16x32_bf16 v[114:117], v[138:141], v[170:173], v[114:117]
	v_mfma_f32_16x16x32_bf16 v[110:113], v[130:133], v[178:181], v[110:113]
	v_mfma_f32_16x16x32_bf16 v[106:109], v[138:141], v[178:181], v[106:109]
	v_mfma_f32_16x16x32_bf16 v[102:105], v[130:133], v[186:189], v[102:105]
	v_mfma_f32_16x16x32_bf16 v[98:101], v[138:141], v[186:189], v[98:101]
	v_mfma_f32_16x16x32_bf16 v[126:129], v[134:137], v[166:169], v[126:129]
	v_mfma_f32_16x16x32_bf16 v[122:125], v[142:145], v[166:169], v[122:125]
	v_mfma_f32_16x16x32_bf16 v[118:121], v[134:137], v[174:177], v[118:121]
	v_mfma_f32_16x16x32_bf16 v[114:117], v[142:145], v[174:177], v[114:117]
	v_mfma_f32_16x16x32_bf16 v[110:113], v[134:137], v[182:185], v[110:113]
	v_mfma_f32_16x16x32_bf16 v[106:109], v[142:145], v[182:185], v[106:109]
	v_mfma_f32_16x16x32_bf16 v[102:105], v[134:137], v[190:193], v[102:105]
	v_mfma_f32_16x16x32_bf16 v[98:101], v[142:145], v[190:193], v[98:101]
	s_setprio 0
	s_setprio 1
	v_mfma_f32_16x16x32_bf16 v[94:97], v[146:149], v[162:165], v[94:97]
	v_mfma_f32_16x16x32_bf16 v[90:93], v[154:157], v[162:165], v[90:93]
	v_mfma_f32_16x16x32_bf16 v[86:89], v[146:149], v[170:173], v[86:89]
	v_mfma_f32_16x16x32_bf16 v[82:85], v[154:157], v[170:173], v[82:85]
	v_mfma_f32_16x16x32_bf16 v[78:81], v[146:149], v[178:181], v[78:81]
	v_mfma_f32_16x16x32_bf16 v[74:77], v[154:157], v[178:181], v[74:77]
	v_mfma_f32_16x16x32_bf16 v[70:73], v[146:149], v[186:189], v[70:73]
	v_mfma_f32_16x16x32_bf16 v[66:69], v[154:157], v[186:189], v[66:69]
	v_mfma_f32_16x16x32_bf16 v[94:97], v[150:153], v[166:169], v[94:97]
	v_mfma_f32_16x16x32_bf16 v[90:93], v[158:161], v[166:169], v[90:93]
	v_mfma_f32_16x16x32_bf16 v[86:89], v[150:153], v[174:177], v[86:89]
	v_mfma_f32_16x16x32_bf16 v[82:85], v[158:161], v[174:177], v[82:85]
	v_mfma_f32_16x16x32_bf16 v[78:81], v[150:153], v[182:185], v[78:81]
	v_mfma_f32_16x16x32_bf16 v[74:77], v[158:161], v[182:185], v[74:77]
	v_mfma_f32_16x16x32_bf16 v[70:73], v[150:153], v[190:193], v[70:73]
	v_mfma_f32_16x16x32_bf16 v[66:69], v[158:161], v[190:193], v[66:69]
	s_setprio 0
	s_barrier
; #define PG8_STAGE(bufoff, gbase, voff) do { _Pragma("unroll") for (int _i = 0; _i < 2; ++_i) \
;         __builtin_amdgcn_global_load_lds((const unsigned*)((const char*)(gbase) + (voff)[_i]), (LAS unsigned*)(lds + (bufoff) + ldsw + _i * 8192), 16, 0, 0); } while (0)
; #define PG8_LDA(dst, b, h) do { _Pragma("unroll") for (int m = 0; m < 4; ++m) _Pragma("unroll") for (int k = 0; k < 2; ++k) dst[m][k] = *(const LAS bf16x8*)(lds + PG8_SA(b, h) + aoff + m * 2048 + k * 1024); } while (0)
; #define PG8_MMA(ai, bj, At, Bt) do { __builtin_amdgcn_s_setprio(1); _Pragma("unroll") for (int m = 0; m < 4; ++m) _Pragma("unroll") for (int n = 0; n < 2; ++n) _Pragma("unroll") for (int k = 0; k < 2; ++k) \
;         acc[ai][bj][m][n] = __builtin_amdgcn_mfma_f32_16x16x32_bf16(Bt[n][k], At[m][k], acc[ai][bj][m][n], 0, 0, 0); __builtin_amdgcn_s_setprio(0); } while (0)
; #define PG8_WAIT_V(n) asm volatile("s_waitcnt vmcnt(" #n ")" ::: "memory")
; #define PG8_WAIT_L(n) asm volatile("s_waitcnt lgkmcnt(" #n ")" ::: "memory")
; #define PG8_BAR __builtin_amdgcn_s_barrier()
; #define PG8_SCHED __builtin_amdgcn_sched_barrier(0)
; template <class Epi>
; __device__ __forceinline__ void gemm_phase(LAS unsigned char* lds, const Gemm g, const Order& S, const Epi& E) {
;     ...
;             PG8_LDA(At, 1, 1); PG8_STAGE(PG8_SB(1, 0), b3, voffB); PG8_STAGE(PG8_SB(1, 1), b3 + hstepB, voffB); PG8_STAGE(PG8_SA(1, 0), a3, voffA);
;             PG8_WAIT_V(8); PG8_WAIT_L(0); PG8_BAR; PG8_MMA(1, 0, At, B0); PG8_MMA(1, 1, At, B1); PG8_BAR; PG8_SCHED;
;         }
	s_add_i32 s11, s11, s20
	v_lshl_add_u64 v[214:215], v[214:215], 0, s[86:87]
	s_mov_b32 m0, s11
	ds_read_b128 v[162:165], v241 offset:49152
	ds_read_b128 v[166:169], v241 offset:50176
	ds_read_b128 v[170:173], v241 offset:51200
	ds_read_b128 v[174:177], v241 offset:52224
	ds_read_b128 v[178:181], v241 offset:53248
	ds_read_b128 v[182:185], v241 offset:54272
	ds_read_b128 v[186:189], v241 offset:55296
	ds_read_b128 v[190:193], v241 offset:56320
	global_load_lds_dwordx4 v[214:215], off
	s_add_i32 m0, s11, 0x2000
	s_add_u32 s12, s38, 0x20080
	v_lshl_add_u64 v[214:215], v[216:217], 0, s[86:87]
	s_addc_u32 s13, s39, 0
	s_add_i32 s11, s14, s20
	global_load_lds_dwordx4 v[214:215], off
	v_lshl_add_u64 v[214:215], s[12:13], 0, v[194:195]
	s_mov_b32 m0, s11
	s_nop 0
	global_load_lds_dwordx4 v[214:215], off
	v_lshl_add_u64 v[214:215], s[12:13], 0, v[204:205]
	s_add_i32 m0, s11, 0x2000
	s_nop 0
	global_load_lds_dwordx4 v[214:215], off
	v_lshl_add_u64 v[214:215], v[218:219], 0, s[86:87]
	s_mov_b32 m0, s58
	s_nop 0
	global_load_lds_dwordx4 v[214:215], off
	v_lshl_add_u64 v[214:215], v[220:221], 0, s[86:87]
	s_mov_b32 m0, s59
	s_nop 0
	global_load_lds_dwordx4 v[214:215], off
	s_waitcnt vmcnt(8)
	s_waitcnt lgkmcnt(0)
	s_barrier
	s_setprio 1
	v_mfma_f32_16x16x32_bf16 v[62:65], v[130:133], v[162:165], v[62:65]
	v_mfma_f32_16x16x32_bf16 v[58:61], v[138:141], v[162:165], v[58:61]
	v_mfma_f32_16x16x32_bf16 v[54:57], v[130:133], v[170:173], v[54:57]
	v_mfma_f32_16x16x32_bf16 v[50:53], v[138:141], v[170:173], v[50:53]
	v_mfma_f32_16x16x32_bf16 v[46:49], v[130:133], v[178:181], v[46:49]
	v_mfma_f32_16x16x32_bf16 v[42:45], v[138:141], v[178:181], v[42:45]
	v_mfma_f32_16x16x32_bf16 v[38:41], v[130:133], v[186:189], v[38:41]
	v_mfma_f32_16x16x32_bf16 v[34:37], v[138:141], v[186:189], v[34:37]
	v_mfma_f32_16x16x32_bf16 v[62:65], v[134:137], v[166:169], v[62:65]
	v_mfma_f32_16x16x32_bf16 v[58:61], v[142:145], v[166:169], v[58:61]
	v_mfma_f32_16x16x32_bf16 v[54:57], v[134:137], v[174:177], v[54:57]
	v_mfma_f32_16x16x32_bf16 v[50:53], v[142:145], v[174:177], v[50:53]
	v_mfma_f32_16x16x32_bf16 v[46:49], v[134:137], v[182:185], v[46:49]
	v_mfma_f32_16x16x32_bf16 v[42:45], v[142:145], v[182:185], v[42:45]
	v_mfma_f32_16x16x32_bf16 v[38:41], v[134:137], v[190:193], v[38:41]
	v_mfma_f32_16x16x32_bf16 v[34:37], v[142:145], v[190:193], v[34:37]
	s_setprio 0
	s_setprio 1
	v_mfma_f32_16x16x32_bf16 v[30:33], v[146:149], v[162:165], v[30:33]
	v_mfma_f32_16x16x32_bf16 v[26:29], v[154:157], v[162:165], v[26:29]
	v_mfma_f32_16x16x32_bf16 v[22:25], v[146:149], v[170:173], v[22:25]
	v_mfma_f32_16x16x32_bf16 v[18:21], v[154:157], v[170:173], v[18:21]
	v_mfma_f32_16x16x32_bf16 v[14:17], v[146:149], v[178:181], v[14:17]
	v_mfma_f32_16x16x32_bf16 v[10:13], v[154:157], v[178:181], v[10:13]
	v_mfma_f32_16x16x32_bf16 v[6:9], v[146:149], v[186:189], v[6:9]
	v_mfma_f32_16x16x32_bf16 v[2:5], v[154:157], v[186:189], v[2:5]
	v_mfma_f32_16x16x32_bf16 v[30:33], v[150:153], v[166:169], v[30:33]
	v_mfma_f32_16x16x32_bf16 v[26:29], v[158:161], v[166:169], v[26:29]
	v_mfma_f32_16x16x32_bf16 v[22:25], v[150:153], v[174:177], v[22:25]
	v_mfma_f32_16x16x32_bf16 v[18:21], v[158:161], v[174:177], v[18:21]
	v_mfma_f32_16x16x32_bf16 v[14:17], v[150:153], v[182:185], v[14:17]
	v_mfma_f32_16x16x32_bf16 v[10:13], v[158:161], v[182:185], v[10:13]
	v_mfma_f32_16x16x32_bf16 v[6:9], v[150:153], v[190:193], v[6:9]
	v_mfma_f32_16x16x32_bf16 v[2:5], v[158:161], v[190:193], v[2:5]
	s_setprio 0
	s_barrier
	s_add_i32 s10, s10, 2
	s_add_u32 s8, s8, 0x100
	s_addc_u32 s9, s9, 0
	s_cmp_gt_u32 s10, 5
	s_mov_b64 s[30:31], s[0:1]
	s_cbranch_scc0 .LBB0_262
	s_and_b64 vcc, exec, s[42:43]
	s_cbranch_vccz .LBB0_265
	s_barrier

; #define LAS __attribute__((address_space(3)))
; __device__ __forceinline__ float bf2f(unsigned short b) { return __uint_as_float(((unsigned)b) << 16); }
; __device__ __forceinline__ unsigned short f2bf(float f) { return (unsigned short)(cvt_pk_bf16(f, 0.f) & 0xffffu); }
; __device__ void gla_C(const Params& P, int l, int item, LAS unsigned char* lds) {
;     ...
;     __syncthreads();
; #pragma unroll
;     for (int rt = 0; rt < 16; ++rt)
; #pragma unroll
;         for (int jj = 0; jj < 4; ++jj) { const int t = rt * 16 + 4 * g + jj; float tot = 0.f;
; #pragma unroll
;             for (int ww = 0; ww < 8; ++ww) tot += SSQ[ww * 256 + t];
;             const float rs = rsqrtf(tot * (1.0f / 128.0f) + EPS);
;             const float gt = bf2f(*(const LAS unsigned short*)(GTL + t * 264 + (16 * w + c) * 2));
;             *(LAS unsigned short*)(OT + t * 272 + (16 * w + c) * 2) = f2bf(O[rt][jj] * rs * ng * (gt * __builtin_amdgcn_rcpf(1.0f + __expf(-gt)))); }
.LBB0_372:
	s_or_b64 exec, exec, s[0:1]
	v_lshl_add_u32 v66, v102, 2, 0
	s_waitcnt lgkmcnt(0)
	s_barrier
	v_and_b32_e32 v116, 0xff, v0
	v_lshlrev_b32_e32 v116, 2, v116
	ds_read2st64_b32 v[118:119], v116 offset1:4
	ds_read2st64_b32 v[120:121], v116 offset0:8 offset1:12
	ds_read2st64_b32 v[122:123], v116 offset0:16 offset1:20
	ds_read2st64_b32 v[124:125], v116 offset0:24 offset1:28
	v_add_u32_e32 v132, 0x23800, v66
	v_add_u32_e32 v116, 0x23800, v116
	s_waitcnt lgkmcnt(3)
	v_add_f32_e32 v117, 0, v118
	v_add_f32_e32 v117, v117, v119
	s_waitcnt lgkmcnt(2)
	v_add_f32_e32 v117, v117, v120
	v_add_f32_e32 v117, v117, v121
	s_waitcnt lgkmcnt(1)
	v_add_f32_e32 v117, v117, v122
	v_add_f32_e32 v117, v117, v123
	s_waitcnt lgkmcnt(0)
	v_add_f32_e32 v117, v117, v124
	v_add_f32_e32 v117, v117, v125
	v_fmamk_f32 v117, v117, 0x3c000000, v1
	v_cmp_gt_f32_e32 vcc, s33, v117
	v_mul_f32_e32 v118, 0x4b800000, v117
	s_nop 0
	v_cndmask_b32_e32 v117, v117, v118, vcc
	v_rsq_f32_e32 v117, v117
	s_nop 0
	v_mul_f32_e32 v118, 0x45800000, v117
	v_cndmask_b32_e32 v117, v117, v118, vcc
	ds_write_b32 v116, v117
	s_waitcnt lgkmcnt(0)
	s_barrier
	ds_read_b32 v243, v132 offset:0
	ds_read_b32 v242, v132 offset:4
	ds_read_b32 v241, v132 offset:8
	v_readlane_b32 s0, v255, 12
	v_lshlrev_b32_e32 v194, 4, v97
	v_add_u32_e32 v74, s0, v100
	s_movk_i32 s0, 0x420
	v_mad_u32_u24 v68, v157, s0, v74
	ds_read_u16 v240, v68
	s_waitcnt lgkmcnt(0)
	v_lshlrev_b32_e32 v68, 16, v240
	s_lshl_b32 s20, s31, 1
	v_mul_f32_e32 v69, 0xbfb8aa3b, v68
	v_exp_f32_e32 v69, v69
	ds_read_b32 v240, v132 offset:12
	s_add_i32 s45, s45, s94
	s_add_i32 s44, s44, s79
	v_add_f32_e32 v69, 1.0, v69
	v_rcp_f32_e32 v69, v69
	v_mul_f32_e32 v62, v62, v243
	v_mul_f32_e32 v62, v99, v62
	v_mul_f32_e32 v67, v69, v68
	v_mul_f32_e32 v62, v67, v62
	v_add_u32_e32 v67, 4, v66
	v_cvt_pk_bf16_f32 v62, v62, v195
	v_mul_u32_u24_e32 v70, 0x440, v157
	v_add_u32_e32 v70, v95, v70
	ds_write_b16 v70, v62 offset:8192
	v_mad_u32_u24 v62, v96, s9, v74
	ds_read_u16 v243, v62
	ds_read_u16 v239, v62 offset:264
	ds_read_u16 v238, v62 offset:528
	ds_read_u16 v237, v62 offset:3960
	s_cmpk_gt_i32 s45, 0xff
	s_waitcnt lgkmcnt(3)
	v_lshlrev_b32_e32 v69, 16, v243
	v_mul_f32_e32 v70, 0xbfb8aa3b, v69
	v_exp_f32_e32 v70, v70
	ds_read_b32 v243, v132 offset:64
	v_add_f32_e32 v70, 1.0, v70
	v_rcp_f32_e32 v70, v70
	v_mul_f32_e32 v63, v63, v242
	v_mul_f32_e32 v63, v99, v63
	v_mul_f32_e32 v68, v70, v69
	v_mul_f32_e32 v63, v68, v63
	v_cvt_pk_bf16_f32 v69, v63, v195
	v_add_u32_e32 v63, 8, v66
	v_mul_u32_u24_e32 v68, 0x110, v96
	v_add_u32_e32 v68, v95, v68
	ds_write_b16 v68, v69 offset:8192
	ds_read_u16 v242, v62 offset:4224
	s_waitcnt lgkmcnt(1)
	v_lshlrev_b32_e32 v70, 16, v239
	v_mul_f32_e32 v71, 0xbfb8aa3b, v70
	v_exp_f32_e32 v71, v71
	ds_read_b32 v239, v132 offset:68
	v_add_f32_e32 v71, 1.0, v71
	v_rcp_f32_e32 v71, v71
	v_mul_f32_e32 v64, v64, v241
	v_mul_f32_e32 v64, v99, v64
	v_mul_f32_e32 v69, v71, v70
	v_mul_f32_e32 v64, v69, v64
	v_cvt_pk_bf16_f32 v69, v64, v195
	v_add_u32_e32 v64, 12, v66
	ds_write_b16 v68, v69 offset:8464
	ds_read_u16 v241, v62 offset:4488
	s_waitcnt lgkmcnt(1)
	v_lshlrev_b32_e32 v70, 16, v238
	v_mul_f32_e32 v71, 0xbfb8aa3b, v70
	v_exp_f32_e32 v71, v71
	ds_read_b32 v238, v132 offset:72
	v_add_f32_e32 v71, 1.0, v71
	v_rcp_f32_e32 v71, v71
	v_mul_f32_e32 v65, v65, v240
	v_mul_f32_e32 v65, v99, v65
	v_mul_f32_e32 v69, v71, v70
	v_mul_f32_e32 v65, v69, v65
	v_cvt_pk_bf16_f32 v69, v65, v195
	v_add_u32_e32 v65, 64, v66
	ds_write_b16 v68, v69 offset:8736
	ds_read_u16 v240, v62 offset:4752
	s_waitcnt lgkmcnt(1)
	v_lshlrev_b32_e32 v70, 16, v237
	v_mul_f32_e32 v71, 0xbfb8aa3b, v70
	v_exp_f32_e32 v71, v71
	ds_read_b32 v237, v132 offset:76
	v_add_f32_e32 v71, 1.0, v71
	v_rcp_f32_e32 v71, v71
	v_mul_f32_e32 v58, v58, v243
	v_mul_f32_e32 v58, v99, v58
	v_mul_f32_e32 v69, v71, v70
	v_mul_f32_e32 v58, v69, v58
	v_cvt_pk_bf16_f32 v69, v58, v195
	v_add_u32_e32 v58, 0x44, v66
	ds_write_b16 v68, v69 offset:12272
	ds_read_u16 v243, v62 offset:8184
	s_waitcnt lgkmcnt(1)
	v_lshlrev_b32_e32 v70, 16, v242
	v_mul_f32_e32 v71, 0xbfb8aa3b, v70
	v_exp_f32_e32 v71, v71
	ds_read_b32 v242, v132 offset:128
	v_add_f32_e32 v71, 1.0, v71
	v_rcp_f32_e32 v71, v71
	v_mul_f32_e32 v59, v59, v239
	v_mul_f32_e32 v59, v99, v59
	v_mul_f32_e32 v69, v71, v70
	v_mul_f32_e32 v59, v69, v59
	v_cvt_pk_bf16_f32 v69, v59, v195
	v_add_u32_e32 v59, 0x48, v66
	ds_write_b16 v68, v69 offset:12544
	ds_read_u16 v239, v62 offset:8448
	s_waitcnt lgkmcnt(1)
	v_lshlrev_b32_e32 v69, 16, v241
	v_mul_f32_e32 v70, 0xbfb8aa3b, v69
	v_exp_f32_e32 v70, v70
	ds_read_b32 v241, v132 offset:132
	v_add_f32_e32 v70, 1.0, v70
	v_rcp_f32_e32 v70, v70
	v_mul_f32_e32 v60, v60, v238
	v_mul_f32_e32 v60, v99, v60
	v_mul_f32_e32 v68, v70, v69
	v_mul_f32_e32 v60, v68, v60
	v_cvt_pk_bf16_f32 v70, v60, v195
	v_add_u32_e32 v60, 0x4c, v66
	ds_write_b16 v94, v70 offset:8192
	ds_read_u16 v238, v62 offset:8712
	s_waitcnt lgkmcnt(1)
	v_lshlrev_b32_e32 v69, 16, v240
	v_mul_f32_e32 v70, 0xbfb8aa3b, v69
	v_exp_f32_e32 v70, v70
	ds_read_b32 v240, v132 offset:136
	v_add_f32_e32 v70, 1.0, v70
	v_rcp_f32_e32 v70, v70
	v_mul_f32_e32 v61, v61, v237
	v_mul_f32_e32 v61, v99, v61
	v_mul_f32_e32 v68, v70, v69
	v_mul_f32_e32 v61, v68, v61
	v_cvt_pk_bf16_f32 v70, v61, v195
	v_add_u32_e32 v61, 0x80, v66
	ds_write_b16 v94, v70 offset:8464
	ds_read_u16 v237, v62 offset:8976
	s_waitcnt lgkmcnt(1)
	v_lshlrev_b32_e32 v69, 16, v243
	v_mul_f32_e32 v70, 0xbfb8aa3b, v69
	v_exp_f32_e32 v70, v70
	ds_read_b32 v243, v132 offset:140
	v_add_f32_e32 v70, 1.0, v70
	v_rcp_f32_e32 v70, v70
	v_mul_f32_e32 v54, v54, v242
	v_mul_f32_e32 v54, v99, v54
	v_mul_f32_e32 v68, v70, v69
	v_mul_f32_e32 v54, v68, v54
	v_add_u32_e32 v68, 0x84, v66
	v_cvt_pk_bf16_f32 v54, v54, v195
	ds_write_b16 v94, v54 offset:12000
	ds_read_u16 v242, v62 offset:12408
	s_waitcnt lgkmcnt(1)
; #define LAS __attribute__((address_space(3)))
; __device__ __forceinline__ float bf2f(unsigned short b) { return __uint_as_float(((unsigned)b) << 16); }
; __device__ __forceinline__ unsigned short f2bf(float f) { return (unsigned short)(cvt_pk_bf16(f, 0.f) & 0xffffu); }
; __device__ void gla_C(const Params& P, int l, int item, LAS unsigned char* lds) {
;     ...
;     for (int rt = 0; rt < 16; ++rt)
; #pragma unroll
;         for (int jj = 0; jj < 4; ++jj) { const int t = rt * 16 + 4 * g + jj; float tot = 0.f;
; #pragma unroll
;             for (int ww = 0; ww < 8; ++ww) tot += SSQ[ww * 256 + t];
;             const float rs = rsqrtf(tot * (1.0f / 128.0f) + EPS);
;             const float gt = bf2f(*(const LAS unsigned short*)(GTL + t * 264 + (16 * w + c) * 2));
;             *(LAS unsigned short*)(OT + t * 272 + (16 * w + c) * 2) = f2bf(O[rt][jj] * rs * ng * (gt * __builtin_amdgcn_rcpf(1.0f + __expf(-gt)))); }
	v_lshlrev_b32_e32 v69, 16, v239
	s_nop 0
	v_mul_f32_e32 v70, 0xbfb8aa3b, v69
	v_exp_f32_e32 v70, v70
	ds_read_b32 v239, v132 offset:192
	v_add_f32_e32 v70, 1.0, v70
	v_rcp_f32_e32 v70, v70
	v_mul_f32_e32 v54, v55, v241
	v_mul_f32_e32 v54, v99, v54
	v_mul_f32_e32 v55, v70, v69
	v_mul_f32_e32 v54, v55, v54
	v_add_u32_e32 v69, 0x88, v66
	v_cvt_pk_bf16_f32 v70, v54, v195
	ds_write_b16 v94, v70 offset:12272
	ds_read_u16 v241, v62 offset:12672
	s_waitcnt lgkmcnt(1)
	v_lshlrev_b32_e32 v55, 16, v238
	v_mul_f32_e32 v70, 0xbfb8aa3b, v55
	v_exp_f32_e32 v70, v70
	ds_read_b32 v238, v132 offset:196
	v_add_f32_e32 v70, 1.0, v70
	v_rcp_f32_e32 v70, v70
	v_mul_f32_e32 v54, v56, v240
	v_mul_f32_e32 v54, v99, v54
	v_mul_f32_e32 v55, v70, v55
	v_mul_f32_e32 v54, v55, v54
	v_add_u32_e32 v56, 0x8c, v66
	v_cvt_pk_bf16_f32 v70, v54, v195
	ds_write_b16 v94, v70 offset:12544
	ds_read_u16 v240, v62 offset:12936
	s_waitcnt lgkmcnt(1)
	v_lshlrev_b32_e32 v55, 16, v237
	v_mul_f32_e32 v70, 0xbfb8aa3b, v55
	v_exp_f32_e32 v70, v70
	ds_read_b32 v237, v132 offset:200
	v_add_f32_e32 v70, 1.0, v70
	v_rcp_f32_e32 v70, v70
	v_mul_f32_e32 v54, v57, v243
	v_mul_f32_e32 v54, v99, v54
	v_mul_f32_e32 v55, v70, v55
	v_mul_f32_e32 v54, v55, v54
	v_add_u32_e32 v55, 0xc0, v66
	v_cvt_pk_bf16_f32 v54, v54, v195
	ds_write_b16 v93, v54 offset:8192
	ds_read_u16 v243, v62 offset:13200
	s_waitcnt lgkmcnt(1)
	v_lshlrev_b32_e32 v57, 16, v242
	s_nop 0
	v_mul_f32_e32 v70, 0xbfb8aa3b, v57
	v_exp_f32_e32 v70, v70
	ds_read_b32 v242, v132 offset:204
	v_add_f32_e32 v70, 1.0, v70
	v_rcp_f32_e32 v70, v70
	v_mul_f32_e32 v50, v50, v239
	v_mul_f32_e32 v50, v99, v50
	v_mul_f32_e32 v54, v70, v57
	v_mul_f32_e32 v50, v54, v50
	v_add_u32_e32 v54, 0xc4, v66
	v_cvt_pk_bf16_f32 v50, v50, v195
	ds_write_b16 v93, v50 offset:11728
	ds_read_u16 v239, v62 offset:16632
	s_waitcnt lgkmcnt(1)
	v_lshlrev_b32_e32 v57, 16, v241
	s_nop 0
	v_mul_f32_e32 v70, 0xbfb8aa3b, v57
	v_exp_f32_e32 v70, v70
	ds_read_b32 v241, v132 offset:256
	v_add_f32_e32 v70, 1.0, v70
	v_rcp_f32_e32 v70, v70
	v_mul_f32_e32 v50, v51, v238
	v_mul_f32_e32 v50, v99, v50
	v_mul_f32_e32 v51, v70, v57
	v_mul_f32_e32 v50, v51, v50
	v_add_u32_e32 v51, 0xc8, v66
	v_cvt_pk_bf16_f32 v50, v50, v195
	ds_write_b16 v93, v50 offset:12000
	ds_read_u16 v238, v62 offset:16896
	s_waitcnt lgkmcnt(1)
	v_lshlrev_b32_e32 v57, 16, v240
	s_nop 0
	v_mul_f32_e32 v70, 0xbfb8aa3b, v57
	v_exp_f32_e32 v70, v70
	ds_read_b32 v240, v132 offset:260
	v_add_f32_e32 v70, 1.0, v70
	v_rcp_f32_e32 v70, v70
	v_mul_f32_e32 v50, v52, v237
	v_mul_f32_e32 v50, v99, v50
	v_mul_f32_e32 v52, v70, v57
	v_mul_f32_e32 v50, v52, v50
	v_cvt_pk_bf16_f32 v52, v50, v195
	v_add_u32_e32 v50, 0xcc, v66
	ds_write_b16 v93, v52 offset:12272
	ds_read_u16 v237, v62 offset:17160
	s_waitcnt lgkmcnt(1)
	v_lshlrev_b32_e32 v57, 16, v243
	s_nop 0
	v_mul_f32_e32 v70, 0xbfb8aa3b, v57
	v_exp_f32_e32 v70, v70
	ds_read_b32 v243, v132 offset:264
	v_add_f32_e32 v70, 1.0, v70
	v_rcp_f32_e32 v70, v70
	v_mul_f32_e32 v52, v53, v242
	v_mul_f32_e32 v52, v99, v52
	v_mul_f32_e32 v53, v70, v57
	v_mul_f32_e32 v52, v53, v52
	v_cvt_pk_bf16_f32 v57, v52, v195
	ds_write_b16 v93, v57 offset:12544
	ds_read_u16 v242, v62 offset:17424
	s_waitcnt lgkmcnt(1)
	v_lshlrev_b32_e32 v53, 16, v239
	v_mul_f32_e32 v57, 0xbfb8aa3b, v53
	v_exp_f32_e32 v57, v57
	ds_read_b32 v239, v132 offset:268
	v_add_f32_e32 v57, 1.0, v57
	v_rcp_f32_e32 v57, v57
	v_mul_f32_e32 v46, v46, v241
	v_mul_f32_e32 v46, v99, v46
	v_mul_f32_e32 v52, v57, v53
	v_mul_f32_e32 v46, v52, v46
	v_cvt_pk_bf16_f32 v46, v46, v195
	ds_write_b16 v92, v46 offset:8192
	ds_read_u16 v241, v62 offset:20856
	s_waitcnt lgkmcnt(1)
	v_lshlrev_b32_e32 v52, 16, v238
	v_mul_f32_e32 v53, 0xbfb8aa3b, v52
	v_exp_f32_e32 v53, v53
	ds_read_b32 v238, v132 offset:320
	v_add_f32_e32 v53, 1.0, v53
	v_rcp_f32_e32 v53, v53
	v_mul_f32_e32 v46, v47, v240
	v_mul_f32_e32 v46, v99, v46
	v_mul_f32_e32 v47, v53, v52
	v_mul_f32_e32 v46, v47, v46
	v_cvt_pk_bf16_f32 v52, v46, v195
	ds_write_b16 v92, v52 offset:8464
	ds_read_u16 v240, v62 offset:21120
	s_waitcnt lgkmcnt(1)
	v_lshlrev_b32_e32 v47, 16, v237
	v_mul_f32_e32 v52, 0xbfb8aa3b, v47
	v_exp_f32_e32 v52, v52
	ds_read_b32 v237, v132 offset:324
	v_add_f32_e32 v52, 1.0, v52
	v_rcp_f32_e32 v52, v52
	v_mul_f32_e32 v46, v48, v243
	v_mul_f32_e32 v46, v99, v46
	v_mul_f32_e32 v47, v52, v47
	v_mul_f32_e32 v46, v47, v46
	v_cvt_pk_bf16_f32 v48, v46, v195
	ds_write_b16 v92, v48 offset:8736
	ds_read_u16 v243, v62 offset:21384
	s_waitcnt lgkmcnt(1)
	v_lshlrev_b32_e32 v47, 16, v242
	v_mul_f32_e32 v48, 0xbfb8aa3b, v47
	v_exp_f32_e32 v48, v48
	ds_read_b32 v242, v132 offset:328
	v_add_f32_e32 v48, 1.0, v48
	v_rcp_f32_e32 v48, v48
	v_mul_f32_e32 v46, v49, v239
	v_mul_f32_e32 v46, v99, v46
	v_mul_f32_e32 v47, v48, v47
	v_mul_f32_e32 v46, v47, v46
	v_cvt_pk_bf16_f32 v48, v46, v195
	ds_write_b16 v92, v48 offset:9008
	ds_read_u16 v239, v62 offset:21648
	s_waitcnt lgkmcnt(1)
	v_lshlrev_b32_e32 v47, 16, v241
	v_mul_f32_e32 v48, 0xbfb8aa3b, v47
	v_exp_f32_e32 v48, v48
	ds_read_b32 v241, v132 offset:332
	v_add_f32_e32 v48, 1.0, v48
	v_rcp_f32_e32 v48, v48
	v_mul_f32_e32 v42, v42, v238
	v_mul_f32_e32 v42, v99, v42
	v_mul_f32_e32 v46, v48, v47
	v_mul_f32_e32 v42, v46, v42
	v_cvt_pk_bf16_f32 v42, v42, v195
	ds_write_b16 v92, v42 offset:12544
	ds_read_u16 v238, v62 offset:25080
	s_waitcnt lgkmcnt(1)
	v_lshlrev_b32_e32 v46, 16, v240
	v_mul_f32_e32 v47, 0xbfb8aa3b, v46
	v_exp_f32_e32 v47, v47
	ds_read_b32 v240, v132 offset:384
	v_add_f32_e32 v47, 1.0, v47
	v_rcp_f32_e32 v47, v47
	v_mul_f32_e32 v42, v43, v237
	v_mul_f32_e32 v42, v99, v42
	v_mul_f32_e32 v43, v47, v46
	v_mul_f32_e32 v42, v43, v42
	v_cvt_pk_bf16_f32 v46, v42, v195
	ds_write_b16 v91, v46 offset:8192
	ds_read_u16 v237, v62 offset:25344
	s_waitcnt lgkmcnt(1)
; #define LAS __attribute__((address_space(3)))
; __device__ __forceinline__ float bf2f(unsigned short b) { return __uint_as_float(((unsigned)b) << 16); }
; __device__ __forceinline__ unsigned short f2bf(float f) { return (unsigned short)(cvt_pk_bf16(f, 0.f) & 0xffffu); }
; __device__ void gla_C(const Params& P, int l, int item, LAS unsigned char* lds) {
;     ...
;     for (int rt = 0; rt < 16; ++rt)
; #pragma unroll
;         for (int jj = 0; jj < 4; ++jj) { const int t = rt * 16 + 4 * g + jj; float tot = 0.f;
; #pragma unroll
;             for (int ww = 0; ww < 8; ++ww) tot += SSQ[ww * 256 + t];
;             const float rs = rsqrtf(tot * (1.0f / 128.0f) + EPS);
;             const float gt = bf2f(*(const LAS unsigned short*)(GTL + t * 264 + (16 * w + c) * 2));
;             *(LAS unsigned short*)(OT + t * 272 + (16 * w + c) * 2) = f2bf(O[rt][jj] * rs * ng * (gt * __builtin_amdgcn_rcpf(1.0f + __expf(-gt)))); }
	v_lshlrev_b32_e32 v43, 16, v243
	v_mul_f32_e32 v46, 0xbfb8aa3b, v43
	v_exp_f32_e32 v46, v46
	ds_read_b32 v243, v132 offset:388
	v_add_f32_e32 v46, 1.0, v46
	v_rcp_f32_e32 v46, v46
	v_mul_f32_e32 v42, v44, v242
	v_mul_f32_e32 v42, v99, v42
	v_mul_f32_e32 v43, v46, v43
	v_mul_f32_e32 v42, v43, v42
	v_cvt_pk_bf16_f32 v44, v42, v195
	ds_write_b16 v91, v44 offset:8464
	ds_read_u16 v242, v62 offset:25608
	s_waitcnt lgkmcnt(1)
	v_lshlrev_b32_e32 v43, 16, v239
	v_mul_f32_e32 v44, 0xbfb8aa3b, v43
	v_exp_f32_e32 v44, v44
	ds_read_b32 v239, v132 offset:392
	v_add_f32_e32 v44, 1.0, v44
	v_rcp_f32_e32 v44, v44
	v_mul_f32_e32 v42, v45, v241
	v_mul_f32_e32 v42, v99, v42
	v_mul_f32_e32 v43, v44, v43
	v_mul_f32_e32 v42, v43, v42
	v_cvt_pk_bf16_f32 v44, v42, v195
	ds_write_b16 v91, v44 offset:8736
	ds_read_u16 v241, v62 offset:25872
	s_waitcnt lgkmcnt(1)
	v_lshlrev_b32_e32 v43, 16, v238
	v_mul_f32_e32 v44, 0xbfb8aa3b, v43
	v_exp_f32_e32 v44, v44
	ds_read_b32 v238, v132 offset:396
	v_add_f32_e32 v44, 1.0, v44
	v_rcp_f32_e32 v44, v44
	v_mul_f32_e32 v38, v38, v240
	v_mul_f32_e32 v38, v99, v38
	v_mul_f32_e32 v42, v44, v43
	v_mul_f32_e32 v38, v42, v38
	v_cvt_pk_bf16_f32 v38, v38, v195
	ds_write_b16 v91, v38 offset:12272
	ds_read_u16 v240, v62 offset:29304
	s_waitcnt lgkmcnt(1)
	v_lshlrev_b32_e32 v42, 16, v237
	v_mul_f32_e32 v43, 0xbfb8aa3b, v42
	v_exp_f32_e32 v43, v43
	ds_read_b32 v237, v132 offset:448
	v_add_f32_e32 v43, 1.0, v43
	v_rcp_f32_e32 v43, v43
	v_mul_f32_e32 v38, v39, v243
	v_mul_f32_e32 v38, v99, v38
	v_mul_f32_e32 v39, v43, v42
	v_mul_f32_e32 v38, v39, v38
	v_cvt_pk_bf16_f32 v42, v38, v195
	ds_write_b16 v91, v42 offset:12544
	ds_read_u16 v243, v62 offset:29568
	s_waitcnt lgkmcnt(1)
	v_lshlrev_b32_e32 v39, 16, v242
	v_mul_f32_e32 v42, 0xbfb8aa3b, v39
	v_exp_f32_e32 v42, v42
	ds_read_b32 v242, v132 offset:452
	v_add_f32_e32 v42, 1.0, v42
	v_rcp_f32_e32 v42, v42
	v_mul_f32_e32 v38, v40, v239
	v_mul_f32_e32 v38, v99, v38
	v_mul_f32_e32 v39, v42, v39
	v_mul_f32_e32 v38, v39, v38
	v_cvt_pk_bf16_f32 v40, v38, v195
	ds_write_b16 v90, v40 offset:8192
	ds_read_u16 v239, v62 offset:29832
	s_waitcnt lgkmcnt(1)
	v_lshlrev_b32_e32 v39, 16, v241
	v_mul_f32_e32 v40, 0xbfb8aa3b, v39
	v_exp_f32_e32 v40, v40
	ds_read_b32 v241, v132 offset:456
	v_add_f32_e32 v40, 1.0, v40
	v_rcp_f32_e32 v40, v40
	v_mul_f32_e32 v38, v41, v238
	v_mul_f32_e32 v38, v99, v38
	v_mul_f32_e32 v39, v40, v39
	v_mul_f32_e32 v38, v39, v38
	v_cvt_pk_bf16_f32 v40, v38, v195
	ds_write_b16 v90, v40 offset:8464
	ds_read_u16 v238, v62 offset:30096
	s_waitcnt lgkmcnt(1)
	v_lshlrev_b32_e32 v39, 16, v240
	v_mul_f32_e32 v40, 0xbfb8aa3b, v39
	v_exp_f32_e32 v40, v40
	ds_read_b32 v240, v132 offset:460
	v_add_f32_e32 v40, 1.0, v40
	v_rcp_f32_e32 v40, v40
	v_mul_f32_e32 v34, v34, v237
	v_mul_f32_e32 v34, v99, v34
	v_mul_f32_e32 v38, v40, v39
	v_mul_f32_e32 v34, v38, v34
	v_cvt_pk_bf16_f32 v34, v34, v195
	ds_write_b16 v90, v34 offset:12000
	ds_read_u16 v237, v62 offset:33528
	s_waitcnt lgkmcnt(1)
	v_lshlrev_b32_e32 v38, 16, v243
	v_mul_f32_e32 v39, 0xbfb8aa3b, v38
	v_exp_f32_e32 v39, v39
	ds_read_b32 v243, v132 offset:512
	v_add_f32_e32 v39, 1.0, v39
	v_rcp_f32_e32 v39, v39
	v_mul_f32_e32 v34, v35, v242
	v_mul_f32_e32 v34, v99, v34
	v_mul_f32_e32 v35, v39, v38
	v_mul_f32_e32 v34, v35, v34
	v_cvt_pk_bf16_f32 v38, v34, v195
	ds_write_b16 v90, v38 offset:12272
	ds_read_u16 v242, v62 offset:33792
	s_waitcnt lgkmcnt(1)
	v_lshlrev_b32_e32 v35, 16, v239
	v_mul_f32_e32 v38, 0xbfb8aa3b, v35
	v_exp_f32_e32 v38, v38
	ds_read_b32 v239, v132 offset:516
	v_add_f32_e32 v38, 1.0, v38
	v_rcp_f32_e32 v38, v38
	v_mul_f32_e32 v34, v36, v241
	v_mul_f32_e32 v34, v99, v34
	v_mul_f32_e32 v35, v38, v35
	v_mul_f32_e32 v34, v35, v34
	v_cvt_pk_bf16_f32 v36, v34, v195
	ds_write_b16 v90, v36 offset:12544
	ds_read_u16 v241, v62 offset:34056
	s_waitcnt lgkmcnt(1)
	v_lshlrev_b32_e32 v35, 16, v238
	v_mul_f32_e32 v36, 0xbfb8aa3b, v35
	v_exp_f32_e32 v36, v36
	ds_read_b32 v238, v132 offset:520
	v_add_f32_e32 v36, 1.0, v36
	v_rcp_f32_e32 v36, v36
	v_mul_f32_e32 v34, v37, v240
	v_mul_f32_e32 v34, v99, v34
	v_mul_f32_e32 v35, v36, v35
	v_mul_f32_e32 v34, v35, v34
	v_cvt_pk_bf16_f32 v36, v34, v195
	ds_write_b16 v89, v36 offset:8192
	ds_read_u16 v240, v62 offset:34320
	s_waitcnt lgkmcnt(1)
	v_lshlrev_b32_e32 v35, 16, v237
	v_mul_f32_e32 v36, 0xbfb8aa3b, v35
	v_exp_f32_e32 v36, v36
	ds_read_b32 v237, v132 offset:524
	v_add_f32_e32 v36, 1.0, v36
	v_rcp_f32_e32 v36, v36
	v_mul_f32_e32 v30, v30, v243
	v_mul_f32_e32 v30, v99, v30
	v_mul_f32_e32 v34, v36, v35
	v_mul_f32_e32 v30, v34, v30
	v_cvt_pk_bf16_f32 v30, v30, v195
	ds_write_b16 v89, v30 offset:11728
	ds_read_u16 v243, v62 offset:37752
	s_waitcnt lgkmcnt(1)
	v_lshlrev_b32_e32 v34, 16, v242
	v_mul_f32_e32 v35, 0xbfb8aa3b, v34
	v_exp_f32_e32 v35, v35
	ds_read_b32 v242, v132 offset:576
	v_add_f32_e32 v35, 1.0, v35
	v_rcp_f32_e32 v35, v35
	v_mul_f32_e32 v30, v31, v239
	v_mul_f32_e32 v30, v99, v30
	v_mul_f32_e32 v31, v35, v34
	v_mul_f32_e32 v30, v31, v30
	v_cvt_pk_bf16_f32 v34, v30, v195
	ds_write_b16 v89, v34 offset:12000
	ds_read_u16 v239, v62 offset:38016
	s_waitcnt lgkmcnt(1)
	v_lshlrev_b32_e32 v31, 16, v241
	v_mul_f32_e32 v34, 0xbfb8aa3b, v31
	v_exp_f32_e32 v34, v34
	ds_read_b32 v241, v132 offset:580
	v_add_f32_e32 v34, 1.0, v34
	v_rcp_f32_e32 v34, v34
	v_mul_f32_e32 v30, v32, v238
	v_mul_f32_e32 v30, v99, v30
	v_mul_f32_e32 v31, v34, v31
	v_mul_f32_e32 v30, v31, v30
	v_cvt_pk_bf16_f32 v32, v30, v195
	ds_write_b16 v89, v32 offset:12272
	ds_read_u16 v238, v62 offset:38280
	s_waitcnt lgkmcnt(1)
; #define LAS __attribute__((address_space(3)))
; __device__ __forceinline__ float bf2f(unsigned short b) { return __uint_as_float(((unsigned)b) << 16); }
; __device__ __forceinline__ unsigned short f2bf(float f) { return (unsigned short)(cvt_pk_bf16(f, 0.f) & 0xffffu); }
; __device__ void gla_C(const Params& P, int l, int item, LAS unsigned char* lds) {
;     ...
;     for (int rt = 0; rt < 16; ++rt)
; #pragma unroll
;         for (int jj = 0; jj < 4; ++jj) { const int t = rt * 16 + 4 * g + jj; float tot = 0.f;
; #pragma unroll
;             for (int ww = 0; ww < 8; ++ww) tot += SSQ[ww * 256 + t];
;             const float rs = rsqrtf(tot * (1.0f / 128.0f) + EPS);
;             const float gt = bf2f(*(const LAS unsigned short*)(GTL + t * 264 + (16 * w + c) * 2));
;             *(LAS unsigned short*)(OT + t * 272 + (16 * w + c) * 2) = f2bf(O[rt][jj] * rs * ng * (gt * __builtin_amdgcn_rcpf(1.0f + __expf(-gt)))); }
	v_lshlrev_b32_e32 v31, 16, v240
	v_mul_f32_e32 v32, 0xbfb8aa3b, v31
	v_exp_f32_e32 v32, v32
	ds_read_b32 v240, v132 offset:584
	v_add_f32_e32 v32, 1.0, v32
	v_rcp_f32_e32 v32, v32
	v_mul_f32_e32 v30, v33, v237
	v_mul_f32_e32 v30, v99, v30
	v_mul_f32_e32 v31, v32, v31
	v_mul_f32_e32 v30, v31, v30
	v_cvt_pk_bf16_f32 v32, v30, v195
	ds_write_b16 v89, v32 offset:12544
	ds_read_u16 v237, v62 offset:38544
	s_waitcnt lgkmcnt(1)
	v_lshlrev_b32_e32 v31, 16, v243
	v_mul_f32_e32 v32, 0xbfb8aa3b, v31
	v_exp_f32_e32 v32, v32
	ds_read_b32 v243, v132 offset:588
	v_add_f32_e32 v32, 1.0, v32
	v_rcp_f32_e32 v32, v32
	v_mul_f32_e32 v26, v26, v242
	v_mul_f32_e32 v26, v99, v26
	v_mul_f32_e32 v30, v32, v31
	v_mul_f32_e32 v26, v30, v26
	v_cvt_pk_bf16_f32 v26, v26, v195
	ds_write_b16 v88, v26 offset:8192
	ds_read_u16 v242, v62 offset:41976
	s_waitcnt lgkmcnt(1)
	v_lshlrev_b32_e32 v30, 16, v239
	v_mul_f32_e32 v31, 0xbfb8aa3b, v30
	v_exp_f32_e32 v31, v31
	ds_read_b32 v239, v132 offset:640
	v_add_f32_e32 v31, 1.0, v31
	v_rcp_f32_e32 v31, v31
	v_mul_f32_e32 v26, v27, v241
	v_mul_f32_e32 v26, v99, v26
	v_mul_f32_e32 v27, v31, v30
	v_mul_f32_e32 v26, v27, v26
	v_cvt_pk_bf16_f32 v30, v26, v195
	ds_write_b16 v88, v30 offset:8464
	ds_read_u16 v241, v62 offset:42240
	s_waitcnt lgkmcnt(1)
	v_lshlrev_b32_e32 v27, 16, v238
	v_mul_f32_e32 v30, 0xbfb8aa3b, v27
	v_exp_f32_e32 v30, v30
	ds_read_b32 v238, v132 offset:644
	v_add_f32_e32 v30, 1.0, v30
	v_rcp_f32_e32 v30, v30
	v_mul_f32_e32 v26, v28, v240
	v_mul_f32_e32 v26, v99, v26
	v_mul_f32_e32 v27, v30, v27
	v_mul_f32_e32 v26, v27, v26
	v_cvt_pk_bf16_f32 v28, v26, v195
	ds_write_b16 v88, v28 offset:8736
	ds_read_u16 v240, v62 offset:42504
	s_waitcnt lgkmcnt(1)
	v_lshlrev_b32_e32 v27, 16, v237
	v_mul_f32_e32 v28, 0xbfb8aa3b, v27
	v_exp_f32_e32 v28, v28
	ds_read_b32 v237, v132 offset:648
	v_add_f32_e32 v28, 1.0, v28
	v_rcp_f32_e32 v28, v28
	v_mul_f32_e32 v26, v29, v243
	v_mul_f32_e32 v26, v99, v26
	v_mul_f32_e32 v27, v28, v27
	v_mul_f32_e32 v26, v27, v26
	v_cvt_pk_bf16_f32 v28, v26, v195
	ds_write_b16 v88, v28 offset:9008
	ds_read_u16 v243, v62 offset:42768
	s_waitcnt lgkmcnt(1)
	v_lshlrev_b32_e32 v27, 16, v242
	v_mul_f32_e32 v28, 0xbfb8aa3b, v27
	v_exp_f32_e32 v28, v28
	ds_read_b32 v242, v132 offset:652
	v_add_f32_e32 v28, 1.0, v28
	v_rcp_f32_e32 v28, v28
	v_mul_f32_e32 v22, v22, v239
	v_mul_f32_e32 v22, v99, v22
	v_mul_f32_e32 v26, v28, v27
	v_mul_f32_e32 v22, v26, v22
	v_cvt_pk_bf16_f32 v22, v22, v195
	ds_write_b16 v88, v22 offset:12544
	ds_read_u16 v239, v62 offset:46200
	s_waitcnt lgkmcnt(1)
	v_lshlrev_b32_e32 v26, 16, v241
	v_mul_f32_e32 v27, 0xbfb8aa3b, v26
	v_exp_f32_e32 v27, v27
	ds_read_b32 v241, v132 offset:704
	v_add_f32_e32 v27, 1.0, v27
	v_rcp_f32_e32 v27, v27
	v_mul_f32_e32 v22, v23, v238
	v_mul_f32_e32 v22, v99, v22
	v_mul_f32_e32 v23, v27, v26
	v_mul_f32_e32 v22, v23, v22
	v_cvt_pk_bf16_f32 v26, v22, v195
	ds_write_b16 v87, v26 offset:8192
	ds_read_u16 v238, v62 offset:46464
	s_waitcnt lgkmcnt(1)
	v_lshlrev_b32_e32 v23, 16, v240
	v_mul_f32_e32 v26, 0xbfb8aa3b, v23
	v_exp_f32_e32 v26, v26
	ds_read_b32 v240, v132 offset:708
	v_add_f32_e32 v26, 1.0, v26
	v_rcp_f32_e32 v26, v26
	v_mul_f32_e32 v22, v24, v237
	v_mul_f32_e32 v22, v99, v22
	v_mul_f32_e32 v23, v26, v23
	v_mul_f32_e32 v22, v23, v22
	v_cvt_pk_bf16_f32 v24, v22, v195
	ds_write_b16 v87, v24 offset:8464
	ds_read_u16 v237, v62 offset:46728
	s_waitcnt lgkmcnt(1)
	v_lshlrev_b32_e32 v23, 16, v243
	v_mul_f32_e32 v24, 0xbfb8aa3b, v23
	v_exp_f32_e32 v24, v24
	ds_read_b32 v243, v132 offset:712
	v_add_f32_e32 v24, 1.0, v24
	v_rcp_f32_e32 v24, v24
	v_mul_f32_e32 v22, v25, v242
	v_mul_f32_e32 v22, v99, v22
	v_mul_f32_e32 v23, v24, v23
	v_mul_f32_e32 v22, v23, v22
	v_cvt_pk_bf16_f32 v24, v22, v195
	ds_write_b16 v87, v24 offset:8736
	ds_read_u16 v242, v62 offset:46992
	s_waitcnt lgkmcnt(1)
	v_lshlrev_b32_e32 v23, 16, v239
	v_mul_f32_e32 v24, 0xbfb8aa3b, v23
	v_exp_f32_e32 v24, v24
	ds_read_b32 v239, v132 offset:716
	v_add_f32_e32 v24, 1.0, v24
	v_rcp_f32_e32 v24, v24
	v_mul_f32_e32 v18, v18, v241
	v_mul_f32_e32 v18, v99, v18
	v_mul_f32_e32 v22, v24, v23
	v_mul_f32_e32 v18, v22, v18
	v_cvt_pk_bf16_f32 v18, v18, v195
	ds_write_b16 v87, v18 offset:12272
	ds_read_u16 v241, v62 offset:50424
	s_waitcnt lgkmcnt(1)
	v_lshlrev_b32_e32 v22, 16, v238
	v_mul_f32_e32 v23, 0xbfb8aa3b, v22
	v_exp_f32_e32 v23, v23
	ds_read_b32 v238, v132 offset:768
	v_add_f32_e32 v23, 1.0, v23
	v_rcp_f32_e32 v23, v23
	v_mul_f32_e32 v18, v19, v240
	v_mul_f32_e32 v18, v99, v18
	v_mul_f32_e32 v19, v23, v22
	v_mul_f32_e32 v18, v19, v18
	v_cvt_pk_bf16_f32 v22, v18, v195
	ds_write_b16 v87, v22 offset:12544
	ds_read_u16 v240, v62 offset:50688
	v_add_u32_e32 v26, 0, v194
	s_waitcnt lgkmcnt(1)
	v_lshlrev_b32_e32 v19, 16, v237
	v_mul_f32_e32 v22, 0xbfb8aa3b, v19
	v_exp_f32_e32 v22, v22
	ds_read_b32 v237, v132 offset:772
	v_add_f32_e32 v22, 1.0, v22
	v_rcp_f32_e32 v22, v22
	v_mul_f32_e32 v18, v20, v243
	v_mul_f32_e32 v18, v99, v18
	v_mul_f32_e32 v19, v22, v19
	v_mul_f32_e32 v18, v19, v18
	v_cvt_pk_bf16_f32 v20, v18, v195
	ds_write_b16 v86, v20 offset:8192
	ds_read_u16 v243, v62 offset:50952
	s_waitcnt lgkmcnt(1)
	v_lshlrev_b32_e32 v19, 16, v242
	v_mul_f32_e32 v20, 0xbfb8aa3b, v19
	v_exp_f32_e32 v20, v20
	ds_read_b32 v242, v132 offset:776
	v_add_f32_e32 v20, 1.0, v20
	v_rcp_f32_e32 v20, v20
	v_mul_f32_e32 v18, v21, v239
	v_mul_f32_e32 v18, v99, v18
	v_mul_f32_e32 v19, v20, v19
	v_mul_f32_e32 v18, v19, v18
	v_cvt_pk_bf16_f32 v20, v18, v195
	ds_write_b16 v86, v20 offset:8464
	ds_read_u16 v239, v62 offset:51216
	s_waitcnt lgkmcnt(1)
; #define LAS __attribute__((address_space(3)))
; __device__ __forceinline__ float bf2f(unsigned short b) { return __uint_as_float(((unsigned)b) << 16); }
; __device__ __forceinline__ unsigned short f2bf(float f) { return (unsigned short)(cvt_pk_bf16(f, 0.f) & 0xffffu); }
; __device__ void gla_C(const Params& P, int l, int item, LAS unsigned char* lds) {
;     ...
;     for (int rt = 0; rt < 16; ++rt)
; #pragma unroll
;         for (int jj = 0; jj < 4; ++jj) { const int t = rt * 16 + 4 * g + jj; float tot = 0.f;
; #pragma unroll
;             for (int ww = 0; ww < 8; ++ww) tot += SSQ[ww * 256 + t];
;             const float rs = rsqrtf(tot * (1.0f / 128.0f) + EPS);
;             const float gt = bf2f(*(const LAS unsigned short*)(GTL + t * 264 + (16 * w + c) * 2));
;             *(LAS unsigned short*)(OT + t * 272 + (16 * w + c) * 2) = f2bf(O[rt][jj] * rs * ng * (gt * __builtin_amdgcn_rcpf(1.0f + __expf(-gt)))); }
	v_lshlrev_b32_e32 v19, 16, v241
	v_mul_f32_e32 v20, 0xbfb8aa3b, v19
	v_exp_f32_e32 v20, v20
	ds_read_b32 v241, v132 offset:780
	v_add_f32_e32 v20, 1.0, v20
	v_rcp_f32_e32 v20, v20
	v_mul_f32_e32 v14, v14, v238
	v_mul_f32_e32 v14, v99, v14
	v_mul_f32_e32 v18, v20, v19
	v_mul_f32_e32 v14, v18, v14
	v_cvt_pk_bf16_f32 v14, v14, v195
	ds_write_b16 v86, v14 offset:12000
	ds_read_u16 v238, v62 offset:54648
	s_waitcnt lgkmcnt(1)
	v_lshlrev_b32_e32 v18, 16, v240
	v_mul_f32_e32 v19, 0xbfb8aa3b, v18
	v_exp_f32_e32 v19, v19
	ds_read_b32 v240, v132 offset:832
	v_add_f32_e32 v19, 1.0, v19
	v_rcp_f32_e32 v19, v19
	v_mul_f32_e32 v14, v15, v237
	v_mul_f32_e32 v14, v99, v14
	v_mul_f32_e32 v15, v19, v18
	v_mul_f32_e32 v14, v15, v14
	v_cvt_pk_bf16_f32 v18, v14, v195
	ds_write_b16 v86, v18 offset:12272
	ds_read_u16 v237, v62 offset:54912
	s_waitcnt lgkmcnt(1)
	v_lshlrev_b32_e32 v15, 16, v243
	v_mul_f32_e32 v18, 0xbfb8aa3b, v15
	v_exp_f32_e32 v18, v18
	ds_read_b32 v243, v132 offset:836
	v_add_f32_e32 v18, 1.0, v18
	v_rcp_f32_e32 v18, v18
	v_mul_f32_e32 v14, v16, v242
	v_mul_f32_e32 v14, v99, v14
	v_mul_f32_e32 v15, v18, v15
	v_mul_f32_e32 v14, v15, v14
	v_cvt_pk_bf16_f32 v16, v14, v195
	ds_write_b16 v86, v16 offset:12544
	ds_read_u16 v242, v62 offset:55176
	s_waitcnt lgkmcnt(1)
	v_lshlrev_b32_e32 v15, 16, v239
	v_mul_f32_e32 v16, 0xbfb8aa3b, v15
	v_exp_f32_e32 v16, v16
	ds_read_b32 v239, v132 offset:840
	v_add_f32_e32 v16, 1.0, v16
	v_rcp_f32_e32 v16, v16
	v_mul_f32_e32 v14, v17, v241
	v_mul_f32_e32 v14, v99, v14
	v_mul_f32_e32 v15, v16, v15
	v_mul_f32_e32 v14, v15, v14
	v_cvt_pk_bf16_f32 v16, v14, v195
	ds_write_b16 v85, v16 offset:8192
	ds_read_u16 v241, v62 offset:55440
	s_waitcnt lgkmcnt(1)
	v_lshlrev_b32_e32 v15, 16, v238
	v_mul_f32_e32 v16, 0xbfb8aa3b, v15
	v_exp_f32_e32 v16, v16
	ds_read_b32 v238, v132 offset:844
	v_add_f32_e32 v16, 1.0, v16
	v_rcp_f32_e32 v16, v16
	v_mul_f32_e32 v10, v10, v240
	v_mul_f32_e32 v10, v99, v10
	v_mul_f32_e32 v14, v16, v15
	v_mul_f32_e32 v10, v14, v10
	v_cvt_pk_bf16_f32 v10, v10, v195
	ds_write_b16 v85, v10 offset:11728
	ds_read_u16 v240, v62 offset:58872
	s_waitcnt lgkmcnt(1)
	v_lshlrev_b32_e32 v14, 16, v237
	v_mul_f32_e32 v15, 0xbfb8aa3b, v14
	v_exp_f32_e32 v15, v15
	ds_read_b32 v237, v132 offset:896
	v_add_f32_e32 v15, 1.0, v15
	v_rcp_f32_e32 v15, v15
	v_mul_f32_e32 v10, v11, v243
	v_mul_f32_e32 v10, v99, v10
	v_mul_f32_e32 v11, v15, v14
	v_mul_f32_e32 v10, v11, v10
	v_cvt_pk_bf16_f32 v14, v10, v195
	ds_write_b16 v85, v14 offset:12000
	ds_read_u16 v243, v62 offset:59136
	s_waitcnt lgkmcnt(1)
	v_lshlrev_b32_e32 v11, 16, v242
	v_mul_f32_e32 v14, 0xbfb8aa3b, v11
	v_exp_f32_e32 v14, v14
	ds_read_b32 v242, v132 offset:900
	v_add_f32_e32 v14, 1.0, v14
	v_rcp_f32_e32 v14, v14
	v_mul_f32_e32 v10, v12, v239
	v_mul_f32_e32 v10, v99, v10
	v_mul_f32_e32 v11, v14, v11
	v_mul_f32_e32 v10, v11, v10
	v_cvt_pk_bf16_f32 v12, v10, v195
	ds_write_b16 v85, v12 offset:12272
	ds_read_u16 v239, v62 offset:59400
	s_waitcnt lgkmcnt(1)
	v_lshlrev_b32_e32 v11, 16, v241
	v_mul_f32_e32 v12, 0xbfb8aa3b, v11
	v_exp_f32_e32 v12, v12
	ds_read_b32 v241, v132 offset:904
	v_add_f32_e32 v12, 1.0, v12
	v_rcp_f32_e32 v12, v12
	v_mul_f32_e32 v10, v13, v238
	v_mul_f32_e32 v10, v99, v10
	v_mul_f32_e32 v11, v12, v11
	v_mul_f32_e32 v10, v11, v10
	v_cvt_pk_bf16_f32 v12, v10, v195
	ds_write_b16 v85, v12 offset:12544
	ds_read_u16 v238, v62 offset:59664
	s_waitcnt lgkmcnt(1)
	v_lshlrev_b32_e32 v11, 16, v240
	v_mul_f32_e32 v12, 0xbfb8aa3b, v11
	v_exp_f32_e32 v12, v12
	ds_read_b32 v240, v132 offset:908
	v_add_f32_e32 v12, 1.0, v12
	v_rcp_f32_e32 v12, v12
	v_mul_f32_e32 v6, v6, v237
	v_mul_f32_e32 v6, v99, v6
	v_mul_f32_e32 v10, v12, v11
	v_mul_f32_e32 v6, v10, v6
	v_cvt_pk_bf16_f32 v6, v6, v195
	ds_write_b16 v84, v6 offset:8192
	ds_read_u16 v237, v62 offset:63096
	s_waitcnt lgkmcnt(1)
	v_lshlrev_b32_e32 v10, 16, v243
	v_mul_f32_e32 v11, 0xbfb8aa3b, v10
	v_exp_f32_e32 v11, v11
	ds_read_b32 v243, v132 offset:960
	v_add_f32_e32 v11, 1.0, v11
	v_rcp_f32_e32 v11, v11
	v_mul_f32_e32 v6, v7, v242
	v_mul_f32_e32 v6, v99, v6
	v_mul_f32_e32 v7, v11, v10
	v_mul_f32_e32 v6, v7, v6
	v_cvt_pk_bf16_f32 v10, v6, v195
	ds_write_b16 v84, v10 offset:8464
	ds_read_u16 v242, v62 offset:63360
	s_waitcnt lgkmcnt(1)
	v_lshlrev_b32_e32 v7, 16, v239
	v_mul_f32_e32 v10, 0xbfb8aa3b, v7
	v_exp_f32_e32 v10, v10
	ds_read_b32 v239, v132 offset:964
	v_add_f32_e32 v10, 1.0, v10
	v_rcp_f32_e32 v10, v10
	v_mul_f32_e32 v6, v8, v241
	v_mul_f32_e32 v6, v99, v6
	v_mul_f32_e32 v7, v10, v7
	v_mul_f32_e32 v6, v7, v6
	v_cvt_pk_bf16_f32 v8, v6, v195
	ds_write_b16 v84, v8 offset:8736
	ds_read_u16 v241, v62 offset:63624
	s_waitcnt lgkmcnt(1)
; #define LAS __attribute__((address_space(3)))
; __device__ __forceinline__ float bf2f(unsigned short b) { return __uint_as_float(((unsigned)b) << 16); }
; __device__ __forceinline__ unsigned short f2bf(float f) { return (unsigned short)(cvt_pk_bf16(f, 0.f) & 0xffffu); }
; __device__ void gla_C(const Params& P, int l, int item, LAS unsigned char* lds) {
;     ...
;     for (int rt = 0; rt < 16; ++rt)
; #pragma unroll
;         for (int jj = 0; jj < 4; ++jj) { const int t = rt * 16 + 4 * g + jj; float tot = 0.f;
; #pragma unroll
;             for (int ww = 0; ww < 8; ++ww) tot += SSQ[ww * 256 + t];
;             const float rs = rsqrtf(tot * (1.0f / 128.0f) + EPS);
;             const float gt = bf2f(*(const LAS unsigned short*)(GTL + t * 264 + (16 * w + c) * 2));
;             *(LAS unsigned short*)(OT + t * 272 + (16 * w + c) * 2) = f2bf(O[rt][jj] * rs * ng * (gt * __builtin_amdgcn_rcpf(1.0f + __expf(-gt)))); }
;     __syncthreads();
; #pragma unroll
;     for (int i = 0; i < 8; ++i) { const int p = tid + i * NTHR, r = p >> 4, sg = p & 15;
;         *(u32x4*)(Z + (size_t)(row0 + r) * ZC + ZG + h * 128 + sg * 8) = *(const LAS u32x4*)(OT + r * 272 + sg * 16); }
;     __syncthreads();
	v_lshlrev_b32_e32 v7, 16, v238
	v_mul_f32_e32 v8, 0xbfb8aa3b, v7
	v_exp_f32_e32 v8, v8
	ds_read_b32 v238, v132 offset:968
	v_add_f32_e32 v8, 1.0, v8
	v_rcp_f32_e32 v8, v8
	v_mul_f32_e32 v6, v9, v240
	v_mul_f32_e32 v6, v99, v6
	v_mul_f32_e32 v7, v8, v7
	v_mul_f32_e32 v6, v7, v6
	v_cvt_pk_bf16_f32 v10, v6, v195
	ds_write_b16 v84, v10 offset:9008
	v_mad_i64_i32 v[6:7], s[0:1], v156, s25, 0
	ds_read_u16 v240, v62 offset:63888
	s_waitcnt lgkmcnt(1)
	v_lshlrev_b32_e32 v11, 16, v237
	ds_read_b32 v237, v132 offset:972
	v_mul_f32_e32 v8, 0xbfb8aa3b, v11
	v_exp_f32_e32 v12, v8
	v_mad_i64_i32 v[8:9], s[0:1], v155, s25, 0
	v_add_f32_e32 v12, 1.0, v12
	v_rcp_f32_e32 v12, v12
	v_mul_f32_e32 v2, v2, v243
	v_mul_f32_e32 v2, v99, v2
	v_mul_f32_e32 v10, v12, v11
	v_mul_f32_e32 v2, v10, v2
	v_cvt_pk_bf16_f32 v2, v2, v195
	ds_write_b16 v84, v2 offset:12544
	v_lshl_add_u64 v[8:9], s[28:29], 0, v[8:9]
	s_nop 0
	s_waitcnt lgkmcnt(0)
	v_lshlrev_b32_e32 v14, 16, v242
	v_mul_f32_e32 v12, 0xbfb8aa3b, v14
	v_exp_f32_e32 v15, v12
	s_nop 0
	v_lshl_add_u64 v[8:9], v[8:9], 0, s[20:21]
	v_add_f32_e32 v15, 1.0, v15
	v_rcp_f32_e32 v15, v15
	v_mul_f32_e32 v2, v3, v239
	v_mul_f32_e32 v2, v99, v2
	v_mul_f32_e32 v3, v15, v14
	v_mul_f32_e32 v2, v3, v2
	v_cvt_pk_bf16_f32 v16, v2, v195
	ds_write_b16 v84, v16 offset:12816
	v_lshl_add_u64 v[8:9], v[8:9], 0, v[194:195]
	s_nop 0
	v_mad_i64_i32 v[10:11], s[0:1], v154, s25, 0
	s_waitcnt lgkmcnt(0)
	v_lshlrev_b32_e32 v15, 16, v241
	v_mul_f32_e32 v16, 0xbfb8aa3b, v15
	v_exp_f32_e32 v16, v16
	s_nop 0
	v_mad_i64_i32 v[12:13], s[0:1], v153, s25, 0
	v_add_f32_e32 v16, 1.0, v16
	v_rcp_f32_e32 v16, v16
	v_mul_f32_e32 v4, v4, v238
	v_mul_f32_e32 v4, v99, v4
	v_mul_f32_e32 v14, v16, v15
	v_mul_f32_e32 v4, v14, v4
	v_cvt_pk_bf16_f32 v4, v4, v195
	ds_write_b16 v84, v4 offset:13088
	v_mad_i64_i32 v[2:3], s[0:1], v152, s25, 0
	s_nop 0
	s_waitcnt lgkmcnt(0)
	v_lshlrev_b32_e32 v14, 16, v240
	v_lshl_add_u64 v[2:3], s[28:29], 0, v[2:3]
	v_mul_f32_e32 v15, 0xbfb8aa3b, v14
	v_exp_f32_e32 v15, v15
	s_nop 0
	v_lshl_add_u64 v[2:3], v[2:3], 0, s[20:21]
	v_mad_i64_i32 v[18:19], s[0:1], v151, s25, 0
	v_add_f32_e32 v15, 1.0, v15
	v_rcp_f32_e32 v15, v15
	v_mul_f32_e32 v4, v5, v237
	v_mul_f32_e32 v4, v99, v4
	v_mul_f32_e32 v5, v15, v14
	v_mul_f32_e32 v4, v5, v4
	v_cvt_pk_bf16_f32 v4, v4, v195
	ds_write_b16 v84, v4 offset:13360
	v_add_u32_e32 v4, v26, v83
	s_waitcnt lgkmcnt(0)
	s_barrier
	ds_read_b128 v[14:17], v4 offset:8192
	v_lshl_add_u64 v[4:5], s[28:29], 0, v[6:7]
	v_lshl_add_u64 v[4:5], v[4:5], 0, s[20:21]
	v_lshl_add_u64 v[24:25], v[4:5], 0, v[194:195]
	v_add_u32_e32 v4, v26, v82
	ds_read_b128 v[4:7], v4 offset:8192
	s_waitcnt lgkmcnt(1)
	global_store_dwordx4 v[24:25], v[14:17], off offset:2048
	v_lshl_add_u64 v[2:3], v[2:3], 0, v[194:195]
	v_mad_i64_i32 v[20:21], s[0:1], v150, s25, 0
	s_waitcnt lgkmcnt(0)
	global_store_dwordx4 v[8:9], v[4:7], off offset:2048
	v_lshl_add_u64 v[8:9], s[28:29], 0, v[10:11]
	v_lshl_add_u64 v[8:9], v[8:9], 0, s[20:21]
	v_add_u32_e32 v4, v26, v81
	ds_read_b128 v[4:7], v4 offset:8192
	v_lshl_add_u64 v[14:15], v[8:9], 0, v[194:195]
	v_add_u32_e32 v8, v26, v80
	ds_read_b128 v[8:11], v8 offset:8192
	v_mad_i64_i32 v[22:23], s[0:1], v101, s25, 0
	s_waitcnt lgkmcnt(1)
	global_store_dwordx4 v[14:15], v[4:7], off offset:2048
	s_nop 1
	v_lshl_add_u64 v[4:5], s[28:29], 0, v[12:13]
	v_lshl_add_u64 v[4:5], v[4:5], 0, s[20:21]
	v_lshl_add_u64 v[4:5], v[4:5], 0, v[194:195]
	s_waitcnt lgkmcnt(0)
	global_store_dwordx4 v[4:5], v[8:11], off offset:2048
	v_add_u32_e32 v4, v26, v79
	ds_read_b128 v[4:7], v4 offset:8192
	v_add_u32_e32 v8, v26, v78
	ds_read_b128 v[8:11], v8 offset:8192
	s_waitcnt lgkmcnt(1)
	global_store_dwordx4 v[2:3], v[4:7], off offset:2048
	v_lshl_add_u64 v[2:3], s[28:29], 0, v[18:19]
	v_lshl_add_u64 v[2:3], v[2:3], 0, s[20:21]
	v_lshl_add_u64 v[2:3], v[2:3], 0, v[194:195]
	s_waitcnt lgkmcnt(0)
	global_store_dwordx4 v[2:3], v[8:11], off offset:2048
	v_add_u32_e32 v2, v26, v77
	ds_read_b128 v[2:5], v2 offset:8192
	v_lshl_add_u64 v[6:7], s[28:29], 0, v[20:21]
	v_lshl_add_u64 v[6:7], v[6:7], 0, s[20:21]
	v_lshl_add_u64 v[10:11], v[6:7], 0, v[194:195]
	v_add_u32_e32 v6, v26, v76
	ds_read_b128 v[6:9], v6 offset:8192
	s_waitcnt lgkmcnt(1)
	global_store_dwordx4 v[10:11], v[2:5], off offset:2048
	s_nop 1
	v_lshl_add_u64 v[2:3], s[28:29], 0, v[22:23]
	v_lshl_add_u64 v[2:3], v[2:3], 0, s[20:21]
	v_lshl_add_u64 v[2:3], v[2:3], 0, v[194:195]
	s_waitcnt lgkmcnt(0)
	global_store_dwordx4 v[2:3], v[6:9], off offset:2048
	s_barrier
	s_cbranch_scc1 .LBB0_446

; #define LAS __attribute__((address_space(3)))
; __device__ __forceinline__ void attn_item(const Params& P, int half, int item, LAS unsigned char* lds, unsigned* ctr) {
;     ...
;     const int m0 = (16 * w < 96) ? 16 * w : 96;
;     f32x4 S[10];
; #pragma unroll
;     for (int jt = 0; jt < 10; ++jt) {
;         S[jt] = (f32x4){0.f, 0.f, 0.f, 0.f};
;         const LAS unsigned char* kr = Ks + (m0 + jt * 16 + c) * KSTR + 16 * g;
; #pragma unroll
;         for (int ks = 0; ks < 4; ++ks) { const bf16x8 a = *(const LAS bf16x8*)(kr + ks * 64); S[jt] = __builtin_amdgcn_mfma_f32_16x16x32_bf16(a, Qf[ks], S[jt], 0, 0, 0); }
;     }
;     float mx = -INFINITY;
;     const int dbase = qi + 128 - m0 - 4 * g;
;     const unsigned dlim = (unsigned)((n == 0) ? (qi < 128 ? qi : 128) : 128);
; #pragma unroll
;     for (int jt = 0; jt < 10; ++jt)
; #pragma unroll
;         for (int jj = 0; jj < 4; ++jj) { const bool ok = (unsigned)(dbase - (jt * 16 + jj)) <= dlim;
;             const float s = ok ? S[jt][jj] : -INFINITY; S[jt][jj] = s; mx = fmaxf(mx, s); }
.LBB0_539:
	s_or_b64 exec, exec, s[30:31]
	s_and_b32 s6, s6, -16
	v_and_b32_e32 v54, 15, v137
	s_min_i32 s6, s6, 0x60
	v_or_b32_e32 v18, s6, v54
	s_movk_i32 s7, 0x110
	v_mul_lo_u32 v18, v18, s7
	v_add3_u32 v55, 0, v194, v18
	ds_read_b128 v[204:207], v55
	ds_read_b128 v[208:211], v55 offset:64
	ds_read_b128 v[212:215], v55 offset:4416
	ds_read_b128 v[216:219], v55 offset:8768
	ds_read_b128 v[220:223], v55 offset:13120
	ds_read_b128 v[224:227], v55 offset:128
	s_and_b32 s5, s5, 0xff
	s_cmp_eq_u32 s5, 0
	s_cselect_b64 vcc, -1, 0
	s_mov_b32 s5, 0xff800000
	v_lshlrev_b32_e32 v194, 3, v136
	v_lshlrev_b32_e32 v150, 2, v136
	v_or_b32_e32 v150, s6, v150
	v_min_i32_e32 v148, 0x80, v138
	v_mov_b32_e32 v151, 0x80
	v_cndmask_b32_e32 v148, v151, v148, vcc
	v_sub_u32_e32 v149, v138, v150
	s_waitcnt lgkmcnt(5)
	v_mfma_f32_16x16x32_bf16 v[18:21], v[204:207], v[6:9], 0
	ds_read_b128 v[204:207], v55 offset:17472
	ds_read_b128 v[236:239], v55 offset:21824
	ds_read_b128 v[240:243], v55 offset:192
	s_waitcnt lgkmcnt(7)
	v_mfma_f32_16x16x32_bf16 v[18:21], v[208:211], v[14:17], v[18:21]
	ds_read_b128 v[208:211], v55 offset:26176
	ds_read_b128 v[244:247], v55 offset:30528
	ds_read_b128 v[176:179], v55 offset:4352
	s_waitcnt lgkmcnt(6)
	v_mfma_f32_16x16x32_bf16 v[18:21], v[224:227], v[2:5], v[18:21]
	ds_read_b128 v[224:227], v55 offset:34880
	ds_read_b128 v[180:183], v55 offset:4480
	ds_read_b128 v[184:187], v55 offset:4544
	s_waitcnt lgkmcnt(6)
	v_mfma_f32_16x16x32_bf16 v[18:21], v[240:243], v[10:13], v[18:21]
	ds_read_b128 v[240:243], v55 offset:8704
	ds_read_b128 v[188:191], v55 offset:8832
	s_waitcnt lgkmcnt(5)
	v_mfma_f32_16x16x32_bf16 v[22:25], v[176:179], v[6:9], 0
	v_mfma_f32_16x16x32_bf16 v[22:25], v[212:215], v[14:17], v[22:25]
	ds_read_b128 v[212:215], v55 offset:8896
	s_waitcnt lgkmcnt(4)
	v_mfma_f32_16x16x32_bf16 v[22:25], v[180:183], v[2:5], v[22:25]
	ds_read_b128 v[176:179], v55 offset:13056
	s_waitcnt lgkmcnt(4)
	v_mfma_f32_16x16x32_bf16 v[22:25], v[184:187], v[10:13], v[22:25]
	ds_read_b128 v[180:183], v55 offset:13184
	s_waitcnt lgkmcnt(4)
	v_mfma_f32_16x16x32_bf16 v[26:29], v[240:243], v[6:9], 0
	v_add_u32_e32 v151, 0x80, v149
	v_cmp_le_u32_e32 vcc, v151, v148
	s_nop 1
	v_cndmask_b32_e32 v160, v235, v18, vcc
	v_mfma_f32_16x16x32_bf16 v[26:29], v[216:219], v[14:17], v[26:29]
	v_add_u32_e32 v151, 0x7f, v149
	v_cmp_le_u32_e32 vcc, v151, v148
	s_nop 1
	v_cndmask_b32_e32 v161, v235, v19, vcc
	v_max3_f32 v159, v160, s5, v161
	ds_read_b128 v[216:219], v55 offset:13248
	s_waitcnt lgkmcnt(4)
	v_mfma_f32_16x16x32_bf16 v[26:29], v[188:191], v[2:5], v[26:29]
	v_add_u32_e32 v151, 0x7e, v149
	v_cmp_le_u32_e32 vcc, v151, v148
	s_nop 1
	v_cndmask_b32_e32 v162, v235, v20, vcc
	ds_read_b128 v[240:243], v55 offset:17408
	s_waitcnt lgkmcnt(4)
	v_mfma_f32_16x16x32_bf16 v[26:29], v[212:215], v[10:13], v[26:29]
	v_add_u32_e32 v151, 0x7d, v149
	v_cmp_le_u32_e32 vcc, v151, v148
	s_nop 1
	v_cndmask_b32_e32 v163, v235, v21, vcc
	v_max3_f32 v159, v159, v162, v163
	ds_read_b128 v[212:215], v55 offset:17536
	s_waitcnt lgkmcnt(4)
	v_mfma_f32_16x16x32_bf16 v[30:33], v[176:179], v[6:9], 0
	v_add_u32_e32 v151, 0x70, v149
	v_cmp_le_u32_e32 vcc, v151, v148
	s_nop 1
	v_cndmask_b32_e32 v164, v235, v22, vcc
	v_mfma_f32_16x16x32_bf16 v[30:33], v[220:223], v[14:17], v[30:33]
	v_add_u32_e32 v151, 0x6f, v149
	v_cmp_le_u32_e32 vcc, v151, v148
	s_nop 1
	v_cndmask_b32_e32 v165, v235, v23, vcc
	v_max3_f32 v159, v159, v164, v165
	ds_read_b128 v[220:223], v55 offset:17600
	s_waitcnt lgkmcnt(4)
	v_mfma_f32_16x16x32_bf16 v[30:33], v[180:183], v[2:5], v[30:33]
	v_add_u32_e32 v151, 0x6e, v149
	v_cmp_le_u32_e32 vcc, v151, v148
	s_nop 1
	v_cndmask_b32_e32 v168, v235, v24, vcc
	ds_read_b128 v[176:179], v55 offset:21760
	s_waitcnt lgkmcnt(4)
	v_mfma_f32_16x16x32_bf16 v[30:33], v[216:219], v[10:13], v[30:33]
	v_add_u32_e32 v151, 0x6d, v149
	v_cmp_le_u32_e32 vcc, v151, v148
	s_nop 1
	v_cndmask_b32_e32 v169, v235, v25, vcc
	v_max3_f32 v159, v159, v168, v169
	ds_read_b128 v[216:219], v55 offset:21888
	s_waitcnt lgkmcnt(4)
	v_mfma_f32_16x16x32_bf16 v[34:37], v[240:243], v[6:9], 0
	v_add_u32_e32 v151, 0x60, v149
	v_cmp_le_u32_e32 vcc, v151, v148
	s_nop 1
	v_cndmask_b32_e32 v18, v235, v26, vcc
	v_mfma_f32_16x16x32_bf16 v[34:37], v[204:207], v[14:17], v[34:37]
	v_add_u32_e32 v151, 0x5f, v149
	v_cmp_le_u32_e32 vcc, v151, v148
	s_nop 1
	v_cndmask_b32_e32 v19, v235, v27, vcc
	v_max3_f32 v159, v159, v18, v19
	ds_read_b128 v[204:207], v55 offset:21952
	s_waitcnt lgkmcnt(4)
	v_mfma_f32_16x16x32_bf16 v[34:37], v[212:215], v[2:5], v[34:37]
	v_add_u32_e32 v151, 0x5e, v149
	v_cmp_le_u32_e32 vcc, v151, v148
	s_nop 1
	v_cndmask_b32_e32 v20, v235, v28, vcc
	ds_read_b128 v[212:215], v55 offset:26112
	s_waitcnt lgkmcnt(4)
	v_mfma_f32_16x16x32_bf16 v[34:37], v[220:223], v[10:13], v[34:37]
	v_add_u32_e32 v151, 0x5d, v149
	v_cmp_le_u32_e32 vcc, v151, v148
	s_nop 1
	v_cndmask_b32_e32 v21, v235, v29, vcc
	v_max3_f32 v159, v159, v20, v21
	ds_read_b128 v[220:223], v55 offset:26240
	s_waitcnt lgkmcnt(4)
	v_mfma_f32_16x16x32_bf16 v[38:41], v[176:179], v[6:9], 0
	v_add_u32_e32 v151, 0x50, v149
	v_cmp_le_u32_e32 vcc, v151, v148
	s_nop 1
	v_cndmask_b32_e32 v22, v235, v30, vcc
	v_mfma_f32_16x16x32_bf16 v[38:41], v[236:239], v[14:17], v[38:41]
	v_add_u32_e32 v151, 0x4f, v149
	v_cmp_le_u32_e32 vcc, v151, v148
	s_nop 1
	v_cndmask_b32_e32 v25, v235, v31, vcc
	v_max3_f32 v159, v159, v22, v25
	ds_read_b128 v[236:239], v55 offset:26304
	s_waitcnt lgkmcnt(4)
	v_mfma_f32_16x16x32_bf16 v[38:41], v[216:219], v[2:5], v[38:41]
	v_add_u32_e32 v151, 0x4e, v149
	v_cmp_le_u32_e32 vcc, v151, v148
	s_nop 1
	v_cndmask_b32_e32 v26, v235, v32, vcc
	ds_read_b128 v[216:219], v55 offset:30464
	s_waitcnt lgkmcnt(4)
; #define LAS __attribute__((address_space(3)))
; __device__ __forceinline__ void attn_item(const Params& P, int half, int item, LAS unsigned char* lds, unsigned* ctr) {
;     ...
;         const LAS unsigned char* kr = Ks + (m0 + jt * 16 + c) * KSTR + 16 * g;
; #pragma unroll
;         for (int ks = 0; ks < 4; ++ks) { const bf16x8 a = *(const LAS bf16x8*)(kr + ks * 64); S[jt] = __builtin_amdgcn_mfma_f32_16x16x32_bf16(a, Qf[ks], S[jt], 0, 0, 0); }
;     }
;     float mx = -INFINITY;
;     const int dbase = qi + 128 - m0 - 4 * g;
;     const unsigned dlim = (unsigned)((n == 0) ? (qi < 128 ? qi : 128) : 128);
; #pragma unroll
;     for (int jt = 0; jt < 10; ++jt)
; #pragma unroll
;         for (int jj = 0; jj < 4; ++jj) { const bool ok = (unsigned)(dbase - (jt * 16 + jj)) <= dlim;
;             const float s = ok ? S[jt][jj] : -INFINITY; S[jt][jj] = s; mx = fmaxf(mx, s); }
;     mx = fmaxf(mx, __shfl_xor(mx, 16)); mx = fmaxf(mx, __shfl_xor(mx, 32));
	v_mfma_f32_16x16x32_bf16 v[38:41], v[204:207], v[10:13], v[38:41]
	v_add_u32_e32 v151, 0x4d, v149
	v_cmp_le_u32_e32 vcc, v151, v148
	s_nop 1
	v_cndmask_b32_e32 v27, v235, v33, vcc
	v_max3_f32 v159, v159, v26, v27
	ds_read_b128 v[204:207], v55 offset:30592
	s_waitcnt lgkmcnt(4)
	v_mfma_f32_16x16x32_bf16 v[42:45], v[212:215], v[6:9], 0
	v_add_u32_e32 v151, 64, v149
	v_cmp_le_u32_e32 vcc, v151, v148
	s_nop 1
	v_cndmask_b32_e32 v28, v235, v34, vcc
	v_mfma_f32_16x16x32_bf16 v[42:45], v[208:211], v[14:17], v[42:45]
	v_add_u32_e32 v151, 63, v149
	v_cmp_le_u32_e32 vcc, v151, v148
	s_nop 1
	v_cndmask_b32_e32 v29, v235, v35, vcc
	v_max3_f32 v159, v159, v28, v29
	ds_read_b128 v[208:211], v55 offset:30656
	s_waitcnt lgkmcnt(4)
	v_mfma_f32_16x16x32_bf16 v[42:45], v[220:223], v[2:5], v[42:45]
	v_add_u32_e32 v151, 62, v149
	v_cmp_le_u32_e32 vcc, v151, v148
	s_nop 1
	v_cndmask_b32_e32 v30, v235, v36, vcc
	ds_read_b128 v[212:215], v55 offset:34816
	s_waitcnt lgkmcnt(4)
	v_mfma_f32_16x16x32_bf16 v[42:45], v[236:239], v[10:13], v[42:45]
	v_add_u32_e32 v151, 61, v149
	v_cmp_le_u32_e32 vcc, v151, v148
	s_nop 1
	v_cndmask_b32_e32 v31, v235, v37, vcc
	v_max3_f32 v159, v159, v30, v31
	ds_read_b128 v[220:223], v55 offset:34944
	s_waitcnt lgkmcnt(4)
	v_mfma_f32_16x16x32_bf16 v[46:49], v[216:219], v[6:9], 0
	v_add_u32_e32 v151, 48, v149
	v_cmp_le_u32_e32 vcc, v151, v148
	s_nop 1
	v_cndmask_b32_e32 v34, v235, v38, vcc
	v_mfma_f32_16x16x32_bf16 v[46:49], v[244:247], v[14:17], v[46:49]
	v_add_u32_e32 v151, 47, v149
	v_cmp_le_u32_e32 vcc, v151, v148
	s_nop 1
	v_cndmask_b32_e32 v35, v235, v39, vcc
	v_max3_f32 v159, v159, v34, v35
	ds_read_b128 v[216:219], v55 offset:35008
	s_waitcnt lgkmcnt(4)
	v_mfma_f32_16x16x32_bf16 v[46:49], v[204:207], v[2:5], v[46:49]
	v_add_u32_e32 v151, 46, v149
	v_cmp_le_u32_e32 vcc, v151, v148
	s_nop 1
	v_cndmask_b32_e32 v36, v235, v40, vcc
	ds_read_b128 v[204:207], v55 offset:39168
	s_waitcnt lgkmcnt(4)
	v_mfma_f32_16x16x32_bf16 v[46:49], v[208:211], v[10:13], v[46:49]
	v_add_u32_e32 v151, 45, v149
	v_cmp_le_u32_e32 vcc, v151, v148
	s_nop 1
	v_cndmask_b32_e32 v37, v235, v41, vcc
	v_max3_f32 v159, v159, v36, v37
	ds_read_b128 v[208:211], v55 offset:39232
	s_waitcnt lgkmcnt(4)
	v_mfma_f32_16x16x32_bf16 v[50:53], v[212:215], v[6:9], 0
	v_add_u32_e32 v151, 32, v149
	v_cmp_le_u32_e32 vcc, v151, v148
	s_nop 1
	v_cndmask_b32_e32 v38, v235, v42, vcc
	v_mfma_f32_16x16x32_bf16 v[50:53], v[224:227], v[14:17], v[50:53]
	v_add_u32_e32 v151, 31, v149
	v_cmp_le_u32_e32 vcc, v151, v148
	s_nop 1
	v_cndmask_b32_e32 v39, v235, v43, vcc
	v_max3_f32 v159, v159, v38, v39
	ds_read_b128 v[212:215], v55 offset:39296
	s_waitcnt lgkmcnt(4)
	v_mfma_f32_16x16x32_bf16 v[50:53], v[220:223], v[2:5], v[50:53]
	v_add_u32_e32 v151, 30, v149
	v_cmp_le_u32_e32 vcc, v151, v148
	s_nop 1
	v_cndmask_b32_e32 v40, v235, v44, vcc
	ds_read_b128 v[220:223], v55 offset:39360
	s_waitcnt lgkmcnt(4)
	v_mfma_f32_16x16x32_bf16 v[50:53], v[216:219], v[10:13], v[50:53]
	v_add_u32_e32 v151, 29, v149
	v_cmp_le_u32_e32 vcc, v151, v148
	s_nop 1
	v_cndmask_b32_e32 v41, v235, v45, vcc
	v_max3_f32 v159, v159, v40, v41
	s_nop 0
	s_waitcnt lgkmcnt(3)
	v_mfma_f32_16x16x32_bf16 v[6:9], v[204:207], v[6:9], 0
	v_add_u32_e32 v151, 16, v149
	v_cmp_le_u32_e32 vcc, v151, v148
	s_nop 1
	v_cndmask_b32_e32 v42, v235, v46, vcc
	s_nop 0
	s_waitcnt lgkmcnt(2)
	v_mfma_f32_16x16x32_bf16 v[6:9], v[208:211], v[14:17], v[6:9]
	v_add_u32_e32 v151, 15, v149
	v_cmp_le_u32_e32 vcc, v151, v148
	s_nop 1
	v_cndmask_b32_e32 v43, v235, v47, vcc
	v_max3_f32 v159, v159, v42, v43
	s_nop 0
	s_waitcnt lgkmcnt(1)
	v_mfma_f32_16x16x32_bf16 v[2:5], v[212:215], v[2:5], v[6:9]
	v_add_u32_e32 v151, 14, v149
	v_cmp_le_u32_e32 vcc, v151, v148
	s_nop 1
	v_cndmask_b32_e32 v44, v235, v48, vcc
	s_nop 4
	s_nop 0
	s_waitcnt lgkmcnt(0)
	v_mfma_f32_16x16x32_bf16 v[2:5], v[220:223], v[10:13], v[2:5]
	v_add_u32_e32 v151, 13, v149
	v_cmp_le_u32_e32 vcc, v151, v148
	s_nop 1
	v_cndmask_b32_e32 v45, v235, v49, vcc
	v_max3_f32 v159, v159, v44, v45
	v_cmp_le_u32_e32 vcc, v149, v148
	s_nop 1
	v_cndmask_b32_e32 v46, v235, v50, vcc
	v_add_u32_e32 v151, -1, v149
	v_cmp_le_u32_e32 vcc, v151, v148
	s_nop 1
	v_cndmask_b32_e32 v47, v235, v51, vcc
	v_max3_f32 v159, v159, v46, v47
	v_add_u32_e32 v151, -2, v149
	v_cmp_le_u32_e32 vcc, v151, v148
	s_nop 1
	v_cndmask_b32_e32 v48, v235, v52, vcc
	v_add_u32_e32 v151, -3, v149
	v_cmp_le_u32_e32 vcc, v151, v148
	s_nop 1
	v_cndmask_b32_e32 v49, v235, v53, vcc
	v_max3_f32 v159, v159, v48, v49
	v_add_u32_e32 v151, -16, v149
	v_cmp_le_u32_e32 vcc, v151, v148
	s_nop 1
	v_cndmask_b32_e32 v50, v235, v2, vcc
	v_subrev_u32_e32 v151, 17, v149
	v_cmp_le_u32_e32 vcc, v151, v148
	s_nop 1
	v_cndmask_b32_e32 v51, v235, v3, vcc
	v_max3_f32 v159, v159, v50, v51
	v_subrev_u32_e32 v151, 18, v149
	v_cmp_le_u32_e32 vcc, v151, v148
	s_nop 1
	v_cndmask_b32_e32 v52, v235, v4, vcc
	v_subrev_u32_e32 v151, 19, v149
	v_cmp_le_u32_e32 vcc, v151, v148
	s_nop 1
	v_cndmask_b32_e32 v53, v235, v5, vcc
	v_max3_f32 v2, v159, v52, v53
	v_mov_b32_e32 v9, v160
	v_mov_b32_e32 v8, v161
	v_mov_b32_e32 v12, v162
	v_mov_b32_e32 v13, v163
	v_mov_b32_e32 v14, v164
	v_mov_b32_e32 v15, v165
	v_mov_b32_e32 v16, v168
	v_mov_b32_e32 v17, v169
	v_mov_b32_e32 v55, v150
	v_readlane_b32 s5, v255, 16
	v_and_b32_e32 v4, 64, v230
	v_xor_b32_e32 v3, 16, v230
	v_add_u32_e32 v4, 64, v4
	v_cmp_lt_i32_e32 vcc, v3, v4
	s_nop 1
	v_cndmask_b32_e32 v3, v230, v3, vcc
	v_lshlrev_b32_e32 v56, 2, v3
	v_mov_b32_e32 v3, v2
	s_nop 1
	v_permlane16_swap_b32_e32 v3, v2
	s_nop 1
	v_max_f32_e32 v3, v3, v3
	v_max_f32_e32 v2, v2, v3
	v_xor_b32_e32 v3, 32, v230
	v_cmp_lt_i32_e32 vcc, v3, v4
	s_nop 1
; #define LAS __attribute__((address_space(3)))
; __device__ __forceinline__ unsigned cvt_pk_bf16(float lo, float hi) { unsigned r; asm volatile("v_cvt_pk_bf16_f32 %0, %1, %2" : "=v"(r) : "v"(lo), "v"(hi)); return r; }
; __device__ __forceinline__ void attn_item(const Params& P, int half, int item, LAS unsigned char* lds, unsigned* ctr) {
;     ...
;     mx = fmaxf(mx, __shfl_xor(mx, 16)); mx = fmaxf(mx, __shfl_xor(mx, 32));
;     float den = 0.f;
; #pragma unroll
;     for (int jt = 0; jt < 10; ++jt) { const f32x4 d = S[jt] - mx; f32x4 p; p[0] = __builtin_amdgcn_exp2f(d[0]); p[1] = __builtin_amdgcn_exp2f(d[1]); p[2] = __builtin_amdgcn_exp2f(d[2]); p[3] = __builtin_amdgcn_exp2f(d[3]);
;         S[jt] = p; den += (p[0] + p[1]) + (p[2] + p[3]); }
;     den += __shfl_xor(den, 16); den += __shfl_xor(den, 32);
;     bf16x8 Pf[5];
; #pragma unroll
;     for (int k5 = 0; k5 < 5; ++k5) { u32x4 pw; pw.x = cvt_pk_bf16(S[2 * k5][0], S[2 * k5][1]); pw.y = cvt_pk_bf16(S[2 * k5][2], S[2 * k5][3]); pw.z = cvt_pk_bf16(S[2 * k5 + 1][0], S[2 * k5 + 1][1]); pw.w = cvt_pk_bf16(S[2 * k5 + 1][2], S[2 * k5 + 1][3]); Pf[k5] = as_bf16x8(pw); }
;     const float inv = 1.0f / den;
;     bf16_t* op = Z + (size_t)qrow * ZC + colq + 4 * g;
; #pragma unroll
;     for (int dt = 0; dt < 8; ++dt) {
;         f32x4 O = (f32x4){0.f, 0.f, 0.f, 0.f};
;         const LAS unsigned char* vr = Vt + (dt * 16 + c) * VSTR + (m0 + 4 * g) * 2;
; #pragma unroll
;         for (int k5 = 0; k5 < 5; ++k5) { const u32x2 lo = *(const LAS u32x2*)(vr + k5 * 64), hi = *(const LAS u32x2*)(vr + k5 * 64 + 32);
;             const bf16x8 a = as_bf16x8((u32x4){lo.x, lo.y, hi.x, hi.y}); O = __builtin_amdgcn_mfma_f32_16x16x32_bf16(a, Pf[k5], O, 0, 0, 0); }
	v_cndmask_b32_e32 v3, v230, v3, vcc
	v_lshlrev_b32_e32 v57, 2, v3
	v_mov_b32_e32 v3, v2
	s_nop 1
	v_permlane32_swap_b32_e32 v3, v2
	s_nop 1
	v_max_f32_e32 v3, v3, v3
	v_max_f32_e32 v24, v2, v3
	v_sub_f32_e32 v2, v13, v24
	v_sub_f32_e32 v3, v12, v24
	v_sub_f32_e32 v5, v8, v24
	v_sub_f32_e32 v4, v9, v24
	v_exp_f32_e32 v4, v4
	v_exp_f32_e32 v6, v5
	v_exp_f32_e32 v5, v3
	v_exp_f32_e32 v7, v2
	v_sub_f32_e32 v9, v16, v24
	v_sub_f32_e32 v10, v15, v24
	v_sub_f32_e32 v8, v14, v24
	v_pk_add_f32 v[2:3], v[4:5], v[6:7]
	v_exp_f32_e32 v8, v8
	v_add_f32_e32 v2, v2, v3
	v_add_f32_e32 v3, 0, v2
	v_sub_f32_e32 v2, v17, v24
	v_exp_f32_e32 v10, v10
	v_exp_f32_e32 v9, v9
	v_exp_f32_e32 v11, v2
	v_sub_f32_e32 v2, v21, v24
	v_sub_f32_e32 v14, v19, v24
	v_sub_f32_e32 v15, v18, v24
	v_pk_add_f32 v[12:13], v[8:9], v[10:11]
	v_exp_f32_e32 v58, v15
	v_pk_add_f32 v[12:13], v[12:13], v[12:13] op_sel_hi:[0,1]
	v_sub_f32_e32 v12, v20, v24
	v_exp_f32_e32 v59, v14
	v_exp_f32_e32 v60, v12
	v_exp_f32_e32 v61, v2
	v_sub_f32_e32 v2, v27, v24
	v_sub_f32_e32 v12, v26, v24
	v_sub_f32_e32 v14, v25, v24
	v_sub_f32_e32 v15, v22, v24
	v_exp_f32_e32 v16, v15
	v_exp_f32_e32 v22, v14
	v_exp_f32_e32 v12, v12
	v_exp_f32_e32 v2, v2
	v_add_f32_e32 v17, v58, v59
	v_add_f32_e32 v23, v60, v61
	v_pk_add_f32 v[14:15], v[16:17], v[22:23]
	v_pk_add_f32 v[18:19], v[12:13], v[2:3]
	v_sub_f32_e32 v3, v31, v24
	v_pk_add_f32 v[14:15], v[14:15], v[18:19]
	v_sub_f32_e32 v13, v30, v24
	v_pk_add_f32 v[26:27], v[14:15], v[14:15] op_sel_hi:[0,1]
	v_sub_f32_e32 v14, v29, v24
	v_sub_f32_e32 v15, v28, v24
	v_exp_f32_e32 v28, v15
	v_exp_f32_e32 v30, v14
	v_exp_f32_e32 v29, v13
	v_exp_f32_e32 v31, v3
	v_sub_f32_e32 v3, v37, v24
	v_sub_f32_e32 v13, v36, v24
	v_exp_f32_e32 v13, v13
	v_pk_add_f32 v[14:15], v[28:29], v[30:31]
	v_exp_f32_e32 v3, v3
	v_pk_add_f32 v[32:33], v[14:15], v[14:15] op_sel_hi:[0,1]
	v_sub_f32_e32 v14, v35, v24
	v_sub_f32_e32 v15, v34, v24
	v_exp_f32_e32 v23, v15
	v_exp_f32_e32 v25, v14
	v_sub_f32_e32 v14, v41, v24
	v_sub_f32_e32 v15, v40, v24
	v_sub_f32_e32 v17, v39, v24
	v_sub_f32_e32 v18, v38, v24
	v_exp_f32_e32 v34, v18
	v_exp_f32_e32 v36, v17
	v_exp_f32_e32 v32, v15
	v_exp_f32_e32 v26, v14
	v_add_f32_e32 v35, v23, v25
	v_add_f32_e32 v37, v13, v3
	v_pk_add_f32 v[14:15], v[34:35], v[36:37]
	v_pk_add_f32 v[18:19], v[32:33], v[26:27]
	v_sub_f32_e32 v17, v43, v24
	v_pk_add_f32 v[14:15], v[14:15], v[18:19]
	v_sub_f32_e32 v18, v42, v24
	v_pk_add_f32 v[38:39], v[14:15], v[14:15] op_sel_hi:[0,1]
	v_sub_f32_e32 v14, v45, v24
	v_sub_f32_e32 v15, v44, v24
	v_exp_f32_e32 v40, v18
	v_exp_f32_e32 v42, v17
	v_exp_f32_e32 v41, v15
	v_exp_f32_e32 v43, v14
	v_sub_f32_e32 v17, v47, v24
	v_sub_f32_e32 v18, v46, v24
	v_exp_f32_e32 v27, v18
	v_pk_add_f32 v[14:15], v[40:41], v[42:43]
	v_exp_f32_e32 v33, v17
	v_pk_add_f32 v[44:45], v[14:15], v[14:15] op_sel_hi:[0,1]
	v_sub_f32_e32 v14, v49, v24
	v_sub_f32_e32 v15, v48, v24
	v_exp_f32_e32 v35, v15
	v_exp_f32_e32 v37, v14
	v_sub_f32_e32 v14, v53, v24
	v_sub_f32_e32 v15, v52, v24
	v_sub_f32_e32 v17, v51, v24
	v_sub_f32_e32 v18, v50, v24
	v_exp_f32_e32 v46, v18
	v_exp_f32_e32 v48, v17
	v_exp_f32_e32 v44, v15
	v_exp_f32_e32 v38, v14
	v_add_f32_e32 v47, v27, v33
	v_add_f32_e32 v49, v35, v37
	v_pk_add_f32 v[14:15], v[46:47], v[48:49]
	v_pk_add_f32 v[18:19], v[44:45], v[38:39]
	s_nop 0
	v_pk_add_f32 v[14:15], v[14:15], v[18:19]
	v_cvt_pk_bf16_f32 v18, v4, v6
	v_cvt_pk_bf16_f32 v19, v5, v7
	v_cvt_pk_bf16_f32 v20, v8, v10
	v_cvt_pk_bf16_f32 v21, v9, v11
	s_nop 0
	v_add_f32_e32 v14, v14, v15
	v_mov_b32_e32 v15, v14
	s_nop 1
	v_permlane16_swap_b32_e32 v15, v14
	s_nop 1
	v_add_f32_e32 v39, v14, v15
	ds_bpermute_b32 v45, v57, v39
	v_cvt_pk_bf16_f32 v14, v58, v59
	v_cvt_pk_bf16_f32 v15, v60, v61
	v_cvt_pk_bf16_f32 v16, v16, v22
	v_cvt_pk_bf16_f32 v17, v12, v2
	v_cvt_pk_bf16_f32 v10, v28, v30
	v_cvt_pk_bf16_f32 v11, v29, v31
	v_cvt_pk_bf16_f32 v12, v23, v25
	s_waitcnt lgkmcnt(0)
	v_add_f32_e32 v25, v39, v45
	v_div_scale_f32 v22, s[6:7], v25, v25, 1.0
	v_rcp_f32_e32 v23, v22
	v_cvt_pk_bf16_f32 v13, v13, v3
	v_cvt_pk_bf16_f32 v6, v34, v36
	v_cvt_pk_bf16_f32 v7, v32, v26
	v_cvt_pk_bf16_f32 v8, v40, v42
	v_cvt_pk_bf16_f32 v9, v41, v43
	s_nop 0
	v_fma_f32 v26, -v22, v23, 1.0
	v_fmac_f32_e32 v23, v26, v23
	v_div_scale_f32 v26, vcc, 1.0, v25, 1.0
	v_cvt_pk_bf16_f32 v2, v27, v33
	v_mul_f32_e32 v27, v26, v23
	v_fma_f32 v28, -v22, v27, v26
	v_fmac_f32_e32 v27, v28, v23
	v_fma_f32 v22, -v22, v27, v26
	v_div_fmas_f32 v22, v22, v23, v27
	v_lshlrev_b32_e32 v27, 1, v55
	v_mul_u32_u24_e32 v28, 0x210, v54
	v_add3_u32 v27, s5, v27, v28
	v_cvt_pk_bf16_f32 v3, v35, v37
	v_cvt_pk_bf16_f32 v4, v46, v48
	v_cvt_pk_bf16_f32 v5, v44, v38
	ds_read2_b64 v[204:207], v27 offset1:4
	ds_read2_b64 v[208:211], v27 offset0:8 offset1:12
	ds_read2_b64 v[212:215], v27 offset0:16 offset1:20
	ds_read2_b64 v[216:219], v27 offset0:24 offset1:28
	ds_read2_b64 v[220:223], v27 offset0:32 offset1:36
	v_add_u32_e32 v156, 0x2100, v27
	ds_read2_b64 v[176:179], v156 offset1:4
	ds_read2_b64 v[180:183], v156 offset0:8 offset1:12
	ds_read2_b64 v[184:187], v156 offset0:16 offset1:20
	ds_read2_b64 v[188:191], v156 offset0:24 offset1:28
	ds_read2_b64 v[172:175], v156 offset0:32 offset1:36
	s_waitcnt lgkmcnt(9)
	v_mfma_f32_16x16x32_bf16 v[28:31], v[204:207], v[18:21], 0
	v_div_fixup_f32 v26, v22, v25, 1.0
	v_lshl_add_u64 v[22:23], v[130:131], 0, v[194:195]
	v_and_b32_e32 v192, 16, v230
	v_lshrrev_b32_e32 v193, 1, v192
	v_add_u32_e32 v192, v192, v193
	v_mov_b32_e32 v193, 0
	v_lshl_add_u64 v[192:193], v[22:23], 0, v[192:193]
	s_waitcnt lgkmcnt(8)
	v_mfma_f32_16x16x32_bf16 v[28:31], v[208:211], v[14:17], v[28:31]
	v_cmp_eq_u32_e32 vcc, 0, v136
	s_waitcnt lgkmcnt(7)
; #define LAS __attribute__((address_space(3)))
; __device__ __forceinline__ unsigned cvt_pk_bf16(float lo, float hi) { unsigned r; asm volatile("v_cvt_pk_bf16_f32 %0, %1, %2" : "=v"(r) : "v"(lo), "v"(hi)); return r; }
; __device__ __forceinline__ void attn_item(const Params& P, int half, int item, LAS unsigned char* lds, unsigned* ctr) {
;     ...
;     bf16_t* op = Z + (size_t)qrow * ZC + colq + 4 * g;
; #pragma unroll
;     for (int dt = 0; dt < 8; ++dt) {
;         f32x4 O = (f32x4){0.f, 0.f, 0.f, 0.f};
;         const LAS unsigned char* vr = Vt + (dt * 16 + c) * VSTR + (m0 + 4 * g) * 2;
; #pragma unroll
;         for (int k5 = 0; k5 < 5; ++k5) { const u32x2 lo = *(const LAS u32x2*)(vr + k5 * 64), hi = *(const LAS u32x2*)(vr + k5 * 64 + 32);
;             const bf16x8 a = as_bf16x8((u32x4){lo.x, lo.y, hi.x, hi.y}); O = __builtin_amdgcn_mfma_f32_16x16x32_bf16(a, Pf[k5], O, 0, 0, 0); }
;         u32x2 ow; ow.x = cvt_pk_bf16(O[0] * inv, O[1] * inv); ow.y = cvt_pk_bf16(O[2] * inv, O[3] * inv);
;         *(u32x2*)(op + dt * 16) = ow;
;     }
	v_mfma_f32_16x16x32_bf16 v[28:31], v[212:215], v[10:13], v[28:31]
	s_waitcnt lgkmcnt(6)
	v_mfma_f32_16x16x32_bf16 v[28:31], v[216:219], v[6:9], v[28:31]
	s_waitcnt lgkmcnt(5)
	v_mfma_f32_16x16x32_bf16 v[28:31], v[220:223], v[2:5], v[28:31]
	v_add_u32_e32 v157, 0x4200, v27
	ds_read2_b64 v[204:207], v157 offset1:4
	ds_read2_b64 v[208:211], v157 offset0:8 offset1:12
	ds_read2_b64 v[212:215], v157 offset0:16 offset1:20
	ds_read2_b64 v[216:219], v157 offset0:24 offset1:28
	ds_read2_b64 v[220:223], v157 offset0:32 offset1:36
	s_waitcnt lgkmcnt(9)
	v_mfma_f32_16x16x32_bf16 v[152:155], v[176:179], v[18:21], 0
	s_nop 3
	v_mul_f32_e32 v28, v26, v28
	v_mul_f32_e32 v29, v26, v29
	s_waitcnt lgkmcnt(8)
	v_mfma_f32_16x16x32_bf16 v[152:155], v[180:183], v[14:17], v[152:155]
	v_cvt_pk_bf16_f32 v28, v28, v29
	v_mul_f32_e32 v29, v26, v30
	s_waitcnt lgkmcnt(7)
	v_mfma_f32_16x16x32_bf16 v[152:155], v[184:187], v[10:13], v[152:155]
	v_mul_f32_e32 v30, v26, v31
	v_cvt_pk_bf16_f32 v29, v29, v30
	s_waitcnt lgkmcnt(6)
	v_mfma_f32_16x16x32_bf16 v[152:155], v[188:191], v[6:9], v[152:155]
	v_mov_b32_e32 v248, v28
	v_mov_b32_e32 v249, v29
	s_waitcnt lgkmcnt(5)
	v_mfma_f32_16x16x32_bf16 v[152:155], v[172:175], v[2:5], v[152:155]
	v_add_u32_e32 v156, 0x6300, v27
	ds_read2_b64 v[176:179], v156 offset1:4
	ds_read2_b64 v[180:183], v156 offset0:8 offset1:12
	ds_read2_b64 v[184:187], v156 offset0:16 offset1:20
	ds_read2_b64 v[188:191], v156 offset0:24 offset1:28
	ds_read2_b64 v[172:175], v156 offset0:32 offset1:36
	s_waitcnt lgkmcnt(9)
	v_mfma_f32_16x16x32_bf16 v[28:31], v[204:207], v[18:21], 0
	s_nop 3
	v_mul_f32_e32 v152, v26, v152
	v_mul_f32_e32 v153, v26, v153
	s_waitcnt lgkmcnt(8)
	v_mfma_f32_16x16x32_bf16 v[28:31], v[208:211], v[14:17], v[28:31]
	v_cvt_pk_bf16_f32 v152, v152, v153
	v_mul_f32_e32 v153, v26, v154
	s_waitcnt lgkmcnt(7)
	v_mfma_f32_16x16x32_bf16 v[28:31], v[212:215], v[10:13], v[28:31]
	v_mul_f32_e32 v154, v26, v155
	v_cvt_pk_bf16_f32 v153, v153, v154
	s_waitcnt lgkmcnt(6)
	v_mfma_f32_16x16x32_bf16 v[28:31], v[216:219], v[6:9], v[28:31]
	v_mov_b32_e32 v154, v152
	v_mov_b32_e32 v155, v153
	v_mov_b32_e32 v152, v248
	v_mov_b32_e32 v153, v249
	s_waitcnt lgkmcnt(5)
	v_mfma_f32_16x16x32_bf16 v[28:31], v[220:223], v[2:5], v[28:31]
	s_nop 1
	v_permlane16_swap_b32_e32 v152, v154
	v_permlane16_swap_b32_e32 v153, v155
	global_store_dwordx4 v[192:193], v[152:155], off
	s_nop 1
	v_add_u32_e32 v157, 0x8400, v27
	ds_read2_b64 v[204:207], v157 offset1:4
	ds_read2_b64 v[208:211], v157 offset0:8 offset1:12
	ds_read2_b64 v[212:215], v157 offset0:16 offset1:20
	ds_read2_b64 v[216:219], v157 offset0:24 offset1:28
	ds_read2_b64 v[220:223], v157 offset0:32 offset1:36
	s_waitcnt lgkmcnt(9)
	v_mfma_f32_16x16x32_bf16 v[152:155], v[176:179], v[18:21], 0
	s_nop 3
	v_mul_f32_e32 v28, v26, v28
	v_mul_f32_e32 v29, v26, v29
	s_waitcnt lgkmcnt(8)
	v_mfma_f32_16x16x32_bf16 v[152:155], v[180:183], v[14:17], v[152:155]
	v_cvt_pk_bf16_f32 v28, v28, v29
	v_mul_f32_e32 v29, v26, v30
	s_waitcnt lgkmcnt(7)
	v_mfma_f32_16x16x32_bf16 v[152:155], v[184:187], v[10:13], v[152:155]
	v_mul_f32_e32 v30, v26, v31
	v_cvt_pk_bf16_f32 v29, v29, v30
	s_waitcnt lgkmcnt(6)
	v_mfma_f32_16x16x32_bf16 v[152:155], v[188:191], v[6:9], v[152:155]
	v_mov_b32_e32 v248, v28
	v_mov_b32_e32 v249, v29
	s_waitcnt lgkmcnt(5)
	v_mfma_f32_16x16x32_bf16 v[152:155], v[172:175], v[2:5], v[152:155]
	v_add_u32_e32 v156, 0xa500, v27
	ds_read2_b64 v[176:179], v156 offset1:4
	ds_read2_b64 v[180:183], v156 offset0:8 offset1:12
	ds_read2_b64 v[184:187], v156 offset0:16 offset1:20
	ds_read2_b64 v[188:191], v156 offset0:24 offset1:28
	ds_read2_b64 v[172:175], v156 offset0:32 offset1:36
	s_waitcnt lgkmcnt(9)
	v_mfma_f32_16x16x32_bf16 v[28:31], v[204:207], v[18:21], 0
	s_nop 3
	v_mul_f32_e32 v152, v26, v152
	v_mul_f32_e32 v153, v26, v153
	s_waitcnt lgkmcnt(8)
	v_mfma_f32_16x16x32_bf16 v[28:31], v[208:211], v[14:17], v[28:31]
	v_cvt_pk_bf16_f32 v152, v152, v153
	v_mul_f32_e32 v153, v26, v154
	s_waitcnt lgkmcnt(7)
	v_mfma_f32_16x16x32_bf16 v[28:31], v[212:215], v[10:13], v[28:31]
	v_mul_f32_e32 v154, v26, v155
	v_cvt_pk_bf16_f32 v153, v153, v154
	s_waitcnt lgkmcnt(6)
	v_mfma_f32_16x16x32_bf16 v[28:31], v[216:219], v[6:9], v[28:31]
	v_mov_b32_e32 v154, v152
	v_mov_b32_e32 v155, v153
	v_mov_b32_e32 v152, v248
	v_mov_b32_e32 v153, v249
	s_waitcnt lgkmcnt(5)
; #define LAS __attribute__((address_space(3)))
; __device__ __forceinline__ unsigned cvt_pk_bf16(float lo, float hi) { unsigned r; asm volatile("v_cvt_pk_bf16_f32 %0, %1, %2" : "=v"(r) : "v"(lo), "v"(hi)); return r; }
; __device__ __forceinline__ void attn_item(const Params& P, int half, int item, LAS unsigned char* lds, unsigned* ctr) {
;     ...
;     bf16_t* op = Z + (size_t)qrow * ZC + colq + 4 * g;
; #pragma unroll
;     for (int dt = 0; dt < 8; ++dt) {
;         f32x4 O = (f32x4){0.f, 0.f, 0.f, 0.f};
;         const LAS unsigned char* vr = Vt + (dt * 16 + c) * VSTR + (m0 + 4 * g) * 2;
; #pragma unroll
;         for (int k5 = 0; k5 < 5; ++k5) { const u32x2 lo = *(const LAS u32x2*)(vr + k5 * 64), hi = *(const LAS u32x2*)(vr + k5 * 64 + 32);
;             const bf16x8 a = as_bf16x8((u32x4){lo.x, lo.y, hi.x, hi.y}); O = __builtin_amdgcn_mfma_f32_16x16x32_bf16(a, Pf[k5], O, 0, 0, 0); }
;         u32x2 ow; ow.x = cvt_pk_bf16(O[0] * inv, O[1] * inv); ow.y = cvt_pk_bf16(O[2] * inv, O[3] * inv);
;         *(u32x2*)(op + dt * 16) = ow;
;     }
;     if (g == 0) LSE[(size_t)qrow * 12 + gi * 4 + hh] = (mx + __builtin_amdgcn_logf(den)) * 0.6931471805599453f;
;     if (tid == 0) *(LAS unsigned*)(lds + LDS_SLOT) = nxt_id;
;     __syncthreads();
	v_mfma_f32_16x16x32_bf16 v[28:31], v[220:223], v[2:5], v[28:31]
	s_nop 1
	v_permlane16_swap_b32_e32 v152, v154
	v_permlane16_swap_b32_e32 v153, v155
	global_store_dwordx4 v[192:193], v[152:155], off offset:64
	s_nop 1
	v_add_u32_e32 v157, 0xc600, v27
	ds_read2_b64 v[204:207], v157 offset1:4
	ds_read2_b64 v[208:211], v157 offset0:8 offset1:12
	ds_read2_b64 v[212:215], v157 offset0:16 offset1:20
	ds_read2_b64 v[216:219], v157 offset0:24 offset1:28
	ds_read2_b64 v[220:223], v157 offset0:32 offset1:36
	s_waitcnt lgkmcnt(9)
	v_mfma_f32_16x16x32_bf16 v[152:155], v[176:179], v[18:21], 0
	s_nop 3
	v_mul_f32_e32 v28, v26, v28
	v_mul_f32_e32 v29, v26, v29
	s_waitcnt lgkmcnt(8)
	v_mfma_f32_16x16x32_bf16 v[152:155], v[180:183], v[14:17], v[152:155]
	v_cvt_pk_bf16_f32 v28, v28, v29
	v_mul_f32_e32 v29, v26, v30
	s_waitcnt lgkmcnt(7)
	v_mfma_f32_16x16x32_bf16 v[152:155], v[184:187], v[10:13], v[152:155]
	v_mul_f32_e32 v30, v26, v31
	v_cvt_pk_bf16_f32 v29, v29, v30
	s_waitcnt lgkmcnt(6)
	v_mfma_f32_16x16x32_bf16 v[152:155], v[188:191], v[6:9], v[152:155]
	v_mov_b32_e32 v248, v28
	v_mov_b32_e32 v249, v29
	s_waitcnt lgkmcnt(5)
	v_mfma_f32_16x16x32_bf16 v[152:155], v[172:175], v[2:5], v[152:155]
	v_add_u32_e32 v156, 0xe700, v27
	ds_read2_b64 v[176:179], v156 offset1:4
	ds_read2_b64 v[180:183], v156 offset0:8 offset1:12
	ds_read2_b64 v[184:187], v156 offset0:16 offset1:20
	ds_read2_b64 v[188:191], v156 offset0:24 offset1:28
	ds_read2_b64 v[172:175], v156 offset0:32 offset1:36
	s_waitcnt lgkmcnt(9)
	v_mfma_f32_16x16x32_bf16 v[28:31], v[204:207], v[18:21], 0
	s_nop 3
	v_mul_f32_e32 v152, v26, v152
	v_mul_f32_e32 v153, v26, v153
	s_waitcnt lgkmcnt(8)
	v_mfma_f32_16x16x32_bf16 v[28:31], v[208:211], v[14:17], v[28:31]
	v_cvt_pk_bf16_f32 v152, v152, v153
	v_mul_f32_e32 v153, v26, v154
	s_waitcnt lgkmcnt(7)
	v_mfma_f32_16x16x32_bf16 v[28:31], v[212:215], v[10:13], v[28:31]
	v_mul_f32_e32 v154, v26, v155
	v_cvt_pk_bf16_f32 v153, v153, v154
	s_waitcnt lgkmcnt(6)
	v_mfma_f32_16x16x32_bf16 v[28:31], v[216:219], v[6:9], v[28:31]
	v_mov_b32_e32 v154, v152
	v_mov_b32_e32 v155, v153
	v_mov_b32_e32 v152, v248
	v_mov_b32_e32 v153, v249
	s_waitcnt lgkmcnt(5)
	v_mfma_f32_16x16x32_bf16 v[28:31], v[220:223], v[2:5], v[28:31]
	s_nop 1
	v_permlane16_swap_b32_e32 v152, v154
	v_permlane16_swap_b32_e32 v153, v155
	global_store_dwordx4 v[192:193], v[152:155], off offset:128
	s_nop 1
	s_waitcnt lgkmcnt(4)
	v_mfma_f32_16x16x32_bf16 v[152:155], v[176:179], v[18:21], 0
	s_nop 3
	v_mul_f32_e32 v28, v26, v28
	v_mul_f32_e32 v29, v26, v29
	s_waitcnt lgkmcnt(3)
	v_mfma_f32_16x16x32_bf16 v[152:155], v[180:183], v[14:17], v[152:155]
	v_cvt_pk_bf16_f32 v28, v28, v29
	v_mul_f32_e32 v29, v26, v30
	s_waitcnt lgkmcnt(2)
	v_mfma_f32_16x16x32_bf16 v[152:155], v[184:187], v[10:13], v[152:155]
	v_mul_f32_e32 v30, v26, v31
	v_cvt_pk_bf16_f32 v29, v29, v30
	s_waitcnt lgkmcnt(1)
	v_mfma_f32_16x16x32_bf16 v[152:155], v[188:191], v[6:9], v[152:155]
	v_mov_b32_e32 v248, v28
	v_mov_b32_e32 v249, v29
	s_waitcnt lgkmcnt(0)
	v_mfma_f32_16x16x32_bf16 v[152:155], v[172:175], v[2:5], v[152:155]
	s_nop 7
	s_nop 3
	v_mul_f32_e32 v152, v26, v152
	v_mul_f32_e32 v153, v26, v153
	v_cvt_pk_bf16_f32 v152, v152, v153
	v_mul_f32_e32 v153, v26, v154
	v_mul_f32_e32 v154, v26, v155
	v_cvt_pk_bf16_f32 v153, v153, v154
	v_mov_b32_e32 v154, v152
	v_mov_b32_e32 v155, v153
	v_mov_b32_e32 v152, v248
	v_mov_b32_e32 v153, v249
	s_nop 1
	v_permlane16_swap_b32_e32 v152, v154
	v_permlane16_swap_b32_e32 v153, v155
	global_store_dwordx4 v[192:193], v[152:155], off offset:192
	s_nop 1
	s_and_saveexec_b64 s[30:31], vcc
	s_cbranch_execz .LBB0_541
	v_log_f32_e32 v2, v25
	v_readlane_b32 s8, v251, 33
	s_lshl_b32 s6, s2, 2
	v_readlane_b32 s9, v251, 34
	v_add_f32_e32 v2, v24, v2
	s_ashr_i32 s7, s6, 31
	v_mul_f32_e32 v4, 0x3f317218, v2
	v_mad_i64_i32 v[2:3], s[8:9], v133, 48, s[8:9]
	v_lshl_add_u64 v[2:3], s[6:7], 2, v[2:3]
	s_lshl_b32 s20, s4, 2
	v_lshl_add_u64 v[2:3], v[2:3], 0, s[20:21]
	global_store_dword v[2:3], v4, off
.LBB0_541:
	s_or_b64 exec, exec, s[30:31]
	s_and_saveexec_b64 s[30:31], s[36:37]
	s_cbranch_execz .LBB0_516
	v_readlane_b32 s2, v255, 15
	s_nop 1
	v_mov_b32_e32 v2, s2
	s_waitcnt vmcnt(4)
	v_add_u32_e32 v135, s94, v135
	ds_write_b32 v2, v135
	s_branch .LBB0_516

; #define PG8_STAGE(bufoff, gbase, voff) do { _Pragma("unroll") for (int _i = 0; _i < 2; ++_i) \
;         __builtin_amdgcn_global_load_lds((const unsigned*)((const char*)(gbase) + (voff)[_i]), (LAS unsigned*)(lds + (bufoff) + ldsw + _i * 8192), 16, 0, 0); } while (0)
; #define PG8_LDA(dst, b, h) do { _Pragma("unroll") for (int m = 0; m < 4; ++m) _Pragma("unroll") for (int k = 0; k < 2; ++k) dst[m][k] = *(const LAS bf16x8*)(lds + PG8_SA(b, h) + aoff + m * 2048 + k * 1024); } while (0)
; #define PG8_LDB(dst, b, h) do { _Pragma("unroll") for (int n = 0; n < 2; ++n) _Pragma("unroll") for (int k = 0; k < 2; ++k) dst[n][k] = *(const LAS bf16x8*)(lds + PG8_SB(b, h) + boff + n * 2048 + k * 1024); } while (0)
; #define PG8_MMA(ai, bj, At, Bt) do { __builtin_amdgcn_s_setprio(1); _Pragma("unroll") for (int m = 0; m < 4; ++m) _Pragma("unroll") for (int n = 0; n < 2; ++n) _Pragma("unroll") for (int k = 0; k < 2; ++k) \
;         acc[ai][bj][m][n] = __builtin_amdgcn_mfma_f32_16x16x32_bf16(Bt[n][k], At[m][k], acc[ai][bj][m][n], 0, 0, 0); __builtin_amdgcn_s_setprio(0); } while (0)
; #define PG8_WAIT_V(n) asm volatile("s_waitcnt vmcnt(" #n ")" ::: "memory")
; #define PG8_WAIT_L(n) asm volatile("s_waitcnt lgkmcnt(" #n ")" ::: "memory")
; #define PG8_BAR __builtin_amdgcn_s_barrier()
; #define PG8_SCHED __builtin_amdgcn_sched_barrier(0)
; template <class Epi>
; __device__ __forceinline__ void gemm_phase(LAS unsigned char* lds, const Gemm g, const Order& S, const Epi& E) {
;     ...
;         for (int t = 0; t < nt; t += 2) {
;             const bool last = (t == nt - 2);
;             const char* a1 = cA + (size_t)(t + 1) * kstep;
;             const char* a2 = last ? nA : cA + (size_t)(t + 2) * kstep; const char* b2 = last ? nB : cB + (size_t)(t + 2) * kstep;
;             const char* a3 = a2 + kstep; const char* b3 = b2 + kstep;
;             PG8_LDB(B0, 0, 0); PG8_LDB(B1, 0, 1); PG8_SCHED; PG8_LDA(At, 0, 0); PG8_STAGE(PG8_SA(1, 1), a1 + hstepA, voffA);
;             PG8_WAIT_V(8); PG8_WAIT_L(0); PG8_BAR; PG8_MMA(0, 0, At, B0); PG8_MMA(0, 1, At, B1); PG8_BAR; PG8_SCHED;
;             PG8_LDA(At, 0, 1); PG8_STAGE(PG8_SB(0, 0), b2, voffB); PG8_STAGE(PG8_SB(0, 1), b2 + hstepB, voffB); PG8_STAGE(PG8_SA(0, 0), a2, voffA);
;             PG8_WAIT_V(8); PG8_WAIT_L(0); PG8_BAR; PG8_MMA(1, 0, At, B0); PG8_MMA(1, 1, At, B1); PG8_BAR; PG8_SCHED;
.LBB0_554:
	s_add_u32 s47, s38, 0xfffc0080
	s_addc_u32 s50, s39, -1
	s_add_i32 s54, 0, 0x10000
	s_cmp_eq_u32 s45, 12
	s_cselect_b32 s53, s15, s50
	s_cselect_b32 s52, s16, s47
	s_cselect_b32 s51, s17, s20
	s_cselect_b32 s50, s18, s19
	s_add_i32 s47, 0, 0x14000
	v_add_u32_e32 v86, s54, v163
	v_add_u32_e32 v160, s47, v163
	ds_read_b128 v[66:69], v86
	ds_read_b128 v[74:77], v86 offset:1024
	ds_read_b128 v[82:85], v86 offset:2048
	ds_read_b128 v[86:89], v86 offset:3072
	ds_read_b128 v[156:159], v160
	ds_read_b128 v[166:169], v160 offset:1024
	ds_read_b128 v[170:173], v160 offset:2048
	ds_read_b128 v[174:177], v160 offset:3072
	v_lshl_add_u64 v[160:161], s[38:39], 0, v[152:153]
	s_add_i32 m0, s6, 0xc000
	ds_read_b128 v[178:181], v165
	ds_read_b128 v[182:185], v165 offset:1024
	ds_read_b128 v[186:189], v165 offset:2048
	ds_read_b128 v[190:193], v165 offset:3072
	ds_read_b128 v[204:207], v165 offset:4096
	ds_read_b128 v[208:211], v165 offset:5120
	ds_read_b128 v[212:215], v165 offset:6144
	ds_read_b128 v[216:219], v165 offset:7168
	global_load_lds_dwordx4 v[160:161], off
	v_lshl_add_u64 v[160:161], s[38:39], 0, v[154:155]
	s_add_i32 m0, s6, 0xe000
	s_nop 0
	global_load_lds_dwordx4 v[160:161], off
	s_waitcnt vmcnt(8)
	s_waitcnt lgkmcnt(0)
	s_barrier
	s_setprio 1
	v_mfma_f32_16x16x32_bf16 v[142:145], v[66:69], v[178:181], v[142:145]
	v_mfma_f32_16x16x32_bf16 v[138:141], v[82:85], v[178:181], v[138:141]
	v_mfma_f32_16x16x32_bf16 v[126:129], v[66:69], v[186:189], v[126:129]
	v_mfma_f32_16x16x32_bf16 v[122:125], v[82:85], v[186:189], v[122:125]
	v_mfma_f32_16x16x32_bf16 v[110:113], v[66:69], v[204:207], v[110:113]
	v_mfma_f32_16x16x32_bf16 v[106:109], v[82:85], v[204:207], v[106:109]
	v_mfma_f32_16x16x32_bf16 v[94:97], v[66:69], v[212:215], v[94:97]
	v_mfma_f32_16x16x32_bf16 v[90:93], v[82:85], v[212:215], v[90:93]
	v_mfma_f32_16x16x32_bf16 v[142:145], v[74:77], v[182:185], v[142:145]
	v_mfma_f32_16x16x32_bf16 v[138:141], v[86:89], v[182:185], v[138:141]
	v_mfma_f32_16x16x32_bf16 v[126:129], v[74:77], v[190:193], v[126:129]
	v_mfma_f32_16x16x32_bf16 v[122:125], v[86:89], v[190:193], v[122:125]
	v_mfma_f32_16x16x32_bf16 v[110:113], v[74:77], v[208:211], v[110:113]
	v_mfma_f32_16x16x32_bf16 v[106:109], v[86:89], v[208:211], v[106:109]
	v_mfma_f32_16x16x32_bf16 v[94:97], v[74:77], v[216:219], v[94:97]
	v_mfma_f32_16x16x32_bf16 v[90:93], v[86:89], v[216:219], v[90:93]
	s_setprio 0
	s_setprio 1
	v_mfma_f32_16x16x32_bf16 v[134:137], v[156:159], v[178:181], v[134:137]
	v_mfma_f32_16x16x32_bf16 v[130:133], v[170:173], v[178:181], v[130:133]
	v_mfma_f32_16x16x32_bf16 v[118:121], v[156:159], v[186:189], v[118:121]
	v_mfma_f32_16x16x32_bf16 v[114:117], v[170:173], v[186:189], v[114:117]
	v_mfma_f32_16x16x32_bf16 v[102:105], v[156:159], v[204:207], v[102:105]
	v_mfma_f32_16x16x32_bf16 v[98:101], v[170:173], v[204:207], v[98:101]
	v_mfma_f32_16x16x32_bf16 v[78:81], v[156:159], v[212:215], v[78:81]
	v_mfma_f32_16x16x32_bf16 v[70:73], v[170:173], v[212:215], v[70:73]
	v_mfma_f32_16x16x32_bf16 v[134:137], v[166:169], v[182:185], v[134:137]
	v_mfma_f32_16x16x32_bf16 v[130:133], v[174:177], v[182:185], v[130:133]
	v_mfma_f32_16x16x32_bf16 v[118:121], v[166:169], v[190:193], v[118:121]
	v_mfma_f32_16x16x32_bf16 v[114:117], v[174:177], v[190:193], v[114:117]
	v_mfma_f32_16x16x32_bf16 v[102:105], v[166:169], v[208:211], v[102:105]
	v_mfma_f32_16x16x32_bf16 v[98:101], v[174:177], v[208:211], v[98:101]
	v_mfma_f32_16x16x32_bf16 v[78:81], v[166:169], v[216:219], v[78:81]
	v_mfma_f32_16x16x32_bf16 v[70:73], v[174:177], v[216:219], v[70:73]
	s_setprio 0
	s_barrier
	s_add_i32 s54, s54, s5
	v_lshl_add_u64 v[160:161], s[50:51], 0, v[150:151]
	s_mov_b32 m0, s54
	ds_read_b128 v[178:181], v165 offset:16384
	ds_read_b128 v[182:185], v165 offset:17408
	ds_read_b128 v[186:189], v165 offset:18432
	ds_read_b128 v[190:193], v165 offset:19456
	ds_read_b128 v[204:207], v165 offset:20480
	ds_read_b128 v[208:211], v165 offset:21504
	ds_read_b128 v[212:215], v165 offset:22528
	ds_read_b128 v[216:219], v165 offset:23552
	global_load_lds_dwordx4 v[160:161], off
	s_add_i32 m0, s54, 0x2000
	s_add_u32 s54, s50, 0x40000
	v_lshl_add_u64 v[220:221], s[50:51], 0, v[146:147]
	s_addc_u32 s55, s51, 0
	s_add_i32 s47, s47, s5
	global_load_lds_dwordx4 v[220:221], off
	v_lshl_add_u64 v[222:223], s[54:55], 0, v[150:151]
	s_mov_b32 m0, s47
	v_lshl_add_u64 v[224:225], s[52:53], 0, v[148:149]
	global_load_lds_dwordx4 v[222:223], off
	v_lshl_add_u64 v[222:223], s[54:55], 0, v[146:147]
	s_add_i32 m0, s47, 0x2000
	s_nop 0
	global_load_lds_dwordx4 v[222:223], off
	v_lshl_add_u64 v[222:223], s[52:53], 0, v[194:195]
	s_mov_b32 m0, s6
	s_nop 0
	global_load_lds_dwordx4 v[222:223], off
	s_mov_b32 m0, s7
	s_nop 0
	global_load_lds_dwordx4 v[224:225], off
	s_waitcnt vmcnt(8)
	s_waitcnt lgkmcnt(0)
	s_barrier
; #define PG8_STAGE(bufoff, gbase, voff) do { _Pragma("unroll") for (int _i = 0; _i < 2; ++_i) \
;         __builtin_amdgcn_global_load_lds((const unsigned*)((const char*)(gbase) + (voff)[_i]), (LAS unsigned*)(lds + (bufoff) + ldsw + _i * 8192), 16, 0, 0); } while (0)
; #define PG8_LDA(dst, b, h) do { _Pragma("unroll") for (int m = 0; m < 4; ++m) _Pragma("unroll") for (int k = 0; k < 2; ++k) dst[m][k] = *(const LAS bf16x8*)(lds + PG8_SA(b, h) + aoff + m * 2048 + k * 1024); } while (0)
; #define PG8_LDB(dst, b, h) do { _Pragma("unroll") for (int n = 0; n < 2; ++n) _Pragma("unroll") for (int k = 0; k < 2; ++k) dst[n][k] = *(const LAS bf16x8*)(lds + PG8_SB(b, h) + boff + n * 2048 + k * 1024); } while (0)
; #define PG8_MMA(ai, bj, At, Bt) do { __builtin_amdgcn_s_setprio(1); _Pragma("unroll") for (int m = 0; m < 4; ++m) _Pragma("unroll") for (int n = 0; n < 2; ++n) _Pragma("unroll") for (int k = 0; k < 2; ++k) \
;         acc[ai][bj][m][n] = __builtin_amdgcn_mfma_f32_16x16x32_bf16(Bt[n][k], At[m][k], acc[ai][bj][m][n], 0, 0, 0); __builtin_amdgcn_s_setprio(0); } while (0)
; #define PG8_WAIT_V(n) asm volatile("s_waitcnt vmcnt(" #n ")" ::: "memory")
; #define PG8_WAIT_L(n) asm volatile("s_waitcnt lgkmcnt(" #n ")" ::: "memory")
; #define PG8_BAR __builtin_amdgcn_s_barrier()
; #define PG8_SCHED __builtin_amdgcn_sched_barrier(0)
; template <class Epi>
; __device__ __forceinline__ void gemm_phase(LAS unsigned char* lds, const Gemm g, const Order& S, const Epi& E) {
;     ...
;             PG8_WAIT_V(8); PG8_WAIT_L(0); PG8_BAR; PG8_MMA(1, 0, At, B0); PG8_MMA(1, 1, At, B1); PG8_BAR; PG8_SCHED;
;             PG8_LDB(B0, 1, 0); PG8_LDB(B1, 1, 1); PG8_SCHED; PG8_LDA(At, 1, 0); PG8_STAGE(PG8_SA(0, 1), a2 + hstepA, voffA);
;             PG8_WAIT_V(8); PG8_WAIT_L(0); PG8_BAR; PG8_MMA(0, 0, At, B0); PG8_MMA(0, 1, At, B1); PG8_BAR; PG8_SCHED;
;             PG8_LDA(At, 1, 1); PG8_STAGE(PG8_SB(1, 0), b3, voffB); PG8_STAGE(PG8_SB(1, 1), b3 + hstepB, voffB); PG8_STAGE(PG8_SA(1, 0), a3, voffA);
;             PG8_WAIT_V(8); PG8_WAIT_L(0); PG8_BAR; PG8_MMA(1, 0, At, B0); PG8_MMA(1, 1, At, B1); PG8_BAR; PG8_SCHED;
	s_setprio 1
	v_mfma_f32_16x16x32_bf16 v[62:65], v[66:69], v[178:181], v[62:65]
	v_mfma_f32_16x16x32_bf16 v[58:61], v[82:85], v[178:181], v[58:61]
	v_mfma_f32_16x16x32_bf16 v[46:49], v[66:69], v[186:189], v[46:49]
	v_mfma_f32_16x16x32_bf16 v[42:45], v[82:85], v[186:189], v[42:45]
	v_mfma_f32_16x16x32_bf16 v[30:33], v[66:69], v[204:207], v[30:33]
	v_mfma_f32_16x16x32_bf16 v[26:29], v[82:85], v[204:207], v[26:29]
	v_mfma_f32_16x16x32_bf16 v[14:17], v[66:69], v[212:215], v[14:17]
	v_mfma_f32_16x16x32_bf16 v[10:13], v[82:85], v[212:215], v[10:13]
	v_mfma_f32_16x16x32_bf16 v[62:65], v[74:77], v[182:185], v[62:65]
	v_mfma_f32_16x16x32_bf16 v[58:61], v[86:89], v[182:185], v[58:61]
	v_mfma_f32_16x16x32_bf16 v[46:49], v[74:77], v[190:193], v[46:49]
	v_mfma_f32_16x16x32_bf16 v[42:45], v[86:89], v[190:193], v[42:45]
	v_mfma_f32_16x16x32_bf16 v[30:33], v[74:77], v[208:211], v[30:33]
	v_mfma_f32_16x16x32_bf16 v[26:29], v[86:89], v[208:211], v[26:29]
	v_mfma_f32_16x16x32_bf16 v[14:17], v[74:77], v[216:219], v[14:17]
	v_mfma_f32_16x16x32_bf16 v[10:13], v[86:89], v[216:219], v[10:13]
	s_setprio 0
	s_setprio 1
	v_mfma_f32_16x16x32_bf16 v[54:57], v[156:159], v[178:181], v[54:57]
	v_mfma_f32_16x16x32_bf16 v[50:53], v[170:173], v[178:181], v[50:53]
	v_mfma_f32_16x16x32_bf16 v[38:41], v[156:159], v[186:189], v[38:41]
	v_mfma_f32_16x16x32_bf16 v[34:37], v[170:173], v[186:189], v[34:37]
	v_mfma_f32_16x16x32_bf16 v[22:25], v[156:159], v[204:207], v[22:25]
	v_mfma_f32_16x16x32_bf16 v[18:21], v[170:173], v[204:207], v[18:21]
	v_mfma_f32_16x16x32_bf16 v[6:9], v[156:159], v[212:215], v[6:9]
	v_mfma_f32_16x16x32_bf16 v[2:5], v[170:173], v[212:215], v[2:5]
	v_mfma_f32_16x16x32_bf16 v[54:57], v[166:169], v[182:185], v[54:57]
	v_mfma_f32_16x16x32_bf16 v[50:53], v[174:177], v[182:185], v[50:53]
	v_mfma_f32_16x16x32_bf16 v[38:41], v[166:169], v[190:193], v[38:41]
	v_mfma_f32_16x16x32_bf16 v[34:37], v[174:177], v[190:193], v[34:37]
	v_mfma_f32_16x16x32_bf16 v[22:25], v[166:169], v[208:211], v[22:25]
	v_mfma_f32_16x16x32_bf16 v[18:21], v[174:177], v[208:211], v[18:21]
	v_mfma_f32_16x16x32_bf16 v[6:9], v[166:169], v[216:219], v[6:9]
	v_mfma_f32_16x16x32_bf16 v[2:5], v[174:177], v[216:219], v[2:5]
	s_setprio 0
	s_barrier
	s_add_i32 s47, 0, 0x18000
	s_add_i32 s54, 0, 0x1c000
	v_add_u32_e32 v86, s47, v163
	v_add_u32_e32 v174, s54, v163
	ds_read_b128 v[66:69], v86
	ds_read_b128 v[74:77], v86 offset:1024
	ds_read_b128 v[82:85], v86 offset:2048
	ds_read_b128 v[86:89], v86 offset:3072
	ds_read_b128 v[156:159], v174
	ds_read_b128 v[166:169], v174 offset:1024
	ds_read_b128 v[170:173], v174 offset:2048
	ds_read_b128 v[174:177], v174 offset:3072
	s_add_u32 s52, s52, 0x40000
	s_addc_u32 s53, s53, 0
	s_mov_b32 m0, s8
	v_lshl_add_u64 v[226:227], s[52:53], 0, v[194:195]
	ds_read_b128 v[178:181], v165 offset:32768
	ds_read_b128 v[182:185], v165 offset:33792
	ds_read_b128 v[186:189], v165 offset:34816
	ds_read_b128 v[190:193], v165 offset:35840
	ds_read_b128 v[204:207], v165 offset:36864
	ds_read_b128 v[208:211], v165 offset:37888
	ds_read_b128 v[212:215], v165 offset:38912
	ds_read_b128 v[216:219], v165 offset:39936
	global_load_lds_dwordx4 v[226:227], off
	v_lshl_add_u64 v[226:227], s[52:53], 0, v[148:149]
	s_mov_b32 m0, s9
	s_nop 0
	global_load_lds_dwordx4 v[226:227], off
	s_waitcnt vmcnt(8)
	s_waitcnt lgkmcnt(0)
	s_barrier
	s_setprio 1
	v_mfma_f32_16x16x32_bf16 v[142:145], v[66:69], v[178:181], v[142:145]
	v_mfma_f32_16x16x32_bf16 v[138:141], v[82:85], v[178:181], v[138:141]
	v_mfma_f32_16x16x32_bf16 v[126:129], v[66:69], v[186:189], v[126:129]
	v_mfma_f32_16x16x32_bf16 v[122:125], v[82:85], v[186:189], v[122:125]
	v_mfma_f32_16x16x32_bf16 v[110:113], v[66:69], v[204:207], v[110:113]
	v_mfma_f32_16x16x32_bf16 v[106:109], v[82:85], v[204:207], v[106:109]
	v_mfma_f32_16x16x32_bf16 v[94:97], v[66:69], v[212:215], v[94:97]
	v_mfma_f32_16x16x32_bf16 v[90:93], v[82:85], v[212:215], v[90:93]
	v_mfma_f32_16x16x32_bf16 v[142:145], v[74:77], v[182:185], v[142:145]
	v_mfma_f32_16x16x32_bf16 v[138:141], v[86:89], v[182:185], v[138:141]
	v_mfma_f32_16x16x32_bf16 v[126:129], v[74:77], v[190:193], v[126:129]
	v_mfma_f32_16x16x32_bf16 v[122:125], v[86:89], v[190:193], v[122:125]
	v_mfma_f32_16x16x32_bf16 v[110:113], v[74:77], v[208:211], v[110:113]
	v_mfma_f32_16x16x32_bf16 v[106:109], v[86:89], v[208:211], v[106:109]
	v_mfma_f32_16x16x32_bf16 v[94:97], v[74:77], v[216:219], v[94:97]
	v_mfma_f32_16x16x32_bf16 v[90:93], v[86:89], v[216:219], v[90:93]
	s_setprio 0
	s_setprio 1
	v_mfma_f32_16x16x32_bf16 v[134:137], v[156:159], v[178:181], v[134:137]
	v_mfma_f32_16x16x32_bf16 v[130:133], v[170:173], v[178:181], v[130:133]
	v_mfma_f32_16x16x32_bf16 v[118:121], v[156:159], v[186:189], v[118:121]
	v_mfma_f32_16x16x32_bf16 v[114:117], v[170:173], v[186:189], v[114:117]
	v_mfma_f32_16x16x32_bf16 v[102:105], v[156:159], v[204:207], v[102:105]
	v_mfma_f32_16x16x32_bf16 v[98:101], v[170:173], v[204:207], v[98:101]
	v_mfma_f32_16x16x32_bf16 v[78:81], v[156:159], v[212:215], v[78:81]
	v_mfma_f32_16x16x32_bf16 v[70:73], v[170:173], v[212:215], v[70:73]
	v_mfma_f32_16x16x32_bf16 v[134:137], v[166:169], v[182:185], v[134:137]
	v_mfma_f32_16x16x32_bf16 v[130:133], v[174:177], v[182:185], v[130:133]
	v_mfma_f32_16x16x32_bf16 v[118:121], v[166:169], v[190:193], v[118:121]
	v_mfma_f32_16x16x32_bf16 v[114:117], v[174:177], v[190:193], v[114:117]
	v_mfma_f32_16x16x32_bf16 v[102:105], v[166:169], v[208:211], v[102:105]
	v_mfma_f32_16x16x32_bf16 v[98:101], v[174:177], v[208:211], v[98:101]
	v_mfma_f32_16x16x32_bf16 v[78:81], v[166:169], v[216:219], v[78:81]
	v_mfma_f32_16x16x32_bf16 v[70:73], v[174:177], v[216:219], v[70:73]
	s_setprio 0
	s_barrier
; #define PG8_STAGE(bufoff, gbase, voff) do { _Pragma("unroll") for (int _i = 0; _i < 2; ++_i) \
;         __builtin_amdgcn_global_load_lds((const unsigned*)((const char*)(gbase) + (voff)[_i]), (LAS unsigned*)(lds + (bufoff) + ldsw + _i * 8192), 16, 0, 0); } while (0)
; #define PG8_LDA(dst, b, h) do { _Pragma("unroll") for (int m = 0; m < 4; ++m) _Pragma("unroll") for (int k = 0; k < 2; ++k) dst[m][k] = *(const LAS bf16x8*)(lds + PG8_SA(b, h) + aoff + m * 2048 + k * 1024); } while (0)
; #define PG8_MMA(ai, bj, At, Bt) do { __builtin_amdgcn_s_setprio(1); _Pragma("unroll") for (int m = 0; m < 4; ++m) _Pragma("unroll") for (int n = 0; n < 2; ++n) _Pragma("unroll") for (int k = 0; k < 2; ++k) \
;         acc[ai][bj][m][n] = __builtin_amdgcn_mfma_f32_16x16x32_bf16(Bt[n][k], At[m][k], acc[ai][bj][m][n], 0, 0, 0); __builtin_amdgcn_s_setprio(0); } while (0)
; #define PG8_WAIT_V(n) asm volatile("s_waitcnt vmcnt(" #n ")" ::: "memory")
; #define PG8_WAIT_L(n) asm volatile("s_waitcnt lgkmcnt(" #n ")" ::: "memory")
; #define PG8_BAR __builtin_amdgcn_s_barrier()
; #define PG8_SCHED __builtin_amdgcn_sched_barrier(0)
; template <class Epi>
; __device__ __forceinline__ void gemm_phase(LAS unsigned char* lds, const Gemm g, const Order& S, const Epi& E) {
;     ...
;             PG8_LDA(At, 1, 1); PG8_STAGE(PG8_SB(1, 0), b3, voffB); PG8_STAGE(PG8_SB(1, 1), b3 + hstepB, voffB); PG8_STAGE(PG8_SA(1, 0), a3, voffA);
;             PG8_WAIT_V(8); PG8_WAIT_L(0); PG8_BAR; PG8_MMA(1, 0, At, B0); PG8_MMA(1, 1, At, B1); PG8_BAR; PG8_SCHED;
;         }
	s_add_i32 s47, s47, s5
	v_lshl_add_u64 v[160:161], v[160:161], 0, s[86:87]
	s_mov_b32 m0, s47
	ds_read_b128 v[178:181], v165 offset:49152
	ds_read_b128 v[182:185], v165 offset:50176
	ds_read_b128 v[186:189], v165 offset:51200
	ds_read_b128 v[190:193], v165 offset:52224
	ds_read_b128 v[204:207], v165 offset:53248
	ds_read_b128 v[208:211], v165 offset:54272
	ds_read_b128 v[212:215], v165 offset:55296
	ds_read_b128 v[216:219], v165 offset:56320
	global_load_lds_dwordx4 v[160:161], off
	s_add_i32 m0, s47, 0x2000
	s_add_u32 s50, s50, 0x40080
	v_lshl_add_u64 v[160:161], v[220:221], 0, s[86:87]
	s_addc_u32 s51, s51, 0
	s_add_i32 s47, s54, s5
	global_load_lds_dwordx4 v[160:161], off
	v_lshl_add_u64 v[160:161], s[50:51], 0, v[150:151]
	s_mov_b32 m0, s47
	s_nop 0
	global_load_lds_dwordx4 v[160:161], off
	v_lshl_add_u64 v[160:161], s[50:51], 0, v[146:147]
	s_add_i32 m0, s47, 0x2000
	s_nop 0
	global_load_lds_dwordx4 v[160:161], off
	v_lshl_add_u64 v[160:161], v[222:223], 0, s[86:87]
	s_mov_b32 m0, s10
	s_nop 0
	global_load_lds_dwordx4 v[160:161], off
	v_lshl_add_u64 v[160:161], v[224:225], 0, s[86:87]
	s_mov_b32 m0, s11
	s_nop 0
	global_load_lds_dwordx4 v[160:161], off
	s_waitcnt vmcnt(8)
	s_waitcnt lgkmcnt(0)
	s_barrier
	s_setprio 1
	v_mfma_f32_16x16x32_bf16 v[62:65], v[66:69], v[178:181], v[62:65]
	v_mfma_f32_16x16x32_bf16 v[58:61], v[82:85], v[178:181], v[58:61]
	v_mfma_f32_16x16x32_bf16 v[46:49], v[66:69], v[186:189], v[46:49]
	v_mfma_f32_16x16x32_bf16 v[42:45], v[82:85], v[186:189], v[42:45]
	v_mfma_f32_16x16x32_bf16 v[30:33], v[66:69], v[204:207], v[30:33]
	v_mfma_f32_16x16x32_bf16 v[26:29], v[82:85], v[204:207], v[26:29]
	v_mfma_f32_16x16x32_bf16 v[14:17], v[66:69], v[212:215], v[14:17]
	v_mfma_f32_16x16x32_bf16 v[10:13], v[82:85], v[212:215], v[10:13]
	v_mfma_f32_16x16x32_bf16 v[62:65], v[74:77], v[182:185], v[62:65]
	v_mfma_f32_16x16x32_bf16 v[58:61], v[86:89], v[182:185], v[58:61]
	v_mfma_f32_16x16x32_bf16 v[46:49], v[74:77], v[190:193], v[46:49]
	v_mfma_f32_16x16x32_bf16 v[42:45], v[86:89], v[190:193], v[42:45]
	v_mfma_f32_16x16x32_bf16 v[30:33], v[74:77], v[208:211], v[30:33]
	v_mfma_f32_16x16x32_bf16 v[26:29], v[86:89], v[208:211], v[26:29]
	v_mfma_f32_16x16x32_bf16 v[14:17], v[74:77], v[216:219], v[14:17]
	v_mfma_f32_16x16x32_bf16 v[10:13], v[86:89], v[216:219], v[10:13]
	s_setprio 0
	s_setprio 1
	v_mfma_f32_16x16x32_bf16 v[54:57], v[156:159], v[178:181], v[54:57]
	v_mfma_f32_16x16x32_bf16 v[50:53], v[170:173], v[178:181], v[50:53]
	v_mfma_f32_16x16x32_bf16 v[38:41], v[156:159], v[186:189], v[38:41]
	v_mfma_f32_16x16x32_bf16 v[34:37], v[170:173], v[186:189], v[34:37]
	v_mfma_f32_16x16x32_bf16 v[22:25], v[156:159], v[204:207], v[22:25]
	v_mfma_f32_16x16x32_bf16 v[18:21], v[170:173], v[204:207], v[18:21]
	v_mfma_f32_16x16x32_bf16 v[6:9], v[156:159], v[212:215], v[6:9]
	v_mfma_f32_16x16x32_bf16 v[2:5], v[170:173], v[212:215], v[2:5]
	v_mfma_f32_16x16x32_bf16 v[54:57], v[166:169], v[182:185], v[54:57]
	v_mfma_f32_16x16x32_bf16 v[50:53], v[174:177], v[182:185], v[50:53]
	v_mfma_f32_16x16x32_bf16 v[38:41], v[166:169], v[190:193], v[38:41]
	v_mfma_f32_16x16x32_bf16 v[34:37], v[174:177], v[190:193], v[34:37]
	v_mfma_f32_16x16x32_bf16 v[22:25], v[166:169], v[208:211], v[22:25]
	v_mfma_f32_16x16x32_bf16 v[18:21], v[174:177], v[208:211], v[18:21]
	v_mfma_f32_16x16x32_bf16 v[6:9], v[166:169], v[216:219], v[6:9]
	v_mfma_f32_16x16x32_bf16 v[2:5], v[174:177], v[216:219], v[2:5]
	s_setprio 0
	s_barrier
	s_add_i32 s45, s45, 2
	s_add_u32 s38, s38, 0x100
	s_addc_u32 s39, s39, 0
	s_add_u32 s19, s19, 0x100
	s_addc_u32 s20, s20, 0
	s_cmp_gt_u32 s45, 13
	s_cbranch_scc0 .LBB0_554
	s_and_b64 vcc, exec, s[42:43]
	s_cbranch_vccz .LBB0_557
	s_barrier

; __device__ __forceinline__ float bflo(unsigned w) { return __uint_as_float(w << 16); }
; __device__ __forceinline__ float bfhi(unsigned w) { return __uint_as_float(w & 0xffff0000u); }
; __device__ void phase_resid(const float* xin, float* xout, const bf16_t* Y, const float* pg, const float* ng, bf16_t* H2, int nrows) {
;     ...
;     for (; row < nrows; row += stride) {
;         f32x4 y[4], xv[4];
; #pragma unroll
;         for (int i = 0; i < 4; ++i) { y[i] = (f32x4){bflo(ny[i].x), bfhi(ny[i].x), bflo(ny[i].y), bfhi(ny[i].y)}; xv[i] = nx[i]; }
;         const int rn = row + stride;
;         if (rn < nrows) {
; #pragma unroll
;             for (int i = 0; i < 4; ++i) { ny[i] = *(const u32x2*)(Y + (size_t)rn * DM + i * 256 + lane * 4); nx[i] = *(const f32x4*)(xin + (size_t)rn * DM + i * 256 + lane * 4); }
;         }
;         float ss = 0.f;
; #pragma unroll
;         for (int i = 0; i < 4; ++i) ss += y[i][0] * y[i][0] + y[i][1] * y[i][1] + y[i][2] * y[i][2] + y[i][3] * y[i][3];
;         ss = wave_sum(ss);
;         const float r = rsqrtf(ss * (1.0f / DM) + EPS);
;         float s2 = 0.f;
; #pragma unroll
;         for (int i = 0; i < 4; ++i) { xv[i] = xv[i] + y[i] * r * pgv[i]; *(f32x4*)(xout + (size_t)row * DM + i * 256 + lane * 4) = xv[i];
;             s2 += xv[i][0] * xv[i][0] + xv[i][1] * xv[i][1] + xv[i][2] * xv[i][2] + xv[i][3] * xv[i][3]; }
.LBB0_609:
	s_or_b64 exec, exec, s[38:39]
	v_and_b32_e32 v83, 0xffff0000, v72
	v_and_b32_e32 v82, 0xffff0000, v70
	v_lshlrev_b32_e32 v81, 16, v72
	v_lshlrev_b32_e32 v80, 16, v70
	v_lshlrev_b32_e32 v84, 16, v71
	v_and_b32_e32 v72, 0xffff0000, v71
	v_lshlrev_b32_e32 v71, 16, v68
	v_lshlrev_b32_e32 v70, 16, v66
	s_waitcnt lgkmcnt(1)
	v_and_b32_e32 v87, 0xffff0000, v68
	v_and_b32_e32 v86, 0xffff0000, v66
	v_lshlrev_b32_e32 v88, 16, v67
	v_and_b32_e32 v68, 0xffff0000, v67
	v_pk_mul_f32 v[66:67], v[82:83], v[82:83]
	v_lshlrev_b32_e32 v85, 16, v73
	v_pk_fma_f32 v[66:67], v[80:81], v[80:81], v[66:67]
	v_pk_mul_f32 v[90:91], v[86:87], v[86:87]
	v_and_b32_e32 v73, 0xffff0000, v73
	v_lshlrev_b32_e32 v89, 16, v69
	v_pk_fma_f32 v[66:67], v[84:85], v[84:85], v[66:67]
	v_pk_fma_f32 v[90:91], v[70:71], v[70:71], v[90:91]
	v_and_b32_e32 v69, 0xffff0000, v69
	v_pk_fma_f32 v[66:67], v[72:73], v[72:73], v[66:67]
	v_pk_fma_f32 v[90:91], v[88:89], v[88:89], v[90:91]
	v_add_f32_e32 v66, v66, v67
	v_pk_fma_f32 v[90:91], v[68:69], v[68:69], v[90:91]
	s_and_b64 s[0:1], exec, vcc
	v_add_f32_e32 v66, v66, v90
	v_add_f32_e32 v66, v66, v91
	v_mov_b32_e32 v67, v66
	s_nop 1
	v_permlane32_swap_b32_e32 v67, v66
	s_nop 1
	v_mov_b32_e32 v90, v80
	v_mov_b32_e32 v93, v72
	v_mov_b32_e32 v92, v84
	s_or_b64 s[36:37], s[0:1], s[36:37]
	s_waitcnt lgkmcnt(0)
	v_add_f32_e32 v66, v66, v67
	v_mov_b32_e32 v67, v66
	s_nop 1
	v_permlane16_swap_b32_e32 v67, v66
	s_nop 1
	v_lshl_add_u64 v[56:57], v[56:57], 0, s[22:23]
	v_lshl_add_u64 v[54:55], v[54:55], 0, s[70:71]
	v_add_f32_e32 v66, v66, v67
	s_nop 1
	v_mov_b32_dpp v67, v66 row_ror:8 row_mask:0xf bank_mask:0xf
	v_add_f32_e32 v66, v66, v67
	s_nop 1
	v_mov_b32_dpp v67, v66 row_shl:4 row_mask:0xf bank_mask:0x5
	s_nop 1
	v_mov_b32_dpp v67, v66 row_shr:4 row_mask:0xf bank_mask:0xa
	v_add_f32_e32 v66, v66, v67
	s_nop 1
	v_mov_b32_dpp v67, v66 quad_perm:[2,3,0,1] row_mask:0xf bank_mask:0xf
	v_add_f32_e32 v79, v66, v67
	s_nop 1
	v_mov_b32_dpp v91, v79 quad_perm:[1,0,3,2] row_mask:0xf bank_mask:0xf
	v_lshl_add_u64 v[66:67], v[52:53], 0, v[194:195]
	v_lshl_add_u64 v[52:53], v[52:53], 0, s[70:71]
	v_add_f32_e32 v79, v79, v91
	v_fmamk_f32 v79, v79, 0x3a800000, v1
	v_mul_f32_e32 v80, 0x4b800000, v79
	v_cmp_gt_f32_e32 vcc, s33, v79
	v_mov_b32_e32 v91, v82
	v_mov_b32_e32 v82, v81
	v_cndmask_b32_e32 v79, v79, v80, vcc
	v_rsq_f32_e32 v79, v79
	s_nop 0
	v_mul_f32_e32 v72, 0x45800000, v79
	v_cndmask_b32_e32 v80, v79, v72, vcc
	v_pk_mul_f32 v[90:91], v[80:81], v[90:91] op_sel_hi:[0,1]
	v_pk_mul_f32 v[92:93], v[80:81], v[92:93] op_sel_hi:[0,1]
	v_pk_fma_f32 v[32:33], v[4:5], v[92:93], v[32:33]
	v_pk_fma_f32 v[30:31], v[2:3], v[90:91], v[30:31]
	v_mov_b32_e32 v72, v85
	global_store_dwordx4 v[66:67], v[30:33], off
	s_nop 1
	v_pk_mul_f32 v[30:31], v[80:81], v[82:83] op_sel_hi:[0,1]
	v_pk_mul_f32 v[32:33], v[80:81], v[72:73] op_sel_hi:[0,1]
	v_pk_fma_f32 v[28:29], v[8:9], v[32:33], v[28:29]
	v_pk_fma_f32 v[26:27], v[6:7], v[30:31], v[26:27]
	global_store_dwordx4 v[66:67], v[26:29], off offset:1024
	s_waitcnt vmcnt(9)
	v_mov_b64_e32 v[30:31], v[34:35]
	v_mov_b64_e32 v[32:33], v[36:37]
	v_mov_b32_e32 v26, v70
	v_mov_b32_e32 v27, v86
	v_mov_b32_e32 v28, v88
	v_mov_b32_e32 v29, v68
	v_pk_mul_f32 v[26:27], v[80:81], v[26:27] op_sel_hi:[0,1]
	v_pk_mul_f32 v[28:29], v[80:81], v[28:29] op_sel_hi:[0,1]
	s_waitcnt vmcnt(3)
	v_pk_fma_f32 v[24:25], v[12:13], v[28:29], v[24:25]
	v_pk_fma_f32 v[22:23], v[10:11], v[26:27], v[22:23]
	v_mov_b32_e32 v86, v71
	v_mov_b32_e32 v68, v89
	global_store_dwordx4 v[66:67], v[22:25], off offset:2048
	v_mov_b64_e32 v[26:27], v[38:39]
	v_mov_b64_e32 v[28:29], v[40:41]
	v_pk_mul_f32 v[22:23], v[80:81], v[86:87] op_sel_hi:[0,1]
	v_pk_mul_f32 v[24:25], v[80:81], v[68:69] op_sel_hi:[0,1]
	s_waitcnt vmcnt(3)
	v_pk_fma_f32 v[20:21], v[16:17], v[24:25], v[20:21]
	v_pk_fma_f32 v[18:19], v[14:15], v[22:23], v[18:19]
	global_store_dwordx4 v[66:67], v[18:21], off offset:3072
	v_mov_b64_e32 v[22:23], v[46:47]
	v_mov_b64_e32 v[24:25], v[48:49]
	v_mov_b64_e32 v[18:19], v[42:43]
	v_mov_b64_e32 v[20:21], v[44:45]
	v_mov_b64_e32 v[70:71], v[58:59]
	v_mov_b64_e32 v[72:73], v[60:61]
	v_mov_b64_e32 v[66:67], v[62:63]
	v_mov_b64_e32 v[68:69], v[64:65]
	s_andn2_b64 exec, exec, s[36:37]
	s_cbranch_execz .LBB0_612

; #define LAS __attribute__((address_space(3)))
; __device__ __forceinline__ unsigned cvt_pk_bf16(float lo, float hi) { unsigned r; asm volatile("v_cvt_pk_bf16_f32 %0, %1, %2" : "=v"(r) : "v"(lo), "v"(hi)); return r; }
; __device__ void phase_norm_alow(const Params& P, int l, int half, LAS unsigned char* lds) {
;     ...
;         ss = wave_sum(ss);
;         const float r = rsqrtf(ss * (1.0f / DM) + EPS);
;         float a[16];
; #pragma unroll
;         for (int c = 0; c < 16; ++c) a[c] = 0.f;
; #pragma unroll
;         for (int i = 0; i < 4; ++i) { f32x4 h = v[i] * r * gv[i];
;             u32x2 w; w.x = cvt_pk_bf16(h[0], h[1]); w.y = cvt_pk_bf16(h[2], h[3]);
;             *(u32x2*)(H + (size_t)row * DM + i * 256 + lane * 4) = w;
; #pragma unroll
;             for (int c = 0; c < 16; ++c) { const f32x4 wv = *(const LAS f32x4*)(WaT + c * 1024 + i * 256 + lane * 4); a[c] += h[0] * wv[0] + h[1] * wv[1] + h[2] * wv[2] + h[3] * wv[3]; } }
.LBB0_680:
	s_or_b64 exec, exec, s[30:31]
	v_mul_f32_e32 v51, v47, v47
	v_mul_f32_e32 v58, v43, v43
	v_fmac_f32_e32 v51, v46, v46
	v_fmac_f32_e32 v58, v42, v42
	v_fmac_f32_e32 v51, v48, v48
	v_fmac_f32_e32 v58, v44, v44
	v_fmac_f32_e32 v51, v49, v49
	v_fmac_f32_e32 v58, v45, v45
	v_add_f32_e32 v51, v51, v58
	v_mul_f32_e32 v58, v39, v39
	v_fmac_f32_e32 v58, v38, v38
	v_fmac_f32_e32 v58, v40, v40
	v_fmac_f32_e32 v58, v41, v41
	v_add_f32_e32 v51, v51, v58
	v_mul_f32_e32 v58, v35, v35
	v_fmac_f32_e32 v58, v34, v34
	v_fmac_f32_e32 v58, v36, v36
	v_fmac_f32_e32 v58, v37, v37
	v_add_f32_e32 v51, v51, v58
	v_mov_b32_e32 v58, v51
	s_nop 1
	v_permlane32_swap_b32_e32 v58, v51
	s_nop 1
	v_lshl_add_u64 v[68:69], s[74:75], 0, v[56:57]
	s_waitcnt lgkmcnt(0)
	v_add_f32_e32 v51, v51, v58
	v_mov_b32_e32 v58, v51
	s_nop 1
	v_permlane16_swap_b32_e32 v58, v51
	s_nop 1
	v_add_f32_e32 v51, v51, v58
	s_nop 1
	v_mov_b32_dpp v58, v51 row_ror:8 row_mask:0xf bank_mask:0xf
	v_add_f32_e32 v51, v51, v58
	s_nop 1
	v_mov_b32_dpp v58, v51 row_shl:4 row_mask:0xf bank_mask:0x5
	s_nop 1
	v_mov_b32_dpp v58, v51 row_shr:4 row_mask:0xf bank_mask:0xa
	v_add_f32_e32 v51, v51, v58
	s_nop 1
	v_mov_b32_dpp v58, v51 quad_perm:[2,3,0,1] row_mask:0xf bank_mask:0xf
	v_add_f32_e32 v51, v51, v58
	s_nop 1
	v_mov_b32_dpp v58, v51 quad_perm:[1,0,3,2] row_mask:0xf bank_mask:0xf
	v_add_f32_e32 v51, v51, v58
	v_fmamk_f32 v51, v51, 0x3a800000, v1
	v_cmp_gt_f32_e64 s[0:1], s33, v51
	v_mul_f32_e32 v58, 0x4b800000, v51
	s_nop 0
	v_cndmask_b32_e64 v51, v51, v58, s[0:1]
	v_rsq_f32_e32 v51, v51
	s_nop 0
	v_mul_f32_e32 v58, 0x45800000, v51
	v_cndmask_b32_e64 v58, v51, v58, s[0:1]
	v_pk_mul_f32 v[46:47], v[46:47], v[58:59] op_sel_hi:[1,0]
	s_mov_b32 s0, 0x3a88000
	v_pk_mul_f32 v[48:49], v[48:49], v[58:59] op_sel_hi:[1,0]
	v_pk_mul_f32 v[60:61], v[14:15], v[46:47]
	v_add_co_u32_e64 v46, s[0:1], s0, v68
	v_pk_mul_f32 v[48:49], v[16:17], v[48:49]
	v_cvt_pk_bf16_f32 v70, v60, v61
	s_nop 0
	v_addc_co_u32_e64 v47, s[0:1], 0, v69, s[0:1]
	v_cvt_pk_bf16_f32 v71, v48, v49
	global_store_dwordx2 v[46:47], v[70:71], off
	ds_read_b128 v[100:103], v67
	ds_read_b128 v[104:107], v67 offset:4096
	ds_read_b128 v[108:111], v67 offset:8192
	ds_read_b128 v[112:115], v67 offset:12288
	ds_read_b128 v[116:119], v67 offset:16384
	ds_read_b128 v[120:123], v67 offset:20480
	ds_read_b128 v[124:127], v67 offset:24576
	s_waitcnt lgkmcnt(6)
	v_pk_mul_f32 v[148:149], v[100:101], v[60:61]
	v_pk_fma_f32 v[148:149], v[102:103], v[48:49], v[148:149]
	ds_read_b128 v[128:131], v67 offset:28672
	s_waitcnt lgkmcnt(6)
	v_pk_mul_f32 v[150:151], v[104:105], v[60:61]
	v_pk_fma_f32 v[150:151], v[106:107], v[48:49], v[150:151]
	ds_read_b128 v[100:103], v67 offset:32768
	s_waitcnt lgkmcnt(6)
	v_pk_mul_f32 v[152:153], v[108:109], v[60:61]
	v_pk_fma_f32 v[152:153], v[110:111], v[48:49], v[152:153]
	ds_read_b128 v[104:107], v67 offset:36864
	s_waitcnt lgkmcnt(6)
	v_pk_mul_f32 v[154:155], v[112:113], v[60:61]
	v_pk_fma_f32 v[154:155], v[114:115], v[48:49], v[154:155]
	ds_read_b128 v[108:111], v67 offset:40960
	s_waitcnt lgkmcnt(6)
	v_pk_mul_f32 v[156:157], v[116:117], v[60:61]
	v_pk_fma_f32 v[156:157], v[118:119], v[48:49], v[156:157]
	ds_read_b128 v[112:115], v67 offset:45056
	s_waitcnt lgkmcnt(6)
	v_pk_mul_f32 v[158:159], v[120:121], v[60:61]
	v_pk_fma_f32 v[158:159], v[122:123], v[48:49], v[158:159]
	ds_read_b128 v[116:119], v67 offset:49152
	s_waitcnt lgkmcnt(6)
	v_pk_mul_f32 v[160:161], v[124:125], v[60:61]
	v_pk_fma_f32 v[160:161], v[126:127], v[48:49], v[160:161]
	ds_read_b128 v[120:123], v67 offset:53248
	s_waitcnt lgkmcnt(6)
	v_pk_mul_f32 v[162:163], v[128:129], v[60:61]
	v_pk_fma_f32 v[162:163], v[130:131], v[48:49], v[162:163]
	ds_read_b128 v[124:127], v67 offset:57344
	s_waitcnt lgkmcnt(6)
	v_pk_mul_f32 v[164:165], v[100:101], v[60:61]
	v_pk_fma_f32 v[164:165], v[102:103], v[48:49], v[164:165]
	ds_read_b128 v[128:131], v67 offset:61440
	s_waitcnt lgkmcnt(6)
	v_pk_mul_f32 v[168:169], v[104:105], v[60:61]
	v_pk_fma_f32 v[168:169], v[106:107], v[48:49], v[168:169]
	ds_read_b128 v[100:103], v67 offset:1024
	s_waitcnt lgkmcnt(6)
	v_pk_mul_f32 v[170:171], v[108:109], v[60:61]
	v_pk_fma_f32 v[170:171], v[110:111], v[48:49], v[170:171]
	ds_read_b128 v[104:107], v67 offset:5120
	s_waitcnt lgkmcnt(6)
	v_pk_mul_f32 v[172:173], v[112:113], v[60:61]
	v_pk_fma_f32 v[172:173], v[114:115], v[48:49], v[172:173]
	ds_read_b128 v[108:111], v67 offset:9216
	s_waitcnt lgkmcnt(6)
	v_pk_mul_f32 v[174:175], v[116:117], v[60:61]
	v_pk_fma_f32 v[174:175], v[118:119], v[48:49], v[174:175]
	ds_read_b128 v[112:115], v67 offset:13312
	s_waitcnt lgkmcnt(6)
	v_pk_mul_f32 v[176:177], v[120:121], v[60:61]
	v_pk_fma_f32 v[176:177], v[122:123], v[48:49], v[176:177]
	ds_read_b128 v[116:119], v67 offset:17408
	s_waitcnt lgkmcnt(6)
	v_pk_mul_f32 v[178:179], v[124:125], v[60:61]
	v_pk_fma_f32 v[178:179], v[126:127], v[48:49], v[178:179]
	ds_read_b128 v[120:123], v67 offset:21504
	s_waitcnt lgkmcnt(6)
	v_pk_mul_f32 v[180:181], v[128:129], v[60:61]
	v_pk_fma_f32 v[180:181], v[130:131], v[48:49], v[180:181]
	v_pk_mul_f32 v[60:61], v[42:43], v[58:59] op_sel_hi:[1,0]
	v_pk_mul_f32 v[42:43], v[44:45], v[58:59] op_sel_hi:[1,0]
	v_pk_mul_f32 v[44:45], v[10:11], v[60:61]
	v_pk_mul_f32 v[42:43], v[12:13], v[42:43]
	v_cvt_pk_bf16_f32 v60, v44, v45
	s_nop 0
	v_cvt_pk_bf16_f32 v61, v42, v43
	ds_read_b128 v[124:127], v67 offset:25600
	global_store_dwordx2 v[46:47], v[60:61], off offset:512
	s_waitcnt lgkmcnt(6)
	v_pk_fma_f32 v[148:149], v[100:101], v[44:45], v[148:149]
	v_pk_fma_f32 v[148:149], v[102:103], v[42:43], v[148:149]
	ds_read_b128 v[128:131], v67 offset:29696
	s_waitcnt lgkmcnt(6)
; #define LAS __attribute__((address_space(3)))
; __device__ __forceinline__ unsigned cvt_pk_bf16(float lo, float hi) { unsigned r; asm volatile("v_cvt_pk_bf16_f32 %0, %1, %2" : "=v"(r) : "v"(lo), "v"(hi)); return r; }
; __device__ void phase_norm_alow(const Params& P, int l, int half, LAS unsigned char* lds) {
;     ...
;         for (int i = 0; i < 4; ++i) { f32x4 h = v[i] * r * gv[i];
;             u32x2 w; w.x = cvt_pk_bf16(h[0], h[1]); w.y = cvt_pk_bf16(h[2], h[3]);
;             *(u32x2*)(H + (size_t)row * DM + i * 256 + lane * 4) = w;
; #pragma unroll
;             for (int c = 0; c < 16; ++c) { const f32x4 wv = *(const LAS f32x4*)(WaT + c * 1024 + i * 256 + lane * 4); a[c] += h[0] * wv[0] + h[1] * wv[1] + h[2] * wv[2] + h[3] * wv[3]; } }
	v_pk_fma_f32 v[150:151], v[104:105], v[44:45], v[150:151]
	v_pk_fma_f32 v[150:151], v[106:107], v[42:43], v[150:151]
	ds_read_b128 v[100:103], v67 offset:33792
	s_waitcnt lgkmcnt(6)
	v_pk_fma_f32 v[152:153], v[108:109], v[44:45], v[152:153]
	v_pk_fma_f32 v[152:153], v[110:111], v[42:43], v[152:153]
	ds_read_b128 v[104:107], v67 offset:37888
	s_waitcnt lgkmcnt(6)
	v_pk_fma_f32 v[154:155], v[112:113], v[44:45], v[154:155]
	v_pk_fma_f32 v[154:155], v[114:115], v[42:43], v[154:155]
	ds_read_b128 v[108:111], v67 offset:41984
	s_waitcnt lgkmcnt(6)
	v_pk_fma_f32 v[156:157], v[116:117], v[44:45], v[156:157]
	v_pk_fma_f32 v[156:157], v[118:119], v[42:43], v[156:157]
	ds_read_b128 v[112:115], v67 offset:46080
	s_waitcnt lgkmcnt(6)
	v_pk_fma_f32 v[158:159], v[120:121], v[44:45], v[158:159]
	v_pk_fma_f32 v[158:159], v[122:123], v[42:43], v[158:159]
	ds_read_b128 v[116:119], v67 offset:50176
	s_waitcnt lgkmcnt(6)
	v_pk_fma_f32 v[160:161], v[124:125], v[44:45], v[160:161]
	v_pk_fma_f32 v[160:161], v[126:127], v[42:43], v[160:161]
	ds_read_b128 v[120:123], v67 offset:54272
	s_waitcnt lgkmcnt(6)
	v_pk_fma_f32 v[162:163], v[128:129], v[44:45], v[162:163]
	v_pk_fma_f32 v[162:163], v[130:131], v[42:43], v[162:163]
	ds_read_b128 v[124:127], v67 offset:58368
	s_waitcnt lgkmcnt(6)
	v_pk_fma_f32 v[164:165], v[100:101], v[44:45], v[164:165]
	v_pk_fma_f32 v[164:165], v[102:103], v[42:43], v[164:165]
	ds_read_b128 v[128:131], v67 offset:62464
	s_waitcnt lgkmcnt(6)
	v_pk_fma_f32 v[168:169], v[104:105], v[44:45], v[168:169]
	v_pk_fma_f32 v[168:169], v[106:107], v[42:43], v[168:169]
	ds_read_b128 v[100:103], v67 offset:2048
	s_waitcnt lgkmcnt(6)
	v_pk_fma_f32 v[170:171], v[108:109], v[44:45], v[170:171]
	v_pk_fma_f32 v[170:171], v[110:111], v[42:43], v[170:171]
	ds_read_b128 v[104:107], v67 offset:6144
	s_waitcnt lgkmcnt(6)
	v_pk_fma_f32 v[172:173], v[112:113], v[44:45], v[172:173]
	v_pk_fma_f32 v[172:173], v[114:115], v[42:43], v[172:173]
	ds_read_b128 v[108:111], v67 offset:10240
	s_waitcnt lgkmcnt(6)
	v_pk_fma_f32 v[174:175], v[116:117], v[44:45], v[174:175]
	v_pk_fma_f32 v[174:175], v[118:119], v[42:43], v[174:175]
	ds_read_b128 v[112:115], v67 offset:14336
	s_waitcnt lgkmcnt(6)
	v_pk_fma_f32 v[176:177], v[120:121], v[44:45], v[176:177]
	v_pk_fma_f32 v[176:177], v[122:123], v[42:43], v[176:177]
	ds_read_b128 v[116:119], v67 offset:18432
	s_waitcnt lgkmcnt(6)
	v_pk_fma_f32 v[178:179], v[124:125], v[44:45], v[178:179]
	v_pk_fma_f32 v[178:179], v[126:127], v[42:43], v[178:179]
	ds_read_b128 v[120:123], v67 offset:22528
	s_waitcnt lgkmcnt(6)
	v_pk_fma_f32 v[180:181], v[128:129], v[44:45], v[180:181]
	v_pk_fma_f32 v[180:181], v[130:131], v[42:43], v[180:181]
	v_pk_mul_f32 v[42:43], v[38:39], v[58:59] op_sel_hi:[1,0]
	v_pk_mul_f32 v[38:39], v[40:41], v[58:59] op_sel_hi:[1,0]
	v_pk_mul_f32 v[40:41], v[6:7], v[42:43]
	v_pk_mul_f32 v[38:39], v[8:9], v[38:39]
	v_cvt_pk_bf16_f32 v42, v40, v41
	v_cvt_pk_bf16_f32 v43, v38, v39
	global_store_dwordx2 v[46:47], v[42:43], off offset:1024
	ds_read_b128 v[124:127], v67 offset:26624
	ds_read_b128 v[128:131], v67 offset:30720
	s_waitcnt lgkmcnt(7)
	v_pk_fma_f32 v[148:149], v[100:101], v[40:41], v[148:149]
	v_pk_fma_f32 v[148:149], v[102:103], v[38:39], v[148:149]
	s_waitcnt lgkmcnt(6)
	v_pk_fma_f32 v[150:151], v[104:105], v[40:41], v[150:151]
	v_pk_fma_f32 v[150:151], v[106:107], v[38:39], v[150:151]
	ds_read_b128 v[100:103], v67 offset:34816
	s_waitcnt lgkmcnt(6)
	v_pk_fma_f32 v[152:153], v[108:109], v[40:41], v[152:153]
	v_pk_fma_f32 v[152:153], v[110:111], v[38:39], v[152:153]
	ds_read_b128 v[104:107], v67 offset:38912
	s_waitcnt lgkmcnt(6)
	v_pk_fma_f32 v[154:155], v[112:113], v[40:41], v[154:155]
	v_pk_fma_f32 v[154:155], v[114:115], v[38:39], v[154:155]
	ds_read_b128 v[108:111], v67 offset:43008
	s_waitcnt lgkmcnt(6)
	v_pk_fma_f32 v[156:157], v[116:117], v[40:41], v[156:157]
	v_pk_fma_f32 v[156:157], v[118:119], v[38:39], v[156:157]
	ds_read_b128 v[112:115], v67 offset:47104
	s_waitcnt lgkmcnt(6)
	v_pk_fma_f32 v[158:159], v[120:121], v[40:41], v[158:159]
	v_pk_fma_f32 v[158:159], v[122:123], v[38:39], v[158:159]
	ds_read_b128 v[116:119], v67 offset:51200
	s_waitcnt lgkmcnt(6)
	v_pk_fma_f32 v[160:161], v[124:125], v[40:41], v[160:161]
	v_pk_fma_f32 v[160:161], v[126:127], v[38:39], v[160:161]
	ds_read_b128 v[120:123], v67 offset:55296
	s_waitcnt lgkmcnt(6)
	v_pk_fma_f32 v[162:163], v[128:129], v[40:41], v[162:163]
	v_pk_fma_f32 v[162:163], v[130:131], v[38:39], v[162:163]
	ds_read_b128 v[124:127], v67 offset:59392
	s_waitcnt lgkmcnt(6)
	v_pk_fma_f32 v[164:165], v[100:101], v[40:41], v[164:165]
	v_pk_fma_f32 v[164:165], v[102:103], v[38:39], v[164:165]
	ds_read_b128 v[128:131], v67 offset:63488
	s_waitcnt lgkmcnt(6)
	v_pk_fma_f32 v[168:169], v[104:105], v[40:41], v[168:169]
	v_pk_fma_f32 v[168:169], v[106:107], v[38:39], v[168:169]
	ds_read_b128 v[100:103], v67 offset:3072
	s_waitcnt lgkmcnt(6)
	v_pk_fma_f32 v[170:171], v[108:109], v[40:41], v[170:171]
	v_pk_fma_f32 v[170:171], v[110:111], v[38:39], v[170:171]
	ds_read_b128 v[104:107], v67 offset:7168
	s_waitcnt lgkmcnt(6)
	v_pk_fma_f32 v[172:173], v[112:113], v[40:41], v[172:173]
	v_pk_fma_f32 v[172:173], v[114:115], v[38:39], v[172:173]
	ds_read_b128 v[108:111], v67 offset:11264
	s_waitcnt lgkmcnt(6)
	v_pk_fma_f32 v[174:175], v[116:117], v[40:41], v[174:175]
	v_pk_fma_f32 v[174:175], v[118:119], v[38:39], v[174:175]
	ds_read_b128 v[112:115], v67 offset:15360
	s_waitcnt lgkmcnt(6)
	v_pk_fma_f32 v[176:177], v[120:121], v[40:41], v[176:177]
	v_pk_fma_f32 v[176:177], v[122:123], v[38:39], v[176:177]
	ds_read_b128 v[116:119], v67 offset:19456
	s_waitcnt lgkmcnt(6)
; #define LAS __attribute__((address_space(3)))
; __device__ __forceinline__ unsigned cvt_pk_bf16(float lo, float hi) { unsigned r; asm volatile("v_cvt_pk_bf16_f32 %0, %1, %2" : "=v"(r) : "v"(lo), "v"(hi)); return r; }
; __device__ void phase_norm_alow(const Params& P, int l, int half, LAS unsigned char* lds) {
;     ...
;         for (int i = 0; i < 4; ++i) { f32x4 h = v[i] * r * gv[i];
;             u32x2 w; w.x = cvt_pk_bf16(h[0], h[1]); w.y = cvt_pk_bf16(h[2], h[3]);
;             *(u32x2*)(H + (size_t)row * DM + i * 256 + lane * 4) = w;
; #pragma unroll
;             for (int c = 0; c < 16; ++c) { const f32x4 wv = *(const LAS f32x4*)(WaT + c * 1024 + i * 256 + lane * 4); a[c] += h[0] * wv[0] + h[1] * wv[1] + h[2] * wv[2] + h[3] * wv[3]; } }
;         float b8[8], b4[4], b2[2], b1;
;         { const bool up = (lane & 32) != 0;
; #pragma unroll
;           for (int c = 0; c < 8; ++c) { const float keep = up ? a[c + 8] : a[c], send = up ? a[c] : a[c + 8]; b8[c] = keep + __shfl_xor(send, 32); } }
;         { const bool up = (lane & 16) != 0;
; #pragma unroll
;           for (int c = 0; c < 4; ++c) { const float keep = up ? b8[c + 4] : b8[c], send = up ? b8[c] : b8[c + 4]; b4[c] = keep + __shfl_xor(send, 16); } }
;         { const bool up = (lane & 8) != 0;
; #pragma unroll
;           for (int c = 0; c < 2; ++c) { const float keep = up ? b4[c + 2] : b4[c], send = up ? b4[c] : b4[c + 2]; b2[c] = keep + __shfl_xor(send, 8); } }
;         { const bool up = (lane & 4) != 0; const float keep = up ? b2[1] : b2[0], send = up ? b2[0] : b2[1]; b1 = keep + __shfl_xor(send, 4); }
;         b1 += __shfl_xor(b1, 2); b1 += __shfl_xor(b1, 1);
;         if ((lane & 3) == 0) { const int co = ((lane >> 5) & 1) * 8 + ((lane >> 4) & 1) * 4 + ((lane >> 3) & 1) * 2 + ((lane >> 2) & 1); AL[(size_t)row * 16 + co] = b1; }
	v_pk_fma_f32 v[178:179], v[124:125], v[40:41], v[178:179]
	v_pk_fma_f32 v[178:179], v[126:127], v[38:39], v[178:179]
	ds_read_b128 v[120:123], v67 offset:23552
	s_waitcnt lgkmcnt(6)
	v_pk_fma_f32 v[180:181], v[128:129], v[40:41], v[180:181]
	v_pk_fma_f32 v[180:181], v[130:131], v[38:39], v[180:181]
	v_pk_mul_f32 v[40:41], v[34:35], v[58:59] op_sel_hi:[1,0]
	v_pk_mul_f32 v[34:35], v[36:37], v[58:59] op_sel_hi:[1,0]
	v_pk_mul_f32 v[36:37], v[2:3], v[40:41]
	v_pk_mul_f32 v[34:35], v[4:5], v[34:35]
	v_cvt_pk_bf16_f32 v40, v36, v37
	s_nop 0
	v_cvt_pk_bf16_f32 v41, v34, v35
	ds_read_b128 v[124:127], v67 offset:27648
	global_store_dwordx2 v[46:47], v[40:41], off offset:1536
	s_waitcnt lgkmcnt(6)
	v_pk_fma_f32 v[148:149], v[100:101], v[36:37], v[148:149]
	v_pk_fma_f32 v[148:149], v[102:103], v[34:35], v[148:149]
	ds_read_b128 v[128:131], v67 offset:31744
	v_add_f32_e32 v39, v148, v149
	s_waitcnt lgkmcnt(6)
	v_pk_fma_f32 v[150:151], v[104:105], v[36:37], v[150:151]
	v_pk_fma_f32 v[150:151], v[106:107], v[34:35], v[150:151]
	ds_read_b128 v[100:103], v67 offset:35840
	v_add_f32_e32 v40, v150, v151
	s_waitcnt lgkmcnt(6)
	v_pk_fma_f32 v[152:153], v[108:109], v[36:37], v[152:153]
	v_pk_fma_f32 v[152:153], v[110:111], v[34:35], v[152:153]
	ds_read_b128 v[104:107], v67 offset:39936
	v_add_f32_e32 v41, v152, v153
	s_waitcnt lgkmcnt(6)
	v_pk_fma_f32 v[154:155], v[112:113], v[36:37], v[154:155]
	v_pk_fma_f32 v[154:155], v[114:115], v[34:35], v[154:155]
	v_add_f32_e32 v42, v154, v155
	ds_read_b128 v[108:111], v67 offset:44032
	s_waitcnt lgkmcnt(6)
	v_pk_fma_f32 v[156:157], v[116:117], v[36:37], v[156:157]
	v_pk_fma_f32 v[156:157], v[118:119], v[34:35], v[156:157]
	ds_read_b128 v[112:115], v67 offset:48128
	v_add_f32_e32 v43, v156, v157
	s_waitcnt lgkmcnt(6)
	v_pk_fma_f32 v[158:159], v[120:121], v[36:37], v[158:159]
	v_pk_fma_f32 v[158:159], v[122:123], v[34:35], v[158:159]
	v_add_f32_e32 v48, v158, v159
	ds_read_b128 v[116:119], v67 offset:52224
	s_waitcnt lgkmcnt(6)
	v_pk_fma_f32 v[160:161], v[124:125], v[36:37], v[160:161]
	v_pk_fma_f32 v[160:161], v[126:127], v[34:35], v[160:161]
	v_add_f32_e32 v49, v160, v161
	ds_read_b128 v[120:123], v67 offset:56320
	s_waitcnt lgkmcnt(6)
	v_pk_fma_f32 v[162:163], v[128:129], v[36:37], v[162:163]
	v_pk_fma_f32 v[162:163], v[130:131], v[34:35], v[162:163]
	v_add_f32_e32 v51, v162, v163
	ds_read_b128 v[124:127], v67 offset:60416
	s_waitcnt lgkmcnt(6)
	v_pk_fma_f32 v[164:165], v[100:101], v[36:37], v[164:165]
	v_pk_fma_f32 v[164:165], v[102:103], v[34:35], v[164:165]
	v_add_f32_e32 v58, v164, v165
	ds_read_b128 v[128:131], v67 offset:64512
	s_waitcnt lgkmcnt(6)
	v_pk_fma_f32 v[168:169], v[104:105], v[36:37], v[168:169]
	v_pk_fma_f32 v[168:169], v[106:107], v[34:35], v[168:169]
	v_add_f32_e32 v60, v168, v169
	s_waitcnt lgkmcnt(5)
	v_pk_fma_f32 v[170:171], v[108:109], v[36:37], v[170:171]
	v_pk_fma_f32 v[170:171], v[110:111], v[34:35], v[170:171]
	v_add_f32_e32 v61, v170, v171
	s_waitcnt lgkmcnt(4)
	v_pk_fma_f32 v[172:173], v[112:113], v[36:37], v[172:173]
	v_pk_fma_f32 v[172:173], v[114:115], v[34:35], v[172:173]
	v_add_f32_e32 v68, v172, v173
	s_waitcnt lgkmcnt(3)
	v_pk_fma_f32 v[174:175], v[116:117], v[36:37], v[174:175]
	v_pk_fma_f32 v[174:175], v[118:119], v[34:35], v[174:175]
	v_add_f32_e32 v69, v174, v175
	s_waitcnt lgkmcnt(2)
	v_pk_fma_f32 v[176:177], v[120:121], v[36:37], v[176:177]
	v_pk_fma_f32 v[176:177], v[122:123], v[34:35], v[176:177]
	v_add_f32_e32 v70, v176, v177
	s_waitcnt lgkmcnt(1)
	v_pk_fma_f32 v[178:179], v[124:125], v[36:37], v[178:179]
	v_pk_fma_f32 v[178:179], v[126:127], v[34:35], v[178:179]
	v_add_f32_e32 v71, v178, v179
	s_waitcnt lgkmcnt(0)
	v_pk_fma_f32 v[180:181], v[128:129], v[36:37], v[180:181]
	v_pk_fma_f32 v[180:181], v[130:131], v[34:35], v[180:181]
	v_add_f32_e32 v34, v180, v181
	s_nop 1
	v_permlane32_swap_b32_e32 v39, v58
	s_nop 1
	v_add_f32_e32 v39, v39, v58
	s_nop 1
	v_permlane32_swap_b32_e32 v40, v60
	s_nop 1
	v_add_f32_e32 v40, v40, v60
	s_nop 1
	v_permlane32_swap_b32_e32 v41, v61
	s_nop 1
	v_add_f32_e32 v41, v41, v61
	s_nop 1
	v_permlane32_swap_b32_e32 v42, v68
	s_nop 1
	v_add_f32_e32 v42, v42, v68
	s_nop 1
	v_permlane32_swap_b32_e32 v43, v69
	s_nop 1
	v_add_f32_e32 v43, v43, v69
	s_nop 1
	v_permlane32_swap_b32_e32 v48, v70
	s_nop 1
	v_add_f32_e32 v48, v48, v70
	s_nop 1
	v_permlane32_swap_b32_e32 v49, v71
	s_nop 1
	v_add_f32_e32 v49, v49, v71
	s_nop 1
	v_permlane32_swap_b32_e32 v51, v34
	s_nop 1
	v_add_f32_e32 v51, v51, v34
	s_nop 1
	v_permlane16_swap_b32_e32 v40, v48
	s_nop 1
	v_add_f32_e32 v40, v40, v48
	s_nop 1
	v_permlane16_swap_b32_e32 v39, v43
	s_nop 1
	v_add_f32_e32 v39, v39, v43
	s_nop 1
	v_permlane16_swap_b32_e32 v41, v49
	s_nop 1
	v_add_f32_e32 v41, v41, v49
	s_nop 1
	v_permlane16_swap_b32_e32 v42, v51
	s_nop 1
	v_add_f32_e32 v42, v42, v51
	s_nop 1
	v_add_f32_dpp v39, v39, v39 row_ror:8 row_mask:0xf bank_mask:0x3
	s_nop 1
	v_add_f32_dpp v39, v41, v41 row_ror:8 row_mask:0xf bank_mask:0xc
	s_nop 1
	v_add_f32_dpp v40, v40, v40 row_ror:8 row_mask:0xf bank_mask:0x3
	s_nop 1
	v_add_f32_dpp v40, v42, v42 row_ror:8 row_mask:0xf bank_mask:0xc
	s_nop 1
	v_add_f32_dpp v39, v39, v39 row_shl:4 row_mask:0xf bank_mask:0x5
	s_nop 1
	v_add_f32_dpp v39, v40, v40 row_shr:4 row_mask:0xf bank_mask:0xa
	v_mov_b32_e32 v34, v39
	s_nop 0
	s_nop 1
	v_mov_b32_dpp v35, v34 quad_perm:[2,3,0,1] row_mask:0xf bank_mask:0xf
	v_add_f32_e32 v34, v34, v35
	s_nop 1
	v_mov_b32_dpp v35, v34 quad_perm:[1,0,3,2] row_mask:0xf bank_mask:0xf
	s_and_saveexec_b64 s[0:1], s[42:43]
	s_cbranch_execz .LBB0_677
	v_lshl_add_u64 v[36:37], s[74:75], 0, v[54:55]
	v_add_f32_e32 v34, v34, v35
	global_store_dword v[36:37], v34, off
	s_branch .LBB0_677

; #define LAS __attribute__((address_space(3)))
; __device__ __forceinline__ unsigned cvt_pk_bf16(float lo, float hi) { unsigned r; asm volatile("v_cvt_pk_bf16_f32 %0, %1, %2" : "=v"(r) : "v"(lo), "v"(hi)); return r; }
; __device__ void phase_norm_alow(const Params& P, int l, int half, LAS unsigned char* lds) {
;     ...
;         ss = wave_sum(ss);
;         const float r = rsqrtf(ss * (1.0f / DM) + EPS);
;         float a[16];
; #pragma unroll
;         for (int c = 0; c < 16; ++c) a[c] = 0.f;
; #pragma unroll
;         for (int i = 0; i < 4; ++i) { f32x4 h = v[i] * r * gv[i];
;             u32x2 w; w.x = cvt_pk_bf16(h[0], h[1]); w.y = cvt_pk_bf16(h[2], h[3]);
;             *(u32x2*)(H + (size_t)row * DM + i * 256 + lane * 4) = w;
; #pragma unroll
;             for (int c = 0; c < 16; ++c) { const f32x4 wv = *(const LAS f32x4*)(WaT + c * 1024 + i * 256 + lane * 4); a[c] += h[0] * wv[0] + h[1] * wv[1] + h[2] * wv[2] + h[3] * wv[3]; } }
.LBB0_755:
	s_or_b64 exec, exec, s[46:47]
	v_mul_f32_e32 v51, v47, v47
	v_mul_f32_e32 v58, v43, v43
	v_fmac_f32_e32 v51, v46, v46
	v_fmac_f32_e32 v58, v42, v42
	v_fmac_f32_e32 v51, v48, v48
	v_fmac_f32_e32 v58, v44, v44
	v_fmac_f32_e32 v51, v49, v49
	v_fmac_f32_e32 v58, v45, v45
	v_add_f32_e32 v51, v51, v58
	v_mul_f32_e32 v58, v39, v39
	v_fmac_f32_e32 v58, v38, v38
	v_fmac_f32_e32 v58, v40, v40
	v_fmac_f32_e32 v58, v41, v41
	v_add_f32_e32 v51, v51, v58
	v_mul_f32_e32 v58, v35, v35
	v_fmac_f32_e32 v58, v34, v34
	v_fmac_f32_e32 v58, v36, v36
	v_fmac_f32_e32 v58, v37, v37
	v_add_f32_e32 v51, v51, v58
	v_mov_b32_e32 v58, v51
	s_nop 1
	v_permlane32_swap_b32_e32 v58, v51
	s_nop 1
	s_mov_b32 s2, 0x3a88000
	s_waitcnt lgkmcnt(0)
	v_add_f32_e32 v51, v51, v58
	v_mov_b32_e32 v58, v51
	s_nop 1
	v_permlane16_swap_b32_e32 v58, v51
	s_nop 1
	v_add_f32_e32 v51, v51, v58
	s_nop 1
	v_mov_b32_dpp v58, v51 row_ror:8 row_mask:0xf bank_mask:0xf
	v_add_f32_e32 v51, v51, v58
	s_nop 1
	v_mov_b32_dpp v58, v51 row_shl:4 row_mask:0xf bank_mask:0x5
	s_nop 1
	v_mov_b32_dpp v58, v51 row_shr:4 row_mask:0xf bank_mask:0xa
	v_add_f32_e32 v51, v51, v58
	s_nop 1
	v_mov_b32_dpp v58, v51 quad_perm:[2,3,0,1] row_mask:0xf bank_mask:0xf
	v_add_f32_e32 v51, v51, v58
	s_nop 1
	v_mov_b32_dpp v60, v51 quad_perm:[1,0,3,2] row_mask:0xf bank_mask:0xf
	v_lshl_add_u64 v[58:59], s[74:75], 0, v[52:53]
	v_add_co_u32_e64 v58, s[46:47], s2, v58
	v_add_f32_e32 v51, v51, v60
	v_fmamk_f32 v51, v51, 0x3a800000, v1
	v_mul_f32_e32 v60, 0x4b800000, v51
	v_cmp_gt_f32_e64 s[0:1], s33, v51
	v_addc_co_u32_e64 v59, s[46:47], 0, v59, s[46:47]
	s_nop 0
	v_cndmask_b32_e64 v51, v51, v60, s[0:1]
	v_rsq_f32_e32 v51, v51
	s_nop 0
	v_mul_f32_e32 v60, 0x45800000, v51
	v_cndmask_b32_e64 v60, v51, v60, s[0:1]
	v_pk_mul_f32 v[46:47], v[46:47], v[60:61] op_sel_hi:[1,0]
	v_pk_mul_f32 v[48:49], v[48:49], v[60:61] op_sel_hi:[1,0]
	s_waitcnt vmcnt(0)
	v_pk_mul_f32 v[82:83], v[14:15], v[46:47]
	v_pk_mul_f32 v[80:81], v[16:17], v[48:49]
	v_cvt_pk_bf16_f32 v84, v82, v83
	v_pk_mul_f32 v[42:43], v[42:43], v[60:61] op_sel_hi:[1,0]
	v_cvt_pk_bf16_f32 v85, v80, v81
	ds_read_b128 v[100:103], v61
	ds_read_b128 v[104:107], v61 offset:4096
	ds_read_b128 v[108:111], v61 offset:8192
	ds_read_b128 v[112:115], v61 offset:12288
	ds_read_b128 v[116:119], v61 offset:16384
	ds_read_b128 v[120:123], v61 offset:20480
	ds_read_b128 v[124:127], v61 offset:24576
	ds_read_b128 v[128:131], v61 offset:28672
	ds_read_b128 v[132:135], v61 offset:32768
	ds_read_b128 v[136:139], v61 offset:36864
	global_store_dwordx2 v[58:59], v[84:85], off
	s_waitcnt lgkmcnt(9)
	v_pk_mul_f32 v[148:149], v[100:101], v[82:83]
	s_waitcnt lgkmcnt(7)
	v_pk_mul_f32 v[150:151], v[108:109], v[82:83]
	v_pk_mul_f32 v[152:153], v[104:105], v[82:83]
	v_pk_fma_f32 v[148:149], v[102:103], v[80:81], v[148:149]
	v_pk_fma_f32 v[150:151], v[110:111], v[80:81], v[150:151]
	s_waitcnt lgkmcnt(6)
	v_pk_mul_f32 v[154:155], v[112:113], v[82:83]
	ds_read_b128 v[100:103], v61 offset:40960
	v_pk_fma_f32 v[154:155], v[114:115], v[80:81], v[154:155]
	v_pk_fma_f32 v[152:153], v[106:107], v[80:81], v[152:153]
	ds_read_b128 v[104:107], v61 offset:45056
	s_waitcnt lgkmcnt(7)
	v_pk_mul_f32 v[156:157], v[116:117], v[82:83]
	v_pk_fma_f32 v[156:157], v[118:119], v[80:81], v[156:157]
	s_waitcnt lgkmcnt(6)
	v_pk_mul_f32 v[158:159], v[120:121], v[82:83]
	ds_read_b128 v[108:111], v61 offset:49152
	v_pk_fma_f32 v[158:159], v[122:123], v[80:81], v[158:159]
	ds_read_b128 v[112:115], v61 offset:53248
	s_waitcnt lgkmcnt(7)
	v_pk_mul_f32 v[160:161], v[124:125], v[82:83]
	v_pk_fma_f32 v[160:161], v[126:127], v[80:81], v[160:161]
	s_waitcnt lgkmcnt(6)
	v_pk_mul_f32 v[162:163], v[128:129], v[82:83]
	ds_read_b128 v[116:119], v61 offset:57344
	v_pk_fma_f32 v[162:163], v[130:131], v[80:81], v[162:163]
	ds_read_b128 v[120:123], v61 offset:61440
	s_waitcnt lgkmcnt(7)
	v_pk_mul_f32 v[164:165], v[132:133], v[82:83]
	v_pk_fma_f32 v[164:165], v[134:135], v[80:81], v[164:165]
	s_waitcnt lgkmcnt(6)
	v_pk_mul_f32 v[168:169], v[136:137], v[82:83]
	ds_read_b128 v[124:127], v61 offset:1024
	v_pk_fma_f32 v[168:169], v[138:139], v[80:81], v[168:169]
	ds_read_b128 v[128:131], v61 offset:5120
	s_waitcnt lgkmcnt(7)
	v_pk_mul_f32 v[170:171], v[100:101], v[82:83]
	v_pk_fma_f32 v[170:171], v[102:103], v[80:81], v[170:171]
	s_waitcnt lgkmcnt(6)
	v_pk_mul_f32 v[172:173], v[104:105], v[82:83]
	ds_read_b128 v[132:135], v61 offset:9216
	v_pk_fma_f32 v[172:173], v[106:107], v[80:81], v[172:173]
	ds_read_b128 v[136:139], v61 offset:13312
	s_waitcnt lgkmcnt(7)
	v_pk_mul_f32 v[174:175], v[108:109], v[82:83]
	v_pk_fma_f32 v[174:175], v[110:111], v[80:81], v[174:175]
	s_waitcnt lgkmcnt(6)
	v_pk_mul_f32 v[176:177], v[112:113], v[82:83]
	ds_read_b128 v[100:103], v61 offset:17408
	v_pk_fma_f32 v[176:177], v[114:115], v[80:81], v[176:177]
	ds_read_b128 v[104:107], v61 offset:21504
	s_waitcnt lgkmcnt(7)
	v_pk_mul_f32 v[178:179], v[116:117], v[82:83]
	v_pk_fma_f32 v[178:179], v[118:119], v[80:81], v[178:179]
	s_waitcnt lgkmcnt(6)
	v_pk_mul_f32 v[180:181], v[120:121], v[82:83]
	v_pk_mul_f32 v[44:45], v[44:45], v[60:61] op_sel_hi:[1,0]
	v_pk_mul_f32 v[68:69], v[12:13], v[44:45]
	v_pk_mul_f32 v[72:73], v[10:11], v[42:43]
	v_pk_fma_f32 v[180:181], v[122:123], v[80:81], v[180:181]
	v_cvt_pk_bf16_f32 v46, v72, v73
	v_cvt_pk_bf16_f32 v47, v68, v69
	ds_read_b128 v[108:111], v61 offset:25600
	global_store_dwordx2 v[58:59], v[46:47], off offset:512
	ds_read_b128 v[112:115], v61 offset:29696
	s_waitcnt lgkmcnt(7)
	v_pk_fma_f32 v[148:149], v[124:125], v[72:73], v[148:149]
	v_pk_fma_f32 v[148:149], v[126:127], v[68:69], v[148:149]
	s_waitcnt lgkmcnt(6)
; #define LAS __attribute__((address_space(3)))
; __device__ __forceinline__ unsigned cvt_pk_bf16(float lo, float hi) { unsigned r; asm volatile("v_cvt_pk_bf16_f32 %0, %1, %2" : "=v"(r) : "v"(lo), "v"(hi)); return r; }
; __device__ void phase_norm_alow(const Params& P, int l, int half, LAS unsigned char* lds) {
;     ...
;         for (int i = 0; i < 4; ++i) { f32x4 h = v[i] * r * gv[i];
;             u32x2 w; w.x = cvt_pk_bf16(h[0], h[1]); w.y = cvt_pk_bf16(h[2], h[3]);
;             *(u32x2*)(H + (size_t)row * DM + i * 256 + lane * 4) = w;
; #pragma unroll
;             for (int c = 0; c < 16; ++c) { const f32x4 wv = *(const LAS f32x4*)(WaT + c * 1024 + i * 256 + lane * 4); a[c] += h[0] * wv[0] + h[1] * wv[1] + h[2] * wv[2] + h[3] * wv[3]; } }
	v_pk_fma_f32 v[152:153], v[128:129], v[72:73], v[152:153]
	ds_read_b128 v[116:119], v61 offset:33792
	v_pk_fma_f32 v[152:153], v[130:131], v[68:69], v[152:153]
	ds_read_b128 v[120:123], v61 offset:37888
	s_waitcnt lgkmcnt(7)
	v_pk_fma_f32 v[150:151], v[132:133], v[72:73], v[150:151]
	v_pk_fma_f32 v[150:151], v[134:135], v[68:69], v[150:151]
	s_waitcnt lgkmcnt(6)
	v_pk_fma_f32 v[154:155], v[136:137], v[72:73], v[154:155]
	ds_read_b128 v[124:127], v61 offset:41984
	v_pk_fma_f32 v[154:155], v[138:139], v[68:69], v[154:155]
	ds_read_b128 v[128:131], v61 offset:46080
	s_waitcnt lgkmcnt(7)
	v_pk_fma_f32 v[156:157], v[100:101], v[72:73], v[156:157]
	v_pk_fma_f32 v[156:157], v[102:103], v[68:69], v[156:157]
	s_waitcnt lgkmcnt(6)
	v_pk_fma_f32 v[158:159], v[104:105], v[72:73], v[158:159]
	ds_read_b128 v[132:135], v61 offset:50176
	v_pk_fma_f32 v[158:159], v[106:107], v[68:69], v[158:159]
	ds_read_b128 v[136:139], v61 offset:54272
	s_waitcnt lgkmcnt(7)
	v_pk_fma_f32 v[160:161], v[108:109], v[72:73], v[160:161]
	v_pk_fma_f32 v[160:161], v[110:111], v[68:69], v[160:161]
	s_waitcnt lgkmcnt(6)
	v_pk_fma_f32 v[162:163], v[112:113], v[72:73], v[162:163]
	ds_read_b128 v[100:103], v61 offset:58368
	v_pk_fma_f32 v[162:163], v[114:115], v[68:69], v[162:163]
	ds_read_b128 v[104:107], v61 offset:62464
	s_waitcnt lgkmcnt(7)
	v_pk_fma_f32 v[164:165], v[116:117], v[72:73], v[164:165]
	v_pk_fma_f32 v[164:165], v[118:119], v[68:69], v[164:165]
	s_waitcnt lgkmcnt(6)
	v_pk_fma_f32 v[168:169], v[120:121], v[72:73], v[168:169]
	ds_read_b128 v[108:111], v61 offset:2048
	v_pk_fma_f32 v[168:169], v[122:123], v[68:69], v[168:169]
	ds_read_b128 v[112:115], v61 offset:6144
	s_waitcnt lgkmcnt(7)
	v_pk_fma_f32 v[170:171], v[124:125], v[72:73], v[170:171]
	v_pk_fma_f32 v[170:171], v[126:127], v[68:69], v[170:171]
	s_waitcnt lgkmcnt(6)
	v_pk_fma_f32 v[172:173], v[128:129], v[72:73], v[172:173]
	ds_read_b128 v[116:119], v61 offset:10240
	v_pk_fma_f32 v[172:173], v[130:131], v[68:69], v[172:173]
	ds_read_b128 v[120:123], v61 offset:14336
	s_waitcnt lgkmcnt(7)
	v_pk_fma_f32 v[174:175], v[132:133], v[72:73], v[174:175]
	v_pk_fma_f32 v[174:175], v[134:135], v[68:69], v[174:175]
	s_waitcnt lgkmcnt(6)
	v_pk_fma_f32 v[176:177], v[136:137], v[72:73], v[176:177]
	ds_read_b128 v[124:127], v61 offset:18432
	v_pk_fma_f32 v[176:177], v[138:139], v[68:69], v[176:177]
	ds_read_b128 v[128:131], v61 offset:22528
	s_waitcnt lgkmcnt(7)
	v_pk_fma_f32 v[178:179], v[100:101], v[72:73], v[178:179]
	v_pk_fma_f32 v[178:179], v[102:103], v[68:69], v[178:179]
	s_waitcnt lgkmcnt(6)
	v_pk_fma_f32 v[180:181], v[104:105], v[72:73], v[180:181]
	v_pk_mul_f32 v[38:39], v[38:39], v[60:61] op_sel_hi:[1,0]
	v_pk_mul_f32 v[40:41], v[40:41], v[60:61] op_sel_hi:[1,0]
	v_pk_mul_f32 v[46:47], v[8:9], v[40:41]
	v_pk_mul_f32 v[70:71], v[6:7], v[38:39]
	v_pk_fma_f32 v[180:181], v[106:107], v[68:69], v[180:181]
	v_cvt_pk_bf16_f32 v42, v70, v71
	v_cvt_pk_bf16_f32 v43, v46, v47
	ds_read_b128 v[132:135], v61 offset:26624
	global_store_dwordx2 v[58:59], v[42:43], off offset:1024
	ds_read_b128 v[136:139], v61 offset:30720
	s_waitcnt lgkmcnt(7)
	v_pk_fma_f32 v[148:149], v[108:109], v[70:71], v[148:149]
	v_pk_fma_f32 v[148:149], v[110:111], v[46:47], v[148:149]
	s_waitcnt lgkmcnt(6)
	v_pk_fma_f32 v[152:153], v[112:113], v[70:71], v[152:153]
	ds_read_b128 v[100:103], v61 offset:34816
	v_pk_fma_f32 v[152:153], v[114:115], v[46:47], v[152:153]
	ds_read_b128 v[104:107], v61 offset:38912
	s_waitcnt lgkmcnt(7)
	v_pk_fma_f32 v[150:151], v[116:117], v[70:71], v[150:151]
	v_pk_fma_f32 v[150:151], v[118:119], v[46:47], v[150:151]
	s_waitcnt lgkmcnt(6)
	v_pk_fma_f32 v[154:155], v[120:121], v[70:71], v[154:155]
	ds_read_b128 v[108:111], v61 offset:43008
	v_pk_fma_f32 v[154:155], v[122:123], v[46:47], v[154:155]
	ds_read_b128 v[112:115], v61 offset:47104
	s_waitcnt lgkmcnt(7)
	v_pk_fma_f32 v[156:157], v[124:125], v[70:71], v[156:157]
	v_pk_fma_f32 v[156:157], v[126:127], v[46:47], v[156:157]
	s_waitcnt lgkmcnt(6)
	v_pk_fma_f32 v[158:159], v[128:129], v[70:71], v[158:159]
	ds_read_b128 v[116:119], v61 offset:51200
	v_pk_fma_f32 v[158:159], v[130:131], v[46:47], v[158:159]
	ds_read_b128 v[120:123], v61 offset:55296
	s_waitcnt lgkmcnt(7)
	v_pk_fma_f32 v[160:161], v[132:133], v[70:71], v[160:161]
	v_pk_fma_f32 v[160:161], v[134:135], v[46:47], v[160:161]
	s_waitcnt lgkmcnt(6)
	v_pk_fma_f32 v[162:163], v[136:137], v[70:71], v[162:163]
	ds_read_b128 v[124:127], v61 offset:59392
	v_pk_fma_f32 v[162:163], v[138:139], v[46:47], v[162:163]
	ds_read_b128 v[128:131], v61 offset:63488
	s_waitcnt lgkmcnt(7)
	v_pk_fma_f32 v[164:165], v[100:101], v[70:71], v[164:165]
	v_pk_fma_f32 v[164:165], v[102:103], v[46:47], v[164:165]
	s_waitcnt lgkmcnt(6)
	v_pk_fma_f32 v[168:169], v[104:105], v[70:71], v[168:169]
	ds_read_b128 v[132:135], v61 offset:3072
	v_pk_fma_f32 v[168:169], v[106:107], v[46:47], v[168:169]
	ds_read_b128 v[136:139], v61 offset:7168
	s_waitcnt lgkmcnt(7)
	v_pk_fma_f32 v[170:171], v[108:109], v[70:71], v[170:171]
	v_pk_fma_f32 v[170:171], v[110:111], v[46:47], v[170:171]
	s_waitcnt lgkmcnt(6)
	v_pk_fma_f32 v[172:173], v[112:113], v[70:71], v[172:173]
	ds_read_b128 v[100:103], v61 offset:11264
	v_pk_fma_f32 v[172:173], v[114:115], v[46:47], v[172:173]
	ds_read_b128 v[104:107], v61 offset:15360
	s_waitcnt lgkmcnt(7)
	v_pk_fma_f32 v[174:175], v[116:117], v[70:71], v[174:175]
	v_pk_fma_f32 v[174:175], v[118:119], v[46:47], v[174:175]
	s_waitcnt lgkmcnt(6)
	v_pk_fma_f32 v[176:177], v[120:121], v[70:71], v[176:177]
	ds_read_b128 v[108:111], v61 offset:19456
	v_pk_fma_f32 v[176:177], v[122:123], v[46:47], v[176:177]
	ds_read_b128 v[112:115], v61 offset:23552
	s_waitcnt lgkmcnt(7)
; #define LAS __attribute__((address_space(3)))
; __device__ __forceinline__ unsigned cvt_pk_bf16(float lo, float hi) { unsigned r; asm volatile("v_cvt_pk_bf16_f32 %0, %1, %2" : "=v"(r) : "v"(lo), "v"(hi)); return r; }
; __device__ void phase_norm_alow(const Params& P, int l, int half, LAS unsigned char* lds) {
;     ...
;         for (int i = 0; i < 4; ++i) { f32x4 h = v[i] * r * gv[i];
;             u32x2 w; w.x = cvt_pk_bf16(h[0], h[1]); w.y = cvt_pk_bf16(h[2], h[3]);
;             *(u32x2*)(H + (size_t)row * DM + i * 256 + lane * 4) = w;
; #pragma unroll
;             for (int c = 0; c < 16; ++c) { const f32x4 wv = *(const LAS f32x4*)(WaT + c * 1024 + i * 256 + lane * 4); a[c] += h[0] * wv[0] + h[1] * wv[1] + h[2] * wv[2] + h[3] * wv[3]; } }
;         float b8[8], b4[4], b2[2], b1;
;         { const bool up = (lane & 32) != 0;
; #pragma unroll
;           for (int c = 0; c < 8; ++c) { const float keep = up ? a[c + 8] : a[c], send = up ? a[c] : a[c + 8]; b8[c] = keep + __shfl_xor(send, 32); } }
;         { const bool up = (lane & 16) != 0;
; #pragma unroll
;           for (int c = 0; c < 4; ++c) { const float keep = up ? b8[c + 4] : b8[c], send = up ? b8[c] : b8[c + 4]; b4[c] = keep + __shfl_xor(send, 16); } }
;         { const bool up = (lane & 8) != 0;
; #pragma unroll
;           for (int c = 0; c < 2; ++c) { const float keep = up ? b4[c + 2] : b4[c], send = up ? b4[c] : b4[c + 2]; b2[c] = keep + __shfl_xor(send, 8); } }
;         { const bool up = (lane & 4) != 0; const float keep = up ? b2[1] : b2[0], send = up ? b2[0] : b2[1]; b1 = keep + __shfl_xor(send, 4); }
;         b1 += __shfl_xor(b1, 2); b1 += __shfl_xor(b1, 1);
;         if ((lane & 3) == 0) { const int co = ((lane >> 5) & 1) * 8 + ((lane >> 4) & 1) * 4 + ((lane >> 3) & 1) * 2 + ((lane >> 2) & 1); AL[(size_t)row * 16 + co] = b1; }
	v_pk_fma_f32 v[178:179], v[124:125], v[70:71], v[178:179]
	v_pk_fma_f32 v[178:179], v[126:127], v[46:47], v[178:179]
	v_pk_mul_f32 v[34:35], v[34:35], v[60:61] op_sel_hi:[1,0]
	v_pk_mul_f32 v[36:37], v[36:37], v[60:61] op_sel_hi:[1,0]
	s_waitcnt lgkmcnt(6)
	v_pk_fma_f32 v[180:181], v[128:129], v[70:71], v[180:181]
	v_pk_mul_f32 v[48:49], v[4:5], v[36:37]
	v_pk_mul_f32 v[68:69], v[2:3], v[34:35]
	v_cvt_pk_bf16_f32 v34, v68, v69
	v_cvt_pk_bf16_f32 v35, v48, v49
	ds_read_b128 v[116:119], v61 offset:27648
	v_pk_fma_f32 v[180:181], v[130:131], v[46:47], v[180:181]
	ds_read_b128 v[120:123], v61 offset:31744
	s_waitcnt lgkmcnt(7)
	v_pk_fma_f32 v[148:149], v[132:133], v[68:69], v[148:149]
	v_pk_fma_f32 v[148:149], v[134:135], v[48:49], v[148:149]
	v_add_f32_e32 v45, v148, v149
	s_waitcnt lgkmcnt(6)
	v_pk_fma_f32 v[152:153], v[136:137], v[68:69], v[152:153]
	ds_read_b128 v[124:127], v61 offset:35840
	v_pk_fma_f32 v[152:153], v[138:139], v[48:49], v[152:153]
	v_add_f32_e32 v46, v152, v153
	ds_read_b128 v[128:131], v61 offset:39936
	s_waitcnt lgkmcnt(7)
	v_pk_fma_f32 v[150:151], v[100:101], v[68:69], v[150:151]
	v_pk_fma_f32 v[150:151], v[102:103], v[48:49], v[150:151]
	v_add_f32_e32 v47, v150, v151
	s_waitcnt lgkmcnt(6)
	v_pk_fma_f32 v[154:155], v[104:105], v[68:69], v[154:155]
	ds_read_b128 v[132:135], v61 offset:44032
	v_pk_fma_f32 v[154:155], v[106:107], v[48:49], v[154:155]
	v_add_f32_e32 v51, v154, v155
	ds_read_b128 v[136:139], v61 offset:48128
	s_waitcnt lgkmcnt(7)
	v_pk_fma_f32 v[156:157], v[108:109], v[68:69], v[156:157]
	v_pk_fma_f32 v[156:157], v[110:111], v[48:49], v[156:157]
	v_add_f32_e32 v60, v156, v157
	s_waitcnt lgkmcnt(6)
	v_pk_fma_f32 v[158:159], v[112:113], v[68:69], v[158:159]
	ds_read_b128 v[100:103], v61 offset:52224
	v_pk_fma_f32 v[158:159], v[114:115], v[48:49], v[158:159]
	v_add_f32_e32 v70, v158, v159
	ds_read_b128 v[104:107], v61 offset:56320
	s_waitcnt lgkmcnt(7)
	v_pk_fma_f32 v[160:161], v[116:117], v[68:69], v[160:161]
	v_pk_fma_f32 v[160:161], v[118:119], v[48:49], v[160:161]
	v_add_f32_e32 v71, v160, v161
	s_waitcnt lgkmcnt(6)
	v_pk_fma_f32 v[162:163], v[120:121], v[68:69], v[162:163]
	ds_read_b128 v[108:111], v61 offset:60416
	v_pk_fma_f32 v[162:163], v[122:123], v[48:49], v[162:163]
	v_add_f32_e32 v72, v162, v163
	ds_read_b128 v[112:115], v61 offset:64512
	s_waitcnt lgkmcnt(7)
	v_pk_fma_f32 v[164:165], v[124:125], v[68:69], v[164:165]
	v_pk_fma_f32 v[164:165], v[126:127], v[48:49], v[164:165]
	v_add_f32_e32 v73, v164, v165
	s_waitcnt lgkmcnt(6)
	v_pk_fma_f32 v[168:169], v[128:129], v[68:69], v[168:169]
	v_pk_fma_f32 v[168:169], v[130:131], v[48:49], v[168:169]
	v_add_f32_e32 v74, v168, v169
	s_waitcnt lgkmcnt(5)
	v_pk_fma_f32 v[170:171], v[132:133], v[68:69], v[170:171]
	v_pk_fma_f32 v[170:171], v[134:135], v[48:49], v[170:171]
	v_add_f32_e32 v75, v170, v171
	s_waitcnt lgkmcnt(4)
	v_pk_fma_f32 v[172:173], v[136:137], v[68:69], v[172:173]
	v_pk_fma_f32 v[172:173], v[138:139], v[48:49], v[172:173]
	v_add_f32_e32 v76, v172, v173
	s_waitcnt lgkmcnt(3)
	v_pk_fma_f32 v[174:175], v[100:101], v[68:69], v[174:175]
	v_pk_fma_f32 v[174:175], v[102:103], v[48:49], v[174:175]
	v_add_f32_e32 v77, v174, v175
	s_waitcnt lgkmcnt(2)
	v_pk_fma_f32 v[176:177], v[104:105], v[68:69], v[176:177]
	v_pk_fma_f32 v[176:177], v[106:107], v[48:49], v[176:177]
	v_add_f32_e32 v78, v176, v177
	s_waitcnt lgkmcnt(1)
	v_pk_fma_f32 v[178:179], v[108:109], v[68:69], v[178:179]
	v_pk_fma_f32 v[178:179], v[110:111], v[48:49], v[178:179]
	v_add_f32_e32 v36, v178, v179
	s_waitcnt lgkmcnt(0)
	v_pk_fma_f32 v[180:181], v[112:113], v[68:69], v[180:181]
	v_pk_fma_f32 v[180:181], v[114:115], v[48:49], v[180:181]
	v_add_f32_e32 v37, v180, v181
	global_store_dwordx2 v[58:59], v[34:35], off offset:1536
	s_nop 1
	v_permlane32_swap_b32_e32 v45, v73
	s_nop 1
	v_add_f32_e32 v45, v45, v73
	s_nop 1
	v_permlane32_swap_b32_e32 v46, v74
	s_nop 1
	v_add_f32_e32 v46, v46, v74
	s_nop 1
	v_permlane32_swap_b32_e32 v47, v75
	s_nop 1
	v_add_f32_e32 v47, v47, v75
	s_nop 1
	v_permlane32_swap_b32_e32 v51, v76
	s_nop 1
	v_add_f32_e32 v51, v51, v76
	s_nop 1
	v_permlane32_swap_b32_e32 v60, v77
	s_nop 1
	v_add_f32_e32 v60, v60, v77
	s_nop 1
	v_permlane32_swap_b32_e32 v70, v78
	s_nop 1
	v_add_f32_e32 v70, v70, v78
	s_nop 1
	v_permlane32_swap_b32_e32 v71, v36
	s_nop 1
	v_add_f32_e32 v71, v71, v36
	s_nop 1
	v_permlane32_swap_b32_e32 v72, v37
	s_nop 1
	v_add_f32_e32 v72, v72, v37
	s_nop 1
	v_permlane16_swap_b32_e32 v45, v60
	s_nop 1
	v_add_f32_e32 v45, v45, v60
	s_nop 1
	v_permlane16_swap_b32_e32 v46, v70
	s_nop 1
	v_add_f32_e32 v46, v46, v70
	s_nop 1
	v_permlane16_swap_b32_e32 v47, v71
	s_nop 1
	v_add_f32_e32 v47, v47, v71
	s_nop 1
	v_permlane16_swap_b32_e32 v51, v72
	s_nop 1
	v_add_f32_e32 v51, v51, v72
	s_nop 1
	v_add_f32_dpp v45, v45, v45 row_ror:8 row_mask:0xf bank_mask:0x3
	s_nop 1
	v_add_f32_dpp v45, v47, v47 row_ror:8 row_mask:0xf bank_mask:0xc
	s_nop 1
	v_add_f32_dpp v46, v46, v46 row_ror:8 row_mask:0xf bank_mask:0x3
	s_nop 1
	v_add_f32_dpp v46, v51, v51 row_ror:8 row_mask:0xf bank_mask:0xc
	s_nop 1
	v_add_f32_dpp v45, v45, v45 row_shl:4 row_mask:0xf bank_mask:0x5
	s_nop 1
	v_add_f32_dpp v45, v46, v46 row_shr:4 row_mask:0xf bank_mask:0xa
	v_mov_b32_e32 v36, v45
	s_nop 0
	s_nop 1
	v_mov_b32_dpp v37, v36 quad_perm:[2,3,0,1] row_mask:0xf bank_mask:0xf
	v_add_f32_e32 v36, v36, v37
	s_nop 1
	v_mov_b32_dpp v37, v36 quad_perm:[1,0,3,2] row_mask:0xf bank_mask:0xf
	s_and_saveexec_b64 s[0:1], s[42:43]
	s_cbranch_execz .LBB0_752
	v_lshl_add_u64 v[34:35], s[74:75], 0, v[56:57]
	v_add_f32_e32 v36, v36, v37
	global_store_dword v[34:35], v36, off
	s_branch .LBB0_752
